# GEMM mainloops: loop-head scalar pointer-select block moved from the first load section into the MFMA burst behind it
# baseline (speedup 1.0000x reference)
.LBB0_413:
	ds_read_b128 v[128:131], v171
	ds_read_b128 v[132:135], v171 offset:1024
	ds_read_b128 v[136:139], v171 offset:2048
	ds_read_b128 v[152:155], v171 offset:3072
	v_lshl_add_u64 v[194:195], s[22:23], 0, v[144:145]
	s_add_i32 m0, s31, 0xc000
	ds_read_b128 v[156:159], v172
	ds_read_b128 v[160:163], v172 offset:1024
	ds_read_b128 v[164:167], v172 offset:2048
	ds_read_b128 v[174:177], v172 offset:3072
	ds_read_b128 v[178:181], v172 offset:4096
	ds_read_b128 v[182:185], v172 offset:5120
	ds_read_b128 v[186:189], v172 offset:6144
	ds_read_b128 v[190:193], v172 offset:7168
	global_load_lds_dwordx4 v[194:195], off
	v_lshl_add_u64 v[194:195], s[22:23], 0, v[146:147]
	s_add_i32 m0, s31, 0xe000
	s_nop 0
	global_load_lds_dwordx4 v[194:195], off
	s_waitcnt lgkmcnt(8)
	s_barrier
	s_waitcnt lgkmcnt(0)
	s_waitcnt lgkmcnt(0)
	v_mfma_f32_16x16x32_bf16 v[124:127], v[128:131], v[156:159], v[124:127]
	s_add_u32 s24, s22, 0x100
	s_addc_u32 s25, s23, 0
	s_cmp_eq_u32 s65, 28
	s_cselect_b32 s29, s13, s25
	s_cselect_b32 s28, s61, s24
	s_cselect_b32 s27, s11, s64
	s_cselect_b32 s26, s62, s63
	v_mfma_f32_16x16x32_bf16 v[120:123], v[136:139], v[156:159], v[120:123]
	v_mfma_f32_16x16x32_bf16 v[116:119], v[128:131], v[164:167], v[116:119]
	v_mfma_f32_16x16x32_bf16 v[112:115], v[136:139], v[164:167], v[112:115]
	v_mfma_f32_16x16x32_bf16 v[108:111], v[128:131], v[178:181], v[108:111]
	v_mfma_f32_16x16x32_bf16 v[104:107], v[136:139], v[178:181], v[104:107]
	v_mfma_f32_16x16x32_bf16 v[100:103], v[128:131], v[186:189], v[100:103]
	v_mfma_f32_16x16x32_bf16 v[96:99], v[136:139], v[186:189], v[96:99]
	v_mfma_f32_16x16x32_bf16 v[124:127], v[132:135], v[160:163], v[124:127]
	v_mfma_f32_16x16x32_bf16 v[120:123], v[152:155], v[160:163], v[120:123]
	v_mfma_f32_16x16x32_bf16 v[116:119], v[132:135], v[174:177], v[116:119]
	v_mfma_f32_16x16x32_bf16 v[112:115], v[152:155], v[174:177], v[112:115]
	v_mfma_f32_16x16x32_bf16 v[108:111], v[132:135], v[182:185], v[108:111]
	v_mfma_f32_16x16x32_bf16 v[104:107], v[152:155], v[182:185], v[104:107]
	v_mfma_f32_16x16x32_bf16 v[100:103], v[132:135], v[190:193], v[100:103]
	v_mfma_f32_16x16x32_bf16 v[96:99], v[152:155], v[190:193], v[96:99]
	s_barrier
	s_add_i32 s22, s47, s2
	v_lshl_add_u64 v[210:211], s[26:27], 0, v[142:143]
	s_mov_b32 m0, s22
	ds_read_b128 v[194:197], v173
	ds_read_b128 v[198:201], v173 offset:1024
	ds_read_b128 v[202:205], v173 offset:2048
	ds_read_b128 v[206:209], v173 offset:3072
	global_load_lds_dwordx4 v[210:211], off
	v_lshl_add_u64 v[212:213], s[26:27], 0, v[140:141]
	s_add_i32 m0, s22, 0x2000
	s_nop 0
	global_load_lds_dwordx4 v[212:213], off
	s_barrier
	s_waitcnt lgkmcnt(0)
	s_waitcnt lgkmcnt(0)
	v_mfma_f32_16x16x32_bf16 v[64:67], v[194:197], v[156:159], v[64:67]
	v_mfma_f32_16x16x32_bf16 v[68:71], v[202:205], v[156:159], v[68:71]
	v_mfma_f32_16x16x32_bf16 v[48:51], v[194:197], v[164:167], v[48:51]
	v_mfma_f32_16x16x32_bf16 v[52:55], v[202:205], v[164:167], v[52:55]
	v_mfma_f32_16x16x32_bf16 v[40:43], v[194:197], v[178:181], v[40:43]
	v_mfma_f32_16x16x32_bf16 v[44:47], v[202:205], v[178:181], v[44:47]
	v_mfma_f32_16x16x32_bf16 v[32:35], v[194:197], v[186:189], v[32:35]
	v_mfma_f32_16x16x32_bf16 v[36:39], v[202:205], v[186:189], v[36:39]
	v_mfma_f32_16x16x32_bf16 v[64:67], v[198:201], v[160:163], v[64:67]
	v_mfma_f32_16x16x32_bf16 v[68:71], v[206:209], v[160:163], v[68:71]
	v_mfma_f32_16x16x32_bf16 v[48:51], v[198:201], v[174:177], v[48:51]
	v_mfma_f32_16x16x32_bf16 v[52:55], v[206:209], v[174:177], v[52:55]
	v_mfma_f32_16x16x32_bf16 v[40:43], v[198:201], v[182:185], v[40:43]
	v_mfma_f32_16x16x32_bf16 v[44:47], v[206:209], v[182:185], v[44:47]
	v_mfma_f32_16x16x32_bf16 v[32:35], v[198:201], v[190:193], v[32:35]
	v_mfma_f32_16x16x32_bf16 v[36:39], v[206:209], v[190:193], v[36:39]
	s_mov_b32 m0, s31
	v_lshl_add_u64 v[214:215], s[28:29], 0, v[142:143]
	s_barrier
	ds_read_b128 v[156:159], v172 offset:16384
	ds_read_b128 v[160:163], v172 offset:17408
	ds_read_b128 v[164:167], v172 offset:18432
	ds_read_b128 v[174:177], v172 offset:19456
	ds_read_b128 v[178:181], v172 offset:20480
	ds_read_b128 v[182:185], v172 offset:21504
	ds_read_b128 v[186:189], v172 offset:22528
	ds_read_b128 v[190:193], v172 offset:23552
	global_load_lds_dwordx4 v[214:215], off
	v_lshl_add_u64 v[216:217], s[28:29], 0, v[140:141]
	s_mov_b32 m0, s34
	s_nop 0
	global_load_lds_dwordx4 v[216:217], off
	s_barrier
	s_waitcnt lgkmcnt(0)
	s_waitcnt lgkmcnt(0)
	v_mfma_f32_16x16x32_bf16 v[92:95], v[128:131], v[156:159], v[92:95]
	v_mfma_f32_16x16x32_bf16 v[88:91], v[136:139], v[156:159], v[88:91]
	v_mfma_f32_16x16x32_bf16 v[84:87], v[128:131], v[164:167], v[84:87]
	v_mfma_f32_16x16x32_bf16 v[80:83], v[136:139], v[164:167], v[80:83]
	v_mfma_f32_16x16x32_bf16 v[76:79], v[128:131], v[178:181], v[76:79]
	v_mfma_f32_16x16x32_bf16 v[72:75], v[136:139], v[178:181], v[72:75]
	v_mfma_f32_16x16x32_bf16 v[60:63], v[128:131], v[186:189], v[60:63]
	v_mfma_f32_16x16x32_bf16 v[56:59], v[136:139], v[186:189], v[56:59]
	v_mfma_f32_16x16x32_bf16 v[92:95], v[132:135], v[160:163], v[92:95]
	v_mfma_f32_16x16x32_bf16 v[88:91], v[152:155], v[160:163], v[88:91]
	v_mfma_f32_16x16x32_bf16 v[84:87], v[132:135], v[174:177], v[84:87]
	v_mfma_f32_16x16x32_bf16 v[80:83], v[152:155], v[174:177], v[80:83]
	v_mfma_f32_16x16x32_bf16 v[76:79], v[132:135], v[182:185], v[76:79]
	v_mfma_f32_16x16x32_bf16 v[72:75], v[152:155], v[182:185], v[72:75]
	v_mfma_f32_16x16x32_bf16 v[60:63], v[132:135], v[190:193], v[60:63]
	v_mfma_f32_16x16x32_bf16 v[56:59], v[152:155], v[190:193], v[56:59]
	s_barrier
	s_add_u32 s22, s26, 0x80000
	s_addc_u32 s23, s27, 0
	s_add_i32 s66, s60, s2
	v_lshl_add_u64 v[128:129], s[22:23], 0, v[142:143]
	s_mov_b32 m0, s66
	s_nop 0
	global_load_lds_dwordx4 v[128:129], off
	v_lshl_add_u64 v[128:129], s[22:23], 0, v[140:141]
	s_add_i32 m0, s66, 0x2000
	s_nop 0
	global_load_lds_dwordx4 v[128:129], off
	s_waitcnt vmcnt(6)
	s_barrier
	v_mfma_f32_16x16x32_bf16 v[24:27], v[194:197], v[156:159], v[24:27]
	v_mfma_f32_16x16x32_bf16 v[28:31], v[202:205], v[156:159], v[28:31]
	v_mfma_f32_16x16x32_bf16 v[16:19], v[194:197], v[164:167], v[16:19]
	v_mfma_f32_16x16x32_bf16 v[20:23], v[202:205], v[164:167], v[20:23]
	v_mfma_f32_16x16x32_bf16 v[8:11], v[194:197], v[178:181], v[8:11]
	v_mfma_f32_16x16x32_bf16 v[12:15], v[202:205], v[178:181], v[12:15]
	v_mfma_f32_16x16x32_bf16 v[4:7], v[194:197], v[186:189], v[4:7]
	v_mfma_f32_16x16x32_bf16 v[0:3], v[202:205], v[186:189], v[0:3]
	v_mfma_f32_16x16x32_bf16 v[24:27], v[198:201], v[160:163], v[24:27]
	v_mfma_f32_16x16x32_bf16 v[28:31], v[206:209], v[160:163], v[28:31]
	v_mfma_f32_16x16x32_bf16 v[16:19], v[198:201], v[174:177], v[16:19]
	v_mfma_f32_16x16x32_bf16 v[20:23], v[206:209], v[174:177], v[20:23]
	v_mfma_f32_16x16x32_bf16 v[8:11], v[198:201], v[182:185], v[8:11]
	v_mfma_f32_16x16x32_bf16 v[12:15], v[206:209], v[182:185], v[12:15]
	v_mfma_f32_16x16x32_bf16 v[4:7], v[198:201], v[190:193], v[4:7]
	v_mfma_f32_16x16x32_bf16 v[0:3], v[206:209], v[190:193], v[0:3]
	s_add_i32 s66, 0, 0x18000
	v_add_u32_e32 v152, s66, v169
	s_barrier
	ds_read_b128 v[128:131], v152
	ds_read_b128 v[132:135], v152 offset:1024
	ds_read_b128 v[136:139], v152 offset:2048
	ds_read_b128 v[152:155], v152 offset:3072
	s_add_u32 s22, s28, 0x80000
	s_addc_u32 s23, s29, 0
	s_mov_b32 m0, s35
	v_lshl_add_u64 v[194:195], s[22:23], 0, v[142:143]
	ds_read_b128 v[156:159], v172 offset:32768
	ds_read_b128 v[160:163], v172 offset:33792
	ds_read_b128 v[164:167], v172 offset:34816
	ds_read_b128 v[174:177], v172 offset:35840
	ds_read_b128 v[178:181], v172 offset:36864
	ds_read_b128 v[182:185], v172 offset:37888
	ds_read_b128 v[186:189], v172 offset:38912
	ds_read_b128 v[190:193], v172 offset:39936
	global_load_lds_dwordx4 v[194:195], off
	v_lshl_add_u64 v[194:195], s[22:23], 0, v[140:141]
	s_mov_b32 m0, s36
	s_nop 0
	global_load_lds_dwordx4 v[194:195], off
	s_waitcnt lgkmcnt(8)
	s_barrier
	s_waitcnt lgkmcnt(0)
	s_waitcnt lgkmcnt(0)
	v_mfma_f32_16x16x32_bf16 v[124:127], v[128:131], v[156:159], v[124:127]
	v_mfma_f32_16x16x32_bf16 v[120:123], v[136:139], v[156:159], v[120:123]
	v_mfma_f32_16x16x32_bf16 v[116:119], v[128:131], v[164:167], v[116:119]
	v_mfma_f32_16x16x32_bf16 v[112:115], v[136:139], v[164:167], v[112:115]
	v_mfma_f32_16x16x32_bf16 v[108:111], v[128:131], v[178:181], v[108:111]
	v_mfma_f32_16x16x32_bf16 v[104:107], v[136:139], v[178:181], v[104:107]
	v_mfma_f32_16x16x32_bf16 v[100:103], v[128:131], v[186:189], v[100:103]
	v_mfma_f32_16x16x32_bf16 v[96:99], v[136:139], v[186:189], v[96:99]
	v_mfma_f32_16x16x32_bf16 v[124:127], v[132:135], v[160:163], v[124:127]
	v_mfma_f32_16x16x32_bf16 v[120:123], v[152:155], v[160:163], v[120:123]
	v_mfma_f32_16x16x32_bf16 v[116:119], v[132:135], v[174:177], v[116:119]
	v_mfma_f32_16x16x32_bf16 v[112:115], v[152:155], v[174:177], v[112:115]
	v_mfma_f32_16x16x32_bf16 v[108:111], v[132:135], v[182:185], v[108:111]
	v_mfma_f32_16x16x32_bf16 v[104:107], v[152:155], v[182:185], v[104:107]
	v_mfma_f32_16x16x32_bf16 v[100:103], v[132:135], v[190:193], v[100:103]
	v_mfma_f32_16x16x32_bf16 v[96:99], v[152:155], v[190:193], v[96:99]
	s_barrier
	s_add_i32 s28, 0, 0x1c000
	s_add_i32 s22, s66, s2
	v_add_u32_e32 v206, s28, v169
	v_lshl_add_u64 v[210:211], v[210:211], 0, s[6:7]
	s_mov_b32 m0, s22
	ds_read_b128 v[194:197], v206
	ds_read_b128 v[198:201], v206 offset:1024
	ds_read_b128 v[202:205], v206 offset:2048
	ds_read_b128 v[206:209], v206 offset:3072
	global_load_lds_dwordx4 v[210:211], off
	v_lshl_add_u64 v[210:211], v[212:213], 0, s[6:7]
	s_add_i32 m0, s22, 0x2000
	s_nop 0
	global_load_lds_dwordx4 v[210:211], off
	s_barrier
	s_waitcnt lgkmcnt(0)
	s_waitcnt lgkmcnt(0)
	v_mfma_f32_16x16x32_bf16 v[64:67], v[194:197], v[156:159], v[64:67]
	v_mfma_f32_16x16x32_bf16 v[68:71], v[202:205], v[156:159], v[68:71]
	v_mfma_f32_16x16x32_bf16 v[48:51], v[194:197], v[164:167], v[48:51]
	v_mfma_f32_16x16x32_bf16 v[52:55], v[202:205], v[164:167], v[52:55]
	v_mfma_f32_16x16x32_bf16 v[40:43], v[194:197], v[178:181], v[40:43]
	v_mfma_f32_16x16x32_bf16 v[44:47], v[202:205], v[178:181], v[44:47]
	v_mfma_f32_16x16x32_bf16 v[32:35], v[194:197], v[186:189], v[32:35]
	v_mfma_f32_16x16x32_bf16 v[36:39], v[202:205], v[186:189], v[36:39]
	v_mfma_f32_16x16x32_bf16 v[64:67], v[198:201], v[160:163], v[64:67]
	v_mfma_f32_16x16x32_bf16 v[68:71], v[206:209], v[160:163], v[68:71]
	v_mfma_f32_16x16x32_bf16 v[48:51], v[198:201], v[174:177], v[48:51]
	v_mfma_f32_16x16x32_bf16 v[52:55], v[206:209], v[174:177], v[52:55]
	v_mfma_f32_16x16x32_bf16 v[40:43], v[198:201], v[182:185], v[40:43]
	v_mfma_f32_16x16x32_bf16 v[44:47], v[206:209], v[182:185], v[44:47]
	v_mfma_f32_16x16x32_bf16 v[32:35], v[198:201], v[190:193], v[32:35]
	v_mfma_f32_16x16x32_bf16 v[36:39], v[206:209], v[190:193], v[36:39]
	s_mov_b32 m0, s38
	v_lshl_add_u64 v[210:211], v[214:215], 0, s[6:7]
	s_barrier
	ds_read_b128 v[156:159], v172 offset:49152
	ds_read_b128 v[160:163], v172 offset:50176
	ds_read_b128 v[164:167], v172 offset:51200
	ds_read_b128 v[174:177], v172 offset:52224
	ds_read_b128 v[178:181], v172 offset:53248
	ds_read_b128 v[182:185], v172 offset:54272
	ds_read_b128 v[186:189], v172 offset:55296
	ds_read_b128 v[190:193], v172 offset:56320
	global_load_lds_dwordx4 v[210:211], off
	v_lshl_add_u64 v[210:211], v[216:217], 0, s[6:7]
	s_mov_b32 m0, s39
	s_nop 0
	global_load_lds_dwordx4 v[210:211], off
	s_barrier
	s_waitcnt lgkmcnt(0)
	s_waitcnt lgkmcnt(0)
	v_mfma_f32_16x16x32_bf16 v[92:95], v[128:131], v[156:159], v[92:95]
	v_mfma_f32_16x16x32_bf16 v[88:91], v[136:139], v[156:159], v[88:91]
	v_mfma_f32_16x16x32_bf16 v[84:87], v[128:131], v[164:167], v[84:87]
	v_mfma_f32_16x16x32_bf16 v[80:83], v[136:139], v[164:167], v[80:83]
	v_mfma_f32_16x16x32_bf16 v[76:79], v[128:131], v[178:181], v[76:79]
	v_mfma_f32_16x16x32_bf16 v[72:75], v[136:139], v[178:181], v[72:75]
	v_mfma_f32_16x16x32_bf16 v[60:63], v[128:131], v[186:189], v[60:63]
	v_mfma_f32_16x16x32_bf16 v[56:59], v[136:139], v[186:189], v[56:59]
	v_mfma_f32_16x16x32_bf16 v[92:95], v[132:135], v[160:163], v[92:95]
	v_mfma_f32_16x16x32_bf16 v[88:91], v[152:155], v[160:163], v[88:91]
	v_mfma_f32_16x16x32_bf16 v[84:87], v[132:135], v[174:177], v[84:87]
	v_mfma_f32_16x16x32_bf16 v[80:83], v[152:155], v[174:177], v[80:83]
	v_mfma_f32_16x16x32_bf16 v[76:79], v[132:135], v[182:185], v[76:79]
	v_mfma_f32_16x16x32_bf16 v[72:75], v[152:155], v[182:185], v[72:75]
	v_mfma_f32_16x16x32_bf16 v[60:63], v[132:135], v[190:193], v[60:63]
	v_mfma_f32_16x16x32_bf16 v[56:59], v[152:155], v[190:193], v[56:59]
	s_barrier
	s_add_u32 s22, s26, 0x80080
	s_addc_u32 s23, s27, 0
	s_add_i32 s26, s28, s2
	v_lshl_add_u64 v[128:129], s[22:23], 0, v[142:143]
	s_mov_b32 m0, s26
	s_nop 0
	global_load_lds_dwordx4 v[128:129], off
	v_lshl_add_u64 v[128:129], s[22:23], 0, v[140:141]
	s_add_i32 m0, s26, 0x2000
	s_nop 0
	global_load_lds_dwordx4 v[128:129], off
	s_waitcnt vmcnt(6)
	s_barrier
	v_mfma_f32_16x16x32_bf16 v[24:27], v[194:197], v[156:159], v[24:27]
	v_mfma_f32_16x16x32_bf16 v[28:31], v[202:205], v[156:159], v[28:31]
	v_mfma_f32_16x16x32_bf16 v[16:19], v[194:197], v[164:167], v[16:19]
	v_mfma_f32_16x16x32_bf16 v[20:23], v[202:205], v[164:167], v[20:23]
	v_mfma_f32_16x16x32_bf16 v[8:11], v[194:197], v[178:181], v[8:11]
	v_mfma_f32_16x16x32_bf16 v[12:15], v[202:205], v[178:181], v[12:15]
	v_mfma_f32_16x16x32_bf16 v[4:7], v[194:197], v[186:189], v[4:7]
	v_mfma_f32_16x16x32_bf16 v[0:3], v[202:205], v[186:189], v[0:3]
	v_mfma_f32_16x16x32_bf16 v[24:27], v[198:201], v[160:163], v[24:27]
	v_mfma_f32_16x16x32_bf16 v[28:31], v[206:209], v[160:163], v[28:31]
	v_mfma_f32_16x16x32_bf16 v[16:19], v[198:201], v[174:177], v[16:19]
	v_mfma_f32_16x16x32_bf16 v[20:23], v[206:209], v[174:177], v[20:23]
	v_mfma_f32_16x16x32_bf16 v[8:11], v[198:201], v[182:185], v[8:11]
	v_mfma_f32_16x16x32_bf16 v[12:15], v[206:209], v[182:185], v[12:15]
	v_mfma_f32_16x16x32_bf16 v[4:7], v[198:201], v[190:193], v[4:7]
	v_mfma_f32_16x16x32_bf16 v[0:3], v[206:209], v[190:193], v[0:3]
	s_add_i32 s65, s65, 2
	s_add_u32 s63, s63, 0x100
	s_addc_u32 s64, s64, 0
	s_cmp_gt_u32 s65, 29
	s_mov_b64 s[22:23], s[24:25]
	s_barrier
	s_cbranch_scc0 .LBB0_413
	v_lshl_or_b32 v154, s19, 7, v170
	v_ashrrev_i32_e32 v155, 31, v154
	v_lshlrev_b64 v[184:185], 2, v[154:155]
	v_readlane_b32 s64, v240, 49
	v_lshl_add_u64 v[128:129], s[8:9], 0, v[184:185]
	v_readlane_b32 s72, v240, 57
	v_readlane_b32 s73, v240, 58
	s_nop 1
	v_lshl_add_u64 v[186:187], s[72:73], 0, v[184:185]
	global_load_dwordx4 v[128:131], v[128:129], off
	s_nop 0
	global_load_dwordx4 v[188:191], v[186:187], off
	s_cmp_lt_u32 s18, 32
	s_movk_i32 s11, 0x3000
	s_cselect_b32 s11, s11, 0x6000
	s_cmp_gt_i32 s18, 15
	s_cselect_b32 s11, s11, 0
	v_lshl_add_u32 v166, s18, 8, v168
	s_lshl_b32 s11, s11, 2
	v_readlane_b32 s65, v240, 50
	v_readlane_b32 s66, v240, 51
	v_readlane_b32 s67, v240, 52
	v_readlane_b32 s68, v240, 53
	v_readlane_b32 s69, v240, 54
	v_readlane_b32 s70, v240, 55
	v_readlane_b32 s71, v240, 56
	v_readlane_b32 s74, v240, 59
	v_readlane_b32 s75, v240, 60
	v_readlane_b32 s76, v240, 61
	v_readlane_b32 s77, v240, 62
	v_readlane_b32 s78, v240, 63
	v_readlane_b32 s79, v239, 0
	v_ashrrev_i32_e32 v167, 31, v166
	s_add_u32 s22, s41, s11
	v_lshlrev_b64 v[138:139], 11, v[166:167]
	s_addc_u32 s23, s42, 0
	v_readlane_b32 s64, v239, 3
	v_lshl_add_u64 v[138:139], v[138:139], 0, v[154:155]
	s_nop 1
	v_lshlrev_b64 v[192:193], 2, v[138:139]
	v_lshl_add_u64 v[194:195], s[22:23], 0, v[184:185]
	global_load_dwordx4 v[196:199], v[194:195], off
	s_cmp_lt_i32 s18, 32
	v_readlane_b32 s65, v239, 4
	s_nop 1
	s_cselect_b32 s19, s65, s46
	s_cselect_b32 s18, s64, s43
	s_nop 0
	v_lshl_add_u64 v[184:185], s[18:19], 0, v[192:193]
	global_load_dwordx4 v[200:203], v[184:185], off
	v_readlane_b32 s66, v239, 5
	v_readlane_b32 s67, v239, 6
	v_readlane_b32 s68, v239, 7
	v_readlane_b32 s69, v239, 8
	v_readlane_b32 s70, v239, 9
	v_readlane_b32 s71, v239, 10
	v_readlane_b32 s72, v239, 11
	v_readlane_b32 s73, v239, 12
	v_readlane_b32 s74, v239, 13
	v_readlane_b32 s75, v239, 14
	v_readlane_b32 s76, v239, 15
	v_readlane_b32 s77, v239, 16
	v_readlane_b32 s78, v239, 17
	v_readlane_b32 s79, v239, 18
	v_or_b32_e32 v160, 16, v166
	v_ashrrev_i32_e32 v161, 31, v160
	v_readlane_b32 s64, v240, 22
	v_lshlrev_b64 v[160:161], 11, v[160:161]
	s_nop 1
	v_lshl_add_u64 v[204:205], v[160:161], 0, v[154:155]
	s_nop 1
	v_lshlrev_b64 v[206:207], 2, v[204:205]
	v_lshl_add_u64 v[208:209], s[18:19], 0, v[206:207]
	global_load_dwordx4 v[212:215], v[208:209], off
	v_readlane_b32 s68, v240, 26
	v_readlane_b32 s69, v240, 27
	v_readlane_b32 s70, v240, 28
	v_readlane_b32 s71, v240, 29
	v_readlane_b32 s72, v240, 30
	v_readlane_b32 s73, v240, 31
	v_readlane_b32 s74, v240, 32
	v_readlane_b32 s75, v240, 33
	v_readlane_b32 s76, v240, 34
	v_readlane_b32 s77, v240, 35
	v_readlane_b32 s78, v240, 36
	v_readlane_b32 s79, v240, 37
	s_mov_b64 s[48:49], s[68:69]
	v_lshl_add_u64 v[160:161], s[48:49], 0, v[192:193]
	s_mov_b64 s[22:23], 0x100000
	s_mov_b64 s[24:25], s[16:17]
	s_and_b64 vcc, exec, s[4:5]
	v_readlane_b32 s65, v240, 23
	v_readlane_b32 s66, v240, 24
	v_readlane_b32 s67, v240, 25
	s_mov_b64 s[50:51], s[70:71]
	s_waitcnt vmcnt(4)
	v_add_f32_e32 v167, v120, v128
	v_add_f32_e32 v180, v121, v129
	v_add_f32_e32 v181, v122, v130
	v_add_f32_e32 v182, v123, v131
	s_waitcnt vmcnt(3)
	v_pk_add_f32 v[120:121], v[126:127], v[190:191]
	v_pk_add_f32 v[122:123], v[124:125], v[188:189]
	v_mul_f32_e32 v124, 0xbfb8aa3b, v167
	v_mul_f32_e32 v125, 0xbfb8aa3b, v180
	v_mul_f32_e32 v126, 0xbfb8aa3b, v181
	v_mul_f32_e32 v127, 0xbfb8aa3b, v182
	v_exp_f32_e32 v124, v124
	v_exp_f32_e32 v125, v125
	v_exp_f32_e32 v126, v126
	v_exp_f32_e32 v127, v127
	v_add_f32_e32 v124, 1.0, v124
	v_add_f32_e32 v125, 1.0, v125
	v_add_f32_e32 v126, 1.0, v126
	v_add_f32_e32 v127, 1.0, v127
	v_rcp_f32_e32 v124, v124
	v_rcp_f32_e32 v126, v126
	v_rcp_f32_e32 v127, v127
	v_rcp_f32_e32 v125, v125
	v_add_f32_e32 v167, v112, v128
	s_mov_b64 s[52:53], s[72:73]
	s_mov_b64 s[54:55], s[74:75]
	s_mov_b64 s[56:57], s[76:77]
	s_mov_b64 s[58:59], s[78:79]
	s_waitcnt vmcnt(2)
	v_pk_mul_f32 v[120:121], v[198:199], v[120:121]
	v_pk_mul_f32 v[180:181], v[196:197], v[122:123]
	s_waitcnt vmcnt(1)
	v_pk_fma_f32 v[122:123], v[120:121], v[126:127], v[202:203]
	v_pk_fma_f32 v[120:121], v[180:181], v[124:125], v[200:201]
	global_store_dwordx4 v[160:161], v[120:123], off
	v_add_f32_e32 v176, v113, v129
	s_nop 0
	v_or_b32_e32 v120, 32, v166
	v_ashrrev_i32_e32 v121, 31, v120
	v_lshlrev_b64 v[120:121], 11, v[120:121]
	v_lshl_add_u64 v[120:121], v[120:121], 0, v[154:155]
	v_lshlrev_b64 v[200:201], 2, v[120:121]
	s_nop 1
	v_lshl_add_u64 v[202:203], s[18:19], 0, v[200:201]
	global_load_dwordx4 v[216:219], v[202:203], off
	v_lshl_add_u64 v[120:121], s[48:49], 0, v[206:207]
	v_add_f32_e32 v177, v114, v130
	v_add_f32_e32 v178, v115, v131
	v_pk_add_f32 v[112:113], v[118:119], v[190:191]
	v_pk_add_f32 v[114:115], v[116:117], v[188:189]
	v_mul_f32_e32 v116, 0xbfb8aa3b, v167
	v_mul_f32_e32 v117, 0xbfb8aa3b, v176
	v_mul_f32_e32 v118, 0xbfb8aa3b, v177
	v_mul_f32_e32 v119, 0xbfb8aa3b, v178
	v_exp_f32_e32 v116, v116
	v_exp_f32_e32 v117, v117
	v_exp_f32_e32 v118, v118
	v_exp_f32_e32 v119, v119
	v_add_f32_e32 v116, 1.0, v116
	v_add_f32_e32 v117, 1.0, v117
	v_add_f32_e32 v118, 1.0, v118
	v_add_f32_e32 v119, 1.0, v119
	v_rcp_f32_e32 v116, v116
	v_rcp_f32_e32 v117, v117
	v_rcp_f32_e32 v118, v118
	v_rcp_f32_e32 v119, v119
	v_pk_mul_f32 v[176:177], v[198:199], v[112:113]
	v_pk_mul_f32 v[112:113], v[196:197], v[114:115]
	s_waitcnt vmcnt(2)
	s_nop 0
	v_pk_fma_f32 v[112:113], v[112:113], v[116:117], v[212:213]
	v_pk_fma_f32 v[114:115], v[176:177], v[118:119], v[214:215]
	global_store_dwordx4 v[120:121], v[112:115], off
	v_add_f32_e32 v126, v104, v128
	s_nop 0
	v_or_b32_e32 v112, 48, v166
	v_ashrrev_i32_e32 v113, 31, v112
	v_lshlrev_b64 v[112:113], 11, v[112:113]
	v_lshl_add_u64 v[112:113], v[112:113], 0, v[154:155]
	s_nop 1
	v_lshlrev_b64 v[204:205], 2, v[112:113]
	s_nop 0
	v_lshl_add_u64 v[206:207], s[18:19], 0, v[204:205]
	global_load_dwordx4 v[212:215], v[206:207], off
	v_lshl_add_u64 v[210:211], v[192:193], 0, s[22:23]
	v_add_f32_e32 v127, v105, v129
	v_add_f32_e32 v155, v106, v130
	v_add_f32_e32 v166, v107, v131
	v_pk_add_f32 v[104:105], v[110:111], v[190:191]
	v_pk_add_f32 v[106:107], v[108:109], v[188:189]
	v_mul_f32_e32 v108, 0xbfb8aa3b, v126
	v_mul_f32_e32 v109, 0xbfb8aa3b, v127
	v_mul_f32_e32 v110, 0xbfb8aa3b, v155
	v_mul_f32_e32 v111, 0xbfb8aa3b, v166
	v_exp_f32_e32 v108, v108
	v_exp_f32_e32 v109, v109
	v_exp_f32_e32 v110, v110
	v_exp_f32_e32 v111, v111
	v_add_f32_e32 v108, 1.0, v108
	v_add_f32_e32 v109, 1.0, v109
	v_add_f32_e32 v110, 1.0, v110
	v_add_f32_e32 v111, 1.0, v111
	v_rcp_f32_e32 v108, v108
	v_rcp_f32_e32 v109, v109
	v_rcp_f32_e32 v110, v110
	v_rcp_f32_e32 v111, v111
	v_pk_mul_f32 v[126:127], v[198:199], v[104:105]
	v_pk_mul_f32 v[104:105], v[196:197], v[106:107]
	v_lshl_add_u64 v[112:113], s[48:49], 0, v[200:201]
	v_lshl_add_u64 v[200:201], s[18:19], 0, v[210:211]
	s_waitcnt vmcnt(2)
	v_pk_fma_f32 v[104:105], v[104:105], v[108:109], v[216:217]
	v_pk_fma_f32 v[106:107], v[126:127], v[110:111], v[218:219]
	global_load_dwordx4 v[216:219], v[200:201], off
	global_store_dwordx4 v[112:113], v[104:107], off
	v_add_f32_e32 v118, v96, v128
	s_nop 0
	v_lshl_add_u64 v[104:105], s[48:49], 0, v[204:205]
	v_add_f32_e32 v119, v97, v129
	v_add_f32_e32 v124, v98, v130
	v_add_f32_e32 v125, v99, v131
	v_pk_add_f32 v[96:97], v[102:103], v[190:191]
	v_pk_add_f32 v[98:99], v[100:101], v[188:189]
	v_mul_f32_e32 v100, 0xbfb8aa3b, v118
	v_mul_f32_e32 v101, 0xbfb8aa3b, v119
	v_mul_f32_e32 v102, 0xbfb8aa3b, v124
	v_mul_f32_e32 v103, 0xbfb8aa3b, v125
	v_exp_f32_e32 v100, v100
	v_exp_f32_e32 v101, v101
	v_exp_f32_e32 v102, v102
	v_exp_f32_e32 v103, v103
	v_add_f32_e32 v100, 1.0, v100
	v_add_f32_e32 v101, 1.0, v101
	v_add_f32_e32 v102, 1.0, v102
	v_add_f32_e32 v103, 1.0, v103
	v_rcp_f32_e32 v100, v100
	v_rcp_f32_e32 v101, v101
	v_rcp_f32_e32 v102, v102
	v_rcp_f32_e32 v103, v103
	v_pk_mul_f32 v[118:119], v[198:199], v[96:97]
	v_pk_mul_f32 v[96:97], v[196:197], v[98:99]
	s_mov_b64 s[22:23], 0x120000
	s_nop 0
	v_lshl_add_u64 v[204:205], v[192:193], 0, s[22:23]
	s_waitcnt vmcnt(2)
	v_pk_fma_f32 v[96:97], v[96:97], v[100:101], v[212:213]
	v_pk_fma_f32 v[98:99], v[118:119], v[102:103], v[214:215]
	v_lshl_add_u64 v[212:213], s[18:19], 0, v[204:205]
	global_store_dwordx4 v[104:105], v[96:99], off
	v_add_f32_e32 v110, v88, v128
	s_nop 0
	v_lshl_add_u64 v[96:97], s[48:49], 0, v[210:211]
	global_load_dwordx4 v[220:223], v[212:213], off
	v_add_f32_e32 v111, v89, v129
	v_add_f32_e32 v116, v90, v130
	v_add_f32_e32 v117, v91, v131
	v_pk_add_f32 v[88:89], v[94:95], v[190:191]
	v_pk_add_f32 v[90:91], v[92:93], v[188:189]
	v_mul_f32_e32 v92, 0xbfb8aa3b, v110
	v_mul_f32_e32 v93, 0xbfb8aa3b, v111
	v_mul_f32_e32 v94, 0xbfb8aa3b, v116
	v_mul_f32_e32 v95, 0xbfb8aa3b, v117
	v_exp_f32_e32 v92, v92
	v_exp_f32_e32 v93, v93
	v_exp_f32_e32 v94, v94
	v_exp_f32_e32 v95, v95
	v_add_f32_e32 v92, 1.0, v92
	v_add_f32_e32 v93, 1.0, v93
	v_add_f32_e32 v94, 1.0, v94
	v_add_f32_e32 v95, 1.0, v95
	v_rcp_f32_e32 v92, v92
	v_rcp_f32_e32 v93, v93
	v_rcp_f32_e32 v94, v94
	v_rcp_f32_e32 v95, v95
	v_pk_mul_f32 v[110:111], v[198:199], v[88:89]
	v_pk_mul_f32 v[88:89], v[196:197], v[90:91]
	s_mov_b64 s[22:23], 0x140000
	s_waitcnt vmcnt(3)
	v_pk_fma_f32 v[88:89], v[88:89], v[92:93], v[216:217]
	v_pk_fma_f32 v[90:91], v[110:111], v[94:95], v[218:219]
	v_lshl_add_u64 v[210:211], v[192:193], 0, s[22:23]
	global_store_dwordx4 v[96:97], v[88:91], off
	v_add_f32_e32 v102, v80, v128
	s_nop 0
	v_lshl_add_u64 v[88:89], s[48:49], 0, v[204:205]
	v_lshl_add_u64 v[204:205], s[18:19], 0, v[210:211]
	v_add_f32_e32 v103, v81, v129
	v_add_f32_e32 v108, v82, v130
	v_add_f32_e32 v109, v83, v131
	v_pk_add_f32 v[80:81], v[86:87], v[190:191]
	v_pk_add_f32 v[82:83], v[84:85], v[188:189]
	v_mul_f32_e32 v84, 0xbfb8aa3b, v102
	v_mul_f32_e32 v85, 0xbfb8aa3b, v103
	v_mul_f32_e32 v86, 0xbfb8aa3b, v108
	v_mul_f32_e32 v87, 0xbfb8aa3b, v109
	v_exp_f32_e32 v84, v84
	v_exp_f32_e32 v85, v85
	v_exp_f32_e32 v86, v86
	v_exp_f32_e32 v87, v87
	v_add_f32_e32 v84, 1.0, v84
	v_add_f32_e32 v85, 1.0, v85
	v_add_f32_e32 v86, 1.0, v86
	v_add_f32_e32 v87, 1.0, v87
	v_rcp_f32_e32 v84, v84
	v_rcp_f32_e32 v85, v85
	v_rcp_f32_e32 v86, v86
	v_rcp_f32_e32 v87, v87
	v_pk_mul_f32 v[102:103], v[198:199], v[80:81]
	v_pk_mul_f32 v[80:81], v[196:197], v[82:83]
	s_mov_b64 s[22:23], 0x160000
	s_waitcnt vmcnt(1)
	v_pk_fma_f32 v[80:81], v[80:81], v[84:85], v[220:221]
	v_pk_fma_f32 v[82:83], v[102:103], v[86:87], v[222:223]
	global_load_dwordx4 v[216:219], v[204:205], off
	global_store_dwordx4 v[88:89], v[80:83], off
	v_add_f32_e32 v94, v72, v128
	s_nop 0
	v_lshl_add_u64 v[80:81], s[48:49], 0, v[210:211]
	v_lshl_add_u64 v[210:211], v[192:193], 0, s[22:23]
	v_add_f32_e32 v95, v73, v129
	v_add_f32_e32 v100, v74, v130
	v_add_f32_e32 v101, v75, v131
	v_pk_add_f32 v[72:73], v[78:79], v[190:191]
	v_pk_add_f32 v[74:75], v[76:77], v[188:189]
	v_mul_f32_e32 v76, 0xbfb8aa3b, v94
	v_mul_f32_e32 v77, 0xbfb8aa3b, v95
	v_mul_f32_e32 v78, 0xbfb8aa3b, v100
	v_mul_f32_e32 v79, 0xbfb8aa3b, v101
	v_exp_f32_e32 v76, v76
	v_exp_f32_e32 v77, v77
	v_exp_f32_e32 v78, v78
	v_exp_f32_e32 v79, v79
	v_add_f32_e32 v76, 1.0, v76
	v_add_f32_e32 v77, 1.0, v77
	v_add_f32_e32 v78, 1.0, v78
	v_add_f32_e32 v79, 1.0, v79
	v_rcp_f32_e32 v76, v76
	v_rcp_f32_e32 v77, v77
	v_rcp_f32_e32 v78, v78
	v_rcp_f32_e32 v79, v79
	v_pk_mul_f32 v[94:95], v[198:199], v[72:73]
	v_pk_mul_f32 v[72:73], v[196:197], v[74:75]
	v_lshl_add_u64 v[192:193], s[18:19], 0, v[210:211]
	s_mov_b32 s19, s10
	s_mov_b64 s[22:23], s[14:15]
	s_mov_b32 s18, s12
	s_waitcnt vmcnt(1)
	v_pk_fma_f32 v[72:73], v[72:73], v[76:77], v[216:217]
	v_pk_fma_f32 v[74:75], v[94:95], v[78:79], v[218:219]
	global_load_dwordx4 v[216:219], v[192:193], off
	v_or_b32_e32 v76, 64, v154
	v_ashrrev_i32_e32 v77, 31, v76
	global_store_dwordx4 v[80:81], v[72:75], off
	v_add_f32_e32 v84, v56, v128
	v_add_f32_e32 v85, v57, v129
	v_add_f32_e32 v86, v58, v130
	v_add_f32_e32 v87, v59, v131
	v_pk_add_f32 v[56:57], v[62:63], v[190:191]
	v_pk_add_f32 v[58:59], v[60:61], v[188:189]
	v_lshl_add_u64 v[188:189], v[76:77], 2, s[8:9]
	v_mul_f32_e32 v60, 0xbfb8aa3b, v84
	v_mul_f32_e32 v61, 0xbfb8aa3b, v85
	v_mul_f32_e32 v62, 0xbfb8aa3b, v86
	v_mul_f32_e32 v63, 0xbfb8aa3b, v87
	v_exp_f32_e32 v60, v60
	v_exp_f32_e32 v61, v61
	v_exp_f32_e32 v62, v62
	v_exp_f32_e32 v63, v63
	v_add_f32_e32 v60, 1.0, v60
	v_add_f32_e32 v61, 1.0, v61
	v_add_f32_e32 v62, 1.0, v62
	v_add_f32_e32 v63, 1.0, v63
	v_rcp_f32_e32 v60, v60
	v_rcp_f32_e32 v61, v61
	v_rcp_f32_e32 v62, v62
	v_rcp_f32_e32 v63, v63
	v_pk_mul_f32 v[84:85], v[198:199], v[56:57]
	v_pk_mul_f32 v[56:57], v[196:197], v[58:59]
	global_load_dwordx4 v[196:199], v[188:189], off
	v_lshl_add_u64 v[76:77], s[48:49], 0, v[210:211]
	global_load_dwordx4 v[220:223], v[186:187], off offset:256
	s_waitcnt vmcnt(3)
	v_pk_fma_f32 v[56:57], v[56:57], v[60:61], v[216:217]
	v_pk_fma_f32 v[58:59], v[84:85], v[62:63], v[218:219]
	global_load_dwordx4 v[216:219], v[194:195], off offset:256
	global_store_dwordx4 v[76:77], v[56:59], off
	global_load_dwordx4 v[188:191], v[184:185], off offset:256
	global_load_dwordx4 v[224:227], v[208:209], off offset:256
	global_load_dwordx4 v[184:187], v[202:203], off offset:256
	global_load_dwordx4 v[228:231], v[206:207], off offset:256
	s_waitcnt vmcnt(7)
	v_add_f32_e32 v68, v68, v196
	v_add_f32_e32 v69, v69, v197
	v_add_f32_e32 v70, v70, v198
	v_add_f32_e32 v71, v71, v199
	v_mul_f32_e32 v68, 0xbfb8aa3b, v68
	v_mul_f32_e32 v69, 0xbfb8aa3b, v69
	v_mul_f32_e32 v70, 0xbfb8aa3b, v70
	v_mul_f32_e32 v71, 0xbfb8aa3b, v71
	v_exp_f32_e32 v68, v68
	v_exp_f32_e32 v69, v69
	v_exp_f32_e32 v70, v70
	v_exp_f32_e32 v71, v71
	v_add_f32_e32 v68, 1.0, v68
	v_add_f32_e32 v69, 1.0, v69
	v_add_f32_e32 v70, 1.0, v70
	v_add_f32_e32 v71, 1.0, v71
	v_rcp_f32_e32 v68, v68
	v_rcp_f32_e32 v70, v70
	v_rcp_f32_e32 v71, v71
	v_rcp_f32_e32 v69, v69
	s_waitcnt vmcnt(6)
	v_pk_add_f32 v[66:67], v[66:67], v[222:223]
	v_pk_add_f32 v[64:65], v[64:65], v[220:221]
	s_waitcnt vmcnt(5)
	v_pk_mul_f32 v[66:67], v[218:219], v[66:67]
	v_pk_mul_f32 v[64:65], v[216:217], v[64:65]
	s_waitcnt vmcnt(3)
	v_pk_fma_f32 v[66:67], v[66:67], v[70:71], v[190:191]
	v_pk_fma_f32 v[64:65], v[64:65], v[68:69], v[188:189]
	global_load_dwordx4 v[188:191], v[200:201], off offset:256
	global_store_dwordx4 v[160:161], v[64:67], off offset:256
	v_add_f32_e32 v52, v52, v196
	global_load_dwordx4 v[208:211], v[212:213], off offset:256
	v_add_f32_e32 v53, v53, v197
	v_add_f32_e32 v54, v54, v198
	v_add_f32_e32 v55, v55, v199
	v_mul_f32_e32 v52, 0xbfb8aa3b, v52
	v_mul_f32_e32 v53, 0xbfb8aa3b, v53
	v_mul_f32_e32 v54, 0xbfb8aa3b, v54
	v_mul_f32_e32 v55, 0xbfb8aa3b, v55
	v_exp_f32_e32 v52, v52
	v_exp_f32_e32 v53, v53
	v_exp_f32_e32 v54, v54
	v_exp_f32_e32 v55, v55
	v_add_f32_e32 v52, 1.0, v52
	v_add_f32_e32 v53, 1.0, v53
	v_add_f32_e32 v54, 1.0, v54
	v_add_f32_e32 v55, 1.0, v55
	v_rcp_f32_e32 v52, v52
	v_rcp_f32_e32 v53, v53
	v_rcp_f32_e32 v54, v54
	v_rcp_f32_e32 v55, v55
	v_pk_add_f32 v[50:51], v[50:51], v[222:223]
	v_pk_add_f32 v[48:49], v[48:49], v[220:221]
	v_pk_mul_f32 v[50:51], v[218:219], v[50:51]
	v_pk_mul_f32 v[48:49], v[216:217], v[48:49]
	v_add_f32_e32 v44, v44, v196
	v_add_f32_e32 v45, v45, v197
	v_add_f32_e32 v46, v46, v198
	v_add_f32_e32 v47, v47, v199
	v_mul_f32_e32 v44, 0xbfb8aa3b, v44
	v_mul_f32_e32 v45, 0xbfb8aa3b, v45
	v_mul_f32_e32 v46, 0xbfb8aa3b, v46
	v_mul_f32_e32 v47, 0xbfb8aa3b, v47
	v_exp_f32_e32 v44, v44
	v_exp_f32_e32 v45, v45
	v_exp_f32_e32 v46, v46
	v_exp_f32_e32 v47, v47
	v_add_f32_e32 v44, 1.0, v44
	v_add_f32_e32 v45, 1.0, v45
	v_add_f32_e32 v46, 1.0, v46
	v_add_f32_e32 v47, 1.0, v47
	v_rcp_f32_e32 v44, v44
	v_rcp_f32_e32 v45, v45
	v_rcp_f32_e32 v46, v46
	v_rcp_f32_e32 v47, v47
	v_pk_add_f32 v[42:43], v[42:43], v[222:223]
	v_pk_add_f32 v[40:41], v[40:41], v[220:221]
	v_pk_mul_f32 v[42:43], v[218:219], v[42:43]
	v_pk_mul_f32 v[40:41], v[216:217], v[40:41]
	v_add_f32_e32 v36, v36, v196
	v_add_f32_e32 v37, v37, v197
	v_add_f32_e32 v38, v38, v198
	v_add_f32_e32 v39, v39, v199
	v_mul_f32_e32 v36, 0xbfb8aa3b, v36
	v_mul_f32_e32 v37, 0xbfb8aa3b, v37
	v_mul_f32_e32 v38, 0xbfb8aa3b, v38
	v_mul_f32_e32 v39, 0xbfb8aa3b, v39
	v_exp_f32_e32 v36, v36
	v_exp_f32_e32 v37, v37
	v_exp_f32_e32 v38, v38
	v_exp_f32_e32 v39, v39
	v_add_f32_e32 v36, 1.0, v36
	v_add_f32_e32 v37, 1.0, v37
	v_add_f32_e32 v38, 1.0, v38
	v_add_f32_e32 v39, 1.0, v39
	v_rcp_f32_e32 v36, v36
	v_rcp_f32_e32 v37, v37
	v_rcp_f32_e32 v38, v38
	v_rcp_f32_e32 v39, v39
	v_pk_add_f32 v[34:35], v[34:35], v[222:223]
	v_pk_add_f32 v[32:33], v[32:33], v[220:221]
	v_pk_mul_f32 v[34:35], v[218:219], v[34:35]
	v_pk_mul_f32 v[32:33], v[216:217], v[32:33]
	v_add_f32_e32 v28, v28, v196
	v_add_f32_e32 v29, v29, v197
	v_add_f32_e32 v30, v30, v198
	v_add_f32_e32 v31, v31, v199
	v_mul_f32_e32 v28, 0xbfb8aa3b, v28
	v_mul_f32_e32 v29, 0xbfb8aa3b, v29
	v_mul_f32_e32 v30, 0xbfb8aa3b, v30
	s_waitcnt vmcnt(5)
	v_pk_fma_f32 v[48:49], v[48:49], v[52:53], v[224:225]
	v_pk_fma_f32 v[50:51], v[50:51], v[54:55], v[226:227]
	global_load_dwordx4 v[224:227], v[204:205], off offset:256
	global_store_dwordx4 v[120:121], v[48:51], off offset:256
	v_mul_f32_e32 v31, 0xbfb8aa3b, v31
	global_load_dwordx4 v[232:235], v[192:193], off offset:256
	v_exp_f32_e32 v28, v28
	v_exp_f32_e32 v29, v29
	v_exp_f32_e32 v30, v30
	v_exp_f32_e32 v31, v31
	v_add_f32_e32 v28, 1.0, v28
	v_add_f32_e32 v29, 1.0, v29
	v_add_f32_e32 v30, 1.0, v30
	v_add_f32_e32 v31, 1.0, v31
	v_rcp_f32_e32 v28, v28
	v_rcp_f32_e32 v29, v29
	v_rcp_f32_e32 v30, v30
	v_rcp_f32_e32 v31, v31
	v_pk_add_f32 v[26:27], v[26:27], v[222:223]
	v_pk_add_f32 v[24:25], v[24:25], v[220:221]
	v_pk_mul_f32 v[26:27], v[218:219], v[26:27]
	v_pk_mul_f32 v[24:25], v[216:217], v[24:25]
	v_add_f32_e32 v20, v20, v196
	v_add_f32_e32 v21, v21, v197
	v_add_f32_e32 v22, v22, v198
	v_add_f32_e32 v23, v23, v199
	v_mul_f32_e32 v20, 0xbfb8aa3b, v20
	v_mul_f32_e32 v21, 0xbfb8aa3b, v21
	v_mul_f32_e32 v22, 0xbfb8aa3b, v22
	v_mul_f32_e32 v23, 0xbfb8aa3b, v23
	v_exp_f32_e32 v20, v20
	v_exp_f32_e32 v21, v21
	v_exp_f32_e32 v22, v22
	v_exp_f32_e32 v23, v23
	v_add_f32_e32 v20, 1.0, v20
	v_add_f32_e32 v21, 1.0, v21
	v_add_f32_e32 v22, 1.0, v22
	v_add_f32_e32 v23, 1.0, v23
	v_rcp_f32_e32 v20, v20
	v_rcp_f32_e32 v21, v21
	v_rcp_f32_e32 v22, v22
	v_rcp_f32_e32 v23, v23
	v_pk_add_f32 v[18:19], v[18:19], v[222:223]
	v_pk_add_f32 v[16:17], v[16:17], v[220:221]
	v_pk_mul_f32 v[18:19], v[218:219], v[18:19]
	v_pk_mul_f32 v[16:17], v[216:217], v[16:17]
	v_add_f32_e32 v12, v12, v196
	v_add_f32_e32 v13, v13, v197
	v_add_f32_e32 v14, v14, v198
	v_add_f32_e32 v15, v15, v199
	v_mul_f32_e32 v12, 0xbfb8aa3b, v12
	v_mul_f32_e32 v13, 0xbfb8aa3b, v13
	v_mul_f32_e32 v14, 0xbfb8aa3b, v14
	v_mul_f32_e32 v15, 0xbfb8aa3b, v15
	v_exp_f32_e32 v12, v12
	v_exp_f32_e32 v13, v13
	v_exp_f32_e32 v14, v14
	v_exp_f32_e32 v15, v15
	v_add_f32_e32 v12, 1.0, v12
	v_add_f32_e32 v13, 1.0, v13
	v_add_f32_e32 v14, 1.0, v14
	v_add_f32_e32 v15, 1.0, v15
	v_rcp_f32_e32 v12, v12
	v_rcp_f32_e32 v13, v13
	v_rcp_f32_e32 v14, v14
	v_rcp_f32_e32 v15, v15
	v_pk_add_f32 v[10:11], v[10:11], v[222:223]
	v_pk_add_f32 v[8:9], v[8:9], v[220:221]
	v_pk_mul_f32 v[10:11], v[218:219], v[10:11]
	v_pk_mul_f32 v[8:9], v[216:217], v[8:9]
	s_waitcnt vmcnt(7)
	v_pk_fma_f32 v[40:41], v[40:41], v[44:45], v[184:185]
	v_pk_fma_f32 v[42:43], v[42:43], v[46:47], v[186:187]
	global_store_dwordx4 v[112:113], v[40:43], off offset:256
	s_waitcnt vmcnt(7)
	v_pk_fma_f32 v[32:33], v[32:33], v[36:37], v[228:229]
	v_pk_fma_f32 v[34:35], v[34:35], v[38:39], v[230:231]
	global_store_dwordx4 v[104:105], v[32:35], off offset:256
	s_waitcnt vmcnt(7)
	v_pk_fma_f32 v[24:25], v[24:25], v[28:29], v[188:189]
	v_pk_fma_f32 v[26:27], v[26:27], v[30:31], v[190:191]
	global_store_dwordx4 v[96:97], v[24:27], off offset:256
	s_waitcnt vmcnt(6)
	v_pk_fma_f32 v[16:17], v[16:17], v[20:21], v[208:209]
	v_pk_fma_f32 v[18:19], v[18:19], v[22:23], v[210:211]
	global_store_dwordx4 v[88:89], v[16:19], off offset:256
	s_waitcnt vmcnt(6)
	v_pk_fma_f32 v[8:9], v[8:9], v[12:13], v[224:225]
	v_pk_fma_f32 v[10:11], v[10:11], v[14:15], v[226:227]
	global_store_dwordx4 v[80:81], v[8:11], off offset:256
	v_add_f32_e32 v12, v0, v196
	v_add_f32_e32 v13, v1, v197
	v_add_f32_e32 v14, v2, v198
	v_add_f32_e32 v15, v3, v199
	v_pk_add_f32 v[0:1], v[6:7], v[222:223]
	v_pk_add_f32 v[2:3], v[4:5], v[220:221]
	v_mul_f32_e32 v4, 0xbfb8aa3b, v12
	v_mul_f32_e32 v5, 0xbfb8aa3b, v13
	v_mul_f32_e32 v6, 0xbfb8aa3b, v14
	v_mul_f32_e32 v7, 0xbfb8aa3b, v15
	v_exp_f32_e32 v4, v4
	v_exp_f32_e32 v5, v5
	v_exp_f32_e32 v6, v6
	v_exp_f32_e32 v7, v7
	v_add_f32_e32 v4, 1.0, v4
	v_add_f32_e32 v5, 1.0, v5
	v_add_f32_e32 v6, 1.0, v6
	v_add_f32_e32 v7, 1.0, v7
	v_rcp_f32_e32 v4, v4
	v_rcp_f32_e32 v5, v5
	v_rcp_f32_e32 v6, v6
	v_rcp_f32_e32 v7, v7
	v_pk_mul_f32 v[12:13], v[218:219], v[0:1]
	v_pk_mul_f32 v[0:1], v[216:217], v[2:3]
	s_waitcnt vmcnt(5)
	v_pk_fma_f32 v[2:3], v[12:13], v[6:7], v[234:235]
	v_pk_fma_f32 v[0:1], v[0:1], v[4:5], v[232:233]
	global_store_dwordx4 v[76:77], v[0:3], off offset:256
	s_cbranch_vccz .LBB0_410
	s_waitcnt vmcnt(0)
	s_cmpk_gt_u32 s1, 0xff
	s_cbranch_scc1 .LBB0_417
	s_barrier

.LBB0_606:
	ds_read_b128 v[148:151], v144
	ds_read_b128 v[152:155], v144 offset:1024
	ds_read_b128 v[156:159], v144 offset:2048
	ds_read_b128 v[160:163], v144 offset:3072
	s_add_i32 m0, s5, 0xc000
	ds_read_b128 v[164:167], v145
	ds_read_b128 v[168:171], v145 offset:1024
	ds_read_b128 v[172:175], v145 offset:2048
	ds_read_b128 v[176:179], v145 offset:3072
	ds_read_b128 v[180:183], v145 offset:4096
	ds_read_b128 v[184:187], v145 offset:5120
	ds_read_b128 v[188:191], v145 offset:6144
	ds_read_b128 v[192:195], v145 offset:7168
	global_load_lds_dwordx4 v134, s[20:21]
	s_add_i32 m0, s5, 0xe000
	s_nop 0
	global_load_lds_dwordx4 v136, s[20:21]
	s_waitcnt lgkmcnt(8)
	s_barrier
	s_waitcnt lgkmcnt(0)
	s_waitcnt lgkmcnt(0)
	v_mfma_f32_16x16x32_bf16 v[124:127], v[148:151], v[164:167], v[124:127]
	s_add_u32 s22, s20, 0x100
	s_addc_u32 s23, s21, 0
	s_cmp_eq_u32 s47, 28
	s_cselect_b32 s27, s13, s23
	s_cselect_b32 s26, s41, s22
	s_cselect_b32 s25, s11, s46
	s_cselect_b32 s24, s42, s43
	v_mfma_f32_16x16x32_bf16 v[120:123], v[156:159], v[164:167], v[120:123]
	v_mfma_f32_16x16x32_bf16 v[108:111], v[148:151], v[172:175], v[108:111]
	v_mfma_f32_16x16x32_bf16 v[104:107], v[156:159], v[172:175], v[104:107]
	v_mfma_f32_16x16x32_bf16 v[92:95], v[148:151], v[180:183], v[92:95]
	v_mfma_f32_16x16x32_bf16 v[88:91], v[156:159], v[180:183], v[88:91]
	v_mfma_f32_16x16x32_bf16 v[76:79], v[148:151], v[188:191], v[76:79]
	v_mfma_f32_16x16x32_bf16 v[72:75], v[156:159], v[188:191], v[72:75]
	v_mfma_f32_16x16x32_bf16 v[124:127], v[152:155], v[168:171], v[124:127]
	v_mfma_f32_16x16x32_bf16 v[120:123], v[160:163], v[168:171], v[120:123]
	v_mfma_f32_16x16x32_bf16 v[108:111], v[152:155], v[176:179], v[108:111]
	v_mfma_f32_16x16x32_bf16 v[104:107], v[160:163], v[176:179], v[104:107]
	v_mfma_f32_16x16x32_bf16 v[92:95], v[152:155], v[184:187], v[92:95]
	v_mfma_f32_16x16x32_bf16 v[88:91], v[160:163], v[184:187], v[88:91]
	v_mfma_f32_16x16x32_bf16 v[76:79], v[152:155], v[192:195], v[76:79]
	v_mfma_f32_16x16x32_bf16 v[72:75], v[160:163], v[192:195], v[72:75]
	s_barrier
	s_add_i32 s20, s38, s2
	s_mov_b32 m0, s20
	ds_read_b128 v[196:199], v146
	ds_read_b128 v[200:203], v146 offset:1024
	ds_read_b128 v[204:207], v146 offset:2048
	ds_read_b128 v[208:211], v146 offset:3072
	global_load_lds_dwordx4 v130, s[24:25]
	s_add_i32 m0, s20, 0x2000
	s_nop 0
	global_load_lds_dwordx4 v128, s[24:25]
	s_barrier
	s_waitcnt lgkmcnt(0)
	s_waitcnt lgkmcnt(0)
	v_mfma_f32_16x16x32_bf16 v[116:119], v[196:199], v[164:167], v[116:119]
	v_mfma_f32_16x16x32_bf16 v[112:115], v[204:207], v[164:167], v[112:115]
	v_mfma_f32_16x16x32_bf16 v[100:103], v[196:199], v[172:175], v[100:103]
	v_mfma_f32_16x16x32_bf16 v[96:99], v[204:207], v[172:175], v[96:99]
	v_mfma_f32_16x16x32_bf16 v[84:87], v[196:199], v[180:183], v[84:87]
	v_mfma_f32_16x16x32_bf16 v[80:83], v[204:207], v[180:183], v[80:83]
	v_mfma_f32_16x16x32_bf16 v[68:71], v[196:199], v[188:191], v[68:71]
	v_mfma_f32_16x16x32_bf16 v[64:67], v[204:207], v[188:191], v[64:67]
	v_mfma_f32_16x16x32_bf16 v[116:119], v[200:203], v[168:171], v[116:119]
	v_mfma_f32_16x16x32_bf16 v[112:115], v[208:211], v[168:171], v[112:115]
	v_mfma_f32_16x16x32_bf16 v[100:103], v[200:203], v[176:179], v[100:103]
	v_mfma_f32_16x16x32_bf16 v[96:99], v[208:211], v[176:179], v[96:99]
	v_mfma_f32_16x16x32_bf16 v[84:87], v[200:203], v[184:187], v[84:87]
	v_mfma_f32_16x16x32_bf16 v[80:83], v[208:211], v[184:187], v[80:83]
	v_mfma_f32_16x16x32_bf16 v[68:71], v[200:203], v[192:195], v[68:71]
	v_mfma_f32_16x16x32_bf16 v[64:67], v[208:211], v[192:195], v[64:67]
	s_mov_b32 m0, s5
	v_lshl_add_u64 v[216:217], s[26:27], 0, v[130:131]
	s_barrier
	ds_read_b128 v[164:167], v145 offset:16384
	ds_read_b128 v[168:171], v145 offset:17408
	ds_read_b128 v[172:175], v145 offset:18432
	ds_read_b128 v[176:179], v145 offset:19456
	ds_read_b128 v[180:183], v145 offset:20480
	ds_read_b128 v[184:187], v145 offset:21504
	ds_read_b128 v[188:191], v145 offset:22528
	ds_read_b128 v[192:195], v145 offset:23552
	global_load_lds_dwordx4 v130, s[26:27]
	v_lshl_add_u64 v[218:219], s[26:27], 0, v[128:129]
	s_mov_b32 m0, s28
	s_nop 0
	global_load_lds_dwordx4 v128, s[26:27]
	s_barrier
	s_waitcnt lgkmcnt(0)
	s_waitcnt lgkmcnt(0)
	v_mfma_f32_16x16x32_bf16 v[60:63], v[148:151], v[164:167], v[60:63]
	v_mfma_f32_16x16x32_bf16 v[56:59], v[156:159], v[164:167], v[56:59]
	v_mfma_f32_16x16x32_bf16 v[44:47], v[148:151], v[172:175], v[44:47]
	v_mfma_f32_16x16x32_bf16 v[40:43], v[156:159], v[172:175], v[40:43]
	v_mfma_f32_16x16x32_bf16 v[28:31], v[148:151], v[180:183], v[28:31]
	v_mfma_f32_16x16x32_bf16 v[24:27], v[156:159], v[180:183], v[24:27]
	v_mfma_f32_16x16x32_bf16 v[12:15], v[148:151], v[188:191], v[12:15]
	v_mfma_f32_16x16x32_bf16 v[8:11], v[156:159], v[188:191], v[8:11]
	v_mfma_f32_16x16x32_bf16 v[60:63], v[152:155], v[168:171], v[60:63]
	v_mfma_f32_16x16x32_bf16 v[56:59], v[160:163], v[168:171], v[56:59]
	v_mfma_f32_16x16x32_bf16 v[44:47], v[152:155], v[176:179], v[44:47]
	v_mfma_f32_16x16x32_bf16 v[40:43], v[160:163], v[176:179], v[40:43]
	v_mfma_f32_16x16x32_bf16 v[28:31], v[152:155], v[184:187], v[28:31]
	v_mfma_f32_16x16x32_bf16 v[24:27], v[160:163], v[184:187], v[24:27]
	v_mfma_f32_16x16x32_bf16 v[12:15], v[152:155], v[192:195], v[12:15]
	v_mfma_f32_16x16x32_bf16 v[8:11], v[160:163], v[192:195], v[8:11]
	s_barrier
	s_add_u32 s20, s24, 0x80000
	s_addc_u32 s21, s25, 0
	s_add_i32 s60, s39, s2
	s_mov_b32 m0, s60
	s_nop 0
	global_load_lds_dwordx4 v130, s[20:21]
	s_add_i32 m0, s60, 0x2000
	s_nop 0
	global_load_lds_dwordx4 v128, s[20:21]
	s_waitcnt vmcnt(6)
	s_barrier
	v_mfma_f32_16x16x32_bf16 v[52:55], v[196:199], v[164:167], v[52:55]
	v_mfma_f32_16x16x32_bf16 v[48:51], v[204:207], v[164:167], v[48:51]
	v_mfma_f32_16x16x32_bf16 v[36:39], v[196:199], v[172:175], v[36:39]
	v_mfma_f32_16x16x32_bf16 v[32:35], v[204:207], v[172:175], v[32:35]
	v_mfma_f32_16x16x32_bf16 v[20:23], v[196:199], v[180:183], v[20:23]
	v_mfma_f32_16x16x32_bf16 v[16:19], v[204:207], v[180:183], v[16:19]
	v_mfma_f32_16x16x32_bf16 v[4:7], v[196:199], v[188:191], v[4:7]
	v_mfma_f32_16x16x32_bf16 v[0:3], v[204:207], v[188:191], v[0:3]
	v_mfma_f32_16x16x32_bf16 v[52:55], v[200:203], v[168:171], v[52:55]
	v_mfma_f32_16x16x32_bf16 v[48:51], v[208:211], v[168:171], v[48:51]
	v_mfma_f32_16x16x32_bf16 v[36:39], v[200:203], v[176:179], v[36:39]
	v_mfma_f32_16x16x32_bf16 v[32:35], v[208:211], v[176:179], v[32:35]
	v_mfma_f32_16x16x32_bf16 v[20:23], v[200:203], v[184:187], v[20:23]
	v_mfma_f32_16x16x32_bf16 v[16:19], v[208:211], v[184:187], v[16:19]
	v_mfma_f32_16x16x32_bf16 v[4:7], v[200:203], v[192:195], v[4:7]
	v_mfma_f32_16x16x32_bf16 v[0:3], v[208:211], v[192:195], v[0:3]
	s_add_i32 s60, 0, 0x18000
	v_add_u32_e32 v147, s60, v143
	s_barrier
	ds_read_b128 v[148:151], v147
	ds_read_b128 v[152:155], v147 offset:1024
	ds_read_b128 v[156:159], v147 offset:2048
	ds_read_b128 v[160:163], v147 offset:3072
	s_add_u32 s20, s26, 0x80000
	s_addc_u32 s21, s27, 0
	s_mov_b32 m0, s29
	ds_read_b128 v[164:167], v145 offset:32768
	ds_read_b128 v[168:171], v145 offset:33792
	ds_read_b128 v[172:175], v145 offset:34816
	ds_read_b128 v[176:179], v145 offset:35840
	ds_read_b128 v[180:183], v145 offset:36864
	ds_read_b128 v[184:187], v145 offset:37888
	ds_read_b128 v[188:191], v145 offset:38912
	ds_read_b128 v[192:195], v145 offset:39936
	global_load_lds_dwordx4 v130, s[20:21]
	s_mov_b32 m0, s30
	s_nop 0
	global_load_lds_dwordx4 v128, s[20:21]
	s_waitcnt lgkmcnt(8)
	s_barrier
	s_waitcnt lgkmcnt(0)
	s_waitcnt lgkmcnt(0)
	v_mfma_f32_16x16x32_bf16 v[124:127], v[148:151], v[164:167], v[124:127]
	v_mfma_f32_16x16x32_bf16 v[120:123], v[156:159], v[164:167], v[120:123]
	v_mfma_f32_16x16x32_bf16 v[108:111], v[148:151], v[172:175], v[108:111]
	v_mfma_f32_16x16x32_bf16 v[104:107], v[156:159], v[172:175], v[104:107]
	v_mfma_f32_16x16x32_bf16 v[92:95], v[148:151], v[180:183], v[92:95]
	v_mfma_f32_16x16x32_bf16 v[88:91], v[156:159], v[180:183], v[88:91]
	v_mfma_f32_16x16x32_bf16 v[76:79], v[148:151], v[188:191], v[76:79]
	v_mfma_f32_16x16x32_bf16 v[72:75], v[156:159], v[188:191], v[72:75]
	v_mfma_f32_16x16x32_bf16 v[124:127], v[152:155], v[168:171], v[124:127]
	v_mfma_f32_16x16x32_bf16 v[120:123], v[160:163], v[168:171], v[120:123]
	v_mfma_f32_16x16x32_bf16 v[108:111], v[152:155], v[176:179], v[108:111]
	v_mfma_f32_16x16x32_bf16 v[104:107], v[160:163], v[176:179], v[104:107]
	v_mfma_f32_16x16x32_bf16 v[92:95], v[152:155], v[184:187], v[92:95]
	v_mfma_f32_16x16x32_bf16 v[88:91], v[160:163], v[184:187], v[88:91]
	v_mfma_f32_16x16x32_bf16 v[76:79], v[152:155], v[192:195], v[76:79]
	v_mfma_f32_16x16x32_bf16 v[72:75], v[160:163], v[192:195], v[72:75]
	s_barrier
	s_add_i32 s26, 0, 0x1c000
	s_add_i32 s20, s60, s2
	v_add_u32_e32 v147, s26, v143
	s_add_u32 s98, s24, s8
	s_addc_u32 s99, s25, s9
	s_mov_b32 m0, s20
	ds_read_b128 v[196:199], v147
	ds_read_b128 v[200:203], v147 offset:1024
	ds_read_b128 v[204:207], v147 offset:2048
	ds_read_b128 v[208:211], v147 offset:3072
	global_load_lds_dwordx4 v130, s[98:99]
	s_add_i32 m0, s20, 0x2000
	s_nop 0
	global_load_lds_dwordx4 v128, s[98:99]
	s_barrier
	s_waitcnt lgkmcnt(0)
	s_waitcnt lgkmcnt(0)
	v_mfma_f32_16x16x32_bf16 v[116:119], v[196:199], v[164:167], v[116:119]
	v_mfma_f32_16x16x32_bf16 v[112:115], v[204:207], v[164:167], v[112:115]
	v_mfma_f32_16x16x32_bf16 v[100:103], v[196:199], v[172:175], v[100:103]
	v_mfma_f32_16x16x32_bf16 v[96:99], v[204:207], v[172:175], v[96:99]
	v_mfma_f32_16x16x32_bf16 v[84:87], v[196:199], v[180:183], v[84:87]
	v_mfma_f32_16x16x32_bf16 v[80:83], v[204:207], v[180:183], v[80:83]
	v_mfma_f32_16x16x32_bf16 v[68:71], v[196:199], v[188:191], v[68:71]
	v_mfma_f32_16x16x32_bf16 v[64:67], v[204:207], v[188:191], v[64:67]
	v_mfma_f32_16x16x32_bf16 v[116:119], v[200:203], v[168:171], v[116:119]
	v_mfma_f32_16x16x32_bf16 v[112:115], v[208:211], v[168:171], v[112:115]
	v_mfma_f32_16x16x32_bf16 v[100:103], v[200:203], v[176:179], v[100:103]
	v_mfma_f32_16x16x32_bf16 v[96:99], v[208:211], v[176:179], v[96:99]
	v_mfma_f32_16x16x32_bf16 v[84:87], v[200:203], v[184:187], v[84:87]
	v_mfma_f32_16x16x32_bf16 v[80:83], v[208:211], v[184:187], v[80:83]
	v_mfma_f32_16x16x32_bf16 v[68:71], v[200:203], v[192:195], v[68:71]
	v_mfma_f32_16x16x32_bf16 v[64:67], v[208:211], v[192:195], v[64:67]
	s_mov_b32 m0, s34
	v_lshl_add_u64 v[212:213], v[216:217], 0, s[8:9]
	s_barrier
	ds_read_b128 v[164:167], v145 offset:49152
	ds_read_b128 v[168:171], v145 offset:50176
	ds_read_b128 v[172:175], v145 offset:51200
	ds_read_b128 v[176:179], v145 offset:52224
	ds_read_b128 v[180:183], v145 offset:53248
	ds_read_b128 v[184:187], v145 offset:54272
	ds_read_b128 v[188:191], v145 offset:55296
	ds_read_b128 v[192:195], v145 offset:56320
	global_load_lds_dwordx4 v[212:213], off
	v_lshl_add_u64 v[212:213], v[218:219], 0, s[8:9]
	s_mov_b32 m0, s35
	s_nop 0
	global_load_lds_dwordx4 v[212:213], off
	s_barrier
	s_waitcnt lgkmcnt(0)
	s_waitcnt lgkmcnt(0)
	v_mfma_f32_16x16x32_bf16 v[60:63], v[148:151], v[164:167], v[60:63]
	v_mfma_f32_16x16x32_bf16 v[56:59], v[156:159], v[164:167], v[56:59]
	v_mfma_f32_16x16x32_bf16 v[44:47], v[148:151], v[172:175], v[44:47]
	v_mfma_f32_16x16x32_bf16 v[40:43], v[156:159], v[172:175], v[40:43]
	v_mfma_f32_16x16x32_bf16 v[28:31], v[148:151], v[180:183], v[28:31]
	v_mfma_f32_16x16x32_bf16 v[24:27], v[156:159], v[180:183], v[24:27]
	v_mfma_f32_16x16x32_bf16 v[12:15], v[148:151], v[188:191], v[12:15]
	v_mfma_f32_16x16x32_bf16 v[8:11], v[156:159], v[188:191], v[8:11]
	v_mfma_f32_16x16x32_bf16 v[60:63], v[152:155], v[168:171], v[60:63]
	v_mfma_f32_16x16x32_bf16 v[56:59], v[160:163], v[168:171], v[56:59]
	v_mfma_f32_16x16x32_bf16 v[44:47], v[152:155], v[176:179], v[44:47]
	v_mfma_f32_16x16x32_bf16 v[40:43], v[160:163], v[176:179], v[40:43]
	v_mfma_f32_16x16x32_bf16 v[28:31], v[152:155], v[184:187], v[28:31]
	v_mfma_f32_16x16x32_bf16 v[24:27], v[160:163], v[184:187], v[24:27]
	v_mfma_f32_16x16x32_bf16 v[12:15], v[152:155], v[192:195], v[12:15]
	v_mfma_f32_16x16x32_bf16 v[8:11], v[160:163], v[192:195], v[8:11]
	s_barrier
	s_add_u32 s20, s24, 0x80080
	s_addc_u32 s21, s25, 0
	s_add_i32 s24, s26, s2
	s_mov_b32 m0, s24
	s_nop 0
	global_load_lds_dwordx4 v130, s[20:21]
	s_add_i32 m0, s24, 0x2000
	s_nop 0
	global_load_lds_dwordx4 v128, s[20:21]
	s_waitcnt vmcnt(6)
	s_barrier
	v_mfma_f32_16x16x32_bf16 v[52:55], v[196:199], v[164:167], v[52:55]
	v_mfma_f32_16x16x32_bf16 v[48:51], v[204:207], v[164:167], v[48:51]
	v_mfma_f32_16x16x32_bf16 v[36:39], v[196:199], v[172:175], v[36:39]
	v_mfma_f32_16x16x32_bf16 v[32:35], v[204:207], v[172:175], v[32:35]
	v_mfma_f32_16x16x32_bf16 v[20:23], v[196:199], v[180:183], v[20:23]
	v_mfma_f32_16x16x32_bf16 v[16:19], v[204:207], v[180:183], v[16:19]
	v_mfma_f32_16x16x32_bf16 v[4:7], v[196:199], v[188:191], v[4:7]
	v_mfma_f32_16x16x32_bf16 v[0:3], v[204:207], v[188:191], v[0:3]
	v_mfma_f32_16x16x32_bf16 v[52:55], v[200:203], v[168:171], v[52:55]
	v_mfma_f32_16x16x32_bf16 v[48:51], v[208:211], v[168:171], v[48:51]
	v_mfma_f32_16x16x32_bf16 v[36:39], v[200:203], v[176:179], v[36:39]
	v_mfma_f32_16x16x32_bf16 v[32:35], v[208:211], v[176:179], v[32:35]
	v_mfma_f32_16x16x32_bf16 v[20:23], v[200:203], v[184:187], v[20:23]
	v_mfma_f32_16x16x32_bf16 v[16:19], v[208:211], v[184:187], v[16:19]
	v_mfma_f32_16x16x32_bf16 v[4:7], v[200:203], v[192:195], v[4:7]
	v_mfma_f32_16x16x32_bf16 v[0:3], v[208:211], v[192:195], v[0:3]
	s_add_i32 s47, s47, 2
	s_add_u32 s43, s43, 0x100
	s_addc_u32 s46, s46, 0
	s_cmp_gt_u32 s47, 29
	s_mov_b64 s[20:21], s[22:23]
	s_barrier
	s_cbranch_scc0 .LBB0_606
	v_mul_f32_e32 v150, 0xbfb8aa3b, v124
	v_mul_f32_e32 v151, 0xbfb8aa3b, v125
	v_exp_f32_e32 v150, v150
	v_exp_f32_e32 v151, v151
	s_lshl_b32 s11, s19, 7
	v_lshl_add_u32 v147, s18, 8, v142
	v_add_f32_e32 v150, 1.0, v150
	v_add_f32_e32 v151, 1.0, v151
	v_rcp_f32_e32 v150, v150
	v_rcp_f32_e32 v151, v151
	s_or_b32 s18, s11, s36
	s_ashr_i32 s19, s18, 31
	v_mad_i64_i32 v[148:149], s[20:21], v147, s40, v[132:133]
	v_pk_mul_f32 v[124:125], v[124:125], v[150:151]
	s_lshl_b64 s[18:19], s[18:19], 1
	v_pk_mul_f32 v[120:121], v[120:121], v[124:125]
	s_and_b64 vcc, exec, s[6:7]
	v_cvt_pk_bf16_f32 v120, v120, v121
	v_mul_f32_e32 v121, 0xbfb8aa3b, v126
	v_exp_f32_e32 v121, v121
	s_mov_b64 s[22:23], s[16:17]
	v_add_f32_e32 v121, 1.0, v121
	v_rcp_f32_e32 v124, v121
	v_mul_f32_e32 v121, 0xbfb8aa3b, v127
	v_exp_f32_e32 v121, v121
	s_nop 0
	v_add_f32_e32 v121, 1.0, v121
	v_rcp_f32_e32 v125, v121
	s_nop 0
	v_pk_mul_f32 v[124:125], v[126:127], v[124:125]
	s_nop 0
	v_pk_mul_f32 v[122:123], v[122:123], v[124:125]
	s_nop 0
	v_cvt_pk_bf16_f32 v121, v122, v123
	v_lshl_add_u64 v[122:123], v[148:149], 0, s[18:19]
	global_store_dwordx2 v[122:123], v[120:121], off
	v_mul_f32_e32 v120, 0xbfb8aa3b, v116
	v_mul_f32_e32 v121, 0xbfb8aa3b, v117
	v_exp_f32_e32 v120, v120
	v_exp_f32_e32 v121, v121
	v_add_f32_e32 v120, 1.0, v120
	v_add_f32_e32 v121, 1.0, v121
	v_rcp_f32_e32 v120, v120
	v_rcp_f32_e32 v121, v121
	s_nop 0
	v_pk_mul_f32 v[116:117], v[116:117], v[120:121]
	s_nop 0
	v_pk_mul_f32 v[112:113], v[112:113], v[116:117]
	s_nop 0
	v_cvt_pk_bf16_f32 v112, v112, v113
	v_mul_f32_e32 v113, 0xbfb8aa3b, v118
	v_exp_f32_e32 v113, v113
	s_nop 0
	v_add_f32_e32 v113, 1.0, v113
	v_rcp_f32_e32 v116, v113
	v_mul_f32_e32 v113, 0xbfb8aa3b, v119
	v_exp_f32_e32 v113, v113
	s_nop 0
	v_add_f32_e32 v113, 1.0, v113
	v_rcp_f32_e32 v117, v113
	s_nop 0
	v_pk_mul_f32 v[116:117], v[118:119], v[116:117]
	s_nop 0
	v_pk_mul_f32 v[114:115], v[114:115], v[116:117]
	s_nop 0
	v_cvt_pk_bf16_f32 v113, v114, v115
	v_mul_f32_e32 v114, 0xbfb8aa3b, v108
	v_mul_f32_e32 v115, 0xbfb8aa3b, v109
	v_exp_f32_e32 v114, v114
	v_exp_f32_e32 v115, v115
	global_store_dwordx2 v[122:123], v[112:113], off offset:128
	v_or_b32_e32 v112, 16, v147
	v_add_f32_e32 v114, 1.0, v114
	v_add_f32_e32 v115, 1.0, v115
	v_rcp_f32_e32 v114, v114
	v_rcp_f32_e32 v115, v115
	v_mad_i64_i32 v[112:113], s[20:21], v112, s40, v[132:133]
	v_pk_mul_f32 v[108:109], v[108:109], v[114:115]
	s_nop 0
	v_pk_mul_f32 v[104:105], v[104:105], v[108:109]
	s_nop 0
	v_cvt_pk_bf16_f32 v104, v104, v105
	v_mul_f32_e32 v105, 0xbfb8aa3b, v110
	v_exp_f32_e32 v105, v105
	s_nop 0
	v_add_f32_e32 v105, 1.0, v105
	v_rcp_f32_e32 v108, v105
	v_mul_f32_e32 v105, 0xbfb8aa3b, v111
	v_exp_f32_e32 v105, v105
	s_nop 0
	v_add_f32_e32 v105, 1.0, v105
	v_rcp_f32_e32 v109, v105
	s_nop 0
	v_pk_mul_f32 v[108:109], v[110:111], v[108:109]
	s_nop 0
	v_pk_mul_f32 v[106:107], v[106:107], v[108:109]
	s_nop 0
	v_cvt_pk_bf16_f32 v105, v106, v107
	v_lshl_add_u64 v[106:107], v[112:113], 0, s[18:19]
	global_store_dwordx2 v[106:107], v[104:105], off
	v_mul_f32_e32 v104, 0xbfb8aa3b, v100
	v_mul_f32_e32 v105, 0xbfb8aa3b, v101
	v_exp_f32_e32 v104, v104
	v_exp_f32_e32 v105, v105
	v_add_f32_e32 v104, 1.0, v104
	v_add_f32_e32 v105, 1.0, v105
	v_rcp_f32_e32 v104, v104
	v_rcp_f32_e32 v105, v105
	s_nop 0
	v_pk_mul_f32 v[100:101], v[100:101], v[104:105]
	s_nop 0
	v_pk_mul_f32 v[96:97], v[96:97], v[100:101]
	s_nop 0
	v_cvt_pk_bf16_f32 v96, v96, v97
	v_mul_f32_e32 v97, 0xbfb8aa3b, v102
	v_exp_f32_e32 v97, v97
	s_nop 0
	v_add_f32_e32 v97, 1.0, v97
	v_rcp_f32_e32 v100, v97
	v_mul_f32_e32 v97, 0xbfb8aa3b, v103
	v_exp_f32_e32 v97, v97
	s_nop 0
	v_add_f32_e32 v97, 1.0, v97
	v_rcp_f32_e32 v101, v97
	s_nop 0
	v_pk_mul_f32 v[100:101], v[102:103], v[100:101]
	s_nop 0
	v_pk_mul_f32 v[98:99], v[98:99], v[100:101]
	s_nop 0
	v_cvt_pk_bf16_f32 v97, v98, v99
	v_mul_f32_e32 v98, 0xbfb8aa3b, v92
	v_mul_f32_e32 v99, 0xbfb8aa3b, v93
	v_exp_f32_e32 v98, v98
	v_exp_f32_e32 v99, v99
	global_store_dwordx2 v[106:107], v[96:97], off offset:128
	v_or_b32_e32 v96, 32, v147
	v_add_f32_e32 v98, 1.0, v98
	v_add_f32_e32 v99, 1.0, v99
	v_rcp_f32_e32 v98, v98
	v_rcp_f32_e32 v99, v99
	v_mad_i64_i32 v[96:97], s[20:21], v96, s40, v[132:133]
	v_pk_mul_f32 v[92:93], v[92:93], v[98:99]
	s_nop 0
	v_pk_mul_f32 v[88:89], v[88:89], v[92:93]
	s_nop 0
	v_cvt_pk_bf16_f32 v88, v88, v89
	v_mul_f32_e32 v89, 0xbfb8aa3b, v94
	v_exp_f32_e32 v89, v89
	s_nop 0
	v_add_f32_e32 v89, 1.0, v89
	v_rcp_f32_e32 v92, v89
	v_mul_f32_e32 v89, 0xbfb8aa3b, v95
	v_exp_f32_e32 v89, v89
	s_nop 0
	v_add_f32_e32 v89, 1.0, v89
	v_rcp_f32_e32 v93, v89
	s_nop 0
	v_pk_mul_f32 v[92:93], v[94:95], v[92:93]
	s_nop 0
	v_pk_mul_f32 v[90:91], v[90:91], v[92:93]
	s_nop 0
	v_cvt_pk_bf16_f32 v89, v90, v91
	v_lshl_add_u64 v[90:91], v[96:97], 0, s[18:19]
	global_store_dwordx2 v[90:91], v[88:89], off
	v_mul_f32_e32 v88, 0xbfb8aa3b, v84
	v_mul_f32_e32 v89, 0xbfb8aa3b, v85
	v_exp_f32_e32 v88, v88
	v_exp_f32_e32 v89, v89
	v_add_f32_e32 v88, 1.0, v88
	v_add_f32_e32 v89, 1.0, v89
	v_rcp_f32_e32 v88, v88
	v_rcp_f32_e32 v89, v89
	s_nop 0
	v_pk_mul_f32 v[84:85], v[84:85], v[88:89]
	s_nop 0
	v_pk_mul_f32 v[80:81], v[80:81], v[84:85]
	s_nop 0
	v_cvt_pk_bf16_f32 v80, v80, v81
	v_mul_f32_e32 v81, 0xbfb8aa3b, v86
	v_exp_f32_e32 v81, v81
	s_nop 0
	v_add_f32_e32 v81, 1.0, v81
	v_rcp_f32_e32 v84, v81
	v_mul_f32_e32 v81, 0xbfb8aa3b, v87
	v_exp_f32_e32 v81, v81
	s_nop 0
	v_add_f32_e32 v81, 1.0, v81
	v_rcp_f32_e32 v85, v81
	s_nop 0
	v_pk_mul_f32 v[84:85], v[86:87], v[84:85]
	s_nop 0
	v_pk_mul_f32 v[82:83], v[82:83], v[84:85]
	s_nop 0
	v_cvt_pk_bf16_f32 v81, v82, v83
	v_mul_f32_e32 v82, 0xbfb8aa3b, v76
	v_mul_f32_e32 v83, 0xbfb8aa3b, v77
	v_exp_f32_e32 v82, v82
	v_exp_f32_e32 v83, v83
	global_store_dwordx2 v[90:91], v[80:81], off offset:128
	v_or_b32_e32 v80, 48, v147
	v_add_f32_e32 v82, 1.0, v82
	v_add_f32_e32 v83, 1.0, v83
	v_rcp_f32_e32 v82, v82
	v_rcp_f32_e32 v83, v83
	v_mad_i64_i32 v[80:81], s[20:21], v80, s40, v[132:133]
	v_pk_mul_f32 v[76:77], v[76:77], v[82:83]
	s_nop 0
	v_pk_mul_f32 v[72:73], v[72:73], v[76:77]
	s_nop 0
	v_cvt_pk_bf16_f32 v72, v72, v73
	v_mul_f32_e32 v73, 0xbfb8aa3b, v78
	v_exp_f32_e32 v73, v73
	s_nop 0
	v_add_f32_e32 v73, 1.0, v73
	v_rcp_f32_e32 v76, v73
	v_mul_f32_e32 v73, 0xbfb8aa3b, v79
	v_exp_f32_e32 v73, v73
	s_nop 0
	v_add_f32_e32 v73, 1.0, v73
	v_rcp_f32_e32 v77, v73
	s_nop 0
	v_pk_mul_f32 v[76:77], v[78:79], v[76:77]
	s_nop 0
	v_pk_mul_f32 v[74:75], v[74:75], v[76:77]
	s_nop 0
	v_cvt_pk_bf16_f32 v73, v74, v75
	v_lshl_add_u64 v[74:75], v[80:81], 0, s[18:19]
	global_store_dwordx2 v[74:75], v[72:73], off
	v_mul_f32_e32 v72, 0xbfb8aa3b, v68
	v_mul_f32_e32 v73, 0xbfb8aa3b, v69
	v_exp_f32_e32 v72, v72
	v_exp_f32_e32 v73, v73
	v_add_f32_e32 v72, 1.0, v72
	v_add_f32_e32 v73, 1.0, v73
	v_rcp_f32_e32 v72, v72
	v_rcp_f32_e32 v73, v73
	s_nop 0
	v_pk_mul_f32 v[68:69], v[68:69], v[72:73]
	s_nop 0
	v_pk_mul_f32 v[64:65], v[64:65], v[68:69]
	s_nop 0
	v_cvt_pk_bf16_f32 v64, v64, v65
	v_mul_f32_e32 v65, 0xbfb8aa3b, v70
	v_exp_f32_e32 v65, v65
	s_nop 0
	v_add_f32_e32 v65, 1.0, v65
	v_rcp_f32_e32 v68, v65
	v_mul_f32_e32 v65, 0xbfb8aa3b, v71
	v_exp_f32_e32 v65, v65
	s_nop 0
	v_add_f32_e32 v65, 1.0, v65
	v_rcp_f32_e32 v69, v65
	s_nop 0
	v_pk_mul_f32 v[68:69], v[70:71], v[68:69]
	s_nop 0
	v_pk_mul_f32 v[66:67], v[66:67], v[68:69]
	s_nop 0
	v_cvt_pk_bf16_f32 v65, v66, v67
	v_mul_f32_e32 v66, 0xbfb8aa3b, v60
	v_mul_f32_e32 v67, 0xbfb8aa3b, v61
	v_exp_f32_e32 v66, v66
	v_exp_f32_e32 v67, v67
	global_store_dwordx2 v[74:75], v[64:65], off offset:128
	v_add_u32_e32 v64, 0x80, v147
	v_add_f32_e32 v66, 1.0, v66
	v_add_f32_e32 v67, 1.0, v67
	v_rcp_f32_e32 v66, v66
	v_rcp_f32_e32 v67, v67
	v_mad_i64_i32 v[64:65], s[20:21], v64, s40, v[132:133]
	v_pk_mul_f32 v[60:61], v[60:61], v[66:67]
	s_nop 0
	v_pk_mul_f32 v[56:57], v[56:57], v[60:61]
	s_nop 0
	v_cvt_pk_bf16_f32 v56, v56, v57
	v_mul_f32_e32 v57, 0xbfb8aa3b, v62
	v_exp_f32_e32 v57, v57
	s_nop 0
	v_add_f32_e32 v57, 1.0, v57
	v_rcp_f32_e32 v60, v57
	v_mul_f32_e32 v57, 0xbfb8aa3b, v63
	v_exp_f32_e32 v57, v57
	s_nop 0
	v_add_f32_e32 v57, 1.0, v57
	v_rcp_f32_e32 v61, v57
	s_nop 0
	v_pk_mul_f32 v[60:61], v[62:63], v[60:61]
	s_nop 0
	v_pk_mul_f32 v[58:59], v[58:59], v[60:61]
	s_nop 0
	v_cvt_pk_bf16_f32 v57, v58, v59
	v_lshl_add_u64 v[58:59], v[64:65], 0, s[18:19]
	global_store_dwordx2 v[58:59], v[56:57], off
	v_mul_f32_e32 v56, 0xbfb8aa3b, v52
	v_mul_f32_e32 v57, 0xbfb8aa3b, v53
	v_exp_f32_e32 v56, v56
	v_exp_f32_e32 v57, v57
	v_add_f32_e32 v56, 1.0, v56
	v_add_f32_e32 v57, 1.0, v57
	v_rcp_f32_e32 v56, v56
	v_rcp_f32_e32 v57, v57
	s_nop 0
	v_pk_mul_f32 v[52:53], v[52:53], v[56:57]
	s_nop 0
	v_pk_mul_f32 v[48:49], v[48:49], v[52:53]
	s_nop 0
	v_cvt_pk_bf16_f32 v48, v48, v49
	v_mul_f32_e32 v49, 0xbfb8aa3b, v54
	v_exp_f32_e32 v49, v49
	s_nop 0
	v_add_f32_e32 v49, 1.0, v49
	v_rcp_f32_e32 v52, v49
	v_mul_f32_e32 v49, 0xbfb8aa3b, v55
	v_exp_f32_e32 v49, v49
	s_nop 0
	v_add_f32_e32 v49, 1.0, v49
	v_rcp_f32_e32 v53, v49
	s_nop 0
	v_pk_mul_f32 v[52:53], v[54:55], v[52:53]
	s_nop 0
	v_pk_mul_f32 v[50:51], v[50:51], v[52:53]
	s_nop 0
	v_cvt_pk_bf16_f32 v49, v50, v51
	v_mul_f32_e32 v50, 0xbfb8aa3b, v44
	v_mul_f32_e32 v51, 0xbfb8aa3b, v45
	v_exp_f32_e32 v50, v50
	v_exp_f32_e32 v51, v51
	global_store_dwordx2 v[58:59], v[48:49], off offset:128
	v_add_u32_e32 v48, 0x90, v147
	v_add_f32_e32 v50, 1.0, v50
	v_add_f32_e32 v51, 1.0, v51
	v_rcp_f32_e32 v50, v50
	v_rcp_f32_e32 v51, v51
	v_mad_i64_i32 v[48:49], s[20:21], v48, s40, v[132:133]
	v_pk_mul_f32 v[44:45], v[44:45], v[50:51]
	s_nop 0
	v_pk_mul_f32 v[40:41], v[40:41], v[44:45]
	s_nop 0
	v_cvt_pk_bf16_f32 v40, v40, v41
	v_mul_f32_e32 v41, 0xbfb8aa3b, v46
	v_exp_f32_e32 v41, v41
	s_nop 0
	v_add_f32_e32 v41, 1.0, v41
	v_rcp_f32_e32 v44, v41
	v_mul_f32_e32 v41, 0xbfb8aa3b, v47
	v_exp_f32_e32 v41, v41
	s_nop 0
	v_add_f32_e32 v41, 1.0, v41
	v_rcp_f32_e32 v45, v41
	s_nop 0
	v_pk_mul_f32 v[44:45], v[46:47], v[44:45]
	s_nop 0
	v_pk_mul_f32 v[42:43], v[42:43], v[44:45]
	s_nop 0
	v_cvt_pk_bf16_f32 v41, v42, v43
	v_lshl_add_u64 v[42:43], v[48:49], 0, s[18:19]
	global_store_dwordx2 v[42:43], v[40:41], off
	v_mul_f32_e32 v40, 0xbfb8aa3b, v36
	v_mul_f32_e32 v41, 0xbfb8aa3b, v37
	v_exp_f32_e32 v40, v40
	v_exp_f32_e32 v41, v41
	v_add_f32_e32 v40, 1.0, v40
	v_add_f32_e32 v41, 1.0, v41
	v_rcp_f32_e32 v40, v40
	v_rcp_f32_e32 v41, v41
	s_nop 0
	v_pk_mul_f32 v[36:37], v[36:37], v[40:41]
	s_nop 0
	v_pk_mul_f32 v[32:33], v[32:33], v[36:37]
	s_nop 0
	v_cvt_pk_bf16_f32 v32, v32, v33
	v_mul_f32_e32 v33, 0xbfb8aa3b, v38
	v_exp_f32_e32 v33, v33
	s_nop 0
	v_add_f32_e32 v33, 1.0, v33
	v_rcp_f32_e32 v36, v33
	v_mul_f32_e32 v33, 0xbfb8aa3b, v39
	v_exp_f32_e32 v33, v33
	s_nop 0
	v_add_f32_e32 v33, 1.0, v33
	v_rcp_f32_e32 v37, v33
	s_nop 0
	v_pk_mul_f32 v[36:37], v[38:39], v[36:37]
	s_nop 0
	v_pk_mul_f32 v[34:35], v[34:35], v[36:37]
	s_nop 0
	v_cvt_pk_bf16_f32 v33, v34, v35
	v_mul_f32_e32 v34, 0xbfb8aa3b, v28
	v_mul_f32_e32 v35, 0xbfb8aa3b, v29
	v_exp_f32_e32 v34, v34
	v_exp_f32_e32 v35, v35
	global_store_dwordx2 v[42:43], v[32:33], off offset:128
	v_add_u32_e32 v32, 0xa0, v147
	v_add_f32_e32 v34, 1.0, v34
	v_add_f32_e32 v35, 1.0, v35
	v_rcp_f32_e32 v34, v34
	v_rcp_f32_e32 v35, v35
	v_mad_i64_i32 v[32:33], s[20:21], v32, s40, v[132:133]
	v_pk_mul_f32 v[28:29], v[28:29], v[34:35]
	s_nop 0
	v_pk_mul_f32 v[24:25], v[24:25], v[28:29]
	s_nop 0
	v_cvt_pk_bf16_f32 v24, v24, v25
	v_mul_f32_e32 v25, 0xbfb8aa3b, v30
	v_exp_f32_e32 v25, v25
	s_nop 0
	v_add_f32_e32 v25, 1.0, v25
	v_rcp_f32_e32 v28, v25
	v_mul_f32_e32 v25, 0xbfb8aa3b, v31
	v_exp_f32_e32 v25, v25
	s_nop 0
	v_add_f32_e32 v25, 1.0, v25
	v_rcp_f32_e32 v29, v25
	s_nop 0
	v_pk_mul_f32 v[28:29], v[30:31], v[28:29]
	s_nop 0
	v_pk_mul_f32 v[26:27], v[26:27], v[28:29]
	s_nop 0
	v_cvt_pk_bf16_f32 v25, v26, v27
	v_lshl_add_u64 v[26:27], v[32:33], 0, s[18:19]
	global_store_dwordx2 v[26:27], v[24:25], off
	v_mul_f32_e32 v24, 0xbfb8aa3b, v20
	v_mul_f32_e32 v25, 0xbfb8aa3b, v21
	v_exp_f32_e32 v24, v24
	v_exp_f32_e32 v25, v25
	v_add_f32_e32 v24, 1.0, v24
	v_add_f32_e32 v25, 1.0, v25
	v_rcp_f32_e32 v24, v24
	v_rcp_f32_e32 v25, v25
	s_nop 0
	v_pk_mul_f32 v[20:21], v[20:21], v[24:25]
	s_nop 0
	v_pk_mul_f32 v[16:17], v[16:17], v[20:21]
	s_nop 0
	v_cvt_pk_bf16_f32 v16, v16, v17
	v_mul_f32_e32 v17, 0xbfb8aa3b, v22
	v_exp_f32_e32 v17, v17
	s_nop 0
	v_add_f32_e32 v17, 1.0, v17
	v_rcp_f32_e32 v20, v17
	v_mul_f32_e32 v17, 0xbfb8aa3b, v23
	v_exp_f32_e32 v17, v17
	s_nop 0
	v_add_f32_e32 v17, 1.0, v17
	v_rcp_f32_e32 v21, v17
	s_nop 0
	v_pk_mul_f32 v[20:21], v[22:23], v[20:21]
	s_nop 0
	v_pk_mul_f32 v[18:19], v[18:19], v[20:21]
	s_nop 0
	v_cvt_pk_bf16_f32 v17, v18, v19
	v_mul_f32_e32 v18, 0xbfb8aa3b, v12
	v_mul_f32_e32 v19, 0xbfb8aa3b, v13
	v_exp_f32_e32 v18, v18
	v_exp_f32_e32 v19, v19
	global_store_dwordx2 v[26:27], v[16:17], off offset:128
	v_add_u32_e32 v16, 0xb0, v147
	v_add_f32_e32 v18, 1.0, v18
	v_add_f32_e32 v19, 1.0, v19
	v_rcp_f32_e32 v18, v18
	v_rcp_f32_e32 v19, v19
	v_mad_i64_i32 v[16:17], s[20:21], v16, s40, v[132:133]
	s_mov_b64 s[20:21], s[14:15]
	v_pk_mul_f32 v[12:13], v[12:13], v[18:19]
	s_nop 0
	v_pk_mul_f32 v[8:9], v[8:9], v[12:13]
	s_nop 0
	v_cvt_pk_bf16_f32 v8, v8, v9
	v_mul_f32_e32 v9, 0xbfb8aa3b, v14
	v_exp_f32_e32 v9, v9
	s_nop 0
	v_add_f32_e32 v9, 1.0, v9
	v_rcp_f32_e32 v12, v9
	v_mul_f32_e32 v9, 0xbfb8aa3b, v15
	v_exp_f32_e32 v9, v9
	s_nop 0
	v_add_f32_e32 v9, 1.0, v9
	v_rcp_f32_e32 v13, v9
	s_nop 0
	v_pk_mul_f32 v[12:13], v[14:15], v[12:13]
	s_nop 0
	v_pk_mul_f32 v[10:11], v[10:11], v[12:13]
	s_nop 0
	v_cvt_pk_bf16_f32 v9, v10, v11
	v_lshl_add_u64 v[10:11], v[16:17], 0, s[18:19]
	global_store_dwordx2 v[10:11], v[8:9], off
	v_mul_f32_e32 v8, 0xbfb8aa3b, v4
	v_mul_f32_e32 v9, 0xbfb8aa3b, v5
	v_exp_f32_e32 v8, v8
	v_exp_f32_e32 v9, v9
	s_mov_b32 s19, s10
	s_mov_b32 s18, s12
	v_add_f32_e32 v8, 1.0, v8
	v_add_f32_e32 v9, 1.0, v9
	v_rcp_f32_e32 v8, v8
	v_rcp_f32_e32 v9, v9
	s_nop 0
	v_pk_mul_f32 v[4:5], v[4:5], v[8:9]
	s_nop 0
	v_pk_mul_f32 v[0:1], v[0:1], v[4:5]
	s_nop 0
	v_cvt_pk_bf16_f32 v0, v0, v1
	v_mul_f32_e32 v1, 0xbfb8aa3b, v6
	v_exp_f32_e32 v1, v1
	s_nop 0
	v_add_f32_e32 v1, 1.0, v1
	v_rcp_f32_e32 v4, v1
	v_mul_f32_e32 v1, 0xbfb8aa3b, v7
	v_exp_f32_e32 v1, v1
	s_nop 0
	v_add_f32_e32 v1, 1.0, v1
	v_rcp_f32_e32 v5, v1
	s_nop 0
	v_pk_mul_f32 v[4:5], v[6:7], v[4:5]
	s_nop 0
	v_pk_mul_f32 v[2:3], v[2:3], v[4:5]
	s_nop 0
	v_cvt_pk_bf16_f32 v1, v2, v3
	global_store_dwordx2 v[10:11], v[0:1], off offset:128
	s_cbranch_vccz .LBB0_603
	s_waitcnt vmcnt(0)
	s_cmpk_gt_u32 s1, 0xff
	s_cbranch_scc1 .LBB0_610
	s_barrier

.LBB0_682:
	ds_read_b128 v[128:131], v151
	ds_read_b128 v[144:147], v151 offset:1024
	ds_read_b128 v[154:157], v151 offset:2048
	ds_read_b128 v[158:161], v151 offset:3072
	s_add_i32 m0, s4, 0xc000
	ds_read_b128 v[162:165], v152
	ds_read_b128 v[166:169], v152 offset:1024
	ds_read_b128 v[170:173], v152 offset:2048
	ds_read_b128 v[174:177], v152 offset:3072
	ds_read_b128 v[178:181], v152 offset:4096
	ds_read_b128 v[182:185], v152 offset:5120
	ds_read_b128 v[186:189], v152 offset:6144
	ds_read_b128 v[190:193], v152 offset:7168
	global_load_lds_dwordx4 v136, s[14:15]
	v_lshl_add_u64 v[194:195], s[14:15], 0, v[138:139]
	s_add_i32 m0, s4, 0xe000
	s_nop 0
	global_load_lds_dwordx4 v[194:195], off
	s_waitcnt lgkmcnt(8)
	s_barrier
	s_waitcnt lgkmcnt(0)
	s_waitcnt lgkmcnt(0)
	v_mfma_f32_16x16x32_bf16 v[124:127], v[128:131], v[162:165], v[124:127]
	s_add_u32 s16, s14, 0x100
	s_addc_u32 s17, s15, 0
	s_cmpk_eq_i32 s40, 0x54
	s_cselect_b32 s21, s9, s17
	s_cselect_b32 s20, s8, s16
	s_cselect_b32 s19, s11, s39
	s_cselect_b32 s18, s10, s38
	v_mfma_f32_16x16x32_bf16 v[92:95], v[154:157], v[162:165], v[92:95]
	v_mfma_f32_16x16x32_bf16 v[120:123], v[128:131], v[170:173], v[120:123]
	v_mfma_f32_16x16x32_bf16 v[88:91], v[154:157], v[170:173], v[88:91]
	v_mfma_f32_16x16x32_bf16 v[116:119], v[128:131], v[178:181], v[116:119]
	v_mfma_f32_16x16x32_bf16 v[84:87], v[154:157], v[178:181], v[84:87]
	v_mfma_f32_16x16x32_bf16 v[112:115], v[128:131], v[186:189], v[112:115]
	v_mfma_f32_16x16x32_bf16 v[80:83], v[154:157], v[186:189], v[80:83]
	v_mfma_f32_16x16x32_bf16 v[124:127], v[144:147], v[166:169], v[124:127]
	v_mfma_f32_16x16x32_bf16 v[92:95], v[158:161], v[166:169], v[92:95]
	v_mfma_f32_16x16x32_bf16 v[120:123], v[144:147], v[174:177], v[120:123]
	v_mfma_f32_16x16x32_bf16 v[88:91], v[158:161], v[174:177], v[88:91]
	v_mfma_f32_16x16x32_bf16 v[116:119], v[144:147], v[182:185], v[116:119]
	v_mfma_f32_16x16x32_bf16 v[84:87], v[158:161], v[182:185], v[84:87]
	v_mfma_f32_16x16x32_bf16 v[112:115], v[144:147], v[190:193], v[112:115]
	v_mfma_f32_16x16x32_bf16 v[80:83], v[158:161], v[190:193], v[80:83]
	s_barrier
	s_add_i32 s14, s30, s3
	v_lshl_add_u64 v[210:211], s[18:19], 0, v[132:133]
	s_mov_b32 m0, s14
	ds_read_b128 v[194:197], v153
	ds_read_b128 v[198:201], v153 offset:1024
	ds_read_b128 v[202:205], v153 offset:2048
	ds_read_b128 v[206:209], v153 offset:3072
	global_load_lds_dwordx4 v[210:211], off
	s_add_i32 m0, s14, 0x2000
	s_nop 0
	global_load_lds_dwordx4 v134, s[18:19]
	s_barrier
	s_waitcnt lgkmcnt(0)
	s_waitcnt lgkmcnt(0)
	v_mfma_f32_16x16x32_bf16 v[76:79], v[194:197], v[162:165], v[76:79]
	v_mfma_f32_16x16x32_bf16 v[48:51], v[202:205], v[162:165], v[48:51]
	v_mfma_f32_16x16x32_bf16 v[68:71], v[194:197], v[170:173], v[68:71]
	v_mfma_f32_16x16x32_bf16 v[40:43], v[202:205], v[170:173], v[40:43]
	v_mfma_f32_16x16x32_bf16 v[60:63], v[194:197], v[178:181], v[60:63]
	v_mfma_f32_16x16x32_bf16 v[36:39], v[202:205], v[178:181], v[36:39]
	v_mfma_f32_16x16x32_bf16 v[52:55], v[194:197], v[186:189], v[52:55]
	v_mfma_f32_16x16x32_bf16 v[28:31], v[202:205], v[186:189], v[28:31]
	v_mfma_f32_16x16x32_bf16 v[76:79], v[198:201], v[166:169], v[76:79]
	v_mfma_f32_16x16x32_bf16 v[48:51], v[206:209], v[166:169], v[48:51]
	v_mfma_f32_16x16x32_bf16 v[68:71], v[198:201], v[174:177], v[68:71]
	v_mfma_f32_16x16x32_bf16 v[40:43], v[206:209], v[174:177], v[40:43]
	v_mfma_f32_16x16x32_bf16 v[60:63], v[198:201], v[182:185], v[60:63]
	v_mfma_f32_16x16x32_bf16 v[36:39], v[206:209], v[182:185], v[36:39]
	v_mfma_f32_16x16x32_bf16 v[52:55], v[198:201], v[190:193], v[52:55]
	v_mfma_f32_16x16x32_bf16 v[28:31], v[206:209], v[190:193], v[28:31]
	s_mov_b32 m0, s4
	v_lshl_add_u64 v[214:215], s[20:21], 0, v[132:133]
	s_barrier
	ds_read_b128 v[162:165], v152 offset:16384
	ds_read_b128 v[166:169], v152 offset:17408
	ds_read_b128 v[170:173], v152 offset:18432
	ds_read_b128 v[174:177], v152 offset:19456
	ds_read_b128 v[178:181], v152 offset:20480
	ds_read_b128 v[182:185], v152 offset:21504
	ds_read_b128 v[186:189], v152 offset:22528
	ds_read_b128 v[190:193], v152 offset:23552
	global_load_lds_dwordx4 v[214:215], off
	v_lshl_add_u64 v[216:217], s[20:21], 0, v[134:135]
	s_mov_b32 m0, s5
	s_nop 0
	global_load_lds_dwordx4 v134, s[20:21]
	s_barrier
	s_waitcnt lgkmcnt(0)
	s_waitcnt lgkmcnt(0)
	v_mfma_f32_16x16x32_bf16 v[108:111], v[128:131], v[162:165], v[108:111]
	v_mfma_f32_16x16x32_bf16 v[72:75], v[154:157], v[162:165], v[72:75]
	v_mfma_f32_16x16x32_bf16 v[104:107], v[128:131], v[170:173], v[104:107]
	v_mfma_f32_16x16x32_bf16 v[64:67], v[154:157], v[170:173], v[64:67]
	v_mfma_f32_16x16x32_bf16 v[100:103], v[128:131], v[178:181], v[100:103]
	v_mfma_f32_16x16x32_bf16 v[56:59], v[154:157], v[178:181], v[56:59]
	v_mfma_f32_16x16x32_bf16 v[96:99], v[128:131], v[186:189], v[96:99]
	v_mfma_f32_16x16x32_bf16 v[44:47], v[154:157], v[186:189], v[44:47]
	v_mfma_f32_16x16x32_bf16 v[108:111], v[144:147], v[166:169], v[108:111]
	v_mfma_f32_16x16x32_bf16 v[72:75], v[158:161], v[166:169], v[72:75]
	v_mfma_f32_16x16x32_bf16 v[104:107], v[144:147], v[174:177], v[104:107]
	v_mfma_f32_16x16x32_bf16 v[64:67], v[158:161], v[174:177], v[64:67]
	v_mfma_f32_16x16x32_bf16 v[100:103], v[144:147], v[182:185], v[100:103]
	v_mfma_f32_16x16x32_bf16 v[56:59], v[158:161], v[182:185], v[56:59]
	v_mfma_f32_16x16x32_bf16 v[96:99], v[144:147], v[190:193], v[96:99]
	v_mfma_f32_16x16x32_bf16 v[44:47], v[158:161], v[190:193], v[44:47]
	s_barrier
	s_add_u32 s14, s18, 0x160000
	s_addc_u32 s15, s19, 0
	s_add_i32 s41, s31, s3
	v_lshl_add_u64 v[128:129], s[14:15], 0, v[132:133]
	s_mov_b32 m0, s41
	s_nop 0
	global_load_lds_dwordx4 v[128:129], off
	s_add_i32 m0, s41, 0x2000
	s_nop 0
	global_load_lds_dwordx4 v134, s[14:15]
	s_waitcnt vmcnt(6)
	s_barrier
	v_mfma_f32_16x16x32_bf16 v[32:35], v[194:197], v[162:165], v[32:35]
	v_mfma_f32_16x16x32_bf16 v[12:15], v[202:205], v[162:165], v[12:15]
	v_mfma_f32_16x16x32_bf16 v[24:27], v[194:197], v[170:173], v[24:27]
	v_mfma_f32_16x16x32_bf16 v[8:11], v[202:205], v[170:173], v[8:11]
	v_mfma_f32_16x16x32_bf16 v[20:23], v[194:197], v[178:181], v[20:23]
	v_mfma_f32_16x16x32_bf16 v[4:7], v[202:205], v[178:181], v[4:7]
	v_mfma_f32_16x16x32_bf16 v[16:19], v[194:197], v[186:189], v[16:19]
	v_mfma_f32_16x16x32_bf16 v[0:3], v[202:205], v[186:189], v[0:3]
	v_mfma_f32_16x16x32_bf16 v[32:35], v[198:201], v[166:169], v[32:35]
	v_mfma_f32_16x16x32_bf16 v[12:15], v[206:209], v[166:169], v[12:15]
	v_mfma_f32_16x16x32_bf16 v[24:27], v[198:201], v[174:177], v[24:27]
	v_mfma_f32_16x16x32_bf16 v[8:11], v[206:209], v[174:177], v[8:11]
	v_mfma_f32_16x16x32_bf16 v[20:23], v[198:201], v[182:185], v[20:23]
	v_mfma_f32_16x16x32_bf16 v[4:7], v[206:209], v[182:185], v[4:7]
	v_mfma_f32_16x16x32_bf16 v[16:19], v[198:201], v[190:193], v[16:19]
	v_mfma_f32_16x16x32_bf16 v[0:3], v[206:209], v[190:193], v[0:3]
	s_add_i32 s41, 0, 0x18000
	v_add_u32_e32 v158, s41, v149
	s_barrier
	ds_read_b128 v[128:131], v158
	ds_read_b128 v[144:147], v158 offset:1024
	ds_read_b128 v[154:157], v158 offset:2048
	ds_read_b128 v[158:161], v158 offset:3072
	s_add_u32 s14, s20, 0x160000
	s_addc_u32 s15, s21, 0
	s_mov_b32 m0, s22
	v_lshl_add_u64 v[194:195], s[14:15], 0, v[132:133]
	ds_read_b128 v[162:165], v152 offset:32768
	ds_read_b128 v[166:169], v152 offset:33792
	ds_read_b128 v[170:173], v152 offset:34816
	ds_read_b128 v[174:177], v152 offset:35840
	ds_read_b128 v[178:181], v152 offset:36864
	ds_read_b128 v[182:185], v152 offset:37888
	ds_read_b128 v[186:189], v152 offset:38912
	ds_read_b128 v[190:193], v152 offset:39936
	global_load_lds_dwordx4 v[194:195], off
	s_mov_b32 m0, s23
	s_nop 0
	global_load_lds_dwordx4 v134, s[14:15]
	s_waitcnt lgkmcnt(8)
	s_barrier
	s_waitcnt lgkmcnt(0)
	s_waitcnt lgkmcnt(0)
	v_mfma_f32_16x16x32_bf16 v[124:127], v[128:131], v[162:165], v[124:127]
	v_mfma_f32_16x16x32_bf16 v[92:95], v[154:157], v[162:165], v[92:95]
	v_mfma_f32_16x16x32_bf16 v[120:123], v[128:131], v[170:173], v[120:123]
	v_mfma_f32_16x16x32_bf16 v[88:91], v[154:157], v[170:173], v[88:91]
	v_mfma_f32_16x16x32_bf16 v[116:119], v[128:131], v[178:181], v[116:119]
	v_mfma_f32_16x16x32_bf16 v[84:87], v[154:157], v[178:181], v[84:87]
	v_mfma_f32_16x16x32_bf16 v[112:115], v[128:131], v[186:189], v[112:115]
	v_mfma_f32_16x16x32_bf16 v[80:83], v[154:157], v[186:189], v[80:83]
	v_mfma_f32_16x16x32_bf16 v[124:127], v[144:147], v[166:169], v[124:127]
	v_mfma_f32_16x16x32_bf16 v[92:95], v[158:161], v[166:169], v[92:95]
	v_mfma_f32_16x16x32_bf16 v[120:123], v[144:147], v[174:177], v[120:123]
	v_mfma_f32_16x16x32_bf16 v[88:91], v[158:161], v[174:177], v[88:91]
	v_mfma_f32_16x16x32_bf16 v[116:119], v[144:147], v[182:185], v[116:119]
	v_mfma_f32_16x16x32_bf16 v[84:87], v[158:161], v[182:185], v[84:87]
	v_mfma_f32_16x16x32_bf16 v[112:115], v[144:147], v[190:193], v[112:115]
	v_mfma_f32_16x16x32_bf16 v[80:83], v[158:161], v[190:193], v[80:83]
	s_barrier
	s_add_i32 s20, 0, 0x1c000
	s_add_i32 s14, s41, s3
	v_add_u32_e32 v206, s20, v149
	v_lshl_add_u64 v[210:211], v[210:211], 0, s[12:13]
	s_mov_b32 m0, s14
	ds_read_b128 v[194:197], v206
	ds_read_b128 v[198:201], v206 offset:1024
	ds_read_b128 v[202:205], v206 offset:2048
	ds_read_b128 v[206:209], v206 offset:3072
	global_load_lds_dwordx4 v[210:211], off
	s_add_u32 s98, s18, s12
	s_addc_u32 s99, s19, s13
	s_add_i32 m0, s14, 0x2000
	s_nop 0
	global_load_lds_dwordx4 v134, s[98:99]
	s_barrier
	s_waitcnt lgkmcnt(0)
	s_waitcnt lgkmcnt(0)
	v_mfma_f32_16x16x32_bf16 v[76:79], v[194:197], v[162:165], v[76:79]
	v_mfma_f32_16x16x32_bf16 v[48:51], v[202:205], v[162:165], v[48:51]
	v_mfma_f32_16x16x32_bf16 v[68:71], v[194:197], v[170:173], v[68:71]
	v_mfma_f32_16x16x32_bf16 v[40:43], v[202:205], v[170:173], v[40:43]
	v_mfma_f32_16x16x32_bf16 v[60:63], v[194:197], v[178:181], v[60:63]
	v_mfma_f32_16x16x32_bf16 v[36:39], v[202:205], v[178:181], v[36:39]
	v_mfma_f32_16x16x32_bf16 v[52:55], v[194:197], v[186:189], v[52:55]
	v_mfma_f32_16x16x32_bf16 v[28:31], v[202:205], v[186:189], v[28:31]
	v_mfma_f32_16x16x32_bf16 v[76:79], v[198:201], v[166:169], v[76:79]
	v_mfma_f32_16x16x32_bf16 v[48:51], v[206:209], v[166:169], v[48:51]
	v_mfma_f32_16x16x32_bf16 v[68:71], v[198:201], v[174:177], v[68:71]
	v_mfma_f32_16x16x32_bf16 v[40:43], v[206:209], v[174:177], v[40:43]
	v_mfma_f32_16x16x32_bf16 v[60:63], v[198:201], v[182:185], v[60:63]
	v_mfma_f32_16x16x32_bf16 v[36:39], v[206:209], v[182:185], v[36:39]
	v_mfma_f32_16x16x32_bf16 v[52:55], v[198:201], v[190:193], v[52:55]
	v_mfma_f32_16x16x32_bf16 v[28:31], v[206:209], v[190:193], v[28:31]
	s_mov_b32 m0, s25
	v_lshl_add_u64 v[210:211], v[214:215], 0, s[12:13]
	s_barrier
	ds_read_b128 v[162:165], v152 offset:49152
	ds_read_b128 v[166:169], v152 offset:50176
	ds_read_b128 v[170:173], v152 offset:51200
	ds_read_b128 v[174:177], v152 offset:52224
	ds_read_b128 v[178:181], v152 offset:53248
	ds_read_b128 v[182:185], v152 offset:54272
	ds_read_b128 v[186:189], v152 offset:55296
	ds_read_b128 v[190:193], v152 offset:56320
	global_load_lds_dwordx4 v[210:211], off
	v_lshl_add_u64 v[210:211], v[216:217], 0, s[12:13]
	s_mov_b32 m0, s26
	s_nop 0
	global_load_lds_dwordx4 v[210:211], off
	s_barrier
	s_waitcnt lgkmcnt(0)
	s_waitcnt lgkmcnt(0)
	v_mfma_f32_16x16x32_bf16 v[108:111], v[128:131], v[162:165], v[108:111]
	v_mfma_f32_16x16x32_bf16 v[72:75], v[154:157], v[162:165], v[72:75]
	v_mfma_f32_16x16x32_bf16 v[104:107], v[128:131], v[170:173], v[104:107]
	v_mfma_f32_16x16x32_bf16 v[64:67], v[154:157], v[170:173], v[64:67]
	v_mfma_f32_16x16x32_bf16 v[100:103], v[128:131], v[178:181], v[100:103]
	v_mfma_f32_16x16x32_bf16 v[56:59], v[154:157], v[178:181], v[56:59]
	v_mfma_f32_16x16x32_bf16 v[96:99], v[128:131], v[186:189], v[96:99]
	v_mfma_f32_16x16x32_bf16 v[44:47], v[154:157], v[186:189], v[44:47]
	v_mfma_f32_16x16x32_bf16 v[108:111], v[144:147], v[166:169], v[108:111]
	v_mfma_f32_16x16x32_bf16 v[72:75], v[158:161], v[166:169], v[72:75]
	v_mfma_f32_16x16x32_bf16 v[104:107], v[144:147], v[174:177], v[104:107]
	v_mfma_f32_16x16x32_bf16 v[64:67], v[158:161], v[174:177], v[64:67]
	v_mfma_f32_16x16x32_bf16 v[100:103], v[144:147], v[182:185], v[100:103]
	v_mfma_f32_16x16x32_bf16 v[56:59], v[158:161], v[182:185], v[56:59]
	v_mfma_f32_16x16x32_bf16 v[96:99], v[144:147], v[190:193], v[96:99]
	v_mfma_f32_16x16x32_bf16 v[44:47], v[158:161], v[190:193], v[44:47]
	s_barrier
	s_add_u32 s14, s18, 0x160080
	s_addc_u32 s15, s19, 0
	s_add_i32 s18, s20, s3
	v_lshl_add_u64 v[128:129], s[14:15], 0, v[132:133]
	s_mov_b32 m0, s18
	s_nop 0
	global_load_lds_dwordx4 v[128:129], off
	s_add_i32 m0, s18, 0x2000
	s_nop 0
	global_load_lds_dwordx4 v134, s[14:15]
	s_waitcnt vmcnt(6)
	s_barrier
	v_mfma_f32_16x16x32_bf16 v[32:35], v[194:197], v[162:165], v[32:35]
	v_mfma_f32_16x16x32_bf16 v[12:15], v[202:205], v[162:165], v[12:15]
	v_mfma_f32_16x16x32_bf16 v[24:27], v[194:197], v[170:173], v[24:27]
	v_mfma_f32_16x16x32_bf16 v[8:11], v[202:205], v[170:173], v[8:11]
	v_mfma_f32_16x16x32_bf16 v[20:23], v[194:197], v[178:181], v[20:23]
	v_mfma_f32_16x16x32_bf16 v[4:7], v[202:205], v[178:181], v[4:7]
	v_mfma_f32_16x16x32_bf16 v[16:19], v[194:197], v[186:189], v[16:19]
	v_mfma_f32_16x16x32_bf16 v[0:3], v[202:205], v[186:189], v[0:3]
	v_mfma_f32_16x16x32_bf16 v[32:35], v[198:201], v[166:169], v[32:35]
	v_mfma_f32_16x16x32_bf16 v[12:15], v[206:209], v[166:169], v[12:15]
	v_mfma_f32_16x16x32_bf16 v[24:27], v[198:201], v[174:177], v[24:27]
	v_mfma_f32_16x16x32_bf16 v[8:11], v[206:209], v[174:177], v[8:11]
	v_mfma_f32_16x16x32_bf16 v[20:23], v[198:201], v[182:185], v[20:23]
	v_mfma_f32_16x16x32_bf16 v[4:7], v[206:209], v[182:185], v[4:7]
	v_mfma_f32_16x16x32_bf16 v[16:19], v[198:201], v[190:193], v[16:19]
	v_mfma_f32_16x16x32_bf16 v[0:3], v[206:209], v[190:193], v[0:3]
	s_add_i32 s40, s40, 2
	s_add_u32 s38, s38, 0x100
	s_addc_u32 s39, s39, 0
	s_cmpk_gt_u32 s40, 0x55
	s_mov_b64 s[14:15], s[16:17]
	s_barrier
	s_cbranch_scc0 .LBB0_682
	s_cmp_lt_u32 s36, 32
	s_movk_i32 s14, 0x3000
	s_cselect_b32 s14, s14, 0x6000
	s_cmp_gt_i32 s36, 15
	v_lshl_add_u32 v158, s36, 8, v148
	s_cselect_b32 s14, s14, 0
	v_lshl_or_b32 v128, s37, 8, v150
	s_lshl_b32 s14, s14, 2
	v_ashrrev_i32_e32 v159, 31, v158
	s_add_u32 s14, s28, s14
	v_ashrrev_i32_e32 v129, 31, v128
	v_lshlrev_b64 v[146:147], 13, v[158:159]
	s_addc_u32 s15, s29, 0
	v_lshlrev_b64 v[160:161], 2, v[128:129]
	v_lshl_add_u64 v[146:147], s[56:57], 0, v[146:147]
	v_lshl_add_u64 v[144:145], s[14:15], 0, v[160:161]
	v_lshl_add_u64 v[146:147], v[146:147], 0, v[160:161]
	s_mov_b64 s[14:15], 0x100000
	s_mov_b32 s37, s34
	s_mov_b32 s36, s35
	s_mov_b64 s[16:17], s[10:11]
	v_or_b32_e32 v162, 16, v158
	v_ashrrev_i32_e32 v163, 31, v162
	v_lshlrev_b64 v[164:165], 13, v[162:163]
	v_lshl_add_u64 v[162:163], s[56:57], 0, v[164:165]
	v_lshl_add_u64 v[164:165], v[162:163], 0, v[160:161]
	v_or_b32_e32 v162, 32, v158
	v_ashrrev_i32_e32 v163, 31, v162
	v_lshlrev_b64 v[166:167], 13, v[162:163]
	v_lshl_add_u64 v[162:163], s[56:57], 0, v[166:167]
	v_lshl_add_u64 v[166:167], v[162:163], 0, v[160:161]
	v_or_b32_e32 v162, 48, v158
	v_ashrrev_i32_e32 v163, 31, v162
	v_lshlrev_b64 v[168:169], 13, v[162:163]
	v_lshl_add_u64 v[162:163], s[56:57], 0, v[168:169]
	v_lshl_add_u64 v[168:169], v[162:163], 0, v[160:161]
	v_lshl_add_u64 v[162:163], v[146:147], 0, s[14:15]
	s_mov_b32 s14, 0x100000
	v_add_co_u32_e32 v170, vcc, s14, v146
	s_mov_b64 s[14:15], 0x120000
	s_nop 0
	v_addc_co_u32_e32 v171, vcc, 0, v147, vcc
	v_lshl_add_u64 v[172:173], v[146:147], 0, s[14:15]
	s_mov_b32 s14, 0x120000
	v_add_co_u32_e32 v174, vcc, s14, v146
	s_mov_b64 s[14:15], 0x140000
	s_nop 0
	v_addc_co_u32_e32 v175, vcc, 0, v147, vcc
	v_lshl_add_u64 v[176:177], v[146:147], 0, s[14:15]
	s_mov_b32 s14, 0x140000
	v_add_co_u32_e32 v178, vcc, s14, v146
	s_mov_b64 s[14:15], 0x160000
	s_nop 0
	v_addc_co_u32_e32 v179, vcc, 0, v147, vcc
	v_lshl_add_u64 v[180:181], v[146:147], 0, s[14:15]
	s_mov_b32 s14, 0x160000
	v_add_co_u32_e32 v182, vcc, s14, v146
	s_mov_b64 s[14:15], s[8:9]
	s_nop 0
	v_addc_co_u32_e32 v183, vcc, 0, v147, vcc
	s_and_b64 vcc, exec, s[6:7]
	global_load_dwordx4 v[184:187], v[144:145], off
	global_load_dwordx4 v[188:191], v[146:147], off
	v_pk_add_f32 v[126:127], v[126:127], 0 op_sel_hi:[1,0]
	v_pk_add_f32 v[124:125], v[124:125], 0 op_sel_hi:[1,0]
	v_pk_add_f32 v[122:123], v[122:123], 0 op_sel_hi:[1,0]
	v_pk_add_f32 v[120:121], v[120:121], 0 op_sel_hi:[1,0]
	v_pk_add_f32 v[118:119], v[118:119], 0 op_sel_hi:[1,0]
	v_pk_add_f32 v[116:117], v[116:117], 0 op_sel_hi:[1,0]
	v_pk_add_f32 v[114:115], v[114:115], 0 op_sel_hi:[1,0]
	v_pk_add_f32 v[112:113], v[112:113], 0 op_sel_hi:[1,0]
	v_pk_add_f32 v[110:111], v[110:111], 0 op_sel_hi:[1,0]
	v_pk_add_f32 v[108:109], v[108:109], 0 op_sel_hi:[1,0]
	v_pk_add_f32 v[106:107], v[106:107], 0 op_sel_hi:[1,0]
	v_pk_add_f32 v[104:105], v[104:105], 0 op_sel_hi:[1,0]
	v_pk_add_f32 v[102:103], v[102:103], 0 op_sel_hi:[1,0]
	v_pk_add_f32 v[100:101], v[100:101], 0 op_sel_hi:[1,0]
	v_pk_add_f32 v[98:99], v[98:99], 0 op_sel_hi:[1,0]
	v_pk_add_f32 v[96:97], v[96:97], 0 op_sel_hi:[1,0]
	v_pk_add_f32 v[94:95], v[94:95], 0 op_sel_hi:[1,0]
	v_pk_add_f32 v[92:93], v[92:93], 0 op_sel_hi:[1,0]
	v_pk_add_f32 v[90:91], v[90:91], 0 op_sel_hi:[1,0]
	v_pk_add_f32 v[88:89], v[88:89], 0 op_sel_hi:[1,0]
	v_pk_add_f32 v[86:87], v[86:87], 0 op_sel_hi:[1,0]
	v_pk_add_f32 v[84:85], v[84:85], 0 op_sel_hi:[1,0]
	v_pk_add_f32 v[82:83], v[82:83], 0 op_sel_hi:[1,0]
	v_pk_add_f32 v[80:81], v[80:81], 0 op_sel_hi:[1,0]
	v_pk_add_f32 v[74:75], v[74:75], 0 op_sel_hi:[1,0]
	v_pk_add_f32 v[72:73], v[72:73], 0 op_sel_hi:[1,0]
	v_pk_add_f32 v[66:67], v[66:67], 0 op_sel_hi:[1,0]
	v_pk_add_f32 v[64:65], v[64:65], 0 op_sel_hi:[1,0]
	v_pk_add_f32 v[58:59], v[58:59], 0 op_sel_hi:[1,0]
	v_pk_add_f32 v[56:57], v[56:57], 0 op_sel_hi:[1,0]
	v_pk_add_f32 v[46:47], v[46:47], 0 op_sel_hi:[1,0]
	v_pk_add_f32 v[44:45], v[44:45], 0 op_sel_hi:[1,0]
	v_pk_add_f32 v[62:63], v[62:63], 0 op_sel_hi:[1,0]
	v_pk_add_f32 v[60:61], v[60:61], 0 op_sel_hi:[1,0]
	v_pk_add_f32 v[54:55], v[54:55], 0 op_sel_hi:[1,0]
	v_pk_add_f32 v[52:53], v[52:53], 0 op_sel_hi:[1,0]
	v_pk_add_f32 v[34:35], v[34:35], 0 op_sel_hi:[1,0]
	v_pk_add_f32 v[32:33], v[32:33], 0 op_sel_hi:[1,0]
	v_pk_add_f32 v[26:27], v[26:27], 0 op_sel_hi:[1,0]
	v_pk_add_f32 v[24:25], v[24:25], 0 op_sel_hi:[1,0]
	v_pk_add_f32 v[22:23], v[22:23], 0 op_sel_hi:[1,0]
	v_pk_add_f32 v[20:21], v[20:21], 0 op_sel_hi:[1,0]
	v_pk_add_f32 v[18:19], v[18:19], 0 op_sel_hi:[1,0]
	v_pk_add_f32 v[16:17], v[16:17], 0 op_sel_hi:[1,0]
	v_pk_add_f32 v[14:15], v[14:15], 0 op_sel_hi:[1,0]
	v_pk_add_f32 v[12:13], v[12:13], 0 op_sel_hi:[1,0]
	v_pk_add_f32 v[10:11], v[10:11], 0 op_sel_hi:[1,0]
	v_pk_add_f32 v[8:9], v[8:9], 0 op_sel_hi:[1,0]
	v_pk_add_f32 v[6:7], v[6:7], 0 op_sel_hi:[1,0]
	v_pk_add_f32 v[4:5], v[4:5], 0 op_sel_hi:[1,0]
	v_pk_add_f32 v[2:3], v[2:3], 0 op_sel_hi:[1,0]
	v_pk_add_f32 v[0:1], v[0:1], 0 op_sel_hi:[1,0]
	s_waitcnt vmcnt(0)
	v_pk_fma_f32 v[126:127], v[126:127], v[186:187], v[190:191]
	v_pk_fma_f32 v[124:125], v[124:125], v[184:185], v[188:189]
	global_store_dwordx4 v[146:147], v[124:127], off
	global_load_dwordx4 v[188:191], v[164:165], off
	global_load_dwordx4 v[192:195], v[166:167], off
	global_load_dwordx4 v[196:199], v[168:169], off
	global_load_dwordx4 v[200:203], v[170:171], off
	global_load_dwordx4 v[204:207], v[174:175], off
	global_load_dwordx4 v[208:211], v[178:179], off
	global_load_dwordx4 v[212:215], v[182:183], off
	global_load_dwordx4 v[216:219], v[144:145], off offset:64
	global_load_dwordx4 v[220:223], v[146:147], off offset:64
	global_load_dwordx4 v[224:227], v[164:165], off offset:64
	global_load_dwordx4 v[228:231], v[166:167], off offset:64
	global_load_dwordx4 v[232:235], v[168:169], off offset:64
	s_waitcnt vmcnt(11)
	v_pk_fma_f32 v[122:123], v[122:123], v[186:187], v[190:191]
	v_pk_fma_f32 v[120:121], v[120:121], v[184:185], v[188:189]
	global_store_dwordx4 v[164:165], v[120:123], off
	global_load_dwordx4 v[188:191], v[162:163], off offset:64
	s_waitcnt vmcnt(12)
	v_pk_fma_f32 v[118:119], v[118:119], v[186:187], v[194:195]
	v_pk_fma_f32 v[116:117], v[116:117], v[184:185], v[192:193]
	global_store_dwordx4 v[166:167], v[116:119], off
	global_load_dwordx4 v[192:195], v[172:173], off offset:64
	s_waitcnt vmcnt(13)
	v_pk_fma_f32 v[114:115], v[114:115], v[186:187], v[198:199]
	v_pk_fma_f32 v[112:113], v[112:113], v[184:185], v[196:197]
	global_store_dwordx4 v[168:169], v[112:115], off
	global_load_dwordx4 v[196:199], v[176:177], off offset:64
	s_waitcnt vmcnt(14)
	v_pk_fma_f32 v[110:111], v[110:111], v[186:187], v[202:203]
	v_pk_fma_f32 v[108:109], v[108:109], v[184:185], v[200:201]
	global_store_dwordx4 v[170:171], v[108:111], off
	global_load_dwordx4 v[200:203], v[180:181], off offset:64
	s_waitcnt vmcnt(15)
	v_pk_fma_f32 v[106:107], v[106:107], v[186:187], v[206:207]
	v_pk_fma_f32 v[104:105], v[104:105], v[184:185], v[204:205]
	global_store_dwordx4 v[174:175], v[104:107], off
	global_load_dwordx4 v[204:207], v[144:145], off offset:512
	s_waitcnt vmcnt(16)
	v_pk_fma_f32 v[102:103], v[102:103], v[186:187], v[210:211]
	v_pk_fma_f32 v[100:101], v[100:101], v[184:185], v[208:209]
	global_store_dwordx4 v[178:179], v[100:103], off
	global_load_dwordx4 v[208:211], v[146:147], off offset:512
	s_waitcnt vmcnt(17)
	v_pk_fma_f32 v[98:99], v[98:99], v[186:187], v[214:215]
	v_pk_fma_f32 v[96:97], v[96:97], v[184:185], v[212:213]
	global_store_dwordx4 v[182:183], v[96:99], off
	global_load_dwordx4 v[184:187], v[164:165], off offset:512
	s_waitcnt vmcnt(17)
	v_pk_fma_f32 v[94:95], v[94:95], v[218:219], v[222:223]
	v_pk_fma_f32 v[92:93], v[92:93], v[216:217], v[220:221]
	global_store_dwordx4 v[146:147], v[92:95], off offset:64
	global_load_dwordx4 v[212:215], v[166:167], off offset:512
	global_load_dwordx4 v[220:223], v[168:169], off offset:512
	s_waitcnt vmcnt(19)
	v_pk_fma_f32 v[90:91], v[90:91], v[218:219], v[226:227]
	v_pk_fma_f32 v[88:89], v[88:89], v[216:217], v[224:225]
	global_store_dwordx4 v[164:165], v[88:91], off offset:64
	global_load_dwordx4 v[224:227], v[162:163], off offset:512
	s_waitcnt vmcnt(20)
	v_pk_fma_f32 v[86:87], v[86:87], v[218:219], v[230:231]
	v_pk_fma_f32 v[84:85], v[84:85], v[216:217], v[228:229]
	global_store_dwordx4 v[166:167], v[84:87], off offset:64
	global_load_dwordx4 v[228:231], v[172:173], off offset:512
	s_waitcnt vmcnt(21)
	v_pk_fma_f32 v[82:83], v[82:83], v[218:219], v[234:235]
	v_pk_fma_f32 v[80:81], v[80:81], v[216:217], v[232:233]
	global_store_dwordx4 v[168:169], v[80:83], off offset:64
	global_load_dwordx4 v[232:235], v[176:177], off offset:512
	s_waitcnt vmcnt(21)
	v_pk_fma_f32 v[74:75], v[74:75], v[218:219], v[190:191]
	v_pk_fma_f32 v[72:73], v[72:73], v[216:217], v[188:189]
	global_store_dwordx4 v[162:163], v[72:75], off offset:64
	global_load_dwordx4 v[188:191], v[180:181], off offset:512
	s_waitcnt vmcnt(21)
	v_pk_fma_f32 v[66:67], v[66:67], v[218:219], v[194:195]
	v_pk_fma_f32 v[64:65], v[64:65], v[216:217], v[192:193]
	global_store_dwordx4 v[172:173], v[64:67], off offset:64
	global_load_dwordx4 v[192:195], v[144:145], off offset:576
	s_waitcnt vmcnt(21)
	v_pk_fma_f32 v[58:59], v[58:59], v[218:219], v[198:199]
	v_pk_fma_f32 v[56:57], v[56:57], v[216:217], v[196:197]
	global_store_dwordx4 v[176:177], v[56:59], off offset:64
	global_load_dwordx4 v[196:199], v[146:147], off offset:576
	v_pk_add_f32 v[64:65], v[78:79], 0 op_sel_hi:[1,0]
	v_pk_add_f32 v[66:67], v[76:77], 0 op_sel_hi:[1,0]
	s_waitcnt vmcnt(21)
	v_pk_fma_f32 v[46:47], v[46:47], v[218:219], v[202:203]
	v_pk_fma_f32 v[44:45], v[44:45], v[216:217], v[200:201]
	global_store_dwordx4 v[180:181], v[44:47], off offset:64
	global_load_dwordx4 v[200:203], v[164:165], off offset:576
	s_waitcnt vmcnt(19)
	v_pk_fma_f32 v[58:59], v[64:65], v[206:207], v[210:211]
	v_pk_fma_f32 v[56:57], v[66:67], v[204:205], v[208:209]
	global_store_dwordx4 v[146:147], v[56:59], off offset:512
	global_load_dwordx4 v[208:211], v[166:167], off offset:576
	global_load_dwordx4 v[216:219], v[168:169], off offset:576
	v_pk_add_f32 v[64:65], v[70:71], 0 op_sel_hi:[1,0]
	v_pk_add_f32 v[66:67], v[68:69], 0 op_sel_hi:[1,0]
	s_waitcnt vmcnt(20)
	v_pk_fma_f32 v[58:59], v[64:65], v[206:207], v[186:187]
	v_pk_fma_f32 v[56:57], v[66:67], v[204:205], v[184:185]
	global_store_dwordx4 v[164:165], v[56:59], off offset:512
	global_load_dwordx4 v[184:187], v[162:163], off offset:576
	s_waitcnt vmcnt(20)
	v_pk_fma_f32 v[58:59], v[62:63], v[206:207], v[214:215]
	v_pk_fma_f32 v[56:57], v[60:61], v[204:205], v[212:213]
	global_store_dwordx4 v[166:167], v[56:59], off offset:512
	global_load_dwordx4 v[212:215], v[172:173], off offset:576
	s_waitcnt vmcnt(21)
	v_pk_fma_f32 v[54:55], v[54:55], v[206:207], v[222:223]
	v_pk_fma_f32 v[52:53], v[52:53], v[204:205], v[220:221]
	global_store_dwordx4 v[168:169], v[52:55], off offset:512
	global_load_dwordx4 v[220:223], v[176:177], off offset:576
	s_waitcnt vmcnt(21)
	v_pk_fma_f32 v[34:35], v[34:35], v[206:207], v[226:227]
	v_pk_fma_f32 v[32:33], v[32:33], v[204:205], v[224:225]
	global_store_dwordx4 v[162:163], v[32:35], off offset:512
	global_load_dwordx4 v[224:227], v[180:181], off offset:576
	s_waitcnt vmcnt(21)
	v_pk_fma_f32 v[26:27], v[26:27], v[206:207], v[230:231]
	v_pk_fma_f32 v[24:25], v[24:25], v[204:205], v[228:229]
	global_store_dwordx4 v[172:173], v[24:27], off offset:512
	s_waitcnt vmcnt(20)
	v_pk_fma_f32 v[22:23], v[22:23], v[206:207], v[234:235]
	v_pk_fma_f32 v[20:21], v[20:21], v[204:205], v[232:233]
	global_store_dwordx4 v[176:177], v[20:23], off offset:512
	v_pk_add_f32 v[24:25], v[50:51], 0 op_sel_hi:[1,0]
	v_pk_add_f32 v[26:27], v[48:49], 0 op_sel_hi:[1,0]
	s_waitcnt vmcnt(19)
	v_pk_fma_f32 v[18:19], v[18:19], v[206:207], v[190:191]
	v_pk_fma_f32 v[16:17], v[16:17], v[204:205], v[188:189]
	global_store_dwordx4 v[180:181], v[16:19], off offset:512
	s_waitcnt vmcnt(16)
	v_pk_fma_f32 v[22:23], v[24:25], v[194:195], v[198:199]
	v_pk_fma_f32 v[20:21], v[26:27], v[192:193], v[196:197]
	global_store_dwordx4 v[146:147], v[20:23], off offset:576
	v_pk_add_f32 v[24:25], v[42:43], 0 op_sel_hi:[1,0]
	v_pk_add_f32 v[26:27], v[40:41], 0 op_sel_hi:[1,0]
	s_waitcnt vmcnt(15)
	v_pk_fma_f32 v[22:23], v[24:25], v[194:195], v[202:203]
	v_pk_fma_f32 v[20:21], v[26:27], v[192:193], v[200:201]
	global_store_dwordx4 v[164:165], v[20:23], off offset:576
	v_pk_add_f32 v[24:25], v[38:39], 0 op_sel_hi:[1,0]
	v_pk_add_f32 v[26:27], v[36:37], 0 op_sel_hi:[1,0]
	s_waitcnt vmcnt(14)
	v_pk_fma_f32 v[22:23], v[24:25], v[194:195], v[210:211]
	v_pk_fma_f32 v[20:21], v[26:27], v[192:193], v[208:209]
	global_store_dwordx4 v[166:167], v[20:23], off offset:576
	v_pk_add_f32 v[24:25], v[30:31], 0 op_sel_hi:[1,0]
	v_pk_add_f32 v[26:27], v[28:29], 0 op_sel_hi:[1,0]
	s_waitcnt vmcnt(14)
	v_pk_fma_f32 v[22:23], v[24:25], v[194:195], v[218:219]
	v_pk_fma_f32 v[20:21], v[26:27], v[192:193], v[216:217]
	global_store_dwordx4 v[168:169], v[20:23], off offset:576
	s_waitcnt vmcnt(13)
	v_pk_fma_f32 v[14:15], v[14:15], v[194:195], v[186:187]
	v_pk_fma_f32 v[12:13], v[12:13], v[192:193], v[184:185]
	global_store_dwordx4 v[162:163], v[12:15], off offset:576
	s_waitcnt vmcnt(12)
	v_pk_fma_f32 v[10:11], v[10:11], v[194:195], v[214:215]
	v_pk_fma_f32 v[8:9], v[8:9], v[192:193], v[212:213]
	global_store_dwordx4 v[172:173], v[8:11], off offset:576
	s_waitcnt vmcnt(11)
	v_pk_fma_f32 v[6:7], v[6:7], v[194:195], v[222:223]
	v_pk_fma_f32 v[4:5], v[4:5], v[192:193], v[220:221]
	global_store_dwordx4 v[176:177], v[4:7], off offset:576
	s_waitcnt vmcnt(10)
	v_pk_fma_f32 v[2:3], v[2:3], v[194:195], v[226:227]
	v_pk_fma_f32 v[0:1], v[0:1], v[192:193], v[224:225]
	global_store_dwordx4 v[180:181], v[0:3], off offset:576
	s_cbranch_vccz .LBB0_671
	s_waitcnt vmcnt(0)
	s_cmpk_gt_u32 s1, 0xff
	s_cbranch_scc1 .LBB0_686
	s_barrier

.LBB0_698:
	ds_read_b128 v[144:147], v139
	ds_read_b128 v[148:151], v139 offset:1024
	ds_read_b128 v[152:155], v139 offset:2048
	ds_read_b128 v[156:159], v139 offset:3072
	s_mov_b32 m0, s29
	v_lshl_add_u64 v[192:193], s[14:15], 0, v[132:133]
	ds_read_b128 v[160:163], v140
	ds_read_b128 v[164:167], v140 offset:1024
	ds_read_b128 v[168:171], v140 offset:2048
	ds_read_b128 v[172:175], v140 offset:3072
	ds_read_b128 v[176:179], v140 offset:4096
	ds_read_b128 v[180:183], v140 offset:5120
	ds_read_b128 v[184:187], v140 offset:6144
	ds_read_b128 v[188:191], v140 offset:7168
	global_load_lds_dwordx4 v[192:193], off
	s_mov_b32 m0, s30
	s_nop 0
	global_load_lds_dwordx4 v134, s[14:15]
	s_waitcnt lgkmcnt(8)
	s_barrier
	s_waitcnt lgkmcnt(0)
	s_waitcnt lgkmcnt(0)
	v_mfma_f32_16x16x32_bf16 v[124:127], v[144:147], v[160:163], v[124:127]
	s_add_u32 s16, s14, 0x100
	s_addc_u32 s17, s15, 0
	s_cmp_eq_u32 s43, 4
	s_cselect_b32 s21, s13, s17
	s_cselect_b32 s20, s12, s16
	s_cselect_b32 s19, s7, s42
	s_cselect_b32 s18, s6, s41
	v_mfma_f32_16x16x32_bf16 v[120:123], v[152:155], v[160:163], v[120:123]
	v_mfma_f32_16x16x32_bf16 v[116:119], v[144:147], v[168:171], v[116:119]
	v_mfma_f32_16x16x32_bf16 v[112:115], v[152:155], v[168:171], v[112:115]
	v_mfma_f32_16x16x32_bf16 v[100:103], v[144:147], v[176:179], v[100:103]
	v_mfma_f32_16x16x32_bf16 v[96:99], v[152:155], v[176:179], v[96:99]
	v_mfma_f32_16x16x32_bf16 v[84:87], v[144:147], v[184:187], v[84:87]
	v_mfma_f32_16x16x32_bf16 v[80:83], v[152:155], v[184:187], v[80:83]
	v_mfma_f32_16x16x32_bf16 v[124:127], v[148:151], v[164:167], v[124:127]
	v_mfma_f32_16x16x32_bf16 v[120:123], v[156:159], v[164:167], v[120:123]
	v_mfma_f32_16x16x32_bf16 v[116:119], v[148:151], v[172:175], v[116:119]
	v_mfma_f32_16x16x32_bf16 v[112:115], v[156:159], v[172:175], v[112:115]
	v_mfma_f32_16x16x32_bf16 v[100:103], v[148:151], v[180:183], v[100:103]
	v_mfma_f32_16x16x32_bf16 v[96:99], v[156:159], v[180:183], v[96:99]
	v_mfma_f32_16x16x32_bf16 v[84:87], v[148:151], v[188:191], v[84:87]
	v_mfma_f32_16x16x32_bf16 v[80:83], v[156:159], v[188:191], v[80:83]
	s_barrier
	s_mov_b32 m0, s31
	ds_read_b128 v[192:195], v141
	ds_read_b128 v[196:199], v141 offset:1024
	ds_read_b128 v[200:203], v141 offset:2048
	ds_read_b128 v[204:207], v141 offset:3072
	global_load_lds_dwordx4 v130, s[18:19]
	s_mov_b32 m0, s34
	s_nop 0
	global_load_lds_dwordx4 v128, s[18:19]
	s_barrier
	s_waitcnt lgkmcnt(0)
	s_waitcnt lgkmcnt(0)
	v_mfma_f32_16x16x32_bf16 v[108:111], v[192:195], v[160:163], v[108:111]
	v_mfma_f32_16x16x32_bf16 v[104:107], v[200:203], v[160:163], v[104:107]
	v_mfma_f32_16x16x32_bf16 v[92:95], v[192:195], v[168:171], v[92:95]
	v_mfma_f32_16x16x32_bf16 v[88:91], v[200:203], v[168:171], v[88:91]
	v_mfma_f32_16x16x32_bf16 v[76:79], v[192:195], v[176:179], v[76:79]
	v_mfma_f32_16x16x32_bf16 v[72:75], v[200:203], v[176:179], v[72:75]
	v_mfma_f32_16x16x32_bf16 v[68:71], v[192:195], v[184:187], v[68:71]
	v_mfma_f32_16x16x32_bf16 v[64:67], v[200:203], v[184:187], v[64:67]
	v_mfma_f32_16x16x32_bf16 v[108:111], v[196:199], v[164:167], v[108:111]
	v_mfma_f32_16x16x32_bf16 v[104:107], v[204:207], v[164:167], v[104:107]
	v_mfma_f32_16x16x32_bf16 v[92:95], v[196:199], v[172:175], v[92:95]
	v_mfma_f32_16x16x32_bf16 v[88:91], v[204:207], v[172:175], v[88:91]
	v_mfma_f32_16x16x32_bf16 v[76:79], v[196:199], v[180:183], v[76:79]
	v_mfma_f32_16x16x32_bf16 v[72:75], v[204:207], v[180:183], v[72:75]
	v_mfma_f32_16x16x32_bf16 v[68:71], v[196:199], v[188:191], v[68:71]
	v_mfma_f32_16x16x32_bf16 v[64:67], v[204:207], v[188:191], v[64:67]
	s_mov_b32 m0, s3
	v_lshl_add_u64 v[212:213], s[20:21], 0, v[130:131]
	s_barrier
	ds_read_b128 v[160:163], v140 offset:16384
	ds_read_b128 v[164:167], v140 offset:17408
	ds_read_b128 v[168:171], v140 offset:18432
	ds_read_b128 v[172:175], v140 offset:19456
	ds_read_b128 v[176:179], v140 offset:20480
	ds_read_b128 v[180:183], v140 offset:21504
	ds_read_b128 v[184:187], v140 offset:22528
	ds_read_b128 v[188:191], v140 offset:23552
	global_load_lds_dwordx4 v130, s[20:21]
	v_lshl_add_u64 v[214:215], s[20:21], 0, v[128:129]
	s_mov_b32 m0, s4
	s_nop 0
	global_load_lds_dwordx4 v128, s[20:21]
	s_barrier
	s_waitcnt lgkmcnt(0)
	s_waitcnt lgkmcnt(0)
	v_mfma_f32_16x16x32_bf16 v[60:63], v[144:147], v[160:163], v[60:63]
	v_mfma_f32_16x16x32_bf16 v[56:59], v[152:155], v[160:163], v[56:59]
	v_mfma_f32_16x16x32_bf16 v[52:55], v[144:147], v[168:171], v[52:55]
	v_mfma_f32_16x16x32_bf16 v[48:51], v[152:155], v[168:171], v[48:51]
	v_mfma_f32_16x16x32_bf16 v[36:39], v[144:147], v[176:179], v[36:39]
	v_mfma_f32_16x16x32_bf16 v[32:35], v[152:155], v[176:179], v[32:35]
	v_mfma_f32_16x16x32_bf16 v[20:23], v[144:147], v[184:187], v[20:23]
	v_mfma_f32_16x16x32_bf16 v[16:19], v[152:155], v[184:187], v[16:19]
	v_mfma_f32_16x16x32_bf16 v[60:63], v[148:151], v[164:167], v[60:63]
	v_mfma_f32_16x16x32_bf16 v[56:59], v[156:159], v[164:167], v[56:59]
	v_mfma_f32_16x16x32_bf16 v[52:55], v[148:151], v[172:175], v[52:55]
	v_mfma_f32_16x16x32_bf16 v[48:51], v[156:159], v[172:175], v[48:51]
	v_mfma_f32_16x16x32_bf16 v[36:39], v[148:151], v[180:183], v[36:39]
	v_mfma_f32_16x16x32_bf16 v[32:35], v[156:159], v[180:183], v[32:35]
	v_mfma_f32_16x16x32_bf16 v[20:23], v[148:151], v[188:191], v[20:23]
	v_mfma_f32_16x16x32_bf16 v[16:19], v[156:159], v[188:191], v[16:19]
	s_barrier
	s_add_u32 s14, s18, 0x160000
	s_addc_u32 s15, s19, 0
	s_mov_b32 m0, s35
	global_load_lds_dwordx4 v130, s[14:15]
	s_mov_b32 m0, s36
	s_nop 0
	global_load_lds_dwordx4 v128, s[14:15]
	s_waitcnt vmcnt(6)
	s_barrier
	v_mfma_f32_16x16x32_bf16 v[44:47], v[192:195], v[160:163], v[44:47]
	v_mfma_f32_16x16x32_bf16 v[40:43], v[200:203], v[160:163], v[40:43]
	v_mfma_f32_16x16x32_bf16 v[28:31], v[192:195], v[168:171], v[28:31]
	v_mfma_f32_16x16x32_bf16 v[24:27], v[200:203], v[168:171], v[24:27]
	v_mfma_f32_16x16x32_bf16 v[12:15], v[192:195], v[176:179], v[12:15]
	v_mfma_f32_16x16x32_bf16 v[8:11], v[200:203], v[176:179], v[8:11]
	v_mfma_f32_16x16x32_bf16 v[4:7], v[192:195], v[184:187], v[4:7]
	v_mfma_f32_16x16x32_bf16 v[0:3], v[200:203], v[184:187], v[0:3]
	v_mfma_f32_16x16x32_bf16 v[44:47], v[196:199], v[164:167], v[44:47]
	v_mfma_f32_16x16x32_bf16 v[40:43], v[204:207], v[164:167], v[40:43]
	v_mfma_f32_16x16x32_bf16 v[28:31], v[196:199], v[172:175], v[28:31]
	v_mfma_f32_16x16x32_bf16 v[24:27], v[204:207], v[172:175], v[24:27]
	v_mfma_f32_16x16x32_bf16 v[12:15], v[196:199], v[180:183], v[12:15]
	v_mfma_f32_16x16x32_bf16 v[8:11], v[204:207], v[180:183], v[8:11]
	v_mfma_f32_16x16x32_bf16 v[4:7], v[196:199], v[188:191], v[4:7]
	v_mfma_f32_16x16x32_bf16 v[0:3], v[204:207], v[188:191], v[0:3]
	s_barrier
	ds_read_b128 v[144:147], v142
	ds_read_b128 v[148:151], v142 offset:1024
	ds_read_b128 v[152:155], v142 offset:2048
	ds_read_b128 v[156:159], v142 offset:3072
	s_add_u32 s14, s20, 0x160000
	s_addc_u32 s15, s21, 0
	s_mov_b32 m0, s5
	ds_read_b128 v[160:163], v140 offset:32768
	ds_read_b128 v[164:167], v140 offset:33792
	ds_read_b128 v[168:171], v140 offset:34816
	ds_read_b128 v[172:175], v140 offset:35840
	ds_read_b128 v[176:179], v140 offset:36864
	ds_read_b128 v[180:183], v140 offset:37888
	ds_read_b128 v[184:187], v140 offset:38912
	ds_read_b128 v[188:191], v140 offset:39936
	global_load_lds_dwordx4 v130, s[14:15]
	s_mov_b32 m0, s22
	s_nop 0
	global_load_lds_dwordx4 v128, s[14:15]
	s_waitcnt lgkmcnt(8)
	s_barrier
	s_waitcnt lgkmcnt(0)
	s_waitcnt lgkmcnt(0)
	v_mfma_f32_16x16x32_bf16 v[124:127], v[144:147], v[160:163], v[124:127]
	v_mfma_f32_16x16x32_bf16 v[120:123], v[152:155], v[160:163], v[120:123]
	v_mfma_f32_16x16x32_bf16 v[116:119], v[144:147], v[168:171], v[116:119]
	v_mfma_f32_16x16x32_bf16 v[112:115], v[152:155], v[168:171], v[112:115]
	v_mfma_f32_16x16x32_bf16 v[100:103], v[144:147], v[176:179], v[100:103]
	v_mfma_f32_16x16x32_bf16 v[96:99], v[152:155], v[176:179], v[96:99]
	v_mfma_f32_16x16x32_bf16 v[84:87], v[144:147], v[184:187], v[84:87]
	v_mfma_f32_16x16x32_bf16 v[80:83], v[152:155], v[184:187], v[80:83]
	v_mfma_f32_16x16x32_bf16 v[124:127], v[148:151], v[164:167], v[124:127]
	v_mfma_f32_16x16x32_bf16 v[120:123], v[156:159], v[164:167], v[120:123]
	v_mfma_f32_16x16x32_bf16 v[116:119], v[148:151], v[172:175], v[116:119]
	v_mfma_f32_16x16x32_bf16 v[112:115], v[156:159], v[172:175], v[112:115]
	v_mfma_f32_16x16x32_bf16 v[100:103], v[148:151], v[180:183], v[100:103]
	v_mfma_f32_16x16x32_bf16 v[96:99], v[156:159], v[180:183], v[96:99]
	v_mfma_f32_16x16x32_bf16 v[84:87], v[148:151], v[188:191], v[84:87]
	v_mfma_f32_16x16x32_bf16 v[80:83], v[156:159], v[188:191], v[80:83]
	s_barrier
	s_add_i32 s20, 0, 0x1c000
	s_add_i32 s14, s37, s2
	v_add_u32_e32 v143, s20, v137
	s_add_u32 s98, s18, s8
	s_addc_u32 s99, s19, s9
	s_mov_b32 m0, s14
	ds_read_b128 v[192:195], v143
	ds_read_b128 v[196:199], v143 offset:1024
	ds_read_b128 v[200:203], v143 offset:2048
	ds_read_b128 v[204:207], v143 offset:3072
	global_load_lds_dwordx4 v130, s[98:99]
	s_add_i32 m0, s14, 0x2000
	s_nop 0
	global_load_lds_dwordx4 v128, s[98:99]
	s_barrier
	s_waitcnt lgkmcnt(0)
	s_waitcnt lgkmcnt(0)
	v_mfma_f32_16x16x32_bf16 v[108:111], v[192:195], v[160:163], v[108:111]
	v_mfma_f32_16x16x32_bf16 v[104:107], v[200:203], v[160:163], v[104:107]
	v_mfma_f32_16x16x32_bf16 v[92:95], v[192:195], v[168:171], v[92:95]
	v_mfma_f32_16x16x32_bf16 v[88:91], v[200:203], v[168:171], v[88:91]
	v_mfma_f32_16x16x32_bf16 v[76:79], v[192:195], v[176:179], v[76:79]
	v_mfma_f32_16x16x32_bf16 v[72:75], v[200:203], v[176:179], v[72:75]
	v_mfma_f32_16x16x32_bf16 v[68:71], v[192:195], v[184:187], v[68:71]
	v_mfma_f32_16x16x32_bf16 v[64:67], v[200:203], v[184:187], v[64:67]
	v_mfma_f32_16x16x32_bf16 v[108:111], v[196:199], v[164:167], v[108:111]
	v_mfma_f32_16x16x32_bf16 v[104:107], v[204:207], v[164:167], v[104:107]
	v_mfma_f32_16x16x32_bf16 v[92:95], v[196:199], v[172:175], v[92:95]
	v_mfma_f32_16x16x32_bf16 v[88:91], v[204:207], v[172:175], v[88:91]
	v_mfma_f32_16x16x32_bf16 v[76:79], v[196:199], v[180:183], v[76:79]
	v_mfma_f32_16x16x32_bf16 v[72:75], v[204:207], v[180:183], v[72:75]
	v_mfma_f32_16x16x32_bf16 v[68:71], v[196:199], v[188:191], v[68:71]
	v_mfma_f32_16x16x32_bf16 v[64:67], v[204:207], v[188:191], v[64:67]
	s_mov_b32 m0, s27
	v_lshl_add_u64 v[208:209], v[212:213], 0, s[8:9]
	s_barrier
	ds_read_b128 v[160:163], v140 offset:49152
	ds_read_b128 v[164:167], v140 offset:50176
	ds_read_b128 v[168:171], v140 offset:51200
	ds_read_b128 v[172:175], v140 offset:52224
	ds_read_b128 v[176:179], v140 offset:53248
	ds_read_b128 v[180:183], v140 offset:54272
	ds_read_b128 v[184:187], v140 offset:55296
	ds_read_b128 v[188:191], v140 offset:56320
	global_load_lds_dwordx4 v[208:209], off
	v_lshl_add_u64 v[208:209], v[214:215], 0, s[8:9]
	s_mov_b32 m0, s28
	s_nop 0
	global_load_lds_dwordx4 v[208:209], off
	s_barrier
	s_waitcnt lgkmcnt(0)
	s_waitcnt lgkmcnt(0)
	v_mfma_f32_16x16x32_bf16 v[60:63], v[144:147], v[160:163], v[60:63]
	v_mfma_f32_16x16x32_bf16 v[56:59], v[152:155], v[160:163], v[56:59]
	v_mfma_f32_16x16x32_bf16 v[52:55], v[144:147], v[168:171], v[52:55]
	v_mfma_f32_16x16x32_bf16 v[48:51], v[152:155], v[168:171], v[48:51]
	v_mfma_f32_16x16x32_bf16 v[36:39], v[144:147], v[176:179], v[36:39]
	v_mfma_f32_16x16x32_bf16 v[32:35], v[152:155], v[176:179], v[32:35]
	v_mfma_f32_16x16x32_bf16 v[20:23], v[144:147], v[184:187], v[20:23]
	v_mfma_f32_16x16x32_bf16 v[16:19], v[152:155], v[184:187], v[16:19]
	v_mfma_f32_16x16x32_bf16 v[60:63], v[148:151], v[164:167], v[60:63]
	v_mfma_f32_16x16x32_bf16 v[56:59], v[156:159], v[164:167], v[56:59]
	v_mfma_f32_16x16x32_bf16 v[52:55], v[148:151], v[172:175], v[52:55]
	v_mfma_f32_16x16x32_bf16 v[48:51], v[156:159], v[172:175], v[48:51]
	v_mfma_f32_16x16x32_bf16 v[36:39], v[148:151], v[180:183], v[36:39]
	v_mfma_f32_16x16x32_bf16 v[32:35], v[156:159], v[180:183], v[32:35]
	v_mfma_f32_16x16x32_bf16 v[20:23], v[148:151], v[188:191], v[20:23]
	v_mfma_f32_16x16x32_bf16 v[16:19], v[156:159], v[188:191], v[16:19]
	s_barrier
	s_add_u32 s14, s18, 0x160080
	s_addc_u32 s15, s19, 0
	s_add_i32 s18, s20, s2
	s_mov_b32 m0, s18
	s_nop 0
	global_load_lds_dwordx4 v130, s[14:15]
	s_add_i32 m0, s18, 0x2000
	s_nop 0
	global_load_lds_dwordx4 v128, s[14:15]
	s_waitcnt vmcnt(6)
	s_barrier
	v_mfma_f32_16x16x32_bf16 v[44:47], v[192:195], v[160:163], v[44:47]
	v_mfma_f32_16x16x32_bf16 v[40:43], v[200:203], v[160:163], v[40:43]
	v_mfma_f32_16x16x32_bf16 v[28:31], v[192:195], v[168:171], v[28:31]
	v_mfma_f32_16x16x32_bf16 v[24:27], v[200:203], v[168:171], v[24:27]
	v_mfma_f32_16x16x32_bf16 v[12:15], v[192:195], v[176:179], v[12:15]
	v_mfma_f32_16x16x32_bf16 v[8:11], v[200:203], v[176:179], v[8:11]
	v_mfma_f32_16x16x32_bf16 v[4:7], v[192:195], v[184:187], v[4:7]
	v_mfma_f32_16x16x32_bf16 v[0:3], v[200:203], v[184:187], v[0:3]
	v_mfma_f32_16x16x32_bf16 v[44:47], v[196:199], v[164:167], v[44:47]
	v_mfma_f32_16x16x32_bf16 v[40:43], v[204:207], v[164:167], v[40:43]
	v_mfma_f32_16x16x32_bf16 v[28:31], v[196:199], v[172:175], v[28:31]
	v_mfma_f32_16x16x32_bf16 v[24:27], v[204:207], v[172:175], v[24:27]
	v_mfma_f32_16x16x32_bf16 v[12:15], v[196:199], v[180:183], v[12:15]
	v_mfma_f32_16x16x32_bf16 v[8:11], v[204:207], v[180:183], v[8:11]
	v_mfma_f32_16x16x32_bf16 v[4:7], v[196:199], v[188:191], v[4:7]
	v_mfma_f32_16x16x32_bf16 v[0:3], v[204:207], v[188:191], v[0:3]
	s_add_i32 s43, s43, 2
	s_add_u32 s41, s41, 0x100
	s_addc_u32 s42, s42, 0
	s_cmp_gt_u32 s43, 5
	s_mov_b64 s[14:15], s[16:17]
	s_barrier
	s_cbranch_scc0 .LBB0_698
	s_ashr_i32 s14, s26, 1
	s_and_b32 s14, s14, 0xfffffe00
	s_lshl_b32 s15, s25, 8
	s_add_i32 s15, s15, s14
	v_add_u32_e32 v146, s15, v136
	v_lshl_or_b32 v144, s24, 8, v138
	v_ashrrev_i32_e32 v147, 31, v146
	v_ashrrev_i32_e32 v145, 31, v144
	v_lshlrev_b64 v[148:149], 13, v[146:147]
	v_lshl_add_u64 v[148:149], s[66:67], 0, v[148:149]
	v_lshlrev_b64 v[144:145], 2, v[144:145]
	v_lshl_add_u64 v[148:149], v[148:149], 0, v[144:145]
	global_store_dwordx4 v[148:149], v[124:127], off
	global_store_dwordx4 v[148:149], v[120:123], off offset:64
	global_store_dwordx4 v[148:149], v[108:111], off offset:512
	global_store_dwordx4 v[148:149], v[104:107], off offset:576
	s_mov_b64 s[14:15], 0x100000
	s_mov_b32 s26, s39
	v_or_b32_e32 v104, 16, v146
	v_ashrrev_i32_e32 v105, 31, v104
	v_lshlrev_b64 v[104:105], 13, v[104:105]
	v_lshl_add_u64 v[104:105], s[66:67], 0, v[104:105]
	v_lshl_add_u64 v[104:105], v[104:105], 0, v[144:145]
	global_store_dwordx4 v[104:105], v[116:119], off
	global_store_dwordx4 v[104:105], v[112:115], off offset:64
	global_store_dwordx4 v[104:105], v[92:95], off offset:512
	global_store_dwordx4 v[104:105], v[88:91], off offset:576
	s_mov_b32 s24, s38
	s_mov_b32 s25, s40
	v_or_b32_e32 v88, 32, v146
	v_ashrrev_i32_e32 v89, 31, v88
	v_lshlrev_b64 v[88:89], 13, v[88:89]
	v_lshl_add_u64 v[88:89], s[66:67], 0, v[88:89]
	v_lshl_add_u64 v[88:89], v[88:89], 0, v[144:145]
	global_store_dwordx4 v[88:89], v[100:103], off
	global_store_dwordx4 v[88:89], v[96:99], off offset:64
	global_store_dwordx4 v[88:89], v[76:79], off offset:512
	global_store_dwordx4 v[88:89], v[72:75], off offset:576
	s_mov_b64 s[16:17], s[6:7]
	s_nop 0
	v_or_b32_e32 v72, 48, v146
	v_ashrrev_i32_e32 v73, 31, v72
	v_lshlrev_b64 v[72:73], 13, v[72:73]
	v_lshl_add_u64 v[72:73], s[66:67], 0, v[72:73]
	v_lshl_add_u64 v[72:73], v[72:73], 0, v[144:145]
	global_store_dwordx4 v[72:73], v[84:87], off
	global_store_dwordx4 v[72:73], v[80:83], off offset:64
	global_store_dwordx4 v[72:73], v[68:71], off offset:512
	global_store_dwordx4 v[72:73], v[64:67], off offset:576
	s_nop 1
	v_lshl_add_u64 v[64:65], v[148:149], 0, s[14:15]
	s_mov_b32 s14, 0x100000
	v_add_co_u32_e32 v66, vcc, s14, v148
	s_mov_b64 s[14:15], 0x120000
	s_nop 0
	v_addc_co_u32_e32 v67, vcc, 0, v149, vcc
	global_store_dwordx4 v[66:67], v[60:63], off
	global_store_dwordx4 v[64:65], v[56:59], off offset:64
	global_store_dwordx4 v[64:65], v[44:47], off offset:512
	global_store_dwordx4 v[64:65], v[40:43], off offset:576
	s_nop 1
	v_lshl_add_u64 v[40:41], v[148:149], 0, s[14:15]
	s_mov_b32 s14, 0x120000
	v_add_co_u32_e32 v42, vcc, s14, v148
	s_mov_b64 s[14:15], 0x140000
	s_nop 0
	v_addc_co_u32_e32 v43, vcc, 0, v149, vcc
	global_store_dwordx4 v[42:43], v[52:55], off
	global_store_dwordx4 v[40:41], v[48:51], off offset:64
	global_store_dwordx4 v[40:41], v[28:31], off offset:512
	global_store_dwordx4 v[40:41], v[24:27], off offset:576
	s_nop 1
	v_lshl_add_u64 v[24:25], v[148:149], 0, s[14:15]
	s_mov_b32 s14, 0x140000
	v_add_co_u32_e32 v26, vcc, s14, v148
	s_mov_b64 s[14:15], 0x160000
	s_nop 0
	v_addc_co_u32_e32 v27, vcc, 0, v149, vcc
	global_store_dwordx4 v[26:27], v[36:39], off
	global_store_dwordx4 v[24:25], v[32:35], off offset:64
	global_store_dwordx4 v[24:25], v[12:15], off offset:512
	global_store_dwordx4 v[24:25], v[8:11], off offset:576
	s_nop 1
	v_add_co_u32_e32 v10, vcc, 0x160000, v148
	v_lshl_add_u64 v[8:9], v[148:149], 0, s[14:15]
	s_nop 0
	v_addc_co_u32_e32 v11, vcc, 0, v149, vcc
	s_and_b64 vcc, exec, s[10:11]
	s_mov_b64 s[14:15], s[12:13]
	global_store_dwordx4 v[10:11], v[20:23], off
	global_store_dwordx4 v[8:9], v[16:19], off offset:64
	global_store_dwordx4 v[8:9], v[4:7], off offset:512
	global_store_dwordx4 v[8:9], v[0:3], off offset:576
	s_cbranch_vccz .LBB0_691
	s_waitcnt vmcnt(0)
	s_cmpk_gt_u32 s1, 0xff
	s_cbranch_scc1 .LBB0_702
	s_barrier

.LBB0_1417:
	ds_read_b128 v[140:143], v151
	ds_read_b128 v[144:147], v151 offset:1024
	ds_read_b128 v[154:157], v151 offset:2048
	ds_read_b128 v[158:161], v151 offset:3072
	v_lshl_add_u64 v[194:195], s[20:21], 0, v[132:133]
	s_add_i32 m0, s5, 0xc000
	ds_read_b128 v[162:165], v152
	ds_read_b128 v[166:169], v152 offset:1024
	ds_read_b128 v[170:173], v152 offset:2048
	ds_read_b128 v[174:177], v152 offset:3072
	ds_read_b128 v[178:181], v152 offset:4096
	ds_read_b128 v[182:185], v152 offset:5120
	ds_read_b128 v[186:189], v152 offset:6144
	ds_read_b128 v[190:193], v152 offset:7168
	global_load_lds_dwordx4 v[194:195], off
	s_add_i32 m0, s5, 0xe000
	s_nop 0
	global_load_lds_dwordx4 v134, s[20:21]
	s_waitcnt lgkmcnt(8)
	s_barrier
	s_waitcnt lgkmcnt(0)
	s_waitcnt lgkmcnt(0)
	v_mfma_f32_16x16x32_bf16 v[124:127], v[140:143], v[162:165], v[124:127]
	s_add_u32 s22, s20, 0x100
	s_addc_u32 s23, s21, 0
	s_cmp_eq_u32 s46, 28
	s_cselect_b32 s27, s13, s23
	s_cselect_b32 s26, s40, s22
	s_cselect_b32 s25, s11, s43
	s_cselect_b32 s24, s41, s42
	v_mfma_f32_16x16x32_bf16 v[120:123], v[154:157], v[162:165], v[120:123]
	v_mfma_f32_16x16x32_bf16 v[108:111], v[140:143], v[170:173], v[108:111]
	v_mfma_f32_16x16x32_bf16 v[104:107], v[154:157], v[170:173], v[104:107]
	v_mfma_f32_16x16x32_bf16 v[92:95], v[140:143], v[178:181], v[92:95]
	v_mfma_f32_16x16x32_bf16 v[88:91], v[154:157], v[178:181], v[88:91]
	v_mfma_f32_16x16x32_bf16 v[76:79], v[140:143], v[186:189], v[76:79]
	v_mfma_f32_16x16x32_bf16 v[72:75], v[154:157], v[186:189], v[72:75]
	v_mfma_f32_16x16x32_bf16 v[124:127], v[144:147], v[166:169], v[124:127]
	v_mfma_f32_16x16x32_bf16 v[120:123], v[158:161], v[166:169], v[120:123]
	v_mfma_f32_16x16x32_bf16 v[108:111], v[144:147], v[174:177], v[108:111]
	v_mfma_f32_16x16x32_bf16 v[104:107], v[158:161], v[174:177], v[104:107]
	v_mfma_f32_16x16x32_bf16 v[92:95], v[144:147], v[182:185], v[92:95]
	v_mfma_f32_16x16x32_bf16 v[88:91], v[158:161], v[182:185], v[88:91]
	v_mfma_f32_16x16x32_bf16 v[76:79], v[144:147], v[190:193], v[76:79]
	v_mfma_f32_16x16x32_bf16 v[72:75], v[158:161], v[190:193], v[72:75]
	s_barrier
	s_add_i32 s20, s36, s2
	s_mov_b32 m0, s20
	ds_read_b128 v[194:197], v153
	ds_read_b128 v[198:201], v153 offset:1024
	ds_read_b128 v[202:205], v153 offset:2048
	ds_read_b128 v[206:209], v153 offset:3072
	global_load_lds_dwordx4 v130, s[24:25]
	s_add_i32 m0, s20, 0x2000
	s_nop 0
	global_load_lds_dwordx4 v128, s[24:25]
	s_barrier
	s_waitcnt lgkmcnt(0)
	s_waitcnt lgkmcnt(0)
	v_mfma_f32_16x16x32_bf16 v[116:119], v[194:197], v[162:165], v[116:119]
	v_mfma_f32_16x16x32_bf16 v[112:115], v[202:205], v[162:165], v[112:115]
	v_mfma_f32_16x16x32_bf16 v[100:103], v[194:197], v[170:173], v[100:103]
	v_mfma_f32_16x16x32_bf16 v[96:99], v[202:205], v[170:173], v[96:99]
	v_mfma_f32_16x16x32_bf16 v[84:87], v[194:197], v[178:181], v[84:87]
	v_mfma_f32_16x16x32_bf16 v[80:83], v[202:205], v[178:181], v[80:83]
	v_mfma_f32_16x16x32_bf16 v[68:71], v[194:197], v[186:189], v[68:71]
	v_mfma_f32_16x16x32_bf16 v[64:67], v[202:205], v[186:189], v[64:67]
	v_mfma_f32_16x16x32_bf16 v[116:119], v[198:201], v[166:169], v[116:119]
	v_mfma_f32_16x16x32_bf16 v[112:115], v[206:209], v[166:169], v[112:115]
	v_mfma_f32_16x16x32_bf16 v[100:103], v[198:201], v[174:177], v[100:103]
	v_mfma_f32_16x16x32_bf16 v[96:99], v[206:209], v[174:177], v[96:99]
	v_mfma_f32_16x16x32_bf16 v[84:87], v[198:201], v[182:185], v[84:87]
	v_mfma_f32_16x16x32_bf16 v[80:83], v[206:209], v[182:185], v[80:83]
	v_mfma_f32_16x16x32_bf16 v[68:71], v[198:201], v[190:193], v[68:71]
	v_mfma_f32_16x16x32_bf16 v[64:67], v[206:209], v[190:193], v[64:67]
	s_mov_b32 m0, s5
	v_lshl_add_u64 v[214:215], s[26:27], 0, v[130:131]
	s_barrier
	ds_read_b128 v[162:165], v152 offset:16384
	ds_read_b128 v[166:169], v152 offset:17408
	ds_read_b128 v[170:173], v152 offset:18432
	ds_read_b128 v[174:177], v152 offset:19456
	ds_read_b128 v[178:181], v152 offset:20480
	ds_read_b128 v[182:185], v152 offset:21504
	ds_read_b128 v[186:189], v152 offset:22528
	ds_read_b128 v[190:193], v152 offset:23552
	global_load_lds_dwordx4 v130, s[26:27]
	v_lshl_add_u64 v[216:217], s[26:27], 0, v[128:129]
	s_mov_b32 m0, s19
	s_nop 0
	global_load_lds_dwordx4 v128, s[26:27]
	s_barrier
	s_waitcnt lgkmcnt(0)
	s_waitcnt lgkmcnt(0)
	v_mfma_f32_16x16x32_bf16 v[60:63], v[140:143], v[162:165], v[60:63]
	v_mfma_f32_16x16x32_bf16 v[56:59], v[154:157], v[162:165], v[56:59]
	v_mfma_f32_16x16x32_bf16 v[44:47], v[140:143], v[170:173], v[44:47]
	v_mfma_f32_16x16x32_bf16 v[40:43], v[154:157], v[170:173], v[40:43]
	v_mfma_f32_16x16x32_bf16 v[28:31], v[140:143], v[178:181], v[28:31]
	v_mfma_f32_16x16x32_bf16 v[24:27], v[154:157], v[178:181], v[24:27]
	v_mfma_f32_16x16x32_bf16 v[12:15], v[140:143], v[186:189], v[12:15]
	v_mfma_f32_16x16x32_bf16 v[8:11], v[154:157], v[186:189], v[8:11]
	v_mfma_f32_16x16x32_bf16 v[60:63], v[144:147], v[166:169], v[60:63]
	v_mfma_f32_16x16x32_bf16 v[56:59], v[158:161], v[166:169], v[56:59]
	v_mfma_f32_16x16x32_bf16 v[44:47], v[144:147], v[174:177], v[44:47]
	v_mfma_f32_16x16x32_bf16 v[40:43], v[158:161], v[174:177], v[40:43]
	v_mfma_f32_16x16x32_bf16 v[28:31], v[144:147], v[182:185], v[28:31]
	v_mfma_f32_16x16x32_bf16 v[24:27], v[158:161], v[182:185], v[24:27]
	v_mfma_f32_16x16x32_bf16 v[12:15], v[144:147], v[190:193], v[12:15]
	v_mfma_f32_16x16x32_bf16 v[8:11], v[158:161], v[190:193], v[8:11]
	s_barrier
	s_add_u32 s20, s24, 0x80000
	s_addc_u32 s21, s25, 0
	s_add_i32 s47, s37, s2
	s_mov_b32 m0, s47
	s_nop 0
	global_load_lds_dwordx4 v130, s[20:21]
	s_add_i32 m0, s47, 0x2000
	s_nop 0
	global_load_lds_dwordx4 v128, s[20:21]
	s_waitcnt vmcnt(6)
	s_barrier
	v_mfma_f32_16x16x32_bf16 v[52:55], v[194:197], v[162:165], v[52:55]
	v_mfma_f32_16x16x32_bf16 v[48:51], v[202:205], v[162:165], v[48:51]
	v_mfma_f32_16x16x32_bf16 v[36:39], v[194:197], v[170:173], v[36:39]
	v_mfma_f32_16x16x32_bf16 v[32:35], v[202:205], v[170:173], v[32:35]
	v_mfma_f32_16x16x32_bf16 v[20:23], v[194:197], v[178:181], v[20:23]
	v_mfma_f32_16x16x32_bf16 v[16:19], v[202:205], v[178:181], v[16:19]
	v_mfma_f32_16x16x32_bf16 v[4:7], v[194:197], v[186:189], v[4:7]
	v_mfma_f32_16x16x32_bf16 v[0:3], v[202:205], v[186:189], v[0:3]
	v_mfma_f32_16x16x32_bf16 v[52:55], v[198:201], v[166:169], v[52:55]
	v_mfma_f32_16x16x32_bf16 v[48:51], v[206:209], v[166:169], v[48:51]
	v_mfma_f32_16x16x32_bf16 v[36:39], v[198:201], v[174:177], v[36:39]
	v_mfma_f32_16x16x32_bf16 v[32:35], v[206:209], v[174:177], v[32:35]
	v_mfma_f32_16x16x32_bf16 v[20:23], v[198:201], v[182:185], v[20:23]
	v_mfma_f32_16x16x32_bf16 v[16:19], v[206:209], v[182:185], v[16:19]
	v_mfma_f32_16x16x32_bf16 v[4:7], v[198:201], v[190:193], v[4:7]
	v_mfma_f32_16x16x32_bf16 v[0:3], v[206:209], v[190:193], v[0:3]
	s_add_i32 s47, 0, 0x18000
	v_add_u32_e32 v158, s47, v149
	s_barrier
	ds_read_b128 v[140:143], v158
	ds_read_b128 v[144:147], v158 offset:1024
	ds_read_b128 v[154:157], v158 offset:2048
	ds_read_b128 v[158:161], v158 offset:3072
	s_add_u32 s20, s26, 0x80000
	s_addc_u32 s21, s27, 0
	s_mov_b32 m0, s28
	ds_read_b128 v[162:165], v152 offset:32768
	ds_read_b128 v[166:169], v152 offset:33792
	ds_read_b128 v[170:173], v152 offset:34816
	ds_read_b128 v[174:177], v152 offset:35840
	ds_read_b128 v[178:181], v152 offset:36864
	ds_read_b128 v[182:185], v152 offset:37888
	ds_read_b128 v[186:189], v152 offset:38912
	ds_read_b128 v[190:193], v152 offset:39936
	global_load_lds_dwordx4 v130, s[20:21]
	s_mov_b32 m0, s29
	s_nop 0
	global_load_lds_dwordx4 v128, s[20:21]
	s_waitcnt lgkmcnt(8)
	s_barrier
	s_waitcnt lgkmcnt(0)
	s_waitcnt lgkmcnt(0)
	v_mfma_f32_16x16x32_bf16 v[124:127], v[140:143], v[162:165], v[124:127]
	v_mfma_f32_16x16x32_bf16 v[120:123], v[154:157], v[162:165], v[120:123]
	v_mfma_f32_16x16x32_bf16 v[108:111], v[140:143], v[170:173], v[108:111]
	v_mfma_f32_16x16x32_bf16 v[104:107], v[154:157], v[170:173], v[104:107]
	v_mfma_f32_16x16x32_bf16 v[92:95], v[140:143], v[178:181], v[92:95]
	v_mfma_f32_16x16x32_bf16 v[88:91], v[154:157], v[178:181], v[88:91]
	v_mfma_f32_16x16x32_bf16 v[76:79], v[140:143], v[186:189], v[76:79]
	v_mfma_f32_16x16x32_bf16 v[72:75], v[154:157], v[186:189], v[72:75]
	v_mfma_f32_16x16x32_bf16 v[124:127], v[144:147], v[166:169], v[124:127]
	v_mfma_f32_16x16x32_bf16 v[120:123], v[158:161], v[166:169], v[120:123]
	v_mfma_f32_16x16x32_bf16 v[108:111], v[144:147], v[174:177], v[108:111]
	v_mfma_f32_16x16x32_bf16 v[104:107], v[158:161], v[174:177], v[104:107]
	v_mfma_f32_16x16x32_bf16 v[92:95], v[144:147], v[182:185], v[92:95]
	v_mfma_f32_16x16x32_bf16 v[88:91], v[158:161], v[182:185], v[88:91]
	v_mfma_f32_16x16x32_bf16 v[76:79], v[144:147], v[190:193], v[76:79]
	v_mfma_f32_16x16x32_bf16 v[72:75], v[158:161], v[190:193], v[72:75]
	s_barrier
	s_add_i32 s26, 0, 0x1c000
	s_add_i32 s20, s47, s2
	v_add_u32_e32 v206, s26, v149
	s_add_u32 s98, s24, s8
	s_addc_u32 s99, s25, s9
	s_mov_b32 m0, s20
	ds_read_b128 v[194:197], v206
	ds_read_b128 v[198:201], v206 offset:1024
	ds_read_b128 v[202:205], v206 offset:2048
	ds_read_b128 v[206:209], v206 offset:3072
	global_load_lds_dwordx4 v130, s[98:99]
	s_add_i32 m0, s20, 0x2000
	s_nop 0
	global_load_lds_dwordx4 v128, s[98:99]
	s_barrier
	s_waitcnt lgkmcnt(0)
	s_waitcnt lgkmcnt(0)
	v_mfma_f32_16x16x32_bf16 v[116:119], v[194:197], v[162:165], v[116:119]
	v_mfma_f32_16x16x32_bf16 v[112:115], v[202:205], v[162:165], v[112:115]
	v_mfma_f32_16x16x32_bf16 v[100:103], v[194:197], v[170:173], v[100:103]
	v_mfma_f32_16x16x32_bf16 v[96:99], v[202:205], v[170:173], v[96:99]
	v_mfma_f32_16x16x32_bf16 v[84:87], v[194:197], v[178:181], v[84:87]
	v_mfma_f32_16x16x32_bf16 v[80:83], v[202:205], v[178:181], v[80:83]
	v_mfma_f32_16x16x32_bf16 v[68:71], v[194:197], v[186:189], v[68:71]
	v_mfma_f32_16x16x32_bf16 v[64:67], v[202:205], v[186:189], v[64:67]
	v_mfma_f32_16x16x32_bf16 v[116:119], v[198:201], v[166:169], v[116:119]
	v_mfma_f32_16x16x32_bf16 v[112:115], v[206:209], v[166:169], v[112:115]
	v_mfma_f32_16x16x32_bf16 v[100:103], v[198:201], v[174:177], v[100:103]
	v_mfma_f32_16x16x32_bf16 v[96:99], v[206:209], v[174:177], v[96:99]
	v_mfma_f32_16x16x32_bf16 v[84:87], v[198:201], v[182:185], v[84:87]
	v_mfma_f32_16x16x32_bf16 v[80:83], v[206:209], v[182:185], v[80:83]
	v_mfma_f32_16x16x32_bf16 v[68:71], v[198:201], v[190:193], v[68:71]
	v_mfma_f32_16x16x32_bf16 v[64:67], v[206:209], v[190:193], v[64:67]
	s_mov_b32 m0, s31
	v_lshl_add_u64 v[210:211], v[214:215], 0, s[8:9]
	s_barrier
	ds_read_b128 v[162:165], v152 offset:49152
	ds_read_b128 v[166:169], v152 offset:50176
	ds_read_b128 v[170:173], v152 offset:51200
	ds_read_b128 v[174:177], v152 offset:52224
	ds_read_b128 v[178:181], v152 offset:53248
	ds_read_b128 v[182:185], v152 offset:54272
	ds_read_b128 v[186:189], v152 offset:55296
	ds_read_b128 v[190:193], v152 offset:56320
	global_load_lds_dwordx4 v[210:211], off
	v_lshl_add_u64 v[210:211], v[216:217], 0, s[8:9]
	s_mov_b32 m0, s34
	s_nop 0
	global_load_lds_dwordx4 v[210:211], off
	s_barrier
	s_waitcnt lgkmcnt(0)
	s_waitcnt lgkmcnt(0)
	v_mfma_f32_16x16x32_bf16 v[60:63], v[140:143], v[162:165], v[60:63]
	v_mfma_f32_16x16x32_bf16 v[56:59], v[154:157], v[162:165], v[56:59]
	v_mfma_f32_16x16x32_bf16 v[44:47], v[140:143], v[170:173], v[44:47]
	v_mfma_f32_16x16x32_bf16 v[40:43], v[154:157], v[170:173], v[40:43]
	v_mfma_f32_16x16x32_bf16 v[28:31], v[140:143], v[178:181], v[28:31]
	v_mfma_f32_16x16x32_bf16 v[24:27], v[154:157], v[178:181], v[24:27]
	v_mfma_f32_16x16x32_bf16 v[12:15], v[140:143], v[186:189], v[12:15]
	v_mfma_f32_16x16x32_bf16 v[8:11], v[154:157], v[186:189], v[8:11]
	v_mfma_f32_16x16x32_bf16 v[60:63], v[144:147], v[166:169], v[60:63]
	v_mfma_f32_16x16x32_bf16 v[56:59], v[158:161], v[166:169], v[56:59]
	v_mfma_f32_16x16x32_bf16 v[44:47], v[144:147], v[174:177], v[44:47]
	v_mfma_f32_16x16x32_bf16 v[40:43], v[158:161], v[174:177], v[40:43]
	v_mfma_f32_16x16x32_bf16 v[28:31], v[144:147], v[182:185], v[28:31]
	v_mfma_f32_16x16x32_bf16 v[24:27], v[158:161], v[182:185], v[24:27]
	v_mfma_f32_16x16x32_bf16 v[12:15], v[144:147], v[190:193], v[12:15]
	v_mfma_f32_16x16x32_bf16 v[8:11], v[158:161], v[190:193], v[8:11]
	s_barrier
	s_add_u32 s20, s24, 0x80080
	s_addc_u32 s21, s25, 0
	s_add_i32 s24, s26, s2
	s_mov_b32 m0, s24
	s_nop 0
	global_load_lds_dwordx4 v130, s[20:21]
	s_add_i32 m0, s24, 0x2000
	s_nop 0
	global_load_lds_dwordx4 v128, s[20:21]
	s_waitcnt vmcnt(6)
	s_barrier
	v_mfma_f32_16x16x32_bf16 v[52:55], v[194:197], v[162:165], v[52:55]
	v_mfma_f32_16x16x32_bf16 v[48:51], v[202:205], v[162:165], v[48:51]
	v_mfma_f32_16x16x32_bf16 v[36:39], v[194:197], v[170:173], v[36:39]
	v_mfma_f32_16x16x32_bf16 v[32:35], v[202:205], v[170:173], v[32:35]
	v_mfma_f32_16x16x32_bf16 v[20:23], v[194:197], v[178:181], v[20:23]
	v_mfma_f32_16x16x32_bf16 v[16:19], v[202:205], v[178:181], v[16:19]
	v_mfma_f32_16x16x32_bf16 v[4:7], v[194:197], v[186:189], v[4:7]
	v_mfma_f32_16x16x32_bf16 v[0:3], v[202:205], v[186:189], v[0:3]
	v_mfma_f32_16x16x32_bf16 v[52:55], v[198:201], v[166:169], v[52:55]
	v_mfma_f32_16x16x32_bf16 v[48:51], v[206:209], v[166:169], v[48:51]
	v_mfma_f32_16x16x32_bf16 v[36:39], v[198:201], v[174:177], v[36:39]
	v_mfma_f32_16x16x32_bf16 v[32:35], v[206:209], v[174:177], v[32:35]
	v_mfma_f32_16x16x32_bf16 v[20:23], v[198:201], v[182:185], v[20:23]
	v_mfma_f32_16x16x32_bf16 v[16:19], v[206:209], v[182:185], v[16:19]
	v_mfma_f32_16x16x32_bf16 v[4:7], v[198:201], v[190:193], v[4:7]
	v_mfma_f32_16x16x32_bf16 v[0:3], v[206:209], v[190:193], v[0:3]
	s_add_i32 s46, s46, 2
	s_add_u32 s42, s42, 0x100
	s_addc_u32 s43, s43, 0
	s_cmp_gt_u32 s46, 29
	s_mov_b64 s[20:21], s[22:23]
	s_barrier
	s_cbranch_scc0 .LBB0_1417
	v_lshl_or_b32 v144, s39, 8, v150
	v_lshl_add_u32 v140, s18, 8, v148
	v_ashrrev_i32_e32 v145, 31, v144
	v_mov_b64_e32 v[142:143], s[52:53]
	v_readlane_b32 s60, v240, 49
	v_ashrrev_i32_e32 v141, 31, v140
	v_mad_i64_i32 v[146:147], s[20:21], v140, s38, v[142:143]
	v_lshlrev_b64 v[144:145], 2, v[144:145]
	v_readlane_b32 s72, v240, 61
	v_readlane_b32 s73, v240, 62
	v_lshl_add_u64 v[154:155], v[146:147], 0, v[144:145]
	s_and_b64 vcc, exec, s[6:7]
	v_lshl_add_u64 v[146:147], v[140:141], 2, s[72:73]
	global_load_dword v156, v[146:147], off
	s_mov_b32 s39, s10
	s_mov_b32 s18, s12
	s_mov_b64 s[22:23], s[16:17]
	v_readlane_b32 s61, v240, 50
	v_readlane_b32 s62, v240, 51
	v_readlane_b32 s63, v240, 52
	v_readlane_b32 s64, v240, 53
	v_readlane_b32 s65, v240, 54
	v_readlane_b32 s66, v240, 55
	v_readlane_b32 s67, v240, 56
	v_readlane_b32 s68, v240, 57
	v_readlane_b32 s69, v240, 58
	v_readlane_b32 s70, v240, 59
	v_readlane_b32 s71, v240, 60
	v_readlane_b32 s74, v240, 63
	v_readlane_b32 s75, v239, 0
	s_waitcnt vmcnt(0)
	v_pk_add_f32 v[126:127], v[126:127], v[156:157] op_sel_hi:[1,0]
	v_pk_add_f32 v[124:125], v[124:125], v[156:157] op_sel_hi:[1,0]
	v_pk_add_f32 v[122:123], v[122:123], v[156:157] op_sel_hi:[1,0]
	v_pk_add_f32 v[120:121], v[120:121], v[156:157] op_sel_hi:[1,0]
	v_pk_add_f32 v[118:119], v[118:119], v[156:157] op_sel_hi:[1,0]
	v_pk_add_f32 v[116:117], v[116:117], v[156:157] op_sel_hi:[1,0]
	v_pk_add_f32 v[114:115], v[114:115], v[156:157] op_sel_hi:[1,0]
	v_pk_add_f32 v[112:113], v[112:113], v[156:157] op_sel_hi:[1,0]
	global_store_dwordx4 v[154:155], v[124:127], off
	global_store_dwordx4 v[154:155], v[120:123], off offset:64
	global_store_dwordx4 v[154:155], v[116:119], off offset:512
	global_store_dwordx4 v[154:155], v[112:115], off offset:576
	global_load_dword v114, v[146:147], off offset:64
	s_waitcnt vmcnt(0)
	v_pk_add_f32 v[110:111], v[110:111], v[114:115] op_sel_hi:[1,0]
	v_or_b32_e32 v112, 16, v140
	v_mad_i64_i32 v[112:113], s[20:21], v112, s38, v[142:143]
	v_lshl_add_u64 v[112:113], v[112:113], 0, v[144:145]
	v_pk_add_f32 v[108:109], v[108:109], v[114:115] op_sel_hi:[1,0]
	v_pk_add_f32 v[106:107], v[106:107], v[114:115] op_sel_hi:[1,0]
	v_pk_add_f32 v[104:105], v[104:105], v[114:115] op_sel_hi:[1,0]
	v_pk_add_f32 v[102:103], v[102:103], v[114:115] op_sel_hi:[1,0]
	v_pk_add_f32 v[100:101], v[100:101], v[114:115] op_sel_hi:[1,0]
	v_pk_add_f32 v[98:99], v[98:99], v[114:115] op_sel_hi:[1,0]
	v_pk_add_f32 v[96:97], v[96:97], v[114:115] op_sel_hi:[1,0]
	global_store_dwordx4 v[112:113], v[108:111], off
	global_store_dwordx4 v[112:113], v[104:107], off offset:64
	global_store_dwordx4 v[112:113], v[100:103], off offset:512
	global_store_dwordx4 v[112:113], v[96:99], off offset:576
	global_load_dword v98, v[146:147], off offset:128
	s_waitcnt vmcnt(0)
	v_pk_add_f32 v[94:95], v[94:95], v[98:99] op_sel_hi:[1,0]
	v_or_b32_e32 v96, 32, v140
	v_mad_i64_i32 v[96:97], s[20:21], v96, s38, v[142:143]
	v_lshl_add_u64 v[96:97], v[96:97], 0, v[144:145]
	v_pk_add_f32 v[92:93], v[92:93], v[98:99] op_sel_hi:[1,0]
	v_pk_add_f32 v[90:91], v[90:91], v[98:99] op_sel_hi:[1,0]
	v_pk_add_f32 v[88:89], v[88:89], v[98:99] op_sel_hi:[1,0]
	v_pk_add_f32 v[86:87], v[86:87], v[98:99] op_sel_hi:[1,0]
	v_pk_add_f32 v[84:85], v[84:85], v[98:99] op_sel_hi:[1,0]
	v_pk_add_f32 v[82:83], v[82:83], v[98:99] op_sel_hi:[1,0]
	v_pk_add_f32 v[80:81], v[80:81], v[98:99] op_sel_hi:[1,0]
	global_store_dwordx4 v[96:97], v[92:95], off
	global_store_dwordx4 v[96:97], v[88:91], off offset:64
	global_store_dwordx4 v[96:97], v[84:87], off offset:512
	global_store_dwordx4 v[96:97], v[80:83], off offset:576
	global_load_dword v82, v[146:147], off offset:192
	s_waitcnt vmcnt(0)
	v_pk_add_f32 v[78:79], v[78:79], v[82:83] op_sel_hi:[1,0]
	v_or_b32_e32 v80, 48, v140
	v_mad_i64_i32 v[80:81], s[20:21], v80, s38, v[142:143]
	v_lshl_add_u64 v[80:81], v[80:81], 0, v[144:145]
	v_pk_add_f32 v[76:77], v[76:77], v[82:83] op_sel_hi:[1,0]
	v_pk_add_f32 v[74:75], v[74:75], v[82:83] op_sel_hi:[1,0]
	v_pk_add_f32 v[72:73], v[72:73], v[82:83] op_sel_hi:[1,0]
	v_pk_add_f32 v[70:71], v[70:71], v[82:83] op_sel_hi:[1,0]
	v_pk_add_f32 v[68:69], v[68:69], v[82:83] op_sel_hi:[1,0]
	v_pk_add_f32 v[66:67], v[66:67], v[82:83] op_sel_hi:[1,0]
	v_pk_add_f32 v[64:65], v[64:65], v[82:83] op_sel_hi:[1,0]
	global_store_dwordx4 v[80:81], v[76:79], off
	global_store_dwordx4 v[80:81], v[72:75], off offset:64
	global_store_dwordx4 v[80:81], v[68:71], off offset:512
	global_store_dwordx4 v[80:81], v[64:67], off offset:576
	global_load_dword v66, v[146:147], off offset:512
	s_waitcnt vmcnt(0)
	v_pk_add_f32 v[62:63], v[62:63], v[66:67] op_sel_hi:[1,0]
	v_add_u32_e32 v64, 0x80, v140
	v_mad_i64_i32 v[64:65], s[20:21], v64, s38, v[142:143]
	v_lshl_add_u64 v[64:65], v[64:65], 0, v[144:145]
	v_pk_add_f32 v[60:61], v[60:61], v[66:67] op_sel_hi:[1,0]
	v_pk_add_f32 v[58:59], v[58:59], v[66:67] op_sel_hi:[1,0]
	v_pk_add_f32 v[56:57], v[56:57], v[66:67] op_sel_hi:[1,0]
	v_pk_add_f32 v[54:55], v[54:55], v[66:67] op_sel_hi:[1,0]
	v_pk_add_f32 v[52:53], v[52:53], v[66:67] op_sel_hi:[1,0]
	v_pk_add_f32 v[50:51], v[50:51], v[66:67] op_sel_hi:[1,0]
	v_pk_add_f32 v[48:49], v[48:49], v[66:67] op_sel_hi:[1,0]
	global_store_dwordx4 v[64:65], v[60:63], off
	global_store_dwordx4 v[64:65], v[56:59], off offset:64
	global_store_dwordx4 v[64:65], v[52:55], off offset:512
	global_store_dwordx4 v[64:65], v[48:51], off offset:576
	global_load_dword v50, v[146:147], off offset:576
	s_waitcnt vmcnt(0)
	v_pk_add_f32 v[46:47], v[46:47], v[50:51] op_sel_hi:[1,0]
	v_add_u32_e32 v48, 0x90, v140
	v_mad_i64_i32 v[48:49], s[20:21], v48, s38, v[142:143]
	v_lshl_add_u64 v[48:49], v[48:49], 0, v[144:145]
	v_pk_add_f32 v[44:45], v[44:45], v[50:51] op_sel_hi:[1,0]
	v_pk_add_f32 v[42:43], v[42:43], v[50:51] op_sel_hi:[1,0]
	v_pk_add_f32 v[40:41], v[40:41], v[50:51] op_sel_hi:[1,0]
	v_pk_add_f32 v[38:39], v[38:39], v[50:51] op_sel_hi:[1,0]
	v_pk_add_f32 v[36:37], v[36:37], v[50:51] op_sel_hi:[1,0]
	v_pk_add_f32 v[34:35], v[34:35], v[50:51] op_sel_hi:[1,0]
	v_pk_add_f32 v[32:33], v[32:33], v[50:51] op_sel_hi:[1,0]
	global_store_dwordx4 v[48:49], v[44:47], off
	global_store_dwordx4 v[48:49], v[40:43], off offset:64
	global_store_dwordx4 v[48:49], v[36:39], off offset:512
	global_store_dwordx4 v[48:49], v[32:35], off offset:576
	global_load_dword v34, v[146:147], off offset:640
	s_waitcnt vmcnt(0)
	v_pk_add_f32 v[30:31], v[30:31], v[34:35] op_sel_hi:[1,0]
	v_add_u32_e32 v32, 0xa0, v140
	v_mad_i64_i32 v[32:33], s[20:21], v32, s38, v[142:143]
	v_lshl_add_u64 v[32:33], v[32:33], 0, v[144:145]
	v_pk_add_f32 v[28:29], v[28:29], v[34:35] op_sel_hi:[1,0]
	v_pk_add_f32 v[26:27], v[26:27], v[34:35] op_sel_hi:[1,0]
	v_pk_add_f32 v[24:25], v[24:25], v[34:35] op_sel_hi:[1,0]
	v_pk_add_f32 v[22:23], v[22:23], v[34:35] op_sel_hi:[1,0]
	v_pk_add_f32 v[20:21], v[20:21], v[34:35] op_sel_hi:[1,0]
	v_pk_add_f32 v[18:19], v[18:19], v[34:35] op_sel_hi:[1,0]
	v_pk_add_f32 v[16:17], v[16:17], v[34:35] op_sel_hi:[1,0]
	global_store_dwordx4 v[32:33], v[28:31], off
	global_store_dwordx4 v[32:33], v[24:27], off offset:64
	global_store_dwordx4 v[32:33], v[20:23], off offset:512
	global_store_dwordx4 v[32:33], v[16:19], off offset:576
	global_load_dword v18, v[146:147], off offset:704
	s_waitcnt vmcnt(0)
	v_pk_add_f32 v[14:15], v[14:15], v[18:19] op_sel_hi:[1,0]
	v_add_u32_e32 v16, 0xb0, v140
	v_mad_i64_i32 v[16:17], s[20:21], v16, s38, v[142:143]
	v_lshl_add_u64 v[16:17], v[16:17], 0, v[144:145]
	v_pk_add_f32 v[12:13], v[12:13], v[18:19] op_sel_hi:[1,0]
	v_pk_add_f32 v[10:11], v[10:11], v[18:19] op_sel_hi:[1,0]
	v_pk_add_f32 v[8:9], v[8:9], v[18:19] op_sel_hi:[1,0]
	v_pk_add_f32 v[6:7], v[6:7], v[18:19] op_sel_hi:[1,0]
	v_pk_add_f32 v[4:5], v[4:5], v[18:19] op_sel_hi:[1,0]
	v_pk_add_f32 v[2:3], v[2:3], v[18:19] op_sel_hi:[1,0]
	v_pk_add_f32 v[0:1], v[0:1], v[18:19] op_sel_hi:[1,0]
	s_mov_b64 s[20:21], s[14:15]
	global_store_dwordx4 v[16:17], v[12:15], off
	global_store_dwordx4 v[16:17], v[8:11], off offset:64
	global_store_dwordx4 v[16:17], v[4:7], off offset:512
	global_store_dwordx4 v[16:17], v[0:3], off offset:576
	s_cbranch_vccz .LBB0_1414
	s_waitcnt vmcnt(0)
	s_cmpk_gt_u32 s1, 0xff
	s_cbranch_scc1 .LBB0_1421
	s_barrier

.LBB0_1846:
	ds_read_b128 v[130:133], v159
	ds_read_b128 v[134:137], v159 offset:1024
	ds_read_b128 v[150:153], v159 offset:2048
	ds_read_b128 v[162:165], v159 offset:3072
	v_lshl_add_u64 v[116:117], s[8:9], 0, v[142:143]
	s_add_i32 m0, s4, 0xc000
	ds_read_b128 v[166:169], v160
	ds_read_b128 v[170:173], v160 offset:1024
	ds_read_b128 v[174:177], v160 offset:2048
	ds_read_b128 v[178:181], v160 offset:3072
	ds_read_b128 v[182:185], v160 offset:4096
	ds_read_b128 v[186:189], v160 offset:5120
	ds_read_b128 v[190:193], v160 offset:6144
	ds_read_b128 v[194:197], v160 offset:7168
	global_load_lds_dwordx4 v[116:117], off
	v_lshl_add_u64 v[116:117], s[8:9], 0, v[144:145]
	s_add_i32 m0, s4, 0xe000
	s_nop 0
	global_load_lds_dwordx4 v[116:117], off
	s_waitcnt lgkmcnt(8)
	s_barrier
	s_waitcnt lgkmcnt(0)
	s_waitcnt lgkmcnt(0)
	v_mfma_f32_16x16x32_bf16 v[126:129], v[130:133], v[166:169], v[126:129]
	s_add_u32 s24, s8, 0x100
	s_addc_u32 s25, s9, 0
	s_cmp_eq_u32 s60, 28
	s_cselect_b32 s29, s17, s25
	s_cselect_b32 s28, s42, s24
	s_cselect_b32 s27, s15, s47
	s_cselect_b32 s26, s43, s46
	v_mfma_f32_16x16x32_bf16 v[92:95], v[150:153], v[166:169], v[92:95]
	v_mfma_f32_16x16x32_bf16 v[122:125], v[130:133], v[174:177], v[122:125]
	v_mfma_f32_16x16x32_bf16 v[88:91], v[150:153], v[174:177], v[88:91]
	v_mfma_f32_16x16x32_bf16 v[116:119], v[130:133], v[182:185], v[118:121]
	v_mfma_f32_16x16x32_bf16 v[84:87], v[150:153], v[182:185], v[84:87]
	v_mfma_f32_16x16x32_bf16 v[112:115], v[130:133], v[190:193], v[112:115]
	v_mfma_f32_16x16x32_bf16 v[80:83], v[150:153], v[190:193], v[80:83]
	v_mfma_f32_16x16x32_bf16 v[126:129], v[134:137], v[170:173], v[126:129]
	v_mfma_f32_16x16x32_bf16 v[92:95], v[162:165], v[170:173], v[92:95]
	v_mfma_f32_16x16x32_bf16 v[122:125], v[134:137], v[178:181], v[122:125]
	v_mfma_f32_16x16x32_bf16 v[88:91], v[162:165], v[178:181], v[88:91]
	v_mfma_f32_16x16x32_bf16 v[116:119], v[134:137], v[186:189], v[116:119]
	v_mfma_f32_16x16x32_bf16 v[84:87], v[162:165], v[186:189], v[84:87]
	v_mfma_f32_16x16x32_bf16 v[112:115], v[134:137], v[194:197], v[112:115]
	v_mfma_f32_16x16x32_bf16 v[80:83], v[162:165], v[194:197], v[80:83]
	s_barrier
	s_add_i32 s8, s39, s3
	v_lshl_add_u64 v[154:155], s[26:27], 0, v[138:139]
	s_mov_b32 m0, s8
	ds_read_b128 v[198:201], v161
	ds_read_b128 v[202:205], v161 offset:1024
	ds_read_b128 v[206:209], v161 offset:2048
	ds_read_b128 v[210:213], v161 offset:3072
	global_load_lds_dwordx4 v[154:155], off
	v_lshl_add_u64 v[214:215], s[26:27], 0, v[140:141]
	s_add_i32 m0, s8, 0x2000
	s_nop 0
	global_load_lds_dwordx4 v[214:215], off
	s_barrier
	s_waitcnt lgkmcnt(0)
	s_waitcnt lgkmcnt(0)
	v_mfma_f32_16x16x32_bf16 v[60:63], v[198:201], v[166:169], v[60:63]
	v_mfma_f32_16x16x32_bf16 v[28:31], v[206:209], v[166:169], v[28:31]
	v_mfma_f32_16x16x32_bf16 v[56:59], v[198:201], v[174:177], v[56:59]
	v_mfma_f32_16x16x32_bf16 v[24:27], v[206:209], v[174:177], v[24:27]
	v_mfma_f32_16x16x32_bf16 v[52:55], v[198:201], v[182:185], v[52:55]
	v_mfma_f32_16x16x32_bf16 v[20:23], v[206:209], v[182:185], v[20:23]
	v_mfma_f32_16x16x32_bf16 v[48:51], v[198:201], v[190:193], v[48:51]
	v_mfma_f32_16x16x32_bf16 v[16:19], v[206:209], v[190:193], v[16:19]
	v_mfma_f32_16x16x32_bf16 v[60:63], v[202:205], v[170:173], v[60:63]
	v_mfma_f32_16x16x32_bf16 v[28:31], v[210:213], v[170:173], v[28:31]
	v_mfma_f32_16x16x32_bf16 v[56:59], v[202:205], v[178:181], v[56:59]
	v_mfma_f32_16x16x32_bf16 v[24:27], v[210:213], v[178:181], v[24:27]
	v_mfma_f32_16x16x32_bf16 v[52:55], v[202:205], v[186:189], v[52:55]
	v_mfma_f32_16x16x32_bf16 v[20:23], v[210:213], v[186:189], v[20:23]
	v_mfma_f32_16x16x32_bf16 v[48:51], v[202:205], v[194:197], v[48:51]
	v_mfma_f32_16x16x32_bf16 v[16:19], v[210:213], v[194:197], v[16:19]
	s_mov_b32 m0, s4
	v_lshl_add_u64 v[216:217], s[28:29], 0, v[138:139]
	s_barrier
	ds_read_b128 v[166:169], v160 offset:16384
	ds_read_b128 v[170:173], v160 offset:17408
	ds_read_b128 v[174:177], v160 offset:18432
	ds_read_b128 v[178:181], v160 offset:19456
	ds_read_b128 v[182:185], v160 offset:20480
	ds_read_b128 v[186:189], v160 offset:21504
	ds_read_b128 v[190:193], v160 offset:22528
	ds_read_b128 v[194:197], v160 offset:23552
	global_load_lds_dwordx4 v[216:217], off
	v_lshl_add_u64 v[218:219], s[28:29], 0, v[140:141]
	s_mov_b32 m0, s5
	s_nop 0
	global_load_lds_dwordx4 v[218:219], off
	s_barrier
	s_waitcnt lgkmcnt(0)
	s_waitcnt lgkmcnt(0)
	v_mfma_f32_16x16x32_bf16 v[108:111], v[130:133], v[166:169], v[108:111]
	v_mfma_f32_16x16x32_bf16 v[76:79], v[150:153], v[166:169], v[76:79]
	v_mfma_f32_16x16x32_bf16 v[104:107], v[130:133], v[174:177], v[104:107]
	v_mfma_f32_16x16x32_bf16 v[72:75], v[150:153], v[174:177], v[72:75]
	v_mfma_f32_16x16x32_bf16 v[100:103], v[130:133], v[182:185], v[100:103]
	v_mfma_f32_16x16x32_bf16 v[68:71], v[150:153], v[182:185], v[68:71]
	v_mfma_f32_16x16x32_bf16 v[96:99], v[130:133], v[190:193], v[96:99]
	v_mfma_f32_16x16x32_bf16 v[64:67], v[150:153], v[190:193], v[64:67]
	v_mfma_f32_16x16x32_bf16 v[108:111], v[134:137], v[170:173], v[108:111]
	v_mfma_f32_16x16x32_bf16 v[76:79], v[162:165], v[170:173], v[76:79]
	v_mfma_f32_16x16x32_bf16 v[104:107], v[134:137], v[178:181], v[104:107]
	v_mfma_f32_16x16x32_bf16 v[72:75], v[162:165], v[178:181], v[72:75]
	v_mfma_f32_16x16x32_bf16 v[100:103], v[134:137], v[186:189], v[100:103]
	v_mfma_f32_16x16x32_bf16 v[68:71], v[162:165], v[186:189], v[68:71]
	v_mfma_f32_16x16x32_bf16 v[96:99], v[134:137], v[194:197], v[96:99]
	v_mfma_f32_16x16x32_bf16 v[64:67], v[162:165], v[194:197], v[64:67]
	s_barrier
	s_add_u32 s8, s26, 0x80000
	s_addc_u32 s9, s27, 0
	s_add_i32 s61, s40, s3
	v_lshl_add_u64 v[120:121], s[8:9], 0, v[138:139]
	s_mov_b32 m0, s61
	s_nop 0
	global_load_lds_dwordx4 v[120:121], off
	v_lshl_add_u64 v[120:121], s[8:9], 0, v[140:141]
	s_add_i32 m0, s61, 0x2000
	s_nop 0
	global_load_lds_dwordx4 v[120:121], off
	s_waitcnt vmcnt(6)
	s_barrier
	v_mfma_f32_16x16x32_bf16 v[44:47], v[198:201], v[166:169], v[44:47]
	v_mfma_f32_16x16x32_bf16 v[12:15], v[206:209], v[166:169], v[12:15]
	v_mfma_f32_16x16x32_bf16 v[40:43], v[198:201], v[174:177], v[40:43]
	v_mfma_f32_16x16x32_bf16 v[8:11], v[206:209], v[174:177], v[8:11]
	v_mfma_f32_16x16x32_bf16 v[36:39], v[198:201], v[182:185], v[36:39]
	v_mfma_f32_16x16x32_bf16 v[4:7], v[206:209], v[182:185], v[4:7]
	v_mfma_f32_16x16x32_bf16 v[32:35], v[198:201], v[190:193], v[32:35]
	v_mfma_f32_16x16x32_bf16 v[0:3], v[206:209], v[190:193], v[0:3]
	v_mfma_f32_16x16x32_bf16 v[44:47], v[202:205], v[170:173], v[44:47]
	v_mfma_f32_16x16x32_bf16 v[12:15], v[210:213], v[170:173], v[12:15]
	v_mfma_f32_16x16x32_bf16 v[40:43], v[202:205], v[178:181], v[40:43]
	v_mfma_f32_16x16x32_bf16 v[8:11], v[210:213], v[178:181], v[8:11]
	v_mfma_f32_16x16x32_bf16 v[36:39], v[202:205], v[186:189], v[36:39]
	v_mfma_f32_16x16x32_bf16 v[4:7], v[210:213], v[186:189], v[4:7]
	v_mfma_f32_16x16x32_bf16 v[32:35], v[202:205], v[194:197], v[32:35]
	v_mfma_f32_16x16x32_bf16 v[0:3], v[210:213], v[194:197], v[0:3]
	s_add_i32 s61, 0, 0x18000
	v_add_u32_e32 v120, s61, v157
	s_barrier
	ds_read_b128 v[130:133], v120
	ds_read_b128 v[134:137], v120 offset:1024
	ds_read_b128 v[150:153], v120 offset:2048
	ds_read_b128 v[162:165], v120 offset:3072
	s_add_u32 s8, s28, 0x80000
	s_addc_u32 s9, s29, 0
	s_mov_b32 m0, s23
	v_lshl_add_u64 v[120:121], s[8:9], 0, v[138:139]
	ds_read_b128 v[166:169], v160 offset:32768
	ds_read_b128 v[170:173], v160 offset:33792
	ds_read_b128 v[174:177], v160 offset:34816
	ds_read_b128 v[178:181], v160 offset:35840
	ds_read_b128 v[182:185], v160 offset:36864
	ds_read_b128 v[186:189], v160 offset:37888
	ds_read_b128 v[190:193], v160 offset:38912
	ds_read_b128 v[194:197], v160 offset:39936
	global_load_lds_dwordx4 v[120:121], off
	v_lshl_add_u64 v[120:121], s[8:9], 0, v[140:141]
	s_mov_b32 m0, s30
	s_nop 0
	global_load_lds_dwordx4 v[120:121], off
	s_waitcnt lgkmcnt(8)
	s_barrier
	s_waitcnt lgkmcnt(0)
	s_waitcnt lgkmcnt(0)
	v_mfma_f32_16x16x32_bf16 v[126:129], v[130:133], v[166:169], v[126:129]
	v_mfma_f32_16x16x32_bf16 v[92:95], v[150:153], v[166:169], v[92:95]
	v_mfma_f32_16x16x32_bf16 v[120:123], v[130:133], v[174:177], v[122:125]
	v_mfma_f32_16x16x32_bf16 v[88:91], v[150:153], v[174:177], v[88:91]
	v_mfma_f32_16x16x32_bf16 v[116:119], v[130:133], v[182:185], v[116:119]
	v_mfma_f32_16x16x32_bf16 v[84:87], v[150:153], v[182:185], v[84:87]
	v_mfma_f32_16x16x32_bf16 v[112:115], v[130:133], v[190:193], v[112:115]
	v_mfma_f32_16x16x32_bf16 v[80:83], v[150:153], v[190:193], v[80:83]
	v_mfma_f32_16x16x32_bf16 v[126:129], v[134:137], v[170:173], v[126:129]
	v_mfma_f32_16x16x32_bf16 v[92:95], v[162:165], v[170:173], v[92:95]
	v_mfma_f32_16x16x32_bf16 v[122:125], v[134:137], v[178:181], v[120:123]
	v_mfma_f32_16x16x32_bf16 v[88:91], v[162:165], v[178:181], v[88:91]
	v_mfma_f32_16x16x32_bf16 v[118:121], v[134:137], v[186:189], v[116:119]
	v_mfma_f32_16x16x32_bf16 v[84:87], v[162:165], v[186:189], v[84:87]
	v_mfma_f32_16x16x32_bf16 v[112:115], v[134:137], v[194:197], v[112:115]
	v_mfma_f32_16x16x32_bf16 v[80:83], v[162:165], v[194:197], v[80:83]
	s_barrier
	s_add_i32 s28, 0, 0x1c000
	v_add_u32_e32 v116, s28, v157
	s_add_i32 s8, s61, s3
	ds_read_b128 v[198:201], v116
	ds_read_b128 v[202:205], v116 offset:1024
	ds_read_b128 v[206:209], v116 offset:2048
	ds_read_b128 v[210:213], v116 offset:3072
	v_lshl_add_u64 v[116:117], v[154:155], 0, s[10:11]
	s_mov_b32 m0, s8
	s_nop 0
	global_load_lds_dwordx4 v[116:117], off
	v_lshl_add_u64 v[116:117], v[214:215], 0, s[10:11]
	s_add_i32 m0, s8, 0x2000
	s_nop 0
	global_load_lds_dwordx4 v[116:117], off
	s_barrier
	s_waitcnt lgkmcnt(0)
	s_waitcnt lgkmcnt(0)
	v_mfma_f32_16x16x32_bf16 v[60:63], v[198:201], v[166:169], v[60:63]
	v_mfma_f32_16x16x32_bf16 v[28:31], v[206:209], v[166:169], v[28:31]
	v_mfma_f32_16x16x32_bf16 v[56:59], v[198:201], v[174:177], v[56:59]
	v_mfma_f32_16x16x32_bf16 v[24:27], v[206:209], v[174:177], v[24:27]
	v_mfma_f32_16x16x32_bf16 v[52:55], v[198:201], v[182:185], v[52:55]
	v_mfma_f32_16x16x32_bf16 v[20:23], v[206:209], v[182:185], v[20:23]
	v_mfma_f32_16x16x32_bf16 v[48:51], v[198:201], v[190:193], v[48:51]
	v_mfma_f32_16x16x32_bf16 v[16:19], v[206:209], v[190:193], v[16:19]
	v_mfma_f32_16x16x32_bf16 v[60:63], v[202:205], v[170:173], v[60:63]
	v_mfma_f32_16x16x32_bf16 v[28:31], v[210:213], v[170:173], v[28:31]
	v_mfma_f32_16x16x32_bf16 v[56:59], v[202:205], v[178:181], v[56:59]
	v_mfma_f32_16x16x32_bf16 v[24:27], v[210:213], v[178:181], v[24:27]
	v_mfma_f32_16x16x32_bf16 v[52:55], v[202:205], v[186:189], v[52:55]
	v_mfma_f32_16x16x32_bf16 v[20:23], v[210:213], v[186:189], v[20:23]
	v_mfma_f32_16x16x32_bf16 v[48:51], v[202:205], v[194:197], v[48:51]
	v_mfma_f32_16x16x32_bf16 v[16:19], v[210:213], v[194:197], v[16:19]
	s_mov_b32 m0, s34
	v_lshl_add_u64 v[116:117], v[216:217], 0, s[10:11]
	s_barrier
	ds_read_b128 v[166:169], v160 offset:49152
	ds_read_b128 v[170:173], v160 offset:50176
	ds_read_b128 v[174:177], v160 offset:51200
	ds_read_b128 v[178:181], v160 offset:52224
	ds_read_b128 v[182:185], v160 offset:53248
	ds_read_b128 v[186:189], v160 offset:54272
	ds_read_b128 v[190:193], v160 offset:55296
	ds_read_b128 v[194:197], v160 offset:56320
	global_load_lds_dwordx4 v[116:117], off
	v_lshl_add_u64 v[116:117], v[218:219], 0, s[10:11]
	s_mov_b32 m0, s35
	s_nop 0
	global_load_lds_dwordx4 v[116:117], off
	s_barrier
	s_waitcnt lgkmcnt(0)
	s_waitcnt lgkmcnt(0)
	v_mfma_f32_16x16x32_bf16 v[108:111], v[130:133], v[166:169], v[108:111]
	v_mfma_f32_16x16x32_bf16 v[76:79], v[150:153], v[166:169], v[76:79]
	v_mfma_f32_16x16x32_bf16 v[104:107], v[130:133], v[174:177], v[104:107]
	v_mfma_f32_16x16x32_bf16 v[72:75], v[150:153], v[174:177], v[72:75]
	v_mfma_f32_16x16x32_bf16 v[100:103], v[130:133], v[182:185], v[100:103]
	v_mfma_f32_16x16x32_bf16 v[68:71], v[150:153], v[182:185], v[68:71]
	v_mfma_f32_16x16x32_bf16 v[96:99], v[130:133], v[190:193], v[96:99]
	v_mfma_f32_16x16x32_bf16 v[64:67], v[150:153], v[190:193], v[64:67]
	v_mfma_f32_16x16x32_bf16 v[108:111], v[134:137], v[170:173], v[108:111]
	v_mfma_f32_16x16x32_bf16 v[76:79], v[162:165], v[170:173], v[76:79]
	v_mfma_f32_16x16x32_bf16 v[104:107], v[134:137], v[178:181], v[104:107]
	v_mfma_f32_16x16x32_bf16 v[72:75], v[162:165], v[178:181], v[72:75]
	v_mfma_f32_16x16x32_bf16 v[100:103], v[134:137], v[186:189], v[100:103]
	v_mfma_f32_16x16x32_bf16 v[68:71], v[162:165], v[186:189], v[68:71]
	v_mfma_f32_16x16x32_bf16 v[96:99], v[134:137], v[194:197], v[96:99]
	v_mfma_f32_16x16x32_bf16 v[64:67], v[162:165], v[194:197], v[64:67]
	s_barrier
	s_add_u32 s8, s26, 0x80080
	s_addc_u32 s9, s27, 0
	s_add_i32 s26, s28, s3
	v_lshl_add_u64 v[116:117], s[8:9], 0, v[138:139]
	s_mov_b32 m0, s26
	s_nop 0
	global_load_lds_dwordx4 v[116:117], off
	v_lshl_add_u64 v[116:117], s[8:9], 0, v[140:141]
	s_add_i32 m0, s26, 0x2000
	s_nop 0
	global_load_lds_dwordx4 v[116:117], off
	s_waitcnt vmcnt(6)
	s_barrier
	v_mfma_f32_16x16x32_bf16 v[44:47], v[198:201], v[166:169], v[44:47]
	v_mfma_f32_16x16x32_bf16 v[12:15], v[206:209], v[166:169], v[12:15]
	v_mfma_f32_16x16x32_bf16 v[40:43], v[198:201], v[174:177], v[40:43]
	v_mfma_f32_16x16x32_bf16 v[8:11], v[206:209], v[174:177], v[8:11]
	v_mfma_f32_16x16x32_bf16 v[36:39], v[198:201], v[182:185], v[36:39]
	v_mfma_f32_16x16x32_bf16 v[4:7], v[206:209], v[182:185], v[4:7]
	v_mfma_f32_16x16x32_bf16 v[32:35], v[198:201], v[190:193], v[32:35]
	v_mfma_f32_16x16x32_bf16 v[0:3], v[206:209], v[190:193], v[0:3]
	v_mfma_f32_16x16x32_bf16 v[44:47], v[202:205], v[170:173], v[44:47]
	v_mfma_f32_16x16x32_bf16 v[12:15], v[210:213], v[170:173], v[12:15]
	v_mfma_f32_16x16x32_bf16 v[40:43], v[202:205], v[178:181], v[40:43]
	v_mfma_f32_16x16x32_bf16 v[8:11], v[210:213], v[178:181], v[8:11]
	v_mfma_f32_16x16x32_bf16 v[36:39], v[202:205], v[186:189], v[36:39]
	v_mfma_f32_16x16x32_bf16 v[4:7], v[210:213], v[186:189], v[4:7]
	v_mfma_f32_16x16x32_bf16 v[32:35], v[202:205], v[194:197], v[32:35]
	v_mfma_f32_16x16x32_bf16 v[0:3], v[210:213], v[194:197], v[0:3]
	s_add_i32 s60, s60, 2
	s_add_u32 s46, s46, 0x100
	s_addc_u32 s47, s47, 0
	s_cmp_gt_u32 s60, 29
	s_mov_b64 s[8:9], s[24:25]
	s_barrier
	s_cbranch_scc0 .LBB0_1846
	s_cmp_lt_u32 s22, 32
	s_movk_i32 s8, 0x3000
	s_cselect_b32 s8, s8, 0x6000
	s_cmp_gt_i32 s22, 15
	s_cselect_b32 s8, s8, 0
	s_lshl_b32 s8, s8, 2
	v_lshl_or_b32 v154, s41, 8, v158
	s_add_u32 s8, s37, s8
	s_addc_u32 s9, s38, 0
	v_ashrrev_i32_e32 v155, 31, v154
	v_lshl_add_u64 v[150:151], v[154:155], 2, s[8:9]
	global_load_dwordx4 v[130:133], v[150:151], off
	v_readlane_b32 s60, v239, 35
	v_cndmask_b32_e64 v117, 0, 1, s[12:13]
	v_readlane_b32 s66, v239, 41
	v_readlane_b32 s67, v239, 42
	v_mov_b32_e32 v116, 0
	v_cmp_ne_u32_e64 s[8:9], 1, v117
	s_andn2_b64 vcc, exec, s[12:13]
	v_lshl_add_u64 v[152:153], v[154:155], 2, s[66:67]
	v_mov_b32_e32 v134, 0
	v_mov_b32_e32 v135, 0
	v_mov_b32_e32 v136, 0
	v_mov_b32_e32 v137, 0
	v_readlane_b32 s61, v239, 36
	v_readlane_b32 s62, v239, 37
	v_readlane_b32 s63, v239, 38
	v_readlane_b32 s64, v239, 39
	v_readlane_b32 s65, v239, 40
	v_readlane_b32 s68, v239, 43
	v_readlane_b32 s69, v239, 44
	v_readlane_b32 s70, v239, 45
	v_readlane_b32 s71, v239, 46
	v_readlane_b32 s72, v239, 47
	v_readlane_b32 s73, v239, 48
	v_readlane_b32 s74, v239, 49
	v_readlane_b32 s75, v239, 50
	s_cbranch_vccnz .LBB0_1849
	global_load_dwordx4 v[134:137], v[152:153], off

.LBB0_1865:
	ds_read_b128 v[142:145], v139
	ds_read_b128 v[146:149], v139 offset:1024
	ds_read_b128 v[150:153], v139 offset:2048
	ds_read_b128 v[154:157], v139 offset:3072
	v_lshl_add_u64 v[190:191], s[22:23], 0, v[132:133]
	s_add_i32 m0, s5, 0xc000
	ds_read_b128 v[158:161], v140
	ds_read_b128 v[162:165], v140 offset:1024
	ds_read_b128 v[166:169], v140 offset:2048
	ds_read_b128 v[170:173], v140 offset:3072
	ds_read_b128 v[174:177], v140 offset:4096
	ds_read_b128 v[178:181], v140 offset:5120
	ds_read_b128 v[182:185], v140 offset:6144
	ds_read_b128 v[186:189], v140 offset:7168
	global_load_lds_dwordx4 v[190:191], off
	s_add_i32 m0, s5, 0xe000
	s_nop 0
	global_load_lds_dwordx4 v134, s[22:23]
	s_waitcnt lgkmcnt(8)
	s_barrier
	s_waitcnt lgkmcnt(0)
	s_waitcnt lgkmcnt(0)
	v_mfma_f32_16x16x32_bf16 v[124:127], v[142:145], v[158:161], v[124:127]
	s_add_u32 s24, s22, 0x100
	s_addc_u32 s25, s23, 0
	s_cmp_eq_u32 s46, 4
	s_cselect_b32 s29, s15, s25
	s_cselect_b32 s28, s40, s24
	s_cselect_b32 s27, s13, s43
	s_cselect_b32 s26, s41, s42
	v_mfma_f32_16x16x32_bf16 v[120:123], v[150:153], v[158:161], v[120:123]
	v_mfma_f32_16x16x32_bf16 v[116:119], v[142:145], v[166:169], v[116:119]
	v_mfma_f32_16x16x32_bf16 v[112:115], v[150:153], v[166:169], v[112:115]
	v_mfma_f32_16x16x32_bf16 v[100:103], v[142:145], v[174:177], v[100:103]
	v_mfma_f32_16x16x32_bf16 v[96:99], v[150:153], v[174:177], v[96:99]
	v_mfma_f32_16x16x32_bf16 v[84:87], v[142:145], v[182:185], v[84:87]
	v_mfma_f32_16x16x32_bf16 v[80:83], v[150:153], v[182:185], v[80:83]
	v_mfma_f32_16x16x32_bf16 v[124:127], v[146:149], v[162:165], v[124:127]
	v_mfma_f32_16x16x32_bf16 v[120:123], v[154:157], v[162:165], v[120:123]
	v_mfma_f32_16x16x32_bf16 v[116:119], v[146:149], v[170:173], v[116:119]
	v_mfma_f32_16x16x32_bf16 v[112:115], v[154:157], v[170:173], v[112:115]
	v_mfma_f32_16x16x32_bf16 v[100:103], v[146:149], v[178:181], v[100:103]
	v_mfma_f32_16x16x32_bf16 v[96:99], v[154:157], v[178:181], v[96:99]
	v_mfma_f32_16x16x32_bf16 v[84:87], v[146:149], v[186:189], v[84:87]
	v_mfma_f32_16x16x32_bf16 v[80:83], v[154:157], v[186:189], v[80:83]
	s_barrier
	s_add_i32 s22, s37, s4
	s_mov_b32 m0, s22
	ds_read_b128 v[190:193], v141
	ds_read_b128 v[194:197], v141 offset:1024
	ds_read_b128 v[198:201], v141 offset:2048
	ds_read_b128 v[202:205], v141 offset:3072
	global_load_lds_dwordx4 v130, s[26:27]
	s_add_i32 m0, s22, 0x2000
	s_nop 0
	global_load_lds_dwordx4 v128, s[26:27]
	s_barrier
	s_waitcnt lgkmcnt(0)
	s_waitcnt lgkmcnt(0)
	v_mfma_f32_16x16x32_bf16 v[108:111], v[190:193], v[158:161], v[108:111]
	v_mfma_f32_16x16x32_bf16 v[104:107], v[198:201], v[158:161], v[104:107]
	v_mfma_f32_16x16x32_bf16 v[92:95], v[190:193], v[166:169], v[92:95]
	v_mfma_f32_16x16x32_bf16 v[88:91], v[198:201], v[166:169], v[88:91]
	v_mfma_f32_16x16x32_bf16 v[76:79], v[190:193], v[174:177], v[76:79]
	v_mfma_f32_16x16x32_bf16 v[72:75], v[198:201], v[174:177], v[72:75]
	v_mfma_f32_16x16x32_bf16 v[68:71], v[190:193], v[182:185], v[68:71]
	v_mfma_f32_16x16x32_bf16 v[64:67], v[198:201], v[182:185], v[64:67]
	v_mfma_f32_16x16x32_bf16 v[108:111], v[194:197], v[162:165], v[108:111]
	v_mfma_f32_16x16x32_bf16 v[104:107], v[202:205], v[162:165], v[104:107]
	v_mfma_f32_16x16x32_bf16 v[92:95], v[194:197], v[170:173], v[92:95]
	v_mfma_f32_16x16x32_bf16 v[88:91], v[202:205], v[170:173], v[88:91]
	v_mfma_f32_16x16x32_bf16 v[76:79], v[194:197], v[178:181], v[76:79]
	v_mfma_f32_16x16x32_bf16 v[72:75], v[202:205], v[178:181], v[72:75]
	v_mfma_f32_16x16x32_bf16 v[68:71], v[194:197], v[186:189], v[68:71]
	v_mfma_f32_16x16x32_bf16 v[64:67], v[202:205], v[186:189], v[64:67]
	s_mov_b32 m0, s5
	v_lshl_add_u64 v[210:211], s[28:29], 0, v[130:131]
	s_barrier
	ds_read_b128 v[158:161], v140 offset:16384
	ds_read_b128 v[162:165], v140 offset:17408
	ds_read_b128 v[166:169], v140 offset:18432
	ds_read_b128 v[170:173], v140 offset:19456
	ds_read_b128 v[174:177], v140 offset:20480
	ds_read_b128 v[178:181], v140 offset:21504
	ds_read_b128 v[182:185], v140 offset:22528
	ds_read_b128 v[186:189], v140 offset:23552
	global_load_lds_dwordx4 v130, s[28:29]
	v_lshl_add_u64 v[212:213], s[28:29], 0, v[128:129]
	s_mov_b32 m0, s7
	s_nop 0
	global_load_lds_dwordx4 v128, s[28:29]
	s_barrier
	s_waitcnt lgkmcnt(0)
	s_waitcnt lgkmcnt(0)
	v_mfma_f32_16x16x32_bf16 v[60:63], v[142:145], v[158:161], v[60:63]
	v_mfma_f32_16x16x32_bf16 v[56:59], v[150:153], v[158:161], v[56:59]
	v_mfma_f32_16x16x32_bf16 v[52:55], v[142:145], v[166:169], v[52:55]
	v_mfma_f32_16x16x32_bf16 v[48:51], v[150:153], v[166:169], v[48:51]
	v_mfma_f32_16x16x32_bf16 v[36:39], v[142:145], v[174:177], v[36:39]
	v_mfma_f32_16x16x32_bf16 v[32:35], v[150:153], v[174:177], v[32:35]
	v_mfma_f32_16x16x32_bf16 v[20:23], v[142:145], v[182:185], v[20:23]
	v_mfma_f32_16x16x32_bf16 v[16:19], v[150:153], v[182:185], v[16:19]
	v_mfma_f32_16x16x32_bf16 v[60:63], v[146:149], v[162:165], v[60:63]
	v_mfma_f32_16x16x32_bf16 v[56:59], v[154:157], v[162:165], v[56:59]
	v_mfma_f32_16x16x32_bf16 v[52:55], v[146:149], v[170:173], v[52:55]
	v_mfma_f32_16x16x32_bf16 v[48:51], v[154:157], v[170:173], v[48:51]
	v_mfma_f32_16x16x32_bf16 v[36:39], v[146:149], v[178:181], v[36:39]
	v_mfma_f32_16x16x32_bf16 v[32:35], v[154:157], v[178:181], v[32:35]
	v_mfma_f32_16x16x32_bf16 v[20:23], v[146:149], v[186:189], v[20:23]
	v_mfma_f32_16x16x32_bf16 v[16:19], v[154:157], v[186:189], v[16:19]
	s_barrier
	s_add_u32 s22, s26, 0x80000
	s_addc_u32 s23, s27, 0
	s_add_i32 s47, s38, s4
	s_mov_b32 m0, s47
	s_nop 0
	global_load_lds_dwordx4 v130, s[22:23]
	s_add_i32 m0, s47, 0x2000
	s_nop 0
	global_load_lds_dwordx4 v128, s[22:23]
	s_waitcnt vmcnt(6)
	s_barrier
	v_mfma_f32_16x16x32_bf16 v[44:47], v[190:193], v[158:161], v[44:47]
	v_mfma_f32_16x16x32_bf16 v[40:43], v[198:201], v[158:161], v[40:43]
	v_mfma_f32_16x16x32_bf16 v[28:31], v[190:193], v[166:169], v[28:31]
	v_mfma_f32_16x16x32_bf16 v[24:27], v[198:201], v[166:169], v[24:27]
	v_mfma_f32_16x16x32_bf16 v[12:15], v[190:193], v[174:177], v[12:15]
	v_mfma_f32_16x16x32_bf16 v[8:11], v[198:201], v[174:177], v[8:11]
	v_mfma_f32_16x16x32_bf16 v[4:7], v[190:193], v[182:185], v[4:7]
	v_mfma_f32_16x16x32_bf16 v[0:3], v[198:201], v[182:185], v[0:3]
	v_mfma_f32_16x16x32_bf16 v[44:47], v[194:197], v[162:165], v[44:47]
	v_mfma_f32_16x16x32_bf16 v[40:43], v[202:205], v[162:165], v[40:43]
	v_mfma_f32_16x16x32_bf16 v[28:31], v[194:197], v[170:173], v[28:31]
	v_mfma_f32_16x16x32_bf16 v[24:27], v[202:205], v[170:173], v[24:27]
	v_mfma_f32_16x16x32_bf16 v[12:15], v[194:197], v[178:181], v[12:15]
	v_mfma_f32_16x16x32_bf16 v[8:11], v[202:205], v[178:181], v[8:11]
	v_mfma_f32_16x16x32_bf16 v[4:7], v[194:197], v[186:189], v[4:7]
	v_mfma_f32_16x16x32_bf16 v[0:3], v[202:205], v[186:189], v[0:3]
	s_add_i32 s47, 0, 0x18000
	v_add_u32_e32 v154, s47, v137
	s_barrier
	ds_read_b128 v[142:145], v154
	ds_read_b128 v[146:149], v154 offset:1024
	ds_read_b128 v[150:153], v154 offset:2048
	ds_read_b128 v[154:157], v154 offset:3072
	s_add_u32 s22, s28, 0x80000
	s_addc_u32 s23, s29, 0
	s_mov_b32 m0, s9
	ds_read_b128 v[158:161], v140 offset:32768
	ds_read_b128 v[162:165], v140 offset:33792
	ds_read_b128 v[166:169], v140 offset:34816
	ds_read_b128 v[170:173], v140 offset:35840
	ds_read_b128 v[174:177], v140 offset:36864
	ds_read_b128 v[178:181], v140 offset:37888
	ds_read_b128 v[182:185], v140 offset:38912
	ds_read_b128 v[186:189], v140 offset:39936
	global_load_lds_dwordx4 v130, s[22:23]
	s_mov_b32 m0, s30
	s_nop 0
	global_load_lds_dwordx4 v128, s[22:23]
	s_waitcnt lgkmcnt(8)
	s_barrier
	s_waitcnt lgkmcnt(0)
	s_waitcnt lgkmcnt(0)
	v_mfma_f32_16x16x32_bf16 v[124:127], v[142:145], v[158:161], v[124:127]
	v_mfma_f32_16x16x32_bf16 v[120:123], v[150:153], v[158:161], v[120:123]
	v_mfma_f32_16x16x32_bf16 v[116:119], v[142:145], v[166:169], v[116:119]
	v_mfma_f32_16x16x32_bf16 v[112:115], v[150:153], v[166:169], v[112:115]
	v_mfma_f32_16x16x32_bf16 v[100:103], v[142:145], v[174:177], v[100:103]
	v_mfma_f32_16x16x32_bf16 v[96:99], v[150:153], v[174:177], v[96:99]
	v_mfma_f32_16x16x32_bf16 v[84:87], v[142:145], v[182:185], v[84:87]
	v_mfma_f32_16x16x32_bf16 v[80:83], v[150:153], v[182:185], v[80:83]
	v_mfma_f32_16x16x32_bf16 v[124:127], v[146:149], v[162:165], v[124:127]
	v_mfma_f32_16x16x32_bf16 v[120:123], v[154:157], v[162:165], v[120:123]
	v_mfma_f32_16x16x32_bf16 v[116:119], v[146:149], v[170:173], v[116:119]
	v_mfma_f32_16x16x32_bf16 v[112:115], v[154:157], v[170:173], v[112:115]
	v_mfma_f32_16x16x32_bf16 v[100:103], v[146:149], v[178:181], v[100:103]
	v_mfma_f32_16x16x32_bf16 v[96:99], v[154:157], v[178:181], v[96:99]
	v_mfma_f32_16x16x32_bf16 v[84:87], v[146:149], v[186:189], v[84:87]
	v_mfma_f32_16x16x32_bf16 v[80:83], v[154:157], v[186:189], v[80:83]
	s_barrier
	s_add_i32 s28, 0, 0x1c000
	s_add_i32 s22, s47, s4
	v_add_u32_e32 v202, s28, v137
	s_add_u32 s98, s26, s10
	s_addc_u32 s99, s27, s11
	s_mov_b32 m0, s22
	ds_read_b128 v[190:193], v202
	ds_read_b128 v[194:197], v202 offset:1024
	ds_read_b128 v[198:201], v202 offset:2048
	ds_read_b128 v[202:205], v202 offset:3072
	global_load_lds_dwordx4 v130, s[98:99]
	s_add_i32 m0, s22, 0x2000
	s_nop 0
	global_load_lds_dwordx4 v128, s[98:99]
	s_barrier
	s_waitcnt lgkmcnt(0)
	s_waitcnt lgkmcnt(0)
	v_mfma_f32_16x16x32_bf16 v[108:111], v[190:193], v[158:161], v[108:111]
	v_mfma_f32_16x16x32_bf16 v[104:107], v[198:201], v[158:161], v[104:107]
	v_mfma_f32_16x16x32_bf16 v[92:95], v[190:193], v[166:169], v[92:95]
	v_mfma_f32_16x16x32_bf16 v[88:91], v[198:201], v[166:169], v[88:91]
	v_mfma_f32_16x16x32_bf16 v[76:79], v[190:193], v[174:177], v[76:79]
	v_mfma_f32_16x16x32_bf16 v[72:75], v[198:201], v[174:177], v[72:75]
	v_mfma_f32_16x16x32_bf16 v[68:71], v[190:193], v[182:185], v[68:71]
	v_mfma_f32_16x16x32_bf16 v[64:67], v[198:201], v[182:185], v[64:67]
	v_mfma_f32_16x16x32_bf16 v[108:111], v[194:197], v[162:165], v[108:111]
	v_mfma_f32_16x16x32_bf16 v[104:107], v[202:205], v[162:165], v[104:107]
	v_mfma_f32_16x16x32_bf16 v[92:95], v[194:197], v[170:173], v[92:95]
	v_mfma_f32_16x16x32_bf16 v[88:91], v[202:205], v[170:173], v[88:91]
	v_mfma_f32_16x16x32_bf16 v[76:79], v[194:197], v[178:181], v[76:79]
	v_mfma_f32_16x16x32_bf16 v[72:75], v[202:205], v[178:181], v[72:75]
	v_mfma_f32_16x16x32_bf16 v[68:71], v[194:197], v[186:189], v[68:71]
	v_mfma_f32_16x16x32_bf16 v[64:67], v[202:205], v[186:189], v[64:67]
	s_mov_b32 m0, s35
	v_lshl_add_u64 v[206:207], v[210:211], 0, s[10:11]
	s_barrier
	ds_read_b128 v[158:161], v140 offset:49152
	ds_read_b128 v[162:165], v140 offset:50176
	ds_read_b128 v[166:169], v140 offset:51200
	ds_read_b128 v[170:173], v140 offset:52224
	ds_read_b128 v[174:177], v140 offset:53248
	ds_read_b128 v[178:181], v140 offset:54272
	ds_read_b128 v[182:185], v140 offset:55296
	ds_read_b128 v[186:189], v140 offset:56320
	global_load_lds_dwordx4 v[206:207], off
	v_lshl_add_u64 v[206:207], v[212:213], 0, s[10:11]
	s_mov_b32 m0, s36
	s_nop 0
	global_load_lds_dwordx4 v[206:207], off
	s_barrier
	s_waitcnt lgkmcnt(0)
	s_waitcnt lgkmcnt(0)
	v_mfma_f32_16x16x32_bf16 v[60:63], v[142:145], v[158:161], v[60:63]
	v_mfma_f32_16x16x32_bf16 v[56:59], v[150:153], v[158:161], v[56:59]
	v_mfma_f32_16x16x32_bf16 v[52:55], v[142:145], v[166:169], v[52:55]
	v_mfma_f32_16x16x32_bf16 v[48:51], v[150:153], v[166:169], v[48:51]
	v_mfma_f32_16x16x32_bf16 v[36:39], v[142:145], v[174:177], v[36:39]
	v_mfma_f32_16x16x32_bf16 v[32:35], v[150:153], v[174:177], v[32:35]
	v_mfma_f32_16x16x32_bf16 v[20:23], v[142:145], v[182:185], v[20:23]
	v_mfma_f32_16x16x32_bf16 v[16:19], v[150:153], v[182:185], v[16:19]
	v_mfma_f32_16x16x32_bf16 v[60:63], v[146:149], v[162:165], v[60:63]
	v_mfma_f32_16x16x32_bf16 v[56:59], v[154:157], v[162:165], v[56:59]
	v_mfma_f32_16x16x32_bf16 v[52:55], v[146:149], v[170:173], v[52:55]
	v_mfma_f32_16x16x32_bf16 v[48:51], v[154:157], v[170:173], v[48:51]
	v_mfma_f32_16x16x32_bf16 v[36:39], v[146:149], v[178:181], v[36:39]
	v_mfma_f32_16x16x32_bf16 v[32:35], v[154:157], v[178:181], v[32:35]
	v_mfma_f32_16x16x32_bf16 v[20:23], v[146:149], v[186:189], v[20:23]
	v_mfma_f32_16x16x32_bf16 v[16:19], v[154:157], v[186:189], v[16:19]
	s_barrier
	s_add_u32 s22, s26, 0x80080
	s_addc_u32 s23, s27, 0
	s_add_i32 s26, s28, s4
	s_mov_b32 m0, s26
	s_nop 0
	global_load_lds_dwordx4 v130, s[22:23]
	s_add_i32 m0, s26, 0x2000
	s_nop 0
	global_load_lds_dwordx4 v128, s[22:23]
	s_waitcnt vmcnt(6)
	s_barrier
	v_mfma_f32_16x16x32_bf16 v[44:47], v[190:193], v[158:161], v[44:47]
	v_mfma_f32_16x16x32_bf16 v[40:43], v[198:201], v[158:161], v[40:43]
	v_mfma_f32_16x16x32_bf16 v[28:31], v[190:193], v[166:169], v[28:31]
	v_mfma_f32_16x16x32_bf16 v[24:27], v[198:201], v[166:169], v[24:27]
	v_mfma_f32_16x16x32_bf16 v[12:15], v[190:193], v[174:177], v[12:15]
	v_mfma_f32_16x16x32_bf16 v[8:11], v[198:201], v[174:177], v[8:11]
	v_mfma_f32_16x16x32_bf16 v[4:7], v[190:193], v[182:185], v[4:7]
	v_mfma_f32_16x16x32_bf16 v[0:3], v[198:201], v[182:185], v[0:3]
	v_mfma_f32_16x16x32_bf16 v[44:47], v[194:197], v[162:165], v[44:47]
	v_mfma_f32_16x16x32_bf16 v[40:43], v[202:205], v[162:165], v[40:43]
	v_mfma_f32_16x16x32_bf16 v[28:31], v[194:197], v[170:173], v[28:31]
	v_mfma_f32_16x16x32_bf16 v[24:27], v[202:205], v[170:173], v[24:27]
	v_mfma_f32_16x16x32_bf16 v[12:15], v[194:197], v[178:181], v[12:15]
	v_mfma_f32_16x16x32_bf16 v[8:11], v[202:205], v[178:181], v[8:11]
	v_mfma_f32_16x16x32_bf16 v[4:7], v[194:197], v[186:189], v[4:7]
	v_mfma_f32_16x16x32_bf16 v[0:3], v[202:205], v[186:189], v[0:3]
	s_add_i32 s46, s46, 2
	s_add_u32 s42, s42, 0x100
	s_addc_u32 s43, s43, 0
	s_cmp_gt_u32 s46, 5
	s_mov_b64 s[22:23], s[24:25]
	s_barrier
	s_cbranch_scc0 .LBB0_1865
	s_ashr_i32 s13, s34, 1
	s_and_b32 s13, s13, 0xfffffe00
	s_lshl_b32 s8, s8, 8
	s_add_i32 s8, s8, s13
	v_add_u32_e32 v144, s8, v136
	v_lshl_or_b32 v142, s6, 8, v138
	v_ashrrev_i32_e32 v145, 31, v144
	v_ashrrev_i32_e32 v143, 31, v142
	v_lshlrev_b64 v[146:147], 13, v[144:145]
	v_lshl_add_u64 v[146:147], s[66:67], 0, v[146:147]
	v_lshlrev_b64 v[142:143], 2, v[142:143]
	v_lshl_add_u64 v[146:147], v[146:147], 0, v[142:143]
	global_store_dwordx4 v[146:147], v[124:127], off
	global_store_dwordx4 v[146:147], v[120:123], off offset:64
	global_store_dwordx4 v[146:147], v[108:111], off offset:512
	global_store_dwordx4 v[146:147], v[104:107], off offset:576
	s_mov_b32 s6, 0x100000
	s_mov_b64 s[22:23], 0x100000
	v_or_b32_e32 v104, 16, v144
	v_ashrrev_i32_e32 v105, 31, v104
	v_lshlrev_b64 v[104:105], 13, v[104:105]
	v_lshl_add_u64 v[104:105], s[66:67], 0, v[104:105]
	v_lshl_add_u64 v[104:105], v[104:105], 0, v[142:143]
	global_store_dwordx4 v[104:105], v[116:119], off
	global_store_dwordx4 v[104:105], v[112:115], off offset:64
	global_store_dwordx4 v[104:105], v[92:95], off offset:512
	global_store_dwordx4 v[104:105], v[88:91], off offset:576
	s_mov_b32 s34, s39
	s_mov_b32 s8, s14
	v_or_b32_e32 v88, 32, v144
	v_ashrrev_i32_e32 v89, 31, v88
	v_lshlrev_b64 v[88:89], 13, v[88:89]
	v_lshl_add_u64 v[88:89], s[66:67], 0, v[88:89]
	v_lshl_add_u64 v[88:89], v[88:89], 0, v[142:143]
	global_store_dwordx4 v[88:89], v[100:103], off
	global_store_dwordx4 v[88:89], v[96:99], off offset:64
	global_store_dwordx4 v[88:89], v[76:79], off offset:512
	global_store_dwordx4 v[88:89], v[72:75], off offset:576
	s_mov_b64 s[24:25], s[20:21]
	s_nop 0
	v_or_b32_e32 v72, 48, v144
	v_ashrrev_i32_e32 v73, 31, v72
	v_lshlrev_b64 v[72:73], 13, v[72:73]
	v_lshl_add_u64 v[72:73], s[66:67], 0, v[72:73]
	v_lshl_add_u64 v[72:73], v[72:73], 0, v[142:143]
	global_store_dwordx4 v[72:73], v[84:87], off
	global_store_dwordx4 v[72:73], v[80:83], off offset:64
	global_store_dwordx4 v[72:73], v[68:71], off offset:512
	global_store_dwordx4 v[72:73], v[64:67], off offset:576
	s_nop 1
	v_add_co_u32_e32 v66, vcc, s6, v146
	s_mov_b32 s6, 0x120000
	s_nop 0
	v_addc_co_u32_e32 v67, vcc, 0, v147, vcc
	v_lshl_add_u64 v[64:65], v[146:147], 0, s[22:23]
	global_store_dwordx4 v[66:67], v[60:63], off
	global_store_dwordx4 v[64:65], v[56:59], off offset:64
	global_store_dwordx4 v[64:65], v[44:47], off offset:512
	global_store_dwordx4 v[64:65], v[40:43], off offset:576
	s_mov_b64 s[22:23], 0x120000
	s_nop 0
	v_add_co_u32_e32 v42, vcc, s6, v146
	s_mov_b32 s6, 0x140000
	s_nop 0
	v_addc_co_u32_e32 v43, vcc, 0, v147, vcc
	v_lshl_add_u64 v[40:41], v[146:147], 0, s[22:23]
	global_store_dwordx4 v[42:43], v[52:55], off
	global_store_dwordx4 v[40:41], v[48:51], off offset:64
	global_store_dwordx4 v[40:41], v[28:31], off offset:512
	global_store_dwordx4 v[40:41], v[24:27], off offset:576
	s_mov_b64 s[22:23], 0x140000
	s_nop 0
	v_add_co_u32_e32 v26, vcc, s6, v146
	v_lshl_add_u64 v[24:25], v[146:147], 0, s[22:23]
	s_nop 0
	v_addc_co_u32_e32 v27, vcc, 0, v147, vcc
	global_store_dwordx4 v[26:27], v[36:39], off
	global_store_dwordx4 v[24:25], v[32:35], off offset:64
	global_store_dwordx4 v[24:25], v[12:15], off offset:512
	global_store_dwordx4 v[24:25], v[8:11], off offset:576
	s_mov_b64 s[22:23], 0x160000
	s_mov_b32 s6, s12
	v_add_co_u32_e32 v10, vcc, 0x160000, v146
	v_lshl_add_u64 v[8:9], v[146:147], 0, s[22:23]
	s_nop 0
	v_addc_co_u32_e32 v11, vcc, 0, v147, vcc
	s_and_b64 vcc, exec, s[16:17]
	s_mov_b64 s[22:23], s[18:19]
	global_store_dwordx4 v[10:11], v[20:23], off
	global_store_dwordx4 v[8:9], v[16:19], off offset:64
	global_store_dwordx4 v[8:9], v[4:7], off offset:512
	global_store_dwordx4 v[8:9], v[0:3], off offset:576
	s_cbranch_vccz .LBB0_1862
	s_waitcnt vmcnt(0)
	s_cmpk_gt_u32 s1, 0xff
	s_cbranch_scc1 .LBB0_1869
	s_barrier

.LBB0_2005:
	ds_read_b128 v[148:151], v144
	ds_read_b128 v[152:155], v144 offset:1024
	ds_read_b128 v[156:159], v144 offset:2048
	ds_read_b128 v[160:163], v144 offset:3072
	s_add_i32 m0, s5, 0xc000
	ds_read_b128 v[164:167], v145
	ds_read_b128 v[168:171], v145 offset:1024
	ds_read_b128 v[172:175], v145 offset:2048
	ds_read_b128 v[176:179], v145 offset:3072
	ds_read_b128 v[180:183], v145 offset:4096
	ds_read_b128 v[184:187], v145 offset:5120
	ds_read_b128 v[188:191], v145 offset:6144
	ds_read_b128 v[192:195], v145 offset:7168
	global_load_lds_dwordx4 v134, s[22:23]
	s_add_i32 m0, s5, 0xe000
	s_nop 0
	global_load_lds_dwordx4 v136, s[22:23]
	s_waitcnt lgkmcnt(8)
	s_barrier
	s_waitcnt lgkmcnt(0)
	s_waitcnt lgkmcnt(0)
	v_mfma_f32_16x16x32_bf16 v[124:127], v[148:151], v[164:167], v[124:127]
	s_add_u32 s24, s22, 0x100
	s_addc_u32 s25, s23, 0
	s_cmp_eq_u32 s61, 28
	s_cselect_b32 s29, s15, s25
	s_cselect_b32 s28, s43, s24
	s_cselect_b32 s27, s13, s60
	s_cselect_b32 s26, s46, s47
	v_mfma_f32_16x16x32_bf16 v[120:123], v[156:159], v[164:167], v[120:123]
	v_mfma_f32_16x16x32_bf16 v[108:111], v[148:151], v[172:175], v[108:111]
	v_mfma_f32_16x16x32_bf16 v[104:107], v[156:159], v[172:175], v[104:107]
	v_mfma_f32_16x16x32_bf16 v[92:95], v[148:151], v[180:183], v[92:95]
	v_mfma_f32_16x16x32_bf16 v[88:91], v[156:159], v[180:183], v[88:91]
	v_mfma_f32_16x16x32_bf16 v[76:79], v[148:151], v[188:191], v[76:79]
	v_mfma_f32_16x16x32_bf16 v[72:75], v[156:159], v[188:191], v[72:75]
	v_mfma_f32_16x16x32_bf16 v[124:127], v[152:155], v[168:171], v[124:127]
	v_mfma_f32_16x16x32_bf16 v[120:123], v[160:163], v[168:171], v[120:123]
	v_mfma_f32_16x16x32_bf16 v[108:111], v[152:155], v[176:179], v[108:111]
	v_mfma_f32_16x16x32_bf16 v[104:107], v[160:163], v[176:179], v[104:107]
	v_mfma_f32_16x16x32_bf16 v[92:95], v[152:155], v[184:187], v[92:95]
	v_mfma_f32_16x16x32_bf16 v[88:91], v[160:163], v[184:187], v[88:91]
	v_mfma_f32_16x16x32_bf16 v[76:79], v[152:155], v[192:195], v[76:79]
	v_mfma_f32_16x16x32_bf16 v[72:75], v[160:163], v[192:195], v[72:75]
	s_barrier
	s_add_i32 s22, s40, s2
	s_mov_b32 m0, s22
	ds_read_b128 v[196:199], v146
	ds_read_b128 v[200:203], v146 offset:1024
	ds_read_b128 v[204:207], v146 offset:2048
	ds_read_b128 v[208:211], v146 offset:3072
	global_load_lds_dwordx4 v130, s[26:27]
	s_add_i32 m0, s22, 0x2000
	s_nop 0
	global_load_lds_dwordx4 v128, s[26:27]
	s_barrier
	s_waitcnt lgkmcnt(0)
	s_waitcnt lgkmcnt(0)
	v_mfma_f32_16x16x32_bf16 v[116:119], v[196:199], v[164:167], v[116:119]
	v_mfma_f32_16x16x32_bf16 v[112:115], v[204:207], v[164:167], v[112:115]
	v_mfma_f32_16x16x32_bf16 v[100:103], v[196:199], v[172:175], v[100:103]
	v_mfma_f32_16x16x32_bf16 v[96:99], v[204:207], v[172:175], v[96:99]
	v_mfma_f32_16x16x32_bf16 v[84:87], v[196:199], v[180:183], v[84:87]
	v_mfma_f32_16x16x32_bf16 v[80:83], v[204:207], v[180:183], v[80:83]
	v_mfma_f32_16x16x32_bf16 v[68:71], v[196:199], v[188:191], v[68:71]
	v_mfma_f32_16x16x32_bf16 v[64:67], v[204:207], v[188:191], v[64:67]
	v_mfma_f32_16x16x32_bf16 v[116:119], v[200:203], v[168:171], v[116:119]
	v_mfma_f32_16x16x32_bf16 v[112:115], v[208:211], v[168:171], v[112:115]
	v_mfma_f32_16x16x32_bf16 v[100:103], v[200:203], v[176:179], v[100:103]
	v_mfma_f32_16x16x32_bf16 v[96:99], v[208:211], v[176:179], v[96:99]
	v_mfma_f32_16x16x32_bf16 v[84:87], v[200:203], v[184:187], v[84:87]
	v_mfma_f32_16x16x32_bf16 v[80:83], v[208:211], v[184:187], v[80:83]
	v_mfma_f32_16x16x32_bf16 v[68:71], v[200:203], v[192:195], v[68:71]
	v_mfma_f32_16x16x32_bf16 v[64:67], v[208:211], v[192:195], v[64:67]
	s_mov_b32 m0, s5
	v_lshl_add_u64 v[216:217], s[28:29], 0, v[130:131]
	s_barrier
	ds_read_b128 v[164:167], v145 offset:16384
	ds_read_b128 v[168:171], v145 offset:17408
	ds_read_b128 v[172:175], v145 offset:18432
	ds_read_b128 v[176:179], v145 offset:19456
	ds_read_b128 v[180:183], v145 offset:20480
	ds_read_b128 v[184:187], v145 offset:21504
	ds_read_b128 v[188:191], v145 offset:22528
	ds_read_b128 v[192:195], v145 offset:23552
	global_load_lds_dwordx4 v130, s[28:29]
	v_lshl_add_u64 v[218:219], s[28:29], 0, v[128:129]
	s_mov_b32 m0, s30
	s_nop 0
	global_load_lds_dwordx4 v128, s[28:29]
	s_barrier
	s_waitcnt lgkmcnt(0)
	s_waitcnt lgkmcnt(0)
	v_mfma_f32_16x16x32_bf16 v[60:63], v[148:151], v[164:167], v[60:63]
	v_mfma_f32_16x16x32_bf16 v[56:59], v[156:159], v[164:167], v[56:59]
	v_mfma_f32_16x16x32_bf16 v[44:47], v[148:151], v[172:175], v[44:47]
	v_mfma_f32_16x16x32_bf16 v[40:43], v[156:159], v[172:175], v[40:43]
	v_mfma_f32_16x16x32_bf16 v[28:31], v[148:151], v[180:183], v[28:31]
	v_mfma_f32_16x16x32_bf16 v[24:27], v[156:159], v[180:183], v[24:27]
	v_mfma_f32_16x16x32_bf16 v[12:15], v[148:151], v[188:191], v[12:15]
	v_mfma_f32_16x16x32_bf16 v[8:11], v[156:159], v[188:191], v[8:11]
	v_mfma_f32_16x16x32_bf16 v[60:63], v[152:155], v[168:171], v[60:63]
	v_mfma_f32_16x16x32_bf16 v[56:59], v[160:163], v[168:171], v[56:59]
	v_mfma_f32_16x16x32_bf16 v[44:47], v[152:155], v[176:179], v[44:47]
	v_mfma_f32_16x16x32_bf16 v[40:43], v[160:163], v[176:179], v[40:43]
	v_mfma_f32_16x16x32_bf16 v[28:31], v[152:155], v[184:187], v[28:31]
	v_mfma_f32_16x16x32_bf16 v[24:27], v[160:163], v[184:187], v[24:27]
	v_mfma_f32_16x16x32_bf16 v[12:15], v[152:155], v[192:195], v[12:15]
	v_mfma_f32_16x16x32_bf16 v[8:11], v[160:163], v[192:195], v[8:11]
	s_barrier
	s_add_u32 s22, s26, 0x80000
	s_addc_u32 s23, s27, 0
	s_add_i32 s62, s41, s2
	s_mov_b32 m0, s62
	s_nop 0
	global_load_lds_dwordx4 v130, s[22:23]
	s_add_i32 m0, s62, 0x2000
	s_nop 0
	global_load_lds_dwordx4 v128, s[22:23]
	s_waitcnt vmcnt(6)
	s_barrier
	v_mfma_f32_16x16x32_bf16 v[52:55], v[196:199], v[164:167], v[52:55]
	v_mfma_f32_16x16x32_bf16 v[48:51], v[204:207], v[164:167], v[48:51]
	v_mfma_f32_16x16x32_bf16 v[36:39], v[196:199], v[172:175], v[36:39]
	v_mfma_f32_16x16x32_bf16 v[32:35], v[204:207], v[172:175], v[32:35]
	v_mfma_f32_16x16x32_bf16 v[20:23], v[196:199], v[180:183], v[20:23]
	v_mfma_f32_16x16x32_bf16 v[16:19], v[204:207], v[180:183], v[16:19]
	v_mfma_f32_16x16x32_bf16 v[4:7], v[196:199], v[188:191], v[4:7]
	v_mfma_f32_16x16x32_bf16 v[0:3], v[204:207], v[188:191], v[0:3]
	v_mfma_f32_16x16x32_bf16 v[52:55], v[200:203], v[168:171], v[52:55]
	v_mfma_f32_16x16x32_bf16 v[48:51], v[208:211], v[168:171], v[48:51]
	v_mfma_f32_16x16x32_bf16 v[36:39], v[200:203], v[176:179], v[36:39]
	v_mfma_f32_16x16x32_bf16 v[32:35], v[208:211], v[176:179], v[32:35]
	v_mfma_f32_16x16x32_bf16 v[20:23], v[200:203], v[184:187], v[20:23]
	v_mfma_f32_16x16x32_bf16 v[16:19], v[208:211], v[184:187], v[16:19]
	v_mfma_f32_16x16x32_bf16 v[4:7], v[200:203], v[192:195], v[4:7]
	v_mfma_f32_16x16x32_bf16 v[0:3], v[208:211], v[192:195], v[0:3]
	s_add_i32 s62, 0, 0x18000
	v_add_u32_e32 v147, s62, v143
	s_barrier
	ds_read_b128 v[148:151], v147
	ds_read_b128 v[152:155], v147 offset:1024
	ds_read_b128 v[156:159], v147 offset:2048
	ds_read_b128 v[160:163], v147 offset:3072
	s_add_u32 s22, s28, 0x80000
	s_addc_u32 s23, s29, 0
	s_mov_b32 m0, s31
	ds_read_b128 v[164:167], v145 offset:32768
	ds_read_b128 v[168:171], v145 offset:33792
	ds_read_b128 v[172:175], v145 offset:34816
	ds_read_b128 v[176:179], v145 offset:35840
	ds_read_b128 v[180:183], v145 offset:36864
	ds_read_b128 v[184:187], v145 offset:37888
	ds_read_b128 v[188:191], v145 offset:38912
	ds_read_b128 v[192:195], v145 offset:39936
	global_load_lds_dwordx4 v130, s[22:23]
	s_mov_b32 m0, s34
	s_nop 0
	global_load_lds_dwordx4 v128, s[22:23]
	s_waitcnt lgkmcnt(8)
	s_barrier
	s_waitcnt lgkmcnt(0)
	s_waitcnt lgkmcnt(0)
	v_mfma_f32_16x16x32_bf16 v[124:127], v[148:151], v[164:167], v[124:127]
	v_mfma_f32_16x16x32_bf16 v[120:123], v[156:159], v[164:167], v[120:123]
	v_mfma_f32_16x16x32_bf16 v[108:111], v[148:151], v[172:175], v[108:111]
	v_mfma_f32_16x16x32_bf16 v[104:107], v[156:159], v[172:175], v[104:107]
	v_mfma_f32_16x16x32_bf16 v[92:95], v[148:151], v[180:183], v[92:95]
	v_mfma_f32_16x16x32_bf16 v[88:91], v[156:159], v[180:183], v[88:91]
	v_mfma_f32_16x16x32_bf16 v[76:79], v[148:151], v[188:191], v[76:79]
	v_mfma_f32_16x16x32_bf16 v[72:75], v[156:159], v[188:191], v[72:75]
	v_mfma_f32_16x16x32_bf16 v[124:127], v[152:155], v[168:171], v[124:127]
	v_mfma_f32_16x16x32_bf16 v[120:123], v[160:163], v[168:171], v[120:123]
	v_mfma_f32_16x16x32_bf16 v[108:111], v[152:155], v[176:179], v[108:111]
	v_mfma_f32_16x16x32_bf16 v[104:107], v[160:163], v[176:179], v[104:107]
	v_mfma_f32_16x16x32_bf16 v[92:95], v[152:155], v[184:187], v[92:95]
	v_mfma_f32_16x16x32_bf16 v[88:91], v[160:163], v[184:187], v[88:91]
	v_mfma_f32_16x16x32_bf16 v[76:79], v[152:155], v[192:195], v[76:79]
	v_mfma_f32_16x16x32_bf16 v[72:75], v[160:163], v[192:195], v[72:75]
	s_barrier
	s_add_i32 s28, 0, 0x1c000
	s_add_i32 s22, s62, s2
	v_add_u32_e32 v147, s28, v143
	s_add_u32 s98, s26, s10
	s_addc_u32 s99, s27, s11
	s_mov_b32 m0, s22
	ds_read_b128 v[196:199], v147
	ds_read_b128 v[200:203], v147 offset:1024
	ds_read_b128 v[204:207], v147 offset:2048
	ds_read_b128 v[208:211], v147 offset:3072
	global_load_lds_dwordx4 v130, s[98:99]
	s_add_i32 m0, s22, 0x2000
	s_nop 0
	global_load_lds_dwordx4 v128, s[98:99]
	s_barrier
	s_waitcnt lgkmcnt(0)
	s_waitcnt lgkmcnt(0)
	v_mfma_f32_16x16x32_bf16 v[116:119], v[196:199], v[164:167], v[116:119]
	v_mfma_f32_16x16x32_bf16 v[112:115], v[204:207], v[164:167], v[112:115]
	v_mfma_f32_16x16x32_bf16 v[100:103], v[196:199], v[172:175], v[100:103]
	v_mfma_f32_16x16x32_bf16 v[96:99], v[204:207], v[172:175], v[96:99]
	v_mfma_f32_16x16x32_bf16 v[84:87], v[196:199], v[180:183], v[84:87]
	v_mfma_f32_16x16x32_bf16 v[80:83], v[204:207], v[180:183], v[80:83]
	v_mfma_f32_16x16x32_bf16 v[68:71], v[196:199], v[188:191], v[68:71]
	v_mfma_f32_16x16x32_bf16 v[64:67], v[204:207], v[188:191], v[64:67]
	v_mfma_f32_16x16x32_bf16 v[116:119], v[200:203], v[168:171], v[116:119]
	v_mfma_f32_16x16x32_bf16 v[112:115], v[208:211], v[168:171], v[112:115]
	v_mfma_f32_16x16x32_bf16 v[100:103], v[200:203], v[176:179], v[100:103]
	v_mfma_f32_16x16x32_bf16 v[96:99], v[208:211], v[176:179], v[96:99]
	v_mfma_f32_16x16x32_bf16 v[84:87], v[200:203], v[184:187], v[84:87]
	v_mfma_f32_16x16x32_bf16 v[80:83], v[208:211], v[184:187], v[80:83]
	v_mfma_f32_16x16x32_bf16 v[68:71], v[200:203], v[192:195], v[68:71]
	v_mfma_f32_16x16x32_bf16 v[64:67], v[208:211], v[192:195], v[64:67]
	s_mov_b32 m0, s36
	v_lshl_add_u64 v[212:213], v[216:217], 0, s[10:11]
	s_barrier
	ds_read_b128 v[164:167], v145 offset:49152
	ds_read_b128 v[168:171], v145 offset:50176
	ds_read_b128 v[172:175], v145 offset:51200
	ds_read_b128 v[176:179], v145 offset:52224
	ds_read_b128 v[180:183], v145 offset:53248
	ds_read_b128 v[184:187], v145 offset:54272
	ds_read_b128 v[188:191], v145 offset:55296
	ds_read_b128 v[192:195], v145 offset:56320
	global_load_lds_dwordx4 v[212:213], off
	v_lshl_add_u64 v[212:213], v[218:219], 0, s[10:11]
	s_mov_b32 m0, s37
	s_nop 0
	global_load_lds_dwordx4 v[212:213], off
	s_barrier
	s_waitcnt lgkmcnt(0)
	s_waitcnt lgkmcnt(0)
	v_mfma_f32_16x16x32_bf16 v[60:63], v[148:151], v[164:167], v[60:63]
	v_mfma_f32_16x16x32_bf16 v[56:59], v[156:159], v[164:167], v[56:59]
	v_mfma_f32_16x16x32_bf16 v[44:47], v[148:151], v[172:175], v[44:47]
	v_mfma_f32_16x16x32_bf16 v[40:43], v[156:159], v[172:175], v[40:43]
	v_mfma_f32_16x16x32_bf16 v[28:31], v[148:151], v[180:183], v[28:31]
	v_mfma_f32_16x16x32_bf16 v[24:27], v[156:159], v[180:183], v[24:27]
	v_mfma_f32_16x16x32_bf16 v[12:15], v[148:151], v[188:191], v[12:15]
	v_mfma_f32_16x16x32_bf16 v[8:11], v[156:159], v[188:191], v[8:11]
	v_mfma_f32_16x16x32_bf16 v[60:63], v[152:155], v[168:171], v[60:63]
	v_mfma_f32_16x16x32_bf16 v[56:59], v[160:163], v[168:171], v[56:59]
	v_mfma_f32_16x16x32_bf16 v[44:47], v[152:155], v[176:179], v[44:47]
	v_mfma_f32_16x16x32_bf16 v[40:43], v[160:163], v[176:179], v[40:43]
	v_mfma_f32_16x16x32_bf16 v[28:31], v[152:155], v[184:187], v[28:31]
	v_mfma_f32_16x16x32_bf16 v[24:27], v[160:163], v[184:187], v[24:27]
	v_mfma_f32_16x16x32_bf16 v[12:15], v[152:155], v[192:195], v[12:15]
	v_mfma_f32_16x16x32_bf16 v[8:11], v[160:163], v[192:195], v[8:11]
	s_barrier
	s_add_u32 s22, s26, 0x80080
	s_addc_u32 s23, s27, 0
	s_add_i32 s26, s28, s2
	s_mov_b32 m0, s26
	s_nop 0
	global_load_lds_dwordx4 v130, s[22:23]
	s_add_i32 m0, s26, 0x2000
	s_nop 0
	global_load_lds_dwordx4 v128, s[22:23]
	s_waitcnt vmcnt(6)
	s_barrier
	v_mfma_f32_16x16x32_bf16 v[52:55], v[196:199], v[164:167], v[52:55]
	v_mfma_f32_16x16x32_bf16 v[48:51], v[204:207], v[164:167], v[48:51]
	v_mfma_f32_16x16x32_bf16 v[36:39], v[196:199], v[172:175], v[36:39]
	v_mfma_f32_16x16x32_bf16 v[32:35], v[204:207], v[172:175], v[32:35]
	v_mfma_f32_16x16x32_bf16 v[20:23], v[196:199], v[180:183], v[20:23]
	v_mfma_f32_16x16x32_bf16 v[16:19], v[204:207], v[180:183], v[16:19]
	v_mfma_f32_16x16x32_bf16 v[4:7], v[196:199], v[188:191], v[4:7]
	v_mfma_f32_16x16x32_bf16 v[0:3], v[204:207], v[188:191], v[0:3]
	v_mfma_f32_16x16x32_bf16 v[52:55], v[200:203], v[168:171], v[52:55]
	v_mfma_f32_16x16x32_bf16 v[48:51], v[208:211], v[168:171], v[48:51]
	v_mfma_f32_16x16x32_bf16 v[36:39], v[200:203], v[176:179], v[36:39]
	v_mfma_f32_16x16x32_bf16 v[32:35], v[208:211], v[176:179], v[32:35]
	v_mfma_f32_16x16x32_bf16 v[20:23], v[200:203], v[184:187], v[20:23]
	v_mfma_f32_16x16x32_bf16 v[16:19], v[208:211], v[184:187], v[16:19]
	v_mfma_f32_16x16x32_bf16 v[4:7], v[200:203], v[192:195], v[4:7]
	v_mfma_f32_16x16x32_bf16 v[0:3], v[208:211], v[192:195], v[0:3]
	s_add_i32 s61, s61, 2
	s_add_u32 s47, s47, 0x100
	s_addc_u32 s60, s60, 0
	s_cmp_gt_u32 s61, 29
	s_mov_b64 s[22:23], s[24:25]
	s_barrier
	s_cbranch_scc0 .LBB0_2005
	v_mul_f32_e32 v150, 0xbfb8aa3b, v124
	v_mul_f32_e32 v151, 0xbfb8aa3b, v125
	v_exp_f32_e32 v150, v150
	v_exp_f32_e32 v151, v151
	s_lshl_b32 s13, s21, 7
	v_lshl_add_u32 v147, s20, 8, v142
	v_add_f32_e32 v150, 1.0, v150
	v_add_f32_e32 v151, 1.0, v151
	v_rcp_f32_e32 v150, v150
	v_rcp_f32_e32 v151, v151
	s_or_b32 s20, s13, s38
	s_ashr_i32 s21, s20, 31
	v_mad_i64_i32 v[148:149], s[22:23], v147, s42, v[132:133]
	v_pk_mul_f32 v[124:125], v[124:125], v[150:151]
	s_lshl_b64 s[20:21], s[20:21], 1
	v_pk_mul_f32 v[120:121], v[120:121], v[124:125]
	s_and_b64 vcc, exec, s[6:7]
	v_cvt_pk_bf16_f32 v120, v120, v121
	v_mul_f32_e32 v121, 0xbfb8aa3b, v126
	v_exp_f32_e32 v121, v121
	s_mov_b64 s[24:25], s[18:19]
	v_add_f32_e32 v121, 1.0, v121
	v_rcp_f32_e32 v124, v121
	v_mul_f32_e32 v121, 0xbfb8aa3b, v127
	v_exp_f32_e32 v121, v121
	s_nop 0
	v_add_f32_e32 v121, 1.0, v121
	v_rcp_f32_e32 v125, v121
	s_nop 0
	v_pk_mul_f32 v[124:125], v[126:127], v[124:125]
	s_nop 0
	v_pk_mul_f32 v[122:123], v[122:123], v[124:125]
	s_nop 0
	v_cvt_pk_bf16_f32 v121, v122, v123
	v_lshl_add_u64 v[122:123], v[148:149], 0, s[20:21]
	global_store_dwordx2 v[122:123], v[120:121], off
	v_mul_f32_e32 v120, 0xbfb8aa3b, v116
	v_mul_f32_e32 v121, 0xbfb8aa3b, v117
	v_exp_f32_e32 v120, v120
	v_exp_f32_e32 v121, v121
	v_add_f32_e32 v120, 1.0, v120
	v_add_f32_e32 v121, 1.0, v121
	v_rcp_f32_e32 v120, v120
	v_rcp_f32_e32 v121, v121
	s_nop 0
	v_pk_mul_f32 v[116:117], v[116:117], v[120:121]
	s_nop 0
	v_pk_mul_f32 v[112:113], v[112:113], v[116:117]
	s_nop 0
	v_cvt_pk_bf16_f32 v112, v112, v113
	v_mul_f32_e32 v113, 0xbfb8aa3b, v118
	v_exp_f32_e32 v113, v113
	s_nop 0
	v_add_f32_e32 v113, 1.0, v113
	v_rcp_f32_e32 v116, v113
	v_mul_f32_e32 v113, 0xbfb8aa3b, v119
	v_exp_f32_e32 v113, v113
	s_nop 0
	v_add_f32_e32 v113, 1.0, v113
	v_rcp_f32_e32 v117, v113
	s_nop 0
	v_pk_mul_f32 v[116:117], v[118:119], v[116:117]
	s_nop 0
	v_pk_mul_f32 v[114:115], v[114:115], v[116:117]
	s_nop 0
	v_cvt_pk_bf16_f32 v113, v114, v115
	v_mul_f32_e32 v114, 0xbfb8aa3b, v108
	v_mul_f32_e32 v115, 0xbfb8aa3b, v109
	v_exp_f32_e32 v114, v114
	v_exp_f32_e32 v115, v115
	global_store_dwordx2 v[122:123], v[112:113], off offset:128
	v_or_b32_e32 v112, 16, v147
	v_add_f32_e32 v114, 1.0, v114
	v_add_f32_e32 v115, 1.0, v115
	v_rcp_f32_e32 v114, v114
	v_rcp_f32_e32 v115, v115
	v_mad_i64_i32 v[112:113], s[22:23], v112, s42, v[132:133]
	v_pk_mul_f32 v[108:109], v[108:109], v[114:115]
	s_nop 0
	v_pk_mul_f32 v[104:105], v[104:105], v[108:109]
	s_nop 0
	v_cvt_pk_bf16_f32 v104, v104, v105
	v_mul_f32_e32 v105, 0xbfb8aa3b, v110
	v_exp_f32_e32 v105, v105
	s_nop 0
	v_add_f32_e32 v105, 1.0, v105
	v_rcp_f32_e32 v108, v105
	v_mul_f32_e32 v105, 0xbfb8aa3b, v111
	v_exp_f32_e32 v105, v105
	s_nop 0
	v_add_f32_e32 v105, 1.0, v105
	v_rcp_f32_e32 v109, v105
	s_nop 0
	v_pk_mul_f32 v[108:109], v[110:111], v[108:109]
	s_nop 0
	v_pk_mul_f32 v[106:107], v[106:107], v[108:109]
	s_nop 0
	v_cvt_pk_bf16_f32 v105, v106, v107
	v_lshl_add_u64 v[106:107], v[112:113], 0, s[20:21]
	global_store_dwordx2 v[106:107], v[104:105], off
	v_mul_f32_e32 v104, 0xbfb8aa3b, v100
	v_mul_f32_e32 v105, 0xbfb8aa3b, v101
	v_exp_f32_e32 v104, v104
	v_exp_f32_e32 v105, v105
	v_add_f32_e32 v104, 1.0, v104
	v_add_f32_e32 v105, 1.0, v105
	v_rcp_f32_e32 v104, v104
	v_rcp_f32_e32 v105, v105
	s_nop 0
	v_pk_mul_f32 v[100:101], v[100:101], v[104:105]
	s_nop 0
	v_pk_mul_f32 v[96:97], v[96:97], v[100:101]
	s_nop 0
	v_cvt_pk_bf16_f32 v96, v96, v97
	v_mul_f32_e32 v97, 0xbfb8aa3b, v102
	v_exp_f32_e32 v97, v97
	s_nop 0
	v_add_f32_e32 v97, 1.0, v97
	v_rcp_f32_e32 v100, v97
	v_mul_f32_e32 v97, 0xbfb8aa3b, v103
	v_exp_f32_e32 v97, v97
	s_nop 0
	v_add_f32_e32 v97, 1.0, v97
	v_rcp_f32_e32 v101, v97
	s_nop 0
	v_pk_mul_f32 v[100:101], v[102:103], v[100:101]
	s_nop 0
	v_pk_mul_f32 v[98:99], v[98:99], v[100:101]
	s_nop 0
	v_cvt_pk_bf16_f32 v97, v98, v99
	v_mul_f32_e32 v98, 0xbfb8aa3b, v92
	v_mul_f32_e32 v99, 0xbfb8aa3b, v93
	v_exp_f32_e32 v98, v98
	v_exp_f32_e32 v99, v99
	global_store_dwordx2 v[106:107], v[96:97], off offset:128
	v_or_b32_e32 v96, 32, v147
	v_add_f32_e32 v98, 1.0, v98
	v_add_f32_e32 v99, 1.0, v99
	v_rcp_f32_e32 v98, v98
	v_rcp_f32_e32 v99, v99
	v_mad_i64_i32 v[96:97], s[22:23], v96, s42, v[132:133]
	v_pk_mul_f32 v[92:93], v[92:93], v[98:99]
	s_nop 0
	v_pk_mul_f32 v[88:89], v[88:89], v[92:93]
	s_nop 0
	v_cvt_pk_bf16_f32 v88, v88, v89
	v_mul_f32_e32 v89, 0xbfb8aa3b, v94
	v_exp_f32_e32 v89, v89
	s_nop 0
	v_add_f32_e32 v89, 1.0, v89
	v_rcp_f32_e32 v92, v89
	v_mul_f32_e32 v89, 0xbfb8aa3b, v95
	v_exp_f32_e32 v89, v89
	s_nop 0
	v_add_f32_e32 v89, 1.0, v89
	v_rcp_f32_e32 v93, v89
	s_nop 0
	v_pk_mul_f32 v[92:93], v[94:95], v[92:93]
	s_nop 0
	v_pk_mul_f32 v[90:91], v[90:91], v[92:93]
	s_nop 0
	v_cvt_pk_bf16_f32 v89, v90, v91
	v_lshl_add_u64 v[90:91], v[96:97], 0, s[20:21]
	global_store_dwordx2 v[90:91], v[88:89], off
	v_mul_f32_e32 v88, 0xbfb8aa3b, v84
	v_mul_f32_e32 v89, 0xbfb8aa3b, v85
	v_exp_f32_e32 v88, v88
	v_exp_f32_e32 v89, v89
	v_add_f32_e32 v88, 1.0, v88
	v_add_f32_e32 v89, 1.0, v89
	v_rcp_f32_e32 v88, v88
	v_rcp_f32_e32 v89, v89
	s_nop 0
	v_pk_mul_f32 v[84:85], v[84:85], v[88:89]
	s_nop 0
	v_pk_mul_f32 v[80:81], v[80:81], v[84:85]
	s_nop 0
	v_cvt_pk_bf16_f32 v80, v80, v81
	v_mul_f32_e32 v81, 0xbfb8aa3b, v86
	v_exp_f32_e32 v81, v81
	s_nop 0
	v_add_f32_e32 v81, 1.0, v81
	v_rcp_f32_e32 v84, v81
	v_mul_f32_e32 v81, 0xbfb8aa3b, v87
	v_exp_f32_e32 v81, v81
	s_nop 0
	v_add_f32_e32 v81, 1.0, v81
	v_rcp_f32_e32 v85, v81
	s_nop 0
	v_pk_mul_f32 v[84:85], v[86:87], v[84:85]
	s_nop 0
	v_pk_mul_f32 v[82:83], v[82:83], v[84:85]
	s_nop 0
	v_cvt_pk_bf16_f32 v81, v82, v83
	v_mul_f32_e32 v82, 0xbfb8aa3b, v76
	v_mul_f32_e32 v83, 0xbfb8aa3b, v77
	v_exp_f32_e32 v82, v82
	v_exp_f32_e32 v83, v83
	global_store_dwordx2 v[90:91], v[80:81], off offset:128
	v_or_b32_e32 v80, 48, v147
	v_add_f32_e32 v82, 1.0, v82
	v_add_f32_e32 v83, 1.0, v83
	v_rcp_f32_e32 v82, v82
	v_rcp_f32_e32 v83, v83
	v_mad_i64_i32 v[80:81], s[22:23], v80, s42, v[132:133]
	v_pk_mul_f32 v[76:77], v[76:77], v[82:83]
	s_nop 0
	v_pk_mul_f32 v[72:73], v[72:73], v[76:77]
	s_nop 0
	v_cvt_pk_bf16_f32 v72, v72, v73
	v_mul_f32_e32 v73, 0xbfb8aa3b, v78
	v_exp_f32_e32 v73, v73
	s_nop 0
	v_add_f32_e32 v73, 1.0, v73
	v_rcp_f32_e32 v76, v73
	v_mul_f32_e32 v73, 0xbfb8aa3b, v79
	v_exp_f32_e32 v73, v73
	s_nop 0
	v_add_f32_e32 v73, 1.0, v73
	v_rcp_f32_e32 v77, v73
	s_nop 0
	v_pk_mul_f32 v[76:77], v[78:79], v[76:77]
	s_nop 0
	v_pk_mul_f32 v[74:75], v[74:75], v[76:77]
	s_nop 0
	v_cvt_pk_bf16_f32 v73, v74, v75
	v_lshl_add_u64 v[74:75], v[80:81], 0, s[20:21]
	global_store_dwordx2 v[74:75], v[72:73], off
	v_mul_f32_e32 v72, 0xbfb8aa3b, v68
	v_mul_f32_e32 v73, 0xbfb8aa3b, v69
	v_exp_f32_e32 v72, v72
	v_exp_f32_e32 v73, v73
	v_add_f32_e32 v72, 1.0, v72
	v_add_f32_e32 v73, 1.0, v73
	v_rcp_f32_e32 v72, v72
	v_rcp_f32_e32 v73, v73
	s_nop 0
	v_pk_mul_f32 v[68:69], v[68:69], v[72:73]
	s_nop 0
	v_pk_mul_f32 v[64:65], v[64:65], v[68:69]
	s_nop 0
	v_cvt_pk_bf16_f32 v64, v64, v65
	v_mul_f32_e32 v65, 0xbfb8aa3b, v70
	v_exp_f32_e32 v65, v65
	s_nop 0
	v_add_f32_e32 v65, 1.0, v65
	v_rcp_f32_e32 v68, v65
	v_mul_f32_e32 v65, 0xbfb8aa3b, v71
	v_exp_f32_e32 v65, v65
	s_nop 0
	v_add_f32_e32 v65, 1.0, v65
	v_rcp_f32_e32 v69, v65
	s_nop 0
	v_pk_mul_f32 v[68:69], v[70:71], v[68:69]
	s_nop 0
	v_pk_mul_f32 v[66:67], v[66:67], v[68:69]
	s_nop 0
	v_cvt_pk_bf16_f32 v65, v66, v67
	v_mul_f32_e32 v66, 0xbfb8aa3b, v60
	v_mul_f32_e32 v67, 0xbfb8aa3b, v61
	v_exp_f32_e32 v66, v66
	v_exp_f32_e32 v67, v67
	global_store_dwordx2 v[74:75], v[64:65], off offset:128
	v_add_u32_e32 v64, 0x80, v147
	v_add_f32_e32 v66, 1.0, v66
	v_add_f32_e32 v67, 1.0, v67
	v_rcp_f32_e32 v66, v66
	v_rcp_f32_e32 v67, v67
	v_mad_i64_i32 v[64:65], s[22:23], v64, s42, v[132:133]
	v_pk_mul_f32 v[60:61], v[60:61], v[66:67]
	s_nop 0
	v_pk_mul_f32 v[56:57], v[56:57], v[60:61]
	s_nop 0
	v_cvt_pk_bf16_f32 v56, v56, v57
	v_mul_f32_e32 v57, 0xbfb8aa3b, v62
	v_exp_f32_e32 v57, v57
	s_nop 0
	v_add_f32_e32 v57, 1.0, v57
	v_rcp_f32_e32 v60, v57
	v_mul_f32_e32 v57, 0xbfb8aa3b, v63
	v_exp_f32_e32 v57, v57
	s_nop 0
	v_add_f32_e32 v57, 1.0, v57
	v_rcp_f32_e32 v61, v57
	s_nop 0
	v_pk_mul_f32 v[60:61], v[62:63], v[60:61]
	s_nop 0
	v_pk_mul_f32 v[58:59], v[58:59], v[60:61]
	s_nop 0
	v_cvt_pk_bf16_f32 v57, v58, v59
	v_lshl_add_u64 v[58:59], v[64:65], 0, s[20:21]
	global_store_dwordx2 v[58:59], v[56:57], off
	v_mul_f32_e32 v56, 0xbfb8aa3b, v52
	v_mul_f32_e32 v57, 0xbfb8aa3b, v53
	v_exp_f32_e32 v56, v56
	v_exp_f32_e32 v57, v57
	v_add_f32_e32 v56, 1.0, v56
	v_add_f32_e32 v57, 1.0, v57
	v_rcp_f32_e32 v56, v56
	v_rcp_f32_e32 v57, v57
	s_nop 0
	v_pk_mul_f32 v[52:53], v[52:53], v[56:57]
	s_nop 0
	v_pk_mul_f32 v[48:49], v[48:49], v[52:53]
	s_nop 0
	v_cvt_pk_bf16_f32 v48, v48, v49
	v_mul_f32_e32 v49, 0xbfb8aa3b, v54
	v_exp_f32_e32 v49, v49
	s_nop 0
	v_add_f32_e32 v49, 1.0, v49
	v_rcp_f32_e32 v52, v49
	v_mul_f32_e32 v49, 0xbfb8aa3b, v55
	v_exp_f32_e32 v49, v49
	s_nop 0
	v_add_f32_e32 v49, 1.0, v49
	v_rcp_f32_e32 v53, v49
	s_nop 0
	v_pk_mul_f32 v[52:53], v[54:55], v[52:53]
	s_nop 0
	v_pk_mul_f32 v[50:51], v[50:51], v[52:53]
	s_nop 0
	v_cvt_pk_bf16_f32 v49, v50, v51
	v_mul_f32_e32 v50, 0xbfb8aa3b, v44
	v_mul_f32_e32 v51, 0xbfb8aa3b, v45
	v_exp_f32_e32 v50, v50
	v_exp_f32_e32 v51, v51
	global_store_dwordx2 v[58:59], v[48:49], off offset:128
	v_add_u32_e32 v48, 0x90, v147
	v_add_f32_e32 v50, 1.0, v50
	v_add_f32_e32 v51, 1.0, v51
	v_rcp_f32_e32 v50, v50
	v_rcp_f32_e32 v51, v51
	v_mad_i64_i32 v[48:49], s[22:23], v48, s42, v[132:133]
	v_pk_mul_f32 v[44:45], v[44:45], v[50:51]
	s_nop 0
	v_pk_mul_f32 v[40:41], v[40:41], v[44:45]
	s_nop 0
	v_cvt_pk_bf16_f32 v40, v40, v41
	v_mul_f32_e32 v41, 0xbfb8aa3b, v46
	v_exp_f32_e32 v41, v41
	s_nop 0
	v_add_f32_e32 v41, 1.0, v41
	v_rcp_f32_e32 v44, v41
	v_mul_f32_e32 v41, 0xbfb8aa3b, v47
	v_exp_f32_e32 v41, v41
	s_nop 0
	v_add_f32_e32 v41, 1.0, v41
	v_rcp_f32_e32 v45, v41
	s_nop 0
	v_pk_mul_f32 v[44:45], v[46:47], v[44:45]
	s_nop 0
	v_pk_mul_f32 v[42:43], v[42:43], v[44:45]
	s_nop 0
	v_cvt_pk_bf16_f32 v41, v42, v43
	v_lshl_add_u64 v[42:43], v[48:49], 0, s[20:21]
	global_store_dwordx2 v[42:43], v[40:41], off
	v_mul_f32_e32 v40, 0xbfb8aa3b, v36
	v_mul_f32_e32 v41, 0xbfb8aa3b, v37
	v_exp_f32_e32 v40, v40
	v_exp_f32_e32 v41, v41
	v_add_f32_e32 v40, 1.0, v40
	v_add_f32_e32 v41, 1.0, v41
	v_rcp_f32_e32 v40, v40
	v_rcp_f32_e32 v41, v41
	s_nop 0
	v_pk_mul_f32 v[36:37], v[36:37], v[40:41]
	s_nop 0
	v_pk_mul_f32 v[32:33], v[32:33], v[36:37]
	s_nop 0
	v_cvt_pk_bf16_f32 v32, v32, v33
	v_mul_f32_e32 v33, 0xbfb8aa3b, v38
	v_exp_f32_e32 v33, v33
	s_nop 0
	v_add_f32_e32 v33, 1.0, v33
	v_rcp_f32_e32 v36, v33
	v_mul_f32_e32 v33, 0xbfb8aa3b, v39
	v_exp_f32_e32 v33, v33
	s_nop 0
	v_add_f32_e32 v33, 1.0, v33
	v_rcp_f32_e32 v37, v33
	s_nop 0
	v_pk_mul_f32 v[36:37], v[38:39], v[36:37]
	s_nop 0
	v_pk_mul_f32 v[34:35], v[34:35], v[36:37]
	s_nop 0
	v_cvt_pk_bf16_f32 v33, v34, v35
	v_mul_f32_e32 v34, 0xbfb8aa3b, v28
	v_mul_f32_e32 v35, 0xbfb8aa3b, v29
	v_exp_f32_e32 v34, v34
	v_exp_f32_e32 v35, v35
	global_store_dwordx2 v[42:43], v[32:33], off offset:128
	v_add_u32_e32 v32, 0xa0, v147
	v_add_f32_e32 v34, 1.0, v34
	v_add_f32_e32 v35, 1.0, v35
	v_rcp_f32_e32 v34, v34
	v_rcp_f32_e32 v35, v35
	v_mad_i64_i32 v[32:33], s[22:23], v32, s42, v[132:133]
	v_pk_mul_f32 v[28:29], v[28:29], v[34:35]
	s_nop 0
	v_pk_mul_f32 v[24:25], v[24:25], v[28:29]
	s_nop 0
	v_cvt_pk_bf16_f32 v24, v24, v25
	v_mul_f32_e32 v25, 0xbfb8aa3b, v30
	v_exp_f32_e32 v25, v25
	s_nop 0
	v_add_f32_e32 v25, 1.0, v25
	v_rcp_f32_e32 v28, v25
	v_mul_f32_e32 v25, 0xbfb8aa3b, v31
	v_exp_f32_e32 v25, v25
	s_nop 0
	v_add_f32_e32 v25, 1.0, v25
	v_rcp_f32_e32 v29, v25
	s_nop 0
	v_pk_mul_f32 v[28:29], v[30:31], v[28:29]
	s_nop 0
	v_pk_mul_f32 v[26:27], v[26:27], v[28:29]
	s_nop 0
	v_cvt_pk_bf16_f32 v25, v26, v27
	v_lshl_add_u64 v[26:27], v[32:33], 0, s[20:21]
	global_store_dwordx2 v[26:27], v[24:25], off
	v_mul_f32_e32 v24, 0xbfb8aa3b, v20
	v_mul_f32_e32 v25, 0xbfb8aa3b, v21
	v_exp_f32_e32 v24, v24
	v_exp_f32_e32 v25, v25
	v_add_f32_e32 v24, 1.0, v24
	v_add_f32_e32 v25, 1.0, v25
	v_rcp_f32_e32 v24, v24
	v_rcp_f32_e32 v25, v25
	s_nop 0
	v_pk_mul_f32 v[20:21], v[20:21], v[24:25]
	s_nop 0
	v_pk_mul_f32 v[16:17], v[16:17], v[20:21]
	s_nop 0
	v_cvt_pk_bf16_f32 v16, v16, v17
	v_mul_f32_e32 v17, 0xbfb8aa3b, v22
	v_exp_f32_e32 v17, v17
	s_nop 0
	v_add_f32_e32 v17, 1.0, v17
	v_rcp_f32_e32 v20, v17
	v_mul_f32_e32 v17, 0xbfb8aa3b, v23
	v_exp_f32_e32 v17, v17
	s_nop 0
	v_add_f32_e32 v17, 1.0, v17
	v_rcp_f32_e32 v21, v17
	s_nop 0
	v_pk_mul_f32 v[20:21], v[22:23], v[20:21]
	s_nop 0
	v_pk_mul_f32 v[18:19], v[18:19], v[20:21]
	s_nop 0
	v_cvt_pk_bf16_f32 v17, v18, v19
	v_mul_f32_e32 v18, 0xbfb8aa3b, v12
	v_mul_f32_e32 v19, 0xbfb8aa3b, v13
	v_exp_f32_e32 v18, v18
	v_exp_f32_e32 v19, v19
	global_store_dwordx2 v[26:27], v[16:17], off offset:128
	v_add_u32_e32 v16, 0xb0, v147
	v_add_f32_e32 v18, 1.0, v18
	v_add_f32_e32 v19, 1.0, v19
	v_rcp_f32_e32 v18, v18
	v_rcp_f32_e32 v19, v19
	v_mad_i64_i32 v[16:17], s[22:23], v16, s42, v[132:133]
	s_mov_b64 s[22:23], s[16:17]
	v_pk_mul_f32 v[12:13], v[12:13], v[18:19]
	s_nop 0
	v_pk_mul_f32 v[8:9], v[8:9], v[12:13]
	s_nop 0
	v_cvt_pk_bf16_f32 v8, v8, v9
	v_mul_f32_e32 v9, 0xbfb8aa3b, v14
	v_exp_f32_e32 v9, v9
	s_nop 0
	v_add_f32_e32 v9, 1.0, v9
	v_rcp_f32_e32 v12, v9
	v_mul_f32_e32 v9, 0xbfb8aa3b, v15
	v_exp_f32_e32 v9, v9
	s_nop 0
	v_add_f32_e32 v9, 1.0, v9
	v_rcp_f32_e32 v13, v9
	s_nop 0
	v_pk_mul_f32 v[12:13], v[14:15], v[12:13]
	s_nop 0
	v_pk_mul_f32 v[10:11], v[10:11], v[12:13]
	s_nop 0
	v_cvt_pk_bf16_f32 v9, v10, v11
	v_lshl_add_u64 v[10:11], v[16:17], 0, s[20:21]
	global_store_dwordx2 v[10:11], v[8:9], off
	v_mul_f32_e32 v8, 0xbfb8aa3b, v4
	v_mul_f32_e32 v9, 0xbfb8aa3b, v5
	v_exp_f32_e32 v8, v8
	v_exp_f32_e32 v9, v9
	s_mov_b32 s21, s12
	s_mov_b32 s20, s14
	v_add_f32_e32 v8, 1.0, v8
	v_add_f32_e32 v9, 1.0, v9
	v_rcp_f32_e32 v8, v8
	v_rcp_f32_e32 v9, v9
	s_nop 0
	v_pk_mul_f32 v[4:5], v[4:5], v[8:9]
	s_nop 0
	v_pk_mul_f32 v[0:1], v[0:1], v[4:5]
	s_nop 0
	v_cvt_pk_bf16_f32 v0, v0, v1
	v_mul_f32_e32 v1, 0xbfb8aa3b, v6
	v_exp_f32_e32 v1, v1
	s_nop 0
	v_add_f32_e32 v1, 1.0, v1
	v_rcp_f32_e32 v4, v1
	v_mul_f32_e32 v1, 0xbfb8aa3b, v7
	v_exp_f32_e32 v1, v1
	s_nop 0
	v_add_f32_e32 v1, 1.0, v1
	v_rcp_f32_e32 v5, v1
	s_nop 0
	v_pk_mul_f32 v[4:5], v[6:7], v[4:5]
	s_nop 0
	v_pk_mul_f32 v[2:3], v[2:3], v[4:5]
	s_nop 0
	v_cvt_pk_bf16_f32 v1, v2, v3
	global_store_dwordx2 v[10:11], v[0:1], off offset:128
	s_cbranch_vccz .LBB0_2002
	s_waitcnt vmcnt(0)
	s_cmpk_gt_u32 s1, 0xff
	s_cbranch_scc1 .LBB0_2009
	s_barrier

.LBB0_2081:
	ds_read_b128 v[128:131], v151
	ds_read_b128 v[144:147], v151 offset:1024
	ds_read_b128 v[154:157], v151 offset:2048
	ds_read_b128 v[158:161], v151 offset:3072
	s_add_i32 m0, s4, 0xc000
	ds_read_b128 v[162:165], v152
	ds_read_b128 v[166:169], v152 offset:1024
	ds_read_b128 v[170:173], v152 offset:2048
	ds_read_b128 v[174:177], v152 offset:3072
	ds_read_b128 v[178:181], v152 offset:4096
	ds_read_b128 v[182:185], v152 offset:5120
	ds_read_b128 v[186:189], v152 offset:6144
	ds_read_b128 v[190:193], v152 offset:7168
	global_load_lds_dwordx4 v136, s[16:17]
	v_lshl_add_u64 v[194:195], s[16:17], 0, v[138:139]
	s_add_i32 m0, s4, 0xe000
	s_nop 0
	global_load_lds_dwordx4 v[194:195], off
	s_waitcnt lgkmcnt(8)
	s_barrier
	s_waitcnt lgkmcnt(0)
	s_waitcnt lgkmcnt(0)
	v_mfma_f32_16x16x32_bf16 v[124:127], v[128:131], v[162:165], v[124:127]
	s_add_u32 s18, s16, 0x100
	s_addc_u32 s19, s17, 0
	s_cmpk_eq_i32 s42, 0x54
	s_cselect_b32 s23, s11, s19
	s_cselect_b32 s22, s10, s18
	s_cselect_b32 s21, s13, s41
	s_cselect_b32 s20, s12, s40
	v_mfma_f32_16x16x32_bf16 v[92:95], v[154:157], v[162:165], v[92:95]
	v_mfma_f32_16x16x32_bf16 v[120:123], v[128:131], v[170:173], v[120:123]
	v_mfma_f32_16x16x32_bf16 v[88:91], v[154:157], v[170:173], v[88:91]
	v_mfma_f32_16x16x32_bf16 v[116:119], v[128:131], v[178:181], v[116:119]
	v_mfma_f32_16x16x32_bf16 v[84:87], v[154:157], v[178:181], v[84:87]
	v_mfma_f32_16x16x32_bf16 v[112:115], v[128:131], v[186:189], v[112:115]
	v_mfma_f32_16x16x32_bf16 v[80:83], v[154:157], v[186:189], v[80:83]
	v_mfma_f32_16x16x32_bf16 v[124:127], v[144:147], v[166:169], v[124:127]
	v_mfma_f32_16x16x32_bf16 v[92:95], v[158:161], v[166:169], v[92:95]
	v_mfma_f32_16x16x32_bf16 v[120:123], v[144:147], v[174:177], v[120:123]
	v_mfma_f32_16x16x32_bf16 v[88:91], v[158:161], v[174:177], v[88:91]
	v_mfma_f32_16x16x32_bf16 v[116:119], v[144:147], v[182:185], v[116:119]
	v_mfma_f32_16x16x32_bf16 v[84:87], v[158:161], v[182:185], v[84:87]
	v_mfma_f32_16x16x32_bf16 v[112:115], v[144:147], v[190:193], v[112:115]
	v_mfma_f32_16x16x32_bf16 v[80:83], v[158:161], v[190:193], v[80:83]
	s_barrier
	s_add_i32 s16, s34, s3
	v_lshl_add_u64 v[210:211], s[20:21], 0, v[132:133]
	s_mov_b32 m0, s16
	ds_read_b128 v[194:197], v153
	ds_read_b128 v[198:201], v153 offset:1024
	ds_read_b128 v[202:205], v153 offset:2048
	ds_read_b128 v[206:209], v153 offset:3072
	global_load_lds_dwordx4 v[210:211], off
	s_add_i32 m0, s16, 0x2000
	s_nop 0
	global_load_lds_dwordx4 v134, s[20:21]
	s_barrier
	s_waitcnt lgkmcnt(0)
	s_waitcnt lgkmcnt(0)
	v_mfma_f32_16x16x32_bf16 v[76:79], v[194:197], v[162:165], v[76:79]
	v_mfma_f32_16x16x32_bf16 v[48:51], v[202:205], v[162:165], v[48:51]
	v_mfma_f32_16x16x32_bf16 v[68:71], v[194:197], v[170:173], v[68:71]
	v_mfma_f32_16x16x32_bf16 v[40:43], v[202:205], v[170:173], v[40:43]
	v_mfma_f32_16x16x32_bf16 v[60:63], v[194:197], v[178:181], v[60:63]
	v_mfma_f32_16x16x32_bf16 v[36:39], v[202:205], v[178:181], v[36:39]
	v_mfma_f32_16x16x32_bf16 v[52:55], v[194:197], v[186:189], v[52:55]
	v_mfma_f32_16x16x32_bf16 v[28:31], v[202:205], v[186:189], v[28:31]
	v_mfma_f32_16x16x32_bf16 v[76:79], v[198:201], v[166:169], v[76:79]
	v_mfma_f32_16x16x32_bf16 v[48:51], v[206:209], v[166:169], v[48:51]
	v_mfma_f32_16x16x32_bf16 v[68:71], v[198:201], v[174:177], v[68:71]
	v_mfma_f32_16x16x32_bf16 v[40:43], v[206:209], v[174:177], v[40:43]
	v_mfma_f32_16x16x32_bf16 v[60:63], v[198:201], v[182:185], v[60:63]
	v_mfma_f32_16x16x32_bf16 v[36:39], v[206:209], v[182:185], v[36:39]
	v_mfma_f32_16x16x32_bf16 v[52:55], v[198:201], v[190:193], v[52:55]
	v_mfma_f32_16x16x32_bf16 v[28:31], v[206:209], v[190:193], v[28:31]
	s_mov_b32 m0, s4
	v_lshl_add_u64 v[214:215], s[22:23], 0, v[132:133]
	s_barrier
	ds_read_b128 v[162:165], v152 offset:16384
	ds_read_b128 v[166:169], v152 offset:17408
	ds_read_b128 v[170:173], v152 offset:18432
	ds_read_b128 v[174:177], v152 offset:19456
	ds_read_b128 v[178:181], v152 offset:20480
	ds_read_b128 v[182:185], v152 offset:21504
	ds_read_b128 v[186:189], v152 offset:22528
	ds_read_b128 v[190:193], v152 offset:23552
	global_load_lds_dwordx4 v[214:215], off
	v_lshl_add_u64 v[216:217], s[22:23], 0, v[134:135]
	s_mov_b32 m0, s5
	s_nop 0
	global_load_lds_dwordx4 v134, s[22:23]
	s_barrier
	s_waitcnt lgkmcnt(0)
	s_waitcnt lgkmcnt(0)
	v_mfma_f32_16x16x32_bf16 v[108:111], v[128:131], v[162:165], v[108:111]
	v_mfma_f32_16x16x32_bf16 v[72:75], v[154:157], v[162:165], v[72:75]
	v_mfma_f32_16x16x32_bf16 v[104:107], v[128:131], v[170:173], v[104:107]
	v_mfma_f32_16x16x32_bf16 v[64:67], v[154:157], v[170:173], v[64:67]
	v_mfma_f32_16x16x32_bf16 v[100:103], v[128:131], v[178:181], v[100:103]
	v_mfma_f32_16x16x32_bf16 v[56:59], v[154:157], v[178:181], v[56:59]
	v_mfma_f32_16x16x32_bf16 v[96:99], v[128:131], v[186:189], v[96:99]
	v_mfma_f32_16x16x32_bf16 v[44:47], v[154:157], v[186:189], v[44:47]
	v_mfma_f32_16x16x32_bf16 v[108:111], v[144:147], v[166:169], v[108:111]
	v_mfma_f32_16x16x32_bf16 v[72:75], v[158:161], v[166:169], v[72:75]
	v_mfma_f32_16x16x32_bf16 v[104:107], v[144:147], v[174:177], v[104:107]
	v_mfma_f32_16x16x32_bf16 v[64:67], v[158:161], v[174:177], v[64:67]
	v_mfma_f32_16x16x32_bf16 v[100:103], v[144:147], v[182:185], v[100:103]
	v_mfma_f32_16x16x32_bf16 v[56:59], v[158:161], v[182:185], v[56:59]
	v_mfma_f32_16x16x32_bf16 v[96:99], v[144:147], v[190:193], v[96:99]
	v_mfma_f32_16x16x32_bf16 v[44:47], v[158:161], v[190:193], v[44:47]
	s_barrier
	s_add_u32 s16, s20, 0x160000
	s_addc_u32 s17, s21, 0
	s_add_i32 s43, s35, s3
	v_lshl_add_u64 v[128:129], s[16:17], 0, v[132:133]
	s_mov_b32 m0, s43
	s_nop 0
	global_load_lds_dwordx4 v[128:129], off
	s_add_i32 m0, s43, 0x2000
	s_nop 0
	global_load_lds_dwordx4 v134, s[16:17]
	s_waitcnt vmcnt(6)
	s_barrier
	v_mfma_f32_16x16x32_bf16 v[32:35], v[194:197], v[162:165], v[32:35]
	v_mfma_f32_16x16x32_bf16 v[12:15], v[202:205], v[162:165], v[12:15]
	v_mfma_f32_16x16x32_bf16 v[24:27], v[194:197], v[170:173], v[24:27]
	v_mfma_f32_16x16x32_bf16 v[8:11], v[202:205], v[170:173], v[8:11]
	v_mfma_f32_16x16x32_bf16 v[20:23], v[194:197], v[178:181], v[20:23]
	v_mfma_f32_16x16x32_bf16 v[4:7], v[202:205], v[178:181], v[4:7]
	v_mfma_f32_16x16x32_bf16 v[16:19], v[194:197], v[186:189], v[16:19]
	v_mfma_f32_16x16x32_bf16 v[0:3], v[202:205], v[186:189], v[0:3]
	v_mfma_f32_16x16x32_bf16 v[32:35], v[198:201], v[166:169], v[32:35]
	v_mfma_f32_16x16x32_bf16 v[12:15], v[206:209], v[166:169], v[12:15]
	v_mfma_f32_16x16x32_bf16 v[24:27], v[198:201], v[174:177], v[24:27]
	v_mfma_f32_16x16x32_bf16 v[8:11], v[206:209], v[174:177], v[8:11]
	v_mfma_f32_16x16x32_bf16 v[20:23], v[198:201], v[182:185], v[20:23]
	v_mfma_f32_16x16x32_bf16 v[4:7], v[206:209], v[182:185], v[4:7]
	v_mfma_f32_16x16x32_bf16 v[16:19], v[198:201], v[190:193], v[16:19]
	v_mfma_f32_16x16x32_bf16 v[0:3], v[206:209], v[190:193], v[0:3]
	s_add_i32 s43, 0, 0x18000
	v_add_u32_e32 v158, s43, v149
	s_barrier
	ds_read_b128 v[128:131], v158
	ds_read_b128 v[144:147], v158 offset:1024
	ds_read_b128 v[154:157], v158 offset:2048
	ds_read_b128 v[158:161], v158 offset:3072
	s_add_u32 s16, s22, 0x160000
	s_addc_u32 s17, s23, 0
	s_mov_b32 m0, s24
	v_lshl_add_u64 v[194:195], s[16:17], 0, v[132:133]
	ds_read_b128 v[162:165], v152 offset:32768
	ds_read_b128 v[166:169], v152 offset:33792
	ds_read_b128 v[170:173], v152 offset:34816
	ds_read_b128 v[174:177], v152 offset:35840
	ds_read_b128 v[178:181], v152 offset:36864
	ds_read_b128 v[182:185], v152 offset:37888
	ds_read_b128 v[186:189], v152 offset:38912
	ds_read_b128 v[190:193], v152 offset:39936
	global_load_lds_dwordx4 v[194:195], off
	s_mov_b32 m0, s25
	s_nop 0
	global_load_lds_dwordx4 v134, s[16:17]
	s_waitcnt lgkmcnt(8)
	s_barrier
	s_waitcnt lgkmcnt(0)
	s_waitcnt lgkmcnt(0)
	v_mfma_f32_16x16x32_bf16 v[124:127], v[128:131], v[162:165], v[124:127]
	v_mfma_f32_16x16x32_bf16 v[92:95], v[154:157], v[162:165], v[92:95]
	v_mfma_f32_16x16x32_bf16 v[120:123], v[128:131], v[170:173], v[120:123]
	v_mfma_f32_16x16x32_bf16 v[88:91], v[154:157], v[170:173], v[88:91]
	v_mfma_f32_16x16x32_bf16 v[116:119], v[128:131], v[178:181], v[116:119]
	v_mfma_f32_16x16x32_bf16 v[84:87], v[154:157], v[178:181], v[84:87]
	v_mfma_f32_16x16x32_bf16 v[112:115], v[128:131], v[186:189], v[112:115]
	v_mfma_f32_16x16x32_bf16 v[80:83], v[154:157], v[186:189], v[80:83]
	v_mfma_f32_16x16x32_bf16 v[124:127], v[144:147], v[166:169], v[124:127]
	v_mfma_f32_16x16x32_bf16 v[92:95], v[158:161], v[166:169], v[92:95]
	v_mfma_f32_16x16x32_bf16 v[120:123], v[144:147], v[174:177], v[120:123]
	v_mfma_f32_16x16x32_bf16 v[88:91], v[158:161], v[174:177], v[88:91]
	v_mfma_f32_16x16x32_bf16 v[116:119], v[144:147], v[182:185], v[116:119]
	v_mfma_f32_16x16x32_bf16 v[84:87], v[158:161], v[182:185], v[84:87]
	v_mfma_f32_16x16x32_bf16 v[112:115], v[144:147], v[190:193], v[112:115]
	v_mfma_f32_16x16x32_bf16 v[80:83], v[158:161], v[190:193], v[80:83]
	s_barrier
	s_add_i32 s22, 0, 0x1c000
	s_add_i32 s16, s43, s3
	v_add_u32_e32 v206, s22, v149
	v_lshl_add_u64 v[210:211], v[210:211], 0, s[14:15]
	s_mov_b32 m0, s16
	ds_read_b128 v[194:197], v206
	ds_read_b128 v[198:201], v206 offset:1024
	ds_read_b128 v[202:205], v206 offset:2048
	ds_read_b128 v[206:209], v206 offset:3072
	global_load_lds_dwordx4 v[210:211], off
	s_add_u32 s98, s20, s14
	s_addc_u32 s99, s21, s15
	s_add_i32 m0, s16, 0x2000
	s_nop 0
	global_load_lds_dwordx4 v134, s[98:99]
	s_barrier
	s_waitcnt lgkmcnt(0)
	s_waitcnt lgkmcnt(0)
	v_mfma_f32_16x16x32_bf16 v[76:79], v[194:197], v[162:165], v[76:79]
	v_mfma_f32_16x16x32_bf16 v[48:51], v[202:205], v[162:165], v[48:51]
	v_mfma_f32_16x16x32_bf16 v[68:71], v[194:197], v[170:173], v[68:71]
	v_mfma_f32_16x16x32_bf16 v[40:43], v[202:205], v[170:173], v[40:43]
	v_mfma_f32_16x16x32_bf16 v[60:63], v[194:197], v[178:181], v[60:63]
	v_mfma_f32_16x16x32_bf16 v[36:39], v[202:205], v[178:181], v[36:39]
	v_mfma_f32_16x16x32_bf16 v[52:55], v[194:197], v[186:189], v[52:55]
	v_mfma_f32_16x16x32_bf16 v[28:31], v[202:205], v[186:189], v[28:31]
	v_mfma_f32_16x16x32_bf16 v[76:79], v[198:201], v[166:169], v[76:79]
	v_mfma_f32_16x16x32_bf16 v[48:51], v[206:209], v[166:169], v[48:51]
	v_mfma_f32_16x16x32_bf16 v[68:71], v[198:201], v[174:177], v[68:71]
	v_mfma_f32_16x16x32_bf16 v[40:43], v[206:209], v[174:177], v[40:43]
	v_mfma_f32_16x16x32_bf16 v[60:63], v[198:201], v[182:185], v[60:63]
	v_mfma_f32_16x16x32_bf16 v[36:39], v[206:209], v[182:185], v[36:39]
	v_mfma_f32_16x16x32_bf16 v[52:55], v[198:201], v[190:193], v[52:55]
	v_mfma_f32_16x16x32_bf16 v[28:31], v[206:209], v[190:193], v[28:31]
	s_mov_b32 m0, s27
	v_lshl_add_u64 v[210:211], v[214:215], 0, s[14:15]
	s_barrier
	ds_read_b128 v[162:165], v152 offset:49152
	ds_read_b128 v[166:169], v152 offset:50176
	ds_read_b128 v[170:173], v152 offset:51200
	ds_read_b128 v[174:177], v152 offset:52224
	ds_read_b128 v[178:181], v152 offset:53248
	ds_read_b128 v[182:185], v152 offset:54272
	ds_read_b128 v[186:189], v152 offset:55296
	ds_read_b128 v[190:193], v152 offset:56320
	global_load_lds_dwordx4 v[210:211], off
	v_lshl_add_u64 v[210:211], v[216:217], 0, s[14:15]
	s_mov_b32 m0, s28
	s_nop 0
	global_load_lds_dwordx4 v[210:211], off
	s_barrier
	s_waitcnt lgkmcnt(0)
	s_waitcnt lgkmcnt(0)
	v_mfma_f32_16x16x32_bf16 v[108:111], v[128:131], v[162:165], v[108:111]
	v_mfma_f32_16x16x32_bf16 v[72:75], v[154:157], v[162:165], v[72:75]
	v_mfma_f32_16x16x32_bf16 v[104:107], v[128:131], v[170:173], v[104:107]
	v_mfma_f32_16x16x32_bf16 v[64:67], v[154:157], v[170:173], v[64:67]
	v_mfma_f32_16x16x32_bf16 v[100:103], v[128:131], v[178:181], v[100:103]
	v_mfma_f32_16x16x32_bf16 v[56:59], v[154:157], v[178:181], v[56:59]
	v_mfma_f32_16x16x32_bf16 v[96:99], v[128:131], v[186:189], v[96:99]
	v_mfma_f32_16x16x32_bf16 v[44:47], v[154:157], v[186:189], v[44:47]
	v_mfma_f32_16x16x32_bf16 v[108:111], v[144:147], v[166:169], v[108:111]
	v_mfma_f32_16x16x32_bf16 v[72:75], v[158:161], v[166:169], v[72:75]
	v_mfma_f32_16x16x32_bf16 v[104:107], v[144:147], v[174:177], v[104:107]
	v_mfma_f32_16x16x32_bf16 v[64:67], v[158:161], v[174:177], v[64:67]
	v_mfma_f32_16x16x32_bf16 v[100:103], v[144:147], v[182:185], v[100:103]
	v_mfma_f32_16x16x32_bf16 v[56:59], v[158:161], v[182:185], v[56:59]
	v_mfma_f32_16x16x32_bf16 v[96:99], v[144:147], v[190:193], v[96:99]
	v_mfma_f32_16x16x32_bf16 v[44:47], v[158:161], v[190:193], v[44:47]
	s_barrier
	s_add_u32 s16, s20, 0x160080
	s_addc_u32 s17, s21, 0
	s_add_i32 s20, s22, s3
	v_lshl_add_u64 v[128:129], s[16:17], 0, v[132:133]
	s_mov_b32 m0, s20
	s_nop 0
	global_load_lds_dwordx4 v[128:129], off
	s_add_i32 m0, s20, 0x2000
	s_nop 0
	global_load_lds_dwordx4 v134, s[16:17]
	s_waitcnt vmcnt(6)
	s_barrier
	v_mfma_f32_16x16x32_bf16 v[32:35], v[194:197], v[162:165], v[32:35]
	v_mfma_f32_16x16x32_bf16 v[12:15], v[202:205], v[162:165], v[12:15]
	v_mfma_f32_16x16x32_bf16 v[24:27], v[194:197], v[170:173], v[24:27]
	v_mfma_f32_16x16x32_bf16 v[8:11], v[202:205], v[170:173], v[8:11]
	v_mfma_f32_16x16x32_bf16 v[20:23], v[194:197], v[178:181], v[20:23]
	v_mfma_f32_16x16x32_bf16 v[4:7], v[202:205], v[178:181], v[4:7]
	v_mfma_f32_16x16x32_bf16 v[16:19], v[194:197], v[186:189], v[16:19]
	v_mfma_f32_16x16x32_bf16 v[0:3], v[202:205], v[186:189], v[0:3]
	v_mfma_f32_16x16x32_bf16 v[32:35], v[198:201], v[166:169], v[32:35]
	v_mfma_f32_16x16x32_bf16 v[12:15], v[206:209], v[166:169], v[12:15]
	v_mfma_f32_16x16x32_bf16 v[24:27], v[198:201], v[174:177], v[24:27]
	v_mfma_f32_16x16x32_bf16 v[8:11], v[206:209], v[174:177], v[8:11]
	v_mfma_f32_16x16x32_bf16 v[20:23], v[198:201], v[182:185], v[20:23]
	v_mfma_f32_16x16x32_bf16 v[4:7], v[206:209], v[182:185], v[4:7]
	v_mfma_f32_16x16x32_bf16 v[16:19], v[198:201], v[190:193], v[16:19]
	v_mfma_f32_16x16x32_bf16 v[0:3], v[206:209], v[190:193], v[0:3]
	s_add_i32 s42, s42, 2
	s_add_u32 s40, s40, 0x100
	s_addc_u32 s41, s41, 0
	s_cmpk_gt_u32 s42, 0x55
	s_mov_b64 s[16:17], s[18:19]
	s_barrier
	s_cbranch_scc0 .LBB0_2081
	s_cmp_lt_u32 s38, 32
	s_movk_i32 s16, 0x3000
	s_cselect_b32 s16, s16, 0x6000
	s_cmp_gt_i32 s38, 15
	v_lshl_add_u32 v158, s38, 8, v148
	s_cselect_b32 s16, s16, 0
	v_lshl_or_b32 v128, s39, 8, v150
	s_lshl_b32 s16, s16, 2
	v_ashrrev_i32_e32 v159, 31, v158
	s_add_u32 s16, s30, s16
	v_ashrrev_i32_e32 v129, 31, v128
	v_lshlrev_b64 v[146:147], 13, v[158:159]
	s_addc_u32 s17, s31, 0
	v_lshlrev_b64 v[160:161], 2, v[128:129]
	v_lshl_add_u64 v[146:147], s[56:57], 0, v[146:147]
	v_lshl_add_u64 v[144:145], s[16:17], 0, v[160:161]
	v_lshl_add_u64 v[146:147], v[146:147], 0, v[160:161]
	s_mov_b64 s[16:17], 0x100000
	s_mov_b32 s39, s36
	s_mov_b32 s38, s37
	s_mov_b64 s[18:19], s[12:13]
	v_or_b32_e32 v162, 16, v158
	v_ashrrev_i32_e32 v163, 31, v162
	v_lshlrev_b64 v[164:165], 13, v[162:163]
	v_lshl_add_u64 v[162:163], s[56:57], 0, v[164:165]
	v_lshl_add_u64 v[164:165], v[162:163], 0, v[160:161]
	v_or_b32_e32 v162, 32, v158
	v_ashrrev_i32_e32 v163, 31, v162
	v_lshlrev_b64 v[166:167], 13, v[162:163]
	v_lshl_add_u64 v[162:163], s[56:57], 0, v[166:167]
	v_lshl_add_u64 v[166:167], v[162:163], 0, v[160:161]
	v_or_b32_e32 v162, 48, v158
	v_ashrrev_i32_e32 v163, 31, v162
	v_lshlrev_b64 v[168:169], 13, v[162:163]
	v_lshl_add_u64 v[162:163], s[56:57], 0, v[168:169]
	v_lshl_add_u64 v[168:169], v[162:163], 0, v[160:161]
	v_lshl_add_u64 v[162:163], v[146:147], 0, s[16:17]
	s_mov_b32 s16, 0x100000
	v_add_co_u32_e32 v170, vcc, s16, v146
	s_mov_b64 s[16:17], 0x120000
	s_nop 0
	v_addc_co_u32_e32 v171, vcc, 0, v147, vcc
	v_lshl_add_u64 v[172:173], v[146:147], 0, s[16:17]
	s_mov_b32 s16, 0x120000
	v_add_co_u32_e32 v174, vcc, s16, v146
	s_mov_b64 s[16:17], 0x140000
	s_nop 0
	v_addc_co_u32_e32 v175, vcc, 0, v147, vcc
	v_lshl_add_u64 v[176:177], v[146:147], 0, s[16:17]
	s_mov_b32 s16, 0x140000
	v_add_co_u32_e32 v178, vcc, s16, v146
	s_mov_b64 s[16:17], 0x160000
	s_nop 0
	v_addc_co_u32_e32 v179, vcc, 0, v147, vcc
	v_lshl_add_u64 v[180:181], v[146:147], 0, s[16:17]
	s_mov_b32 s16, 0x160000
	v_add_co_u32_e32 v182, vcc, s16, v146
	s_mov_b64 s[16:17], s[10:11]
	s_nop 0
	v_addc_co_u32_e32 v183, vcc, 0, v147, vcc
	s_and_b64 vcc, exec, s[6:7]
	global_load_dwordx4 v[184:187], v[144:145], off
	global_load_dwordx4 v[188:191], v[146:147], off
	v_pk_add_f32 v[126:127], v[126:127], 0 op_sel_hi:[1,0]
	v_pk_add_f32 v[124:125], v[124:125], 0 op_sel_hi:[1,0]
	v_pk_add_f32 v[122:123], v[122:123], 0 op_sel_hi:[1,0]
	v_pk_add_f32 v[120:121], v[120:121], 0 op_sel_hi:[1,0]
	v_pk_add_f32 v[118:119], v[118:119], 0 op_sel_hi:[1,0]
	v_pk_add_f32 v[116:117], v[116:117], 0 op_sel_hi:[1,0]
	v_pk_add_f32 v[114:115], v[114:115], 0 op_sel_hi:[1,0]
	v_pk_add_f32 v[112:113], v[112:113], 0 op_sel_hi:[1,0]
	v_pk_add_f32 v[110:111], v[110:111], 0 op_sel_hi:[1,0]
	v_pk_add_f32 v[108:109], v[108:109], 0 op_sel_hi:[1,0]
	v_pk_add_f32 v[106:107], v[106:107], 0 op_sel_hi:[1,0]
	v_pk_add_f32 v[104:105], v[104:105], 0 op_sel_hi:[1,0]
	v_pk_add_f32 v[102:103], v[102:103], 0 op_sel_hi:[1,0]
	v_pk_add_f32 v[100:101], v[100:101], 0 op_sel_hi:[1,0]
	v_pk_add_f32 v[98:99], v[98:99], 0 op_sel_hi:[1,0]
	v_pk_add_f32 v[96:97], v[96:97], 0 op_sel_hi:[1,0]
	v_pk_add_f32 v[94:95], v[94:95], 0 op_sel_hi:[1,0]
	v_pk_add_f32 v[92:93], v[92:93], 0 op_sel_hi:[1,0]
	v_pk_add_f32 v[90:91], v[90:91], 0 op_sel_hi:[1,0]
	v_pk_add_f32 v[88:89], v[88:89], 0 op_sel_hi:[1,0]
	v_pk_add_f32 v[86:87], v[86:87], 0 op_sel_hi:[1,0]
	v_pk_add_f32 v[84:85], v[84:85], 0 op_sel_hi:[1,0]
	v_pk_add_f32 v[82:83], v[82:83], 0 op_sel_hi:[1,0]
	v_pk_add_f32 v[80:81], v[80:81], 0 op_sel_hi:[1,0]
	v_pk_add_f32 v[74:75], v[74:75], 0 op_sel_hi:[1,0]
	v_pk_add_f32 v[72:73], v[72:73], 0 op_sel_hi:[1,0]
	v_pk_add_f32 v[66:67], v[66:67], 0 op_sel_hi:[1,0]
	v_pk_add_f32 v[64:65], v[64:65], 0 op_sel_hi:[1,0]
	v_pk_add_f32 v[58:59], v[58:59], 0 op_sel_hi:[1,0]
	v_pk_add_f32 v[56:57], v[56:57], 0 op_sel_hi:[1,0]
	v_pk_add_f32 v[46:47], v[46:47], 0 op_sel_hi:[1,0]
	v_pk_add_f32 v[44:45], v[44:45], 0 op_sel_hi:[1,0]
	v_pk_add_f32 v[62:63], v[62:63], 0 op_sel_hi:[1,0]
	v_pk_add_f32 v[60:61], v[60:61], 0 op_sel_hi:[1,0]
	v_pk_add_f32 v[54:55], v[54:55], 0 op_sel_hi:[1,0]
	v_pk_add_f32 v[52:53], v[52:53], 0 op_sel_hi:[1,0]
	v_pk_add_f32 v[34:35], v[34:35], 0 op_sel_hi:[1,0]
	v_pk_add_f32 v[32:33], v[32:33], 0 op_sel_hi:[1,0]
	v_pk_add_f32 v[26:27], v[26:27], 0 op_sel_hi:[1,0]
	v_pk_add_f32 v[24:25], v[24:25], 0 op_sel_hi:[1,0]
	v_pk_add_f32 v[22:23], v[22:23], 0 op_sel_hi:[1,0]
	v_pk_add_f32 v[20:21], v[20:21], 0 op_sel_hi:[1,0]
	v_pk_add_f32 v[18:19], v[18:19], 0 op_sel_hi:[1,0]
	v_pk_add_f32 v[16:17], v[16:17], 0 op_sel_hi:[1,0]
	v_pk_add_f32 v[14:15], v[14:15], 0 op_sel_hi:[1,0]
	v_pk_add_f32 v[12:13], v[12:13], 0 op_sel_hi:[1,0]
	v_pk_add_f32 v[10:11], v[10:11], 0 op_sel_hi:[1,0]
	v_pk_add_f32 v[8:9], v[8:9], 0 op_sel_hi:[1,0]
	v_pk_add_f32 v[6:7], v[6:7], 0 op_sel_hi:[1,0]
	v_pk_add_f32 v[4:5], v[4:5], 0 op_sel_hi:[1,0]
	v_pk_add_f32 v[2:3], v[2:3], 0 op_sel_hi:[1,0]
	v_pk_add_f32 v[0:1], v[0:1], 0 op_sel_hi:[1,0]
	s_waitcnt vmcnt(0)
	v_pk_fma_f32 v[126:127], v[126:127], v[186:187], v[190:191]
	v_pk_fma_f32 v[124:125], v[124:125], v[184:185], v[188:189]
	global_store_dwordx4 v[146:147], v[124:127], off
	global_load_dwordx4 v[188:191], v[164:165], off
	global_load_dwordx4 v[192:195], v[166:167], off
	global_load_dwordx4 v[196:199], v[168:169], off
	global_load_dwordx4 v[200:203], v[170:171], off
	global_load_dwordx4 v[204:207], v[174:175], off
	global_load_dwordx4 v[208:211], v[178:179], off
	global_load_dwordx4 v[212:215], v[182:183], off
	global_load_dwordx4 v[216:219], v[144:145], off offset:64
	global_load_dwordx4 v[220:223], v[146:147], off offset:64
	global_load_dwordx4 v[224:227], v[164:165], off offset:64
	global_load_dwordx4 v[228:231], v[166:167], off offset:64
	global_load_dwordx4 v[232:235], v[168:169], off offset:64
	s_waitcnt vmcnt(11)
	v_pk_fma_f32 v[122:123], v[122:123], v[186:187], v[190:191]
	v_pk_fma_f32 v[120:121], v[120:121], v[184:185], v[188:189]
	global_store_dwordx4 v[164:165], v[120:123], off
	global_load_dwordx4 v[188:191], v[162:163], off offset:64
	s_waitcnt vmcnt(12)
	v_pk_fma_f32 v[118:119], v[118:119], v[186:187], v[194:195]
	v_pk_fma_f32 v[116:117], v[116:117], v[184:185], v[192:193]
	global_store_dwordx4 v[166:167], v[116:119], off
	global_load_dwordx4 v[192:195], v[172:173], off offset:64
	s_waitcnt vmcnt(13)
	v_pk_fma_f32 v[114:115], v[114:115], v[186:187], v[198:199]
	v_pk_fma_f32 v[112:113], v[112:113], v[184:185], v[196:197]
	global_store_dwordx4 v[168:169], v[112:115], off
	global_load_dwordx4 v[196:199], v[176:177], off offset:64
	s_waitcnt vmcnt(14)
	v_pk_fma_f32 v[110:111], v[110:111], v[186:187], v[202:203]
	v_pk_fma_f32 v[108:109], v[108:109], v[184:185], v[200:201]
	global_store_dwordx4 v[170:171], v[108:111], off
	global_load_dwordx4 v[200:203], v[180:181], off offset:64
	s_waitcnt vmcnt(15)
	v_pk_fma_f32 v[106:107], v[106:107], v[186:187], v[206:207]
	v_pk_fma_f32 v[104:105], v[104:105], v[184:185], v[204:205]
	global_store_dwordx4 v[174:175], v[104:107], off
	global_load_dwordx4 v[204:207], v[144:145], off offset:512
	s_waitcnt vmcnt(16)
	v_pk_fma_f32 v[102:103], v[102:103], v[186:187], v[210:211]
	v_pk_fma_f32 v[100:101], v[100:101], v[184:185], v[208:209]
	global_store_dwordx4 v[178:179], v[100:103], off
	global_load_dwordx4 v[208:211], v[146:147], off offset:512
	s_waitcnt vmcnt(17)
	v_pk_fma_f32 v[98:99], v[98:99], v[186:187], v[214:215]
	v_pk_fma_f32 v[96:97], v[96:97], v[184:185], v[212:213]
	global_store_dwordx4 v[182:183], v[96:99], off
	global_load_dwordx4 v[184:187], v[164:165], off offset:512
	s_waitcnt vmcnt(17)
	v_pk_fma_f32 v[94:95], v[94:95], v[218:219], v[222:223]
	v_pk_fma_f32 v[92:93], v[92:93], v[216:217], v[220:221]
	global_store_dwordx4 v[146:147], v[92:95], off offset:64
	global_load_dwordx4 v[212:215], v[166:167], off offset:512
	global_load_dwordx4 v[220:223], v[168:169], off offset:512
	s_waitcnt vmcnt(19)
	v_pk_fma_f32 v[90:91], v[90:91], v[218:219], v[226:227]
	v_pk_fma_f32 v[88:89], v[88:89], v[216:217], v[224:225]
	global_store_dwordx4 v[164:165], v[88:91], off offset:64
	global_load_dwordx4 v[224:227], v[162:163], off offset:512
	s_waitcnt vmcnt(20)
	v_pk_fma_f32 v[86:87], v[86:87], v[218:219], v[230:231]
	v_pk_fma_f32 v[84:85], v[84:85], v[216:217], v[228:229]
	global_store_dwordx4 v[166:167], v[84:87], off offset:64
	global_load_dwordx4 v[228:231], v[172:173], off offset:512
	s_waitcnt vmcnt(21)
	v_pk_fma_f32 v[82:83], v[82:83], v[218:219], v[234:235]
	v_pk_fma_f32 v[80:81], v[80:81], v[216:217], v[232:233]
	global_store_dwordx4 v[168:169], v[80:83], off offset:64
	global_load_dwordx4 v[232:235], v[176:177], off offset:512
	s_waitcnt vmcnt(21)
	v_pk_fma_f32 v[74:75], v[74:75], v[218:219], v[190:191]
	v_pk_fma_f32 v[72:73], v[72:73], v[216:217], v[188:189]
	global_store_dwordx4 v[162:163], v[72:75], off offset:64
	global_load_dwordx4 v[188:191], v[180:181], off offset:512
	s_waitcnt vmcnt(21)
	v_pk_fma_f32 v[66:67], v[66:67], v[218:219], v[194:195]
	v_pk_fma_f32 v[64:65], v[64:65], v[216:217], v[192:193]
	global_store_dwordx4 v[172:173], v[64:67], off offset:64
	global_load_dwordx4 v[192:195], v[144:145], off offset:576
	s_waitcnt vmcnt(21)
	v_pk_fma_f32 v[58:59], v[58:59], v[218:219], v[198:199]
	v_pk_fma_f32 v[56:57], v[56:57], v[216:217], v[196:197]
	global_store_dwordx4 v[176:177], v[56:59], off offset:64
	global_load_dwordx4 v[196:199], v[146:147], off offset:576
	v_pk_add_f32 v[64:65], v[78:79], 0 op_sel_hi:[1,0]
	v_pk_add_f32 v[66:67], v[76:77], 0 op_sel_hi:[1,0]
	s_waitcnt vmcnt(21)
	v_pk_fma_f32 v[46:47], v[46:47], v[218:219], v[202:203]
	v_pk_fma_f32 v[44:45], v[44:45], v[216:217], v[200:201]
	global_store_dwordx4 v[180:181], v[44:47], off offset:64
	global_load_dwordx4 v[200:203], v[164:165], off offset:576
	s_waitcnt vmcnt(19)
	v_pk_fma_f32 v[58:59], v[64:65], v[206:207], v[210:211]
	v_pk_fma_f32 v[56:57], v[66:67], v[204:205], v[208:209]
	global_store_dwordx4 v[146:147], v[56:59], off offset:512
	global_load_dwordx4 v[208:211], v[166:167], off offset:576
	global_load_dwordx4 v[216:219], v[168:169], off offset:576
	v_pk_add_f32 v[64:65], v[70:71], 0 op_sel_hi:[1,0]
	v_pk_add_f32 v[66:67], v[68:69], 0 op_sel_hi:[1,0]
	s_waitcnt vmcnt(20)
	v_pk_fma_f32 v[58:59], v[64:65], v[206:207], v[186:187]
	v_pk_fma_f32 v[56:57], v[66:67], v[204:205], v[184:185]
	global_store_dwordx4 v[164:165], v[56:59], off offset:512
	global_load_dwordx4 v[184:187], v[162:163], off offset:576
	s_waitcnt vmcnt(20)
	v_pk_fma_f32 v[58:59], v[62:63], v[206:207], v[214:215]
	v_pk_fma_f32 v[56:57], v[60:61], v[204:205], v[212:213]
	global_store_dwordx4 v[166:167], v[56:59], off offset:512
	global_load_dwordx4 v[212:215], v[172:173], off offset:576
	s_waitcnt vmcnt(21)
	v_pk_fma_f32 v[54:55], v[54:55], v[206:207], v[222:223]
	v_pk_fma_f32 v[52:53], v[52:53], v[204:205], v[220:221]
	global_store_dwordx4 v[168:169], v[52:55], off offset:512
	global_load_dwordx4 v[220:223], v[176:177], off offset:576
	s_waitcnt vmcnt(21)
	v_pk_fma_f32 v[34:35], v[34:35], v[206:207], v[226:227]
	v_pk_fma_f32 v[32:33], v[32:33], v[204:205], v[224:225]
	global_store_dwordx4 v[162:163], v[32:35], off offset:512
	global_load_dwordx4 v[224:227], v[180:181], off offset:576
	s_waitcnt vmcnt(21)
	v_pk_fma_f32 v[26:27], v[26:27], v[206:207], v[230:231]
	v_pk_fma_f32 v[24:25], v[24:25], v[204:205], v[228:229]
	global_store_dwordx4 v[172:173], v[24:27], off offset:512
	s_waitcnt vmcnt(20)
	v_pk_fma_f32 v[22:23], v[22:23], v[206:207], v[234:235]
	v_pk_fma_f32 v[20:21], v[20:21], v[204:205], v[232:233]
	global_store_dwordx4 v[176:177], v[20:23], off offset:512
	v_pk_add_f32 v[24:25], v[50:51], 0 op_sel_hi:[1,0]
	v_pk_add_f32 v[26:27], v[48:49], 0 op_sel_hi:[1,0]
	s_waitcnt vmcnt(19)
	v_pk_fma_f32 v[18:19], v[18:19], v[206:207], v[190:191]
	v_pk_fma_f32 v[16:17], v[16:17], v[204:205], v[188:189]
	global_store_dwordx4 v[180:181], v[16:19], off offset:512
	s_waitcnt vmcnt(16)
	v_pk_fma_f32 v[22:23], v[24:25], v[194:195], v[198:199]
	v_pk_fma_f32 v[20:21], v[26:27], v[192:193], v[196:197]
	global_store_dwordx4 v[146:147], v[20:23], off offset:576
	v_pk_add_f32 v[24:25], v[42:43], 0 op_sel_hi:[1,0]
	v_pk_add_f32 v[26:27], v[40:41], 0 op_sel_hi:[1,0]
	s_waitcnt vmcnt(15)
	v_pk_fma_f32 v[22:23], v[24:25], v[194:195], v[202:203]
	v_pk_fma_f32 v[20:21], v[26:27], v[192:193], v[200:201]
	global_store_dwordx4 v[164:165], v[20:23], off offset:576
	v_pk_add_f32 v[24:25], v[38:39], 0 op_sel_hi:[1,0]
	v_pk_add_f32 v[26:27], v[36:37], 0 op_sel_hi:[1,0]
	s_waitcnt vmcnt(14)
	v_pk_fma_f32 v[22:23], v[24:25], v[194:195], v[210:211]
	v_pk_fma_f32 v[20:21], v[26:27], v[192:193], v[208:209]
	global_store_dwordx4 v[166:167], v[20:23], off offset:576
	v_pk_add_f32 v[24:25], v[30:31], 0 op_sel_hi:[1,0]
	v_pk_add_f32 v[26:27], v[28:29], 0 op_sel_hi:[1,0]
	s_waitcnt vmcnt(14)
	v_pk_fma_f32 v[22:23], v[24:25], v[194:195], v[218:219]
	v_pk_fma_f32 v[20:21], v[26:27], v[192:193], v[216:217]
	global_store_dwordx4 v[168:169], v[20:23], off offset:576
	s_waitcnt vmcnt(13)
	v_pk_fma_f32 v[14:15], v[14:15], v[194:195], v[186:187]
	v_pk_fma_f32 v[12:13], v[12:13], v[192:193], v[184:185]
	global_store_dwordx4 v[162:163], v[12:15], off offset:576
	s_waitcnt vmcnt(12)
	v_pk_fma_f32 v[10:11], v[10:11], v[194:195], v[214:215]
	v_pk_fma_f32 v[8:9], v[8:9], v[192:193], v[212:213]
	global_store_dwordx4 v[172:173], v[8:11], off offset:576
	s_waitcnt vmcnt(11)
	v_pk_fma_f32 v[6:7], v[6:7], v[194:195], v[222:223]
	v_pk_fma_f32 v[4:5], v[4:5], v[192:193], v[220:221]
	global_store_dwordx4 v[176:177], v[4:7], off offset:576
	s_waitcnt vmcnt(10)
	v_pk_fma_f32 v[2:3], v[2:3], v[194:195], v[226:227]
	v_pk_fma_f32 v[0:1], v[0:1], v[192:193], v[224:225]
	global_store_dwordx4 v[180:181], v[0:3], off offset:576
	s_cbranch_vccz .LBB0_2070
	s_waitcnt vmcnt(0)
	s_cmpk_gt_u32 s1, 0xff
	s_cbranch_scc1 .LBB0_2085
	s_barrier

.LBB0_2097:
	ds_read_b128 v[144:147], v139
	ds_read_b128 v[148:151], v139 offset:1024
	ds_read_b128 v[152:155], v139 offset:2048
	ds_read_b128 v[156:159], v139 offset:3072
	s_mov_b32 m0, s35
	v_lshl_add_u64 v[192:193], s[18:19], 0, v[132:133]
	ds_read_b128 v[160:163], v140
	ds_read_b128 v[164:167], v140 offset:1024
	ds_read_b128 v[168:171], v140 offset:2048
	ds_read_b128 v[172:175], v140 offset:3072
	ds_read_b128 v[176:179], v140 offset:4096
	ds_read_b128 v[180:183], v140 offset:5120
	ds_read_b128 v[184:187], v140 offset:6144
	ds_read_b128 v[188:191], v140 offset:7168
	global_load_lds_dwordx4 v[192:193], off
	s_mov_b32 m0, s36
	s_nop 0
	global_load_lds_dwordx4 v134, s[18:19]
	s_waitcnt lgkmcnt(8)
	s_barrier
	s_waitcnt lgkmcnt(0)
	s_waitcnt lgkmcnt(0)
	v_mfma_f32_16x16x32_bf16 v[124:127], v[144:147], v[160:163], v[124:127]
	s_add_u32 s20, s18, 0x100
	s_addc_u32 s21, s19, 0
	s_cmp_eq_u32 s61, 4
	s_cselect_b32 s25, s17, s21
	s_cselect_b32 s24, s16, s20
	s_cselect_b32 s23, s11, s60
	s_cselect_b32 s22, s10, s47
	v_mfma_f32_16x16x32_bf16 v[120:123], v[152:155], v[160:163], v[120:123]
	v_mfma_f32_16x16x32_bf16 v[116:119], v[144:147], v[168:171], v[116:119]
	v_mfma_f32_16x16x32_bf16 v[112:115], v[152:155], v[168:171], v[112:115]
	v_mfma_f32_16x16x32_bf16 v[100:103], v[144:147], v[176:179], v[100:103]
	v_mfma_f32_16x16x32_bf16 v[96:99], v[152:155], v[176:179], v[96:99]
	v_mfma_f32_16x16x32_bf16 v[84:87], v[144:147], v[184:187], v[84:87]
	v_mfma_f32_16x16x32_bf16 v[80:83], v[152:155], v[184:187], v[80:83]
	v_mfma_f32_16x16x32_bf16 v[124:127], v[148:151], v[164:167], v[124:127]
	v_mfma_f32_16x16x32_bf16 v[120:123], v[156:159], v[164:167], v[120:123]
	v_mfma_f32_16x16x32_bf16 v[116:119], v[148:151], v[172:175], v[116:119]
	v_mfma_f32_16x16x32_bf16 v[112:115], v[156:159], v[172:175], v[112:115]
	v_mfma_f32_16x16x32_bf16 v[100:103], v[148:151], v[180:183], v[100:103]
	v_mfma_f32_16x16x32_bf16 v[96:99], v[156:159], v[180:183], v[96:99]
	v_mfma_f32_16x16x32_bf16 v[84:87], v[148:151], v[188:191], v[84:87]
	v_mfma_f32_16x16x32_bf16 v[80:83], v[156:159], v[188:191], v[80:83]
	s_barrier
	s_mov_b32 m0, s37
	ds_read_b128 v[192:195], v141
	ds_read_b128 v[196:199], v141 offset:1024
	ds_read_b128 v[200:203], v141 offset:2048
	ds_read_b128 v[204:207], v141 offset:3072
	global_load_lds_dwordx4 v130, s[22:23]
	s_mov_b32 m0, s38
	s_nop 0
	global_load_lds_dwordx4 v128, s[22:23]
	s_barrier
	s_waitcnt lgkmcnt(0)
	s_waitcnt lgkmcnt(0)
	v_mfma_f32_16x16x32_bf16 v[108:111], v[192:195], v[160:163], v[108:111]
	v_mfma_f32_16x16x32_bf16 v[104:107], v[200:203], v[160:163], v[104:107]
	v_mfma_f32_16x16x32_bf16 v[92:95], v[192:195], v[168:171], v[92:95]
	v_mfma_f32_16x16x32_bf16 v[88:91], v[200:203], v[168:171], v[88:91]
	v_mfma_f32_16x16x32_bf16 v[76:79], v[192:195], v[176:179], v[76:79]
	v_mfma_f32_16x16x32_bf16 v[72:75], v[200:203], v[176:179], v[72:75]
	v_mfma_f32_16x16x32_bf16 v[68:71], v[192:195], v[184:187], v[68:71]
	v_mfma_f32_16x16x32_bf16 v[64:67], v[200:203], v[184:187], v[64:67]
	v_mfma_f32_16x16x32_bf16 v[108:111], v[196:199], v[164:167], v[108:111]
	v_mfma_f32_16x16x32_bf16 v[104:107], v[204:207], v[164:167], v[104:107]
	v_mfma_f32_16x16x32_bf16 v[92:95], v[196:199], v[172:175], v[92:95]
	v_mfma_f32_16x16x32_bf16 v[88:91], v[204:207], v[172:175], v[88:91]
	v_mfma_f32_16x16x32_bf16 v[76:79], v[196:199], v[180:183], v[76:79]
	v_mfma_f32_16x16x32_bf16 v[72:75], v[204:207], v[180:183], v[72:75]
	v_mfma_f32_16x16x32_bf16 v[68:71], v[196:199], v[188:191], v[68:71]
	v_mfma_f32_16x16x32_bf16 v[64:67], v[204:207], v[188:191], v[64:67]
	s_mov_b32 m0, s3
	v_lshl_add_u64 v[212:213], s[24:25], 0, v[130:131]
	s_barrier
	ds_read_b128 v[160:163], v140 offset:16384
	ds_read_b128 v[164:167], v140 offset:17408
	ds_read_b128 v[168:171], v140 offset:18432
	ds_read_b128 v[172:175], v140 offset:19456
	ds_read_b128 v[176:179], v140 offset:20480
	ds_read_b128 v[180:183], v140 offset:21504
	ds_read_b128 v[184:187], v140 offset:22528
	ds_read_b128 v[188:191], v140 offset:23552
	global_load_lds_dwordx4 v130, s[24:25]
	v_lshl_add_u64 v[214:215], s[24:25], 0, v[128:129]
	s_mov_b32 m0, s4
	s_nop 0
	global_load_lds_dwordx4 v128, s[24:25]
	s_barrier
	s_waitcnt lgkmcnt(0)
	s_waitcnt lgkmcnt(0)
	v_mfma_f32_16x16x32_bf16 v[60:63], v[144:147], v[160:163], v[60:63]
	v_mfma_f32_16x16x32_bf16 v[56:59], v[152:155], v[160:163], v[56:59]
	v_mfma_f32_16x16x32_bf16 v[52:55], v[144:147], v[168:171], v[52:55]
	v_mfma_f32_16x16x32_bf16 v[48:51], v[152:155], v[168:171], v[48:51]
	v_mfma_f32_16x16x32_bf16 v[36:39], v[144:147], v[176:179], v[36:39]
	v_mfma_f32_16x16x32_bf16 v[32:35], v[152:155], v[176:179], v[32:35]
	v_mfma_f32_16x16x32_bf16 v[20:23], v[144:147], v[184:187], v[20:23]
	v_mfma_f32_16x16x32_bf16 v[16:19], v[152:155], v[184:187], v[16:19]
	v_mfma_f32_16x16x32_bf16 v[60:63], v[148:151], v[164:167], v[60:63]
	v_mfma_f32_16x16x32_bf16 v[56:59], v[156:159], v[164:167], v[56:59]
	v_mfma_f32_16x16x32_bf16 v[52:55], v[148:151], v[172:175], v[52:55]
	v_mfma_f32_16x16x32_bf16 v[48:51], v[156:159], v[172:175], v[48:51]
	v_mfma_f32_16x16x32_bf16 v[36:39], v[148:151], v[180:183], v[36:39]
	v_mfma_f32_16x16x32_bf16 v[32:35], v[156:159], v[180:183], v[32:35]
	v_mfma_f32_16x16x32_bf16 v[20:23], v[148:151], v[188:191], v[20:23]
	v_mfma_f32_16x16x32_bf16 v[16:19], v[156:159], v[188:191], v[16:19]
	s_barrier
	s_add_u32 s18, s22, 0x160000
	s_addc_u32 s19, s23, 0
	s_mov_b32 m0, s39
	global_load_lds_dwordx4 v130, s[18:19]
	s_mov_b32 m0, s40
	s_nop 0
	global_load_lds_dwordx4 v128, s[18:19]
	s_waitcnt vmcnt(6)
	s_barrier
	v_mfma_f32_16x16x32_bf16 v[44:47], v[192:195], v[160:163], v[44:47]
	v_mfma_f32_16x16x32_bf16 v[40:43], v[200:203], v[160:163], v[40:43]
	v_mfma_f32_16x16x32_bf16 v[28:31], v[192:195], v[168:171], v[28:31]
	v_mfma_f32_16x16x32_bf16 v[24:27], v[200:203], v[168:171], v[24:27]
	v_mfma_f32_16x16x32_bf16 v[12:15], v[192:195], v[176:179], v[12:15]
	v_mfma_f32_16x16x32_bf16 v[8:11], v[200:203], v[176:179], v[8:11]
	v_mfma_f32_16x16x32_bf16 v[4:7], v[192:195], v[184:187], v[4:7]
	v_mfma_f32_16x16x32_bf16 v[0:3], v[200:203], v[184:187], v[0:3]
	v_mfma_f32_16x16x32_bf16 v[44:47], v[196:199], v[164:167], v[44:47]
	v_mfma_f32_16x16x32_bf16 v[40:43], v[204:207], v[164:167], v[40:43]
	v_mfma_f32_16x16x32_bf16 v[28:31], v[196:199], v[172:175], v[28:31]
	v_mfma_f32_16x16x32_bf16 v[24:27], v[204:207], v[172:175], v[24:27]
	v_mfma_f32_16x16x32_bf16 v[12:15], v[196:199], v[180:183], v[12:15]
	v_mfma_f32_16x16x32_bf16 v[8:11], v[204:207], v[180:183], v[8:11]
	v_mfma_f32_16x16x32_bf16 v[4:7], v[196:199], v[188:191], v[4:7]
	v_mfma_f32_16x16x32_bf16 v[0:3], v[204:207], v[188:191], v[0:3]
	s_barrier
	ds_read_b128 v[144:147], v142
	ds_read_b128 v[148:151], v142 offset:1024
	ds_read_b128 v[152:155], v142 offset:2048
	ds_read_b128 v[156:159], v142 offset:3072
	s_add_u32 s18, s24, 0x160000
	s_addc_u32 s19, s25, 0
	s_mov_b32 m0, s5
	ds_read_b128 v[160:163], v140 offset:32768
	ds_read_b128 v[164:167], v140 offset:33792
	ds_read_b128 v[168:171], v140 offset:34816
	ds_read_b128 v[172:175], v140 offset:35840
	ds_read_b128 v[176:179], v140 offset:36864
	ds_read_b128 v[180:183], v140 offset:37888
	ds_read_b128 v[184:187], v140 offset:38912
	ds_read_b128 v[188:191], v140 offset:39936
	global_load_lds_dwordx4 v130, s[18:19]
	s_mov_b32 m0, s26
	s_nop 0
	global_load_lds_dwordx4 v128, s[18:19]
	s_waitcnt lgkmcnt(8)
	s_barrier
	s_waitcnt lgkmcnt(0)
	s_waitcnt lgkmcnt(0)
	v_mfma_f32_16x16x32_bf16 v[124:127], v[144:147], v[160:163], v[124:127]
	v_mfma_f32_16x16x32_bf16 v[120:123], v[152:155], v[160:163], v[120:123]
	v_mfma_f32_16x16x32_bf16 v[116:119], v[144:147], v[168:171], v[116:119]
	v_mfma_f32_16x16x32_bf16 v[112:115], v[152:155], v[168:171], v[112:115]
	v_mfma_f32_16x16x32_bf16 v[100:103], v[144:147], v[176:179], v[100:103]
	v_mfma_f32_16x16x32_bf16 v[96:99], v[152:155], v[176:179], v[96:99]
	v_mfma_f32_16x16x32_bf16 v[84:87], v[144:147], v[184:187], v[84:87]
	v_mfma_f32_16x16x32_bf16 v[80:83], v[152:155], v[184:187], v[80:83]
	v_mfma_f32_16x16x32_bf16 v[124:127], v[148:151], v[164:167], v[124:127]
	v_mfma_f32_16x16x32_bf16 v[120:123], v[156:159], v[164:167], v[120:123]
	v_mfma_f32_16x16x32_bf16 v[116:119], v[148:151], v[172:175], v[116:119]
	v_mfma_f32_16x16x32_bf16 v[112:115], v[156:159], v[172:175], v[112:115]
	v_mfma_f32_16x16x32_bf16 v[100:103], v[148:151], v[180:183], v[100:103]
	v_mfma_f32_16x16x32_bf16 v[96:99], v[156:159], v[180:183], v[96:99]
	v_mfma_f32_16x16x32_bf16 v[84:87], v[148:151], v[188:191], v[84:87]
	v_mfma_f32_16x16x32_bf16 v[80:83], v[156:159], v[188:191], v[80:83]
	s_barrier
	s_add_i32 s24, 0, 0x1c000
	s_add_i32 s18, s41, s2
	v_add_u32_e32 v143, s24, v137
	s_add_u32 s98, s22, s12
	s_addc_u32 s99, s23, s13
	s_mov_b32 m0, s18
	ds_read_b128 v[192:195], v143
	ds_read_b128 v[196:199], v143 offset:1024
	ds_read_b128 v[200:203], v143 offset:2048
	ds_read_b128 v[204:207], v143 offset:3072
	global_load_lds_dwordx4 v130, s[98:99]
	s_add_i32 m0, s18, 0x2000
	s_nop 0
	global_load_lds_dwordx4 v128, s[98:99]
	s_barrier
	s_waitcnt lgkmcnt(0)
	s_waitcnt lgkmcnt(0)
	v_mfma_f32_16x16x32_bf16 v[108:111], v[192:195], v[160:163], v[108:111]
	v_mfma_f32_16x16x32_bf16 v[104:107], v[200:203], v[160:163], v[104:107]
	v_mfma_f32_16x16x32_bf16 v[92:95], v[192:195], v[168:171], v[92:95]
	v_mfma_f32_16x16x32_bf16 v[88:91], v[200:203], v[168:171], v[88:91]
	v_mfma_f32_16x16x32_bf16 v[76:79], v[192:195], v[176:179], v[76:79]
	v_mfma_f32_16x16x32_bf16 v[72:75], v[200:203], v[176:179], v[72:75]
	v_mfma_f32_16x16x32_bf16 v[68:71], v[192:195], v[184:187], v[68:71]
	v_mfma_f32_16x16x32_bf16 v[64:67], v[200:203], v[184:187], v[64:67]
	v_mfma_f32_16x16x32_bf16 v[108:111], v[196:199], v[164:167], v[108:111]
	v_mfma_f32_16x16x32_bf16 v[104:107], v[204:207], v[164:167], v[104:107]
	v_mfma_f32_16x16x32_bf16 v[92:95], v[196:199], v[172:175], v[92:95]
	v_mfma_f32_16x16x32_bf16 v[88:91], v[204:207], v[172:175], v[88:91]
	v_mfma_f32_16x16x32_bf16 v[76:79], v[196:199], v[180:183], v[76:79]
	v_mfma_f32_16x16x32_bf16 v[72:75], v[204:207], v[180:183], v[72:75]
	v_mfma_f32_16x16x32_bf16 v[68:71], v[196:199], v[188:191], v[68:71]
	v_mfma_f32_16x16x32_bf16 v[64:67], v[204:207], v[188:191], v[64:67]
	s_mov_b32 m0, s31
	v_lshl_add_u64 v[208:209], v[212:213], 0, s[12:13]
	s_barrier
	ds_read_b128 v[160:163], v140 offset:49152
	ds_read_b128 v[164:167], v140 offset:50176
	ds_read_b128 v[168:171], v140 offset:51200
	ds_read_b128 v[172:175], v140 offset:52224
	ds_read_b128 v[176:179], v140 offset:53248
	ds_read_b128 v[180:183], v140 offset:54272
	ds_read_b128 v[184:187], v140 offset:55296
	ds_read_b128 v[188:191], v140 offset:56320
	global_load_lds_dwordx4 v[208:209], off
	v_lshl_add_u64 v[208:209], v[214:215], 0, s[12:13]
	s_mov_b32 m0, s34
	s_nop 0
	global_load_lds_dwordx4 v[208:209], off
	s_barrier
	s_waitcnt lgkmcnt(0)
	s_waitcnt lgkmcnt(0)
	v_mfma_f32_16x16x32_bf16 v[60:63], v[144:147], v[160:163], v[60:63]
	v_mfma_f32_16x16x32_bf16 v[56:59], v[152:155], v[160:163], v[56:59]
	v_mfma_f32_16x16x32_bf16 v[52:55], v[144:147], v[168:171], v[52:55]
	v_mfma_f32_16x16x32_bf16 v[48:51], v[152:155], v[168:171], v[48:51]
	v_mfma_f32_16x16x32_bf16 v[36:39], v[144:147], v[176:179], v[36:39]
	v_mfma_f32_16x16x32_bf16 v[32:35], v[152:155], v[176:179], v[32:35]
	v_mfma_f32_16x16x32_bf16 v[20:23], v[144:147], v[184:187], v[20:23]
	v_mfma_f32_16x16x32_bf16 v[16:19], v[152:155], v[184:187], v[16:19]
	v_mfma_f32_16x16x32_bf16 v[60:63], v[148:151], v[164:167], v[60:63]
	v_mfma_f32_16x16x32_bf16 v[56:59], v[156:159], v[164:167], v[56:59]
	v_mfma_f32_16x16x32_bf16 v[52:55], v[148:151], v[172:175], v[52:55]
	v_mfma_f32_16x16x32_bf16 v[48:51], v[156:159], v[172:175], v[48:51]
	v_mfma_f32_16x16x32_bf16 v[36:39], v[148:151], v[180:183], v[36:39]
	v_mfma_f32_16x16x32_bf16 v[32:35], v[156:159], v[180:183], v[32:35]
	v_mfma_f32_16x16x32_bf16 v[20:23], v[148:151], v[188:191], v[20:23]
	v_mfma_f32_16x16x32_bf16 v[16:19], v[156:159], v[188:191], v[16:19]
	s_barrier
	s_add_u32 s18, s22, 0x160080
	s_addc_u32 s19, s23, 0
	s_add_i32 s22, s24, s2
	s_mov_b32 m0, s22
	s_nop 0
	global_load_lds_dwordx4 v130, s[18:19]
	s_add_i32 m0, s22, 0x2000
	s_nop 0
	global_load_lds_dwordx4 v128, s[18:19]
	s_waitcnt vmcnt(6)
	s_barrier
	v_mfma_f32_16x16x32_bf16 v[44:47], v[192:195], v[160:163], v[44:47]
	v_mfma_f32_16x16x32_bf16 v[40:43], v[200:203], v[160:163], v[40:43]
	v_mfma_f32_16x16x32_bf16 v[28:31], v[192:195], v[168:171], v[28:31]
	v_mfma_f32_16x16x32_bf16 v[24:27], v[200:203], v[168:171], v[24:27]
	v_mfma_f32_16x16x32_bf16 v[12:15], v[192:195], v[176:179], v[12:15]
	v_mfma_f32_16x16x32_bf16 v[8:11], v[200:203], v[176:179], v[8:11]
	v_mfma_f32_16x16x32_bf16 v[4:7], v[192:195], v[184:187], v[4:7]
	v_mfma_f32_16x16x32_bf16 v[0:3], v[200:203], v[184:187], v[0:3]
	v_mfma_f32_16x16x32_bf16 v[44:47], v[196:199], v[164:167], v[44:47]
	v_mfma_f32_16x16x32_bf16 v[40:43], v[204:207], v[164:167], v[40:43]
	v_mfma_f32_16x16x32_bf16 v[28:31], v[196:199], v[172:175], v[28:31]
	v_mfma_f32_16x16x32_bf16 v[24:27], v[204:207], v[172:175], v[24:27]
	v_mfma_f32_16x16x32_bf16 v[12:15], v[196:199], v[180:183], v[12:15]
	v_mfma_f32_16x16x32_bf16 v[8:11], v[204:207], v[180:183], v[8:11]
	v_mfma_f32_16x16x32_bf16 v[4:7], v[196:199], v[188:191], v[4:7]
	v_mfma_f32_16x16x32_bf16 v[0:3], v[204:207], v[188:191], v[0:3]
	s_add_i32 s61, s61, 2
	s_add_u32 s47, s47, 0x100
	s_addc_u32 s60, s60, 0
	s_cmp_gt_u32 s61, 5
	s_mov_b64 s[18:19], s[20:21]
	s_barrier
	s_cbranch_scc0 .LBB0_2097
	s_ashr_i32 s18, s30, 1
	s_and_b32 s18, s18, 0xfffffe00
	s_lshl_b32 s19, s29, 8
	s_add_i32 s19, s19, s18
	v_add_u32_e32 v146, s19, v136
	v_lshl_or_b32 v144, s28, 8, v138
	v_ashrrev_i32_e32 v147, 31, v146
	v_readlane_b32 s52, v240, 22
	v_ashrrev_i32_e32 v145, 31, v144
	v_lshlrev_b64 v[148:149], 13, v[146:147]
	v_readlane_b32 s66, v240, 36
	v_readlane_b32 s67, v240, 37
	v_lshlrev_b64 v[144:145], 2, v[144:145]
	s_mov_b64 s[18:19], 0x100000
	v_lshl_add_u64 v[148:149], s[66:67], 0, v[148:149]
	v_lshl_add_u64 v[148:149], v[148:149], 0, v[144:145]
	global_store_dwordx4 v[148:149], v[124:127], off
	global_store_dwordx4 v[148:149], v[120:123], off offset:64
	global_store_dwordx4 v[148:149], v[108:111], off offset:512
	global_store_dwordx4 v[148:149], v[104:107], off offset:576
	v_readlane_b32 s53, v240, 23
	v_readlane_b32 s56, v240, 26
	v_or_b32_e32 v104, 16, v146
	v_ashrrev_i32_e32 v105, 31, v104
	v_lshlrev_b64 v[104:105], 13, v[104:105]
	v_lshl_add_u64 v[104:105], s[66:67], 0, v[104:105]
	v_lshl_add_u64 v[104:105], v[104:105], 0, v[144:145]
	global_store_dwordx4 v[104:105], v[116:119], off
	global_store_dwordx4 v[104:105], v[112:115], off offset:64
	global_store_dwordx4 v[104:105], v[92:95], off offset:512
	global_store_dwordx4 v[104:105], v[88:91], off offset:576
	v_readlane_b32 s57, v240, 27
	v_readlane_b32 s60, v240, 30
	v_or_b32_e32 v88, 32, v146
	v_ashrrev_i32_e32 v89, 31, v88
	v_lshlrev_b64 v[88:89], 13, v[88:89]
	v_lshl_add_u64 v[88:89], s[66:67], 0, v[88:89]
	v_lshl_add_u64 v[88:89], v[88:89], 0, v[144:145]
	global_store_dwordx4 v[88:89], v[100:103], off
	global_store_dwordx4 v[88:89], v[96:99], off offset:64
	global_store_dwordx4 v[88:89], v[76:79], off offset:512
	global_store_dwordx4 v[88:89], v[72:75], off offset:576
	v_readlane_b32 s61, v240, 31
	v_readlane_b32 s62, v240, 32
	v_or_b32_e32 v72, 48, v146
	v_ashrrev_i32_e32 v73, 31, v72
	v_lshlrev_b64 v[72:73], 13, v[72:73]
	v_lshl_add_u64 v[72:73], s[66:67], 0, v[72:73]
	v_lshl_add_u64 v[72:73], v[72:73], 0, v[144:145]
	global_store_dwordx4 v[72:73], v[84:87], off
	global_store_dwordx4 v[72:73], v[80:83], off offset:64
	global_store_dwordx4 v[72:73], v[68:71], off offset:512
	global_store_dwordx4 v[72:73], v[64:67], off offset:576
	v_readlane_b32 s63, v240, 33
	s_mov_b32 s30, s43
	v_lshl_add_u64 v[64:65], v[148:149], 0, s[18:19]
	s_mov_b32 s18, 0x100000
	v_add_co_u32_e32 v66, vcc, s18, v148
	s_mov_b64 s[18:19], 0x120000
	s_nop 0
	v_addc_co_u32_e32 v67, vcc, 0, v149, vcc
	global_store_dwordx4 v[66:67], v[60:63], off
	global_store_dwordx4 v[64:65], v[56:59], off offset:64
	global_store_dwordx4 v[64:65], v[44:47], off offset:512
	global_store_dwordx4 v[64:65], v[40:43], off offset:576
	s_mov_b32 s28, s42
	s_mov_b32 s29, s46
	v_lshl_add_u64 v[40:41], v[148:149], 0, s[18:19]
	s_mov_b32 s18, 0x120000
	v_add_co_u32_e32 v42, vcc, s18, v148
	s_mov_b64 s[18:19], 0x140000
	s_nop 0
	v_addc_co_u32_e32 v43, vcc, 0, v149, vcc
	global_store_dwordx4 v[42:43], v[52:55], off
	global_store_dwordx4 v[40:41], v[48:51], off offset:64
	global_store_dwordx4 v[40:41], v[28:31], off offset:512
	global_store_dwordx4 v[40:41], v[24:27], off offset:576
	s_mov_b64 s[20:21], s[10:11]
	v_readlane_b32 s54, v240, 24
	v_lshl_add_u64 v[24:25], v[148:149], 0, s[18:19]
	s_mov_b32 s18, 0x140000
	v_add_co_u32_e32 v26, vcc, s18, v148
	s_mov_b64 s[18:19], 0x160000
	s_nop 0
	v_addc_co_u32_e32 v27, vcc, 0, v149, vcc
	global_store_dwordx4 v[26:27], v[36:39], off
	global_store_dwordx4 v[24:25], v[32:35], off offset:64
	global_store_dwordx4 v[24:25], v[12:15], off offset:512
	global_store_dwordx4 v[24:25], v[8:11], off offset:576
	v_readlane_b32 s55, v240, 25
	v_readlane_b32 s58, v240, 28
	v_add_co_u32_e32 v10, vcc, 0x160000, v148
	v_lshl_add_u64 v[8:9], v[148:149], 0, s[18:19]
	s_nop 0
	v_addc_co_u32_e32 v11, vcc, 0, v149, vcc
	s_and_b64 vcc, exec, s[14:15]
	s_mov_b64 s[18:19], s[16:17]
	v_readlane_b32 s59, v240, 29
	v_readlane_b32 s64, v240, 34
	v_readlane_b32 s65, v240, 35
	global_store_dwordx4 v[10:11], v[20:23], off
	global_store_dwordx4 v[8:9], v[16:19], off offset:64
	global_store_dwordx4 v[8:9], v[4:7], off offset:512
	global_store_dwordx4 v[8:9], v[0:3], off offset:576
	s_cbranch_vccz .LBB0_2090
	s_waitcnt vmcnt(0)
	s_cmpk_gt_u32 s1, 0xff
	s_cbranch_scc1 .LBB0_2101
	s_barrier

.LBB0_2281:
	ds_read_b128 v[140:143], v157
	ds_read_b128 v[144:147], v157 offset:1024
	ds_read_b128 v[148:151], v157 offset:2048
	ds_read_b128 v[160:163], v157 offset:3072
	v_lshl_add_u64 v[152:153], s[28:29], 0, v[132:133]
	s_add_i32 m0, s4, 0xc000
	ds_read_b128 v[164:167], v158
	ds_read_b128 v[168:171], v158 offset:1024
	ds_read_b128 v[172:175], v158 offset:2048
	ds_read_b128 v[176:179], v158 offset:3072
	ds_read_b128 v[180:183], v158 offset:4096
	ds_read_b128 v[184:187], v158 offset:5120
	ds_read_b128 v[188:191], v158 offset:6144
	ds_read_b128 v[192:195], v158 offset:7168
	global_load_lds_dwordx4 v[152:153], off
	s_add_i32 m0, s4, 0xe000
	s_nop 0
	global_load_lds_dwordx4 v134, s[28:29]
	s_waitcnt lgkmcnt(8)
	s_barrier
	s_waitcnt lgkmcnt(0)
	s_waitcnt lgkmcnt(0)
	v_mfma_f32_16x16x32_bf16 v[124:127], v[140:143], v[164:167], v[124:127]
	s_add_u32 s30, s28, 0x100
	s_addc_u32 s31, s29, 0
	s_cmp_eq_u32 s69, 28
	s_cselect_b32 s37, s19, s31
	s_cselect_b32 s36, s65, s30
	s_cselect_b32 s35, s17, s68
	s_cselect_b32 s34, s66, s67
	v_mfma_f32_16x16x32_bf16 v[120:123], v[148:151], v[164:167], v[120:123]
	v_mfma_f32_16x16x32_bf16 v[116:119], v[140:143], v[172:175], v[116:119]
	v_mfma_f32_16x16x32_bf16 v[108:111], v[148:151], v[172:175], v[108:111]
	v_mfma_f32_16x16x32_bf16 v[100:103], v[140:143], v[180:183], v[100:103]
	v_mfma_f32_16x16x32_bf16 v[92:95], v[148:151], v[180:183], v[92:95]
	v_mfma_f32_16x16x32_bf16 v[84:87], v[140:143], v[188:191], v[84:87]
	v_mfma_f32_16x16x32_bf16 v[76:79], v[148:151], v[188:191], v[76:79]
	v_mfma_f32_16x16x32_bf16 v[124:127], v[144:147], v[168:171], v[124:127]
	v_mfma_f32_16x16x32_bf16 v[120:123], v[160:163], v[168:171], v[120:123]
	v_mfma_f32_16x16x32_bf16 v[116:119], v[144:147], v[176:179], v[116:119]
	v_mfma_f32_16x16x32_bf16 v[108:111], v[160:163], v[176:179], v[108:111]
	v_mfma_f32_16x16x32_bf16 v[100:103], v[144:147], v[184:187], v[100:103]
	v_mfma_f32_16x16x32_bf16 v[92:95], v[160:163], v[184:187], v[92:95]
	v_mfma_f32_16x16x32_bf16 v[84:87], v[144:147], v[192:195], v[84:87]
	v_mfma_f32_16x16x32_bf16 v[76:79], v[160:163], v[192:195], v[76:79]
	s_barrier
	s_add_i32 s28, s47, s3
	s_mov_b32 m0, s28
	ds_read_b128 v[196:199], v159
	ds_read_b128 v[200:203], v159 offset:1024
	ds_read_b128 v[204:207], v159 offset:2048
	ds_read_b128 v[208:211], v159 offset:3072
	global_load_lds_dwordx4 v128, s[34:35]
	s_add_i32 m0, s28, 0x2000
	s_nop 0
	global_load_lds_dwordx4 v130, s[34:35]
	s_barrier
	s_waitcnt lgkmcnt(0)
	s_waitcnt lgkmcnt(0)
	v_mfma_f32_16x16x32_bf16 v[112:115], v[196:199], v[164:167], v[112:115]
	v_mfma_f32_16x16x32_bf16 v[104:107], v[204:207], v[164:167], v[104:107]
	v_mfma_f32_16x16x32_bf16 v[96:99], v[196:199], v[172:175], v[96:99]
	v_mfma_f32_16x16x32_bf16 v[88:91], v[204:207], v[172:175], v[88:91]
	v_mfma_f32_16x16x32_bf16 v[80:83], v[196:199], v[180:183], v[80:83]
	v_mfma_f32_16x16x32_bf16 v[72:75], v[204:207], v[180:183], v[72:75]
	v_mfma_f32_16x16x32_bf16 v[68:71], v[196:199], v[188:191], v[68:71]
	v_mfma_f32_16x16x32_bf16 v[64:67], v[204:207], v[188:191], v[64:67]
	v_mfma_f32_16x16x32_bf16 v[112:115], v[200:203], v[168:171], v[112:115]
	v_mfma_f32_16x16x32_bf16 v[104:107], v[208:211], v[168:171], v[104:107]
	v_mfma_f32_16x16x32_bf16 v[96:99], v[200:203], v[176:179], v[96:99]
	v_mfma_f32_16x16x32_bf16 v[88:91], v[208:211], v[176:179], v[88:91]
	v_mfma_f32_16x16x32_bf16 v[80:83], v[200:203], v[184:187], v[80:83]
	v_mfma_f32_16x16x32_bf16 v[72:75], v[208:211], v[184:187], v[72:75]
	v_mfma_f32_16x16x32_bf16 v[68:71], v[200:203], v[192:195], v[68:71]
	v_mfma_f32_16x16x32_bf16 v[64:67], v[208:211], v[192:195], v[64:67]
	s_mov_b32 m0, s4
	v_lshl_add_u64 v[214:215], s[36:37], 0, v[128:129]
	s_barrier
	ds_read_b128 v[164:167], v158 offset:16384
	ds_read_b128 v[168:171], v158 offset:17408
	ds_read_b128 v[172:175], v158 offset:18432
	ds_read_b128 v[176:179], v158 offset:19456
	ds_read_b128 v[180:183], v158 offset:20480
	ds_read_b128 v[184:187], v158 offset:21504
	ds_read_b128 v[188:191], v158 offset:22528
	ds_read_b128 v[192:195], v158 offset:23552
	global_load_lds_dwordx4 v128, s[36:37]
	v_lshl_add_u64 v[216:217], s[36:37], 0, v[130:131]
	s_mov_b32 m0, s5
	s_nop 0
	global_load_lds_dwordx4 v130, s[36:37]
	s_barrier
	s_waitcnt lgkmcnt(0)
	s_waitcnt lgkmcnt(0)
	v_mfma_f32_16x16x32_bf16 v[60:63], v[140:143], v[164:167], v[60:63]
	v_mfma_f32_16x16x32_bf16 v[56:59], v[148:151], v[164:167], v[56:59]
	v_mfma_f32_16x16x32_bf16 v[52:55], v[140:143], v[172:175], v[52:55]
	v_mfma_f32_16x16x32_bf16 v[48:51], v[148:151], v[172:175], v[48:51]
	v_mfma_f32_16x16x32_bf16 v[40:43], v[140:143], v[180:183], v[40:43]
	v_mfma_f32_16x16x32_bf16 v[32:35], v[148:151], v[180:183], v[32:35]
	v_mfma_f32_16x16x32_bf16 v[24:27], v[140:143], v[188:191], v[24:27]
	v_mfma_f32_16x16x32_bf16 v[16:19], v[148:151], v[188:191], v[16:19]
	v_mfma_f32_16x16x32_bf16 v[60:63], v[144:147], v[168:171], v[60:63]
	v_mfma_f32_16x16x32_bf16 v[56:59], v[160:163], v[168:171], v[56:59]
	v_mfma_f32_16x16x32_bf16 v[52:55], v[144:147], v[176:179], v[52:55]
	v_mfma_f32_16x16x32_bf16 v[48:51], v[160:163], v[176:179], v[48:51]
	v_mfma_f32_16x16x32_bf16 v[40:43], v[144:147], v[184:187], v[40:43]
	v_mfma_f32_16x16x32_bf16 v[32:35], v[160:163], v[184:187], v[32:35]
	v_mfma_f32_16x16x32_bf16 v[24:27], v[144:147], v[192:195], v[24:27]
	v_mfma_f32_16x16x32_bf16 v[16:19], v[160:163], v[192:195], v[16:19]
	s_barrier
	s_add_u32 s28, s34, 0x80000
	s_addc_u32 s29, s35, 0
	s_add_i32 s70, s62, s3
	s_mov_b32 m0, s70
	s_nop 0
	global_load_lds_dwordx4 v128, s[28:29]
	s_add_i32 m0, s70, 0x2000
	s_nop 0
	global_load_lds_dwordx4 v130, s[28:29]
	s_waitcnt vmcnt(6)
	s_barrier
	v_mfma_f32_16x16x32_bf16 v[44:47], v[196:199], v[164:167], v[44:47]
	v_mfma_f32_16x16x32_bf16 v[36:39], v[204:207], v[164:167], v[36:39]
	v_mfma_f32_16x16x32_bf16 v[28:31], v[196:199], v[172:175], v[28:31]
	v_mfma_f32_16x16x32_bf16 v[20:23], v[204:207], v[172:175], v[20:23]
	v_mfma_f32_16x16x32_bf16 v[12:15], v[196:199], v[180:183], v[12:15]
	v_mfma_f32_16x16x32_bf16 v[8:11], v[204:207], v[180:183], v[8:11]
	v_mfma_f32_16x16x32_bf16 v[4:7], v[196:199], v[188:191], v[4:7]
	v_mfma_f32_16x16x32_bf16 v[0:3], v[204:207], v[188:191], v[0:3]
	v_mfma_f32_16x16x32_bf16 v[44:47], v[200:203], v[168:171], v[44:47]
	v_mfma_f32_16x16x32_bf16 v[36:39], v[208:211], v[168:171], v[36:39]
	v_mfma_f32_16x16x32_bf16 v[28:31], v[200:203], v[176:179], v[28:31]
	v_mfma_f32_16x16x32_bf16 v[20:23], v[208:211], v[176:179], v[20:23]
	v_mfma_f32_16x16x32_bf16 v[12:15], v[200:203], v[184:187], v[12:15]
	v_mfma_f32_16x16x32_bf16 v[8:11], v[208:211], v[184:187], v[8:11]
	v_mfma_f32_16x16x32_bf16 v[4:7], v[200:203], v[192:195], v[4:7]
	v_mfma_f32_16x16x32_bf16 v[0:3], v[208:211], v[192:195], v[0:3]
	s_add_i32 s70, 0, 0x18000
	v_add_u32_e32 v160, s70, v155
	s_barrier
	ds_read_b128 v[140:143], v160
	ds_read_b128 v[144:147], v160 offset:1024
	ds_read_b128 v[148:151], v160 offset:2048
	ds_read_b128 v[160:163], v160 offset:3072
	s_add_u32 s28, s36, 0x80000
	s_addc_u32 s29, s37, 0
	s_mov_b32 m0, s38
	ds_read_b128 v[164:167], v158 offset:32768
	ds_read_b128 v[168:171], v158 offset:33792
	ds_read_b128 v[172:175], v158 offset:34816
	ds_read_b128 v[176:179], v158 offset:35840
	ds_read_b128 v[180:183], v158 offset:36864
	ds_read_b128 v[184:187], v158 offset:37888
	ds_read_b128 v[188:191], v158 offset:38912
	ds_read_b128 v[192:195], v158 offset:39936
	global_load_lds_dwordx4 v128, s[28:29]
	s_mov_b32 m0, s39
	s_nop 0
	global_load_lds_dwordx4 v130, s[28:29]
	s_waitcnt lgkmcnt(8)
	s_barrier
	s_waitcnt lgkmcnt(0)
	s_waitcnt lgkmcnt(0)
	v_mfma_f32_16x16x32_bf16 v[124:127], v[140:143], v[164:167], v[124:127]
	v_mfma_f32_16x16x32_bf16 v[120:123], v[148:151], v[164:167], v[120:123]
	v_mfma_f32_16x16x32_bf16 v[116:119], v[140:143], v[172:175], v[116:119]
	v_mfma_f32_16x16x32_bf16 v[108:111], v[148:151], v[172:175], v[108:111]
	v_mfma_f32_16x16x32_bf16 v[100:103], v[140:143], v[180:183], v[100:103]
	v_mfma_f32_16x16x32_bf16 v[92:95], v[148:151], v[180:183], v[92:95]
	v_mfma_f32_16x16x32_bf16 v[84:87], v[140:143], v[188:191], v[84:87]
	v_mfma_f32_16x16x32_bf16 v[76:79], v[148:151], v[188:191], v[76:79]
	v_mfma_f32_16x16x32_bf16 v[124:127], v[144:147], v[168:171], v[124:127]
	v_mfma_f32_16x16x32_bf16 v[120:123], v[160:163], v[168:171], v[120:123]
	v_mfma_f32_16x16x32_bf16 v[116:119], v[144:147], v[176:179], v[116:119]
	v_mfma_f32_16x16x32_bf16 v[108:111], v[160:163], v[176:179], v[108:111]
	v_mfma_f32_16x16x32_bf16 v[100:103], v[144:147], v[184:187], v[100:103]
	v_mfma_f32_16x16x32_bf16 v[92:95], v[160:163], v[184:187], v[92:95]
	v_mfma_f32_16x16x32_bf16 v[84:87], v[144:147], v[192:195], v[84:87]
	v_mfma_f32_16x16x32_bf16 v[76:79], v[160:163], v[192:195], v[76:79]
	s_barrier
	s_add_i32 s36, 0, 0x1c000
	s_add_i32 s28, s70, s3
	v_add_u32_e32 v208, s36, v155
	s_add_u32 s98, s34, s12
	s_addc_u32 s99, s35, s13
	s_mov_b32 m0, s28
	ds_read_b128 v[196:199], v208
	ds_read_b128 v[200:203], v208 offset:1024
	ds_read_b128 v[204:207], v208 offset:2048
	ds_read_b128 v[208:211], v208 offset:3072
	global_load_lds_dwordx4 v128, s[98:99]
	s_add_i32 m0, s28, 0x2000
	s_nop 0
	global_load_lds_dwordx4 v130, s[98:99]
	s_barrier
	s_waitcnt lgkmcnt(0)
	s_waitcnt lgkmcnt(0)
	v_mfma_f32_16x16x32_bf16 v[112:115], v[196:199], v[164:167], v[112:115]
	v_mfma_f32_16x16x32_bf16 v[104:107], v[204:207], v[164:167], v[104:107]
	v_mfma_f32_16x16x32_bf16 v[96:99], v[196:199], v[172:175], v[96:99]
	v_mfma_f32_16x16x32_bf16 v[88:91], v[204:207], v[172:175], v[88:91]
	v_mfma_f32_16x16x32_bf16 v[80:83], v[196:199], v[180:183], v[80:83]
	v_mfma_f32_16x16x32_bf16 v[72:75], v[204:207], v[180:183], v[72:75]
	v_mfma_f32_16x16x32_bf16 v[68:71], v[196:199], v[188:191], v[68:71]
	v_mfma_f32_16x16x32_bf16 v[64:67], v[204:207], v[188:191], v[64:67]
	v_mfma_f32_16x16x32_bf16 v[112:115], v[200:203], v[168:171], v[112:115]
	v_mfma_f32_16x16x32_bf16 v[104:107], v[208:211], v[168:171], v[104:107]
	v_mfma_f32_16x16x32_bf16 v[96:99], v[200:203], v[176:179], v[96:99]
	v_mfma_f32_16x16x32_bf16 v[88:91], v[208:211], v[176:179], v[88:91]
	v_mfma_f32_16x16x32_bf16 v[80:83], v[200:203], v[184:187], v[80:83]
	v_mfma_f32_16x16x32_bf16 v[72:75], v[208:211], v[184:187], v[72:75]
	v_mfma_f32_16x16x32_bf16 v[68:71], v[200:203], v[192:195], v[68:71]
	v_mfma_f32_16x16x32_bf16 v[64:67], v[208:211], v[192:195], v[64:67]
	s_mov_b32 m0, s42
	v_lshl_add_u64 v[152:153], v[214:215], 0, s[12:13]
	s_barrier
	ds_read_b128 v[164:167], v158 offset:49152
	ds_read_b128 v[168:171], v158 offset:50176
	ds_read_b128 v[172:175], v158 offset:51200
	ds_read_b128 v[176:179], v158 offset:52224
	ds_read_b128 v[180:183], v158 offset:53248
	ds_read_b128 v[184:187], v158 offset:54272
	ds_read_b128 v[188:191], v158 offset:55296
	ds_read_b128 v[192:195], v158 offset:56320
	global_load_lds_dwordx4 v[152:153], off
	v_lshl_add_u64 v[152:153], v[216:217], 0, s[12:13]
	s_mov_b32 m0, s43
	s_nop 0
	global_load_lds_dwordx4 v[152:153], off
	s_barrier
	s_waitcnt lgkmcnt(0)
	s_waitcnt lgkmcnt(0)
	v_mfma_f32_16x16x32_bf16 v[60:63], v[140:143], v[164:167], v[60:63]
	v_mfma_f32_16x16x32_bf16 v[56:59], v[148:151], v[164:167], v[56:59]
	v_mfma_f32_16x16x32_bf16 v[52:55], v[140:143], v[172:175], v[52:55]
	v_mfma_f32_16x16x32_bf16 v[48:51], v[148:151], v[172:175], v[48:51]
	v_mfma_f32_16x16x32_bf16 v[40:43], v[140:143], v[180:183], v[40:43]
	v_mfma_f32_16x16x32_bf16 v[32:35], v[148:151], v[180:183], v[32:35]
	v_mfma_f32_16x16x32_bf16 v[24:27], v[140:143], v[188:191], v[24:27]
	v_mfma_f32_16x16x32_bf16 v[16:19], v[148:151], v[188:191], v[16:19]
	v_mfma_f32_16x16x32_bf16 v[60:63], v[144:147], v[168:171], v[60:63]
	v_mfma_f32_16x16x32_bf16 v[56:59], v[160:163], v[168:171], v[56:59]
	v_mfma_f32_16x16x32_bf16 v[52:55], v[144:147], v[176:179], v[52:55]
	v_mfma_f32_16x16x32_bf16 v[48:51], v[160:163], v[176:179], v[48:51]
	v_mfma_f32_16x16x32_bf16 v[40:43], v[144:147], v[184:187], v[40:43]
	v_mfma_f32_16x16x32_bf16 v[32:35], v[160:163], v[184:187], v[32:35]
	v_mfma_f32_16x16x32_bf16 v[24:27], v[144:147], v[192:195], v[24:27]
	v_mfma_f32_16x16x32_bf16 v[16:19], v[160:163], v[192:195], v[16:19]
	s_barrier
	s_add_u32 s28, s34, 0x80080
	s_addc_u32 s29, s35, 0
	s_add_i32 s34, s36, s3
	s_mov_b32 m0, s34
	s_nop 0
	global_load_lds_dwordx4 v128, s[28:29]
	s_add_i32 m0, s34, 0x2000
	s_nop 0
	global_load_lds_dwordx4 v130, s[28:29]
	s_waitcnt vmcnt(6)
	s_barrier
	v_mfma_f32_16x16x32_bf16 v[44:47], v[196:199], v[164:167], v[44:47]
	v_mfma_f32_16x16x32_bf16 v[36:39], v[204:207], v[164:167], v[36:39]
	v_mfma_f32_16x16x32_bf16 v[28:31], v[196:199], v[172:175], v[28:31]
	v_mfma_f32_16x16x32_bf16 v[20:23], v[204:207], v[172:175], v[20:23]
	v_mfma_f32_16x16x32_bf16 v[12:15], v[196:199], v[180:183], v[12:15]
	v_mfma_f32_16x16x32_bf16 v[8:11], v[204:207], v[180:183], v[8:11]
	v_mfma_f32_16x16x32_bf16 v[4:7], v[196:199], v[188:191], v[4:7]
	v_mfma_f32_16x16x32_bf16 v[0:3], v[204:207], v[188:191], v[0:3]
	v_mfma_f32_16x16x32_bf16 v[44:47], v[200:203], v[168:171], v[44:47]
	v_mfma_f32_16x16x32_bf16 v[36:39], v[208:211], v[168:171], v[36:39]
	v_mfma_f32_16x16x32_bf16 v[28:31], v[200:203], v[176:179], v[28:31]
	v_mfma_f32_16x16x32_bf16 v[20:23], v[208:211], v[176:179], v[20:23]
	v_mfma_f32_16x16x32_bf16 v[12:15], v[200:203], v[184:187], v[12:15]
	v_mfma_f32_16x16x32_bf16 v[8:11], v[208:211], v[184:187], v[8:11]
	v_mfma_f32_16x16x32_bf16 v[4:7], v[200:203], v[192:195], v[4:7]
	v_mfma_f32_16x16x32_bf16 v[0:3], v[208:211], v[192:195], v[0:3]
	s_add_i32 s69, s69, 2
	s_add_u32 s67, s67, 0x100
	s_addc_u32 s68, s68, 0
	s_cmp_gt_u32 s69, 29
	s_mov_b64 s[28:29], s[30:31]
	s_barrier
	s_cbranch_scc0 .LBB0_2281
	v_lshl_add_u32 v148, s26, 8, v154
	v_lshl_or_b32 v146, s27, 8, v156
	s_cmp_eq_u32 s27, 48
	v_ashrrev_i32_e32 v149, 31, v148
	s_mov_b64 s[26:27], -1
	v_or_b32_e32 v144, 16, v148
	v_or_b32_e32 v142, 32, v148
	v_or_b32_e32 v140, 48, v148
	s_cbranch_scc1 .LBB0_2284
	v_readlane_b32 s64, v240, 22
	v_readlane_b32 s72, v240, 30
	v_readlane_b32 s73, v240, 31
	v_ashrrev_i32_e32 v147, 31, v146
	v_lshlrev_b64 v[152:153], 1, v[146:147]
	v_mov_b64_e32 v[150:151], s[72:73]
	v_mad_i64_i32 v[160:161], s[26:27], v148, s41, v[150:151]
	v_pk_add_f32 v[162:163], v[126:127], 0 op_sel_hi:[1,0]
	v_pk_add_f32 v[164:165], v[124:125], 0 op_sel_hi:[1,0]
	v_lshl_add_u64 v[160:161], v[160:161], 0, v[152:153]
	v_cvt_pk_bf16_f32 v164, v164, v165
	v_cvt_pk_bf16_f32 v165, v162, v163
	global_store_dwordx2 v[160:161], v[164:165], off
	v_pk_add_f32 v[162:163], v[122:123], 0 op_sel_hi:[1,0]
	v_pk_add_f32 v[164:165], v[120:121], 0 op_sel_hi:[1,0]
	v_add_u32_e32 v141, 0x80, v148
	v_cvt_pk_bf16_f32 v164, v164, v165
	v_cvt_pk_bf16_f32 v165, v162, v163
	global_store_dwordx2 v[160:161], v[164:165], off offset:32
	v_pk_add_f32 v[162:163], v[114:115], 0 op_sel_hi:[1,0]
	v_pk_add_f32 v[164:165], v[112:113], 0 op_sel_hi:[1,0]
	v_readlane_b32 s65, v240, 23
	v_cvt_pk_bf16_f32 v164, v164, v165
	v_cvt_pk_bf16_f32 v165, v162, v163
	global_store_dwordx2 v[160:161], v[164:165], off offset:256
	v_pk_add_f32 v[162:163], v[106:107], 0 op_sel_hi:[1,0]
	v_pk_add_f32 v[164:165], v[104:105], 0 op_sel_hi:[1,0]
	v_readlane_b32 s66, v240, 24
	v_cvt_pk_bf16_f32 v164, v164, v165
	v_cvt_pk_bf16_f32 v165, v162, v163
	global_store_dwordx2 v[160:161], v[164:165], off offset:288
	v_mad_i64_i32 v[160:161], s[26:27], v144, s41, v[150:151]
	v_pk_add_f32 v[162:163], v[118:119], 0 op_sel_hi:[1,0]
	v_pk_add_f32 v[164:165], v[116:117], 0 op_sel_hi:[1,0]
	v_lshl_add_u64 v[160:161], v[160:161], 0, v[152:153]
	v_cvt_pk_bf16_f32 v164, v164, v165
	v_cvt_pk_bf16_f32 v165, v162, v163
	global_store_dwordx2 v[160:161], v[164:165], off
	v_pk_add_f32 v[162:163], v[110:111], 0 op_sel_hi:[1,0]
	v_pk_add_f32 v[164:165], v[108:109], 0 op_sel_hi:[1,0]
	v_readlane_b32 s67, v240, 25
	v_cvt_pk_bf16_f32 v164, v164, v165
	v_cvt_pk_bf16_f32 v165, v162, v163
	global_store_dwordx2 v[160:161], v[164:165], off offset:32
	v_pk_add_f32 v[162:163], v[98:99], 0 op_sel_hi:[1,0]
	v_pk_add_f32 v[164:165], v[96:97], 0 op_sel_hi:[1,0]
	v_readlane_b32 s68, v240, 26
	v_cvt_pk_bf16_f32 v164, v164, v165
	v_cvt_pk_bf16_f32 v165, v162, v163
	global_store_dwordx2 v[160:161], v[164:165], off offset:256
	v_pk_add_f32 v[162:163], v[90:91], 0 op_sel_hi:[1,0]
	v_pk_add_f32 v[164:165], v[88:89], 0 op_sel_hi:[1,0]
	v_readlane_b32 s69, v240, 27
	v_cvt_pk_bf16_f32 v164, v164, v165
	v_cvt_pk_bf16_f32 v165, v162, v163
	global_store_dwordx2 v[160:161], v[164:165], off offset:288
	v_mad_i64_i32 v[160:161], s[26:27], v142, s41, v[150:151]
	v_pk_add_f32 v[162:163], v[102:103], 0 op_sel_hi:[1,0]
	v_pk_add_f32 v[164:165], v[100:101], 0 op_sel_hi:[1,0]
	v_lshl_add_u64 v[160:161], v[160:161], 0, v[152:153]
	v_cvt_pk_bf16_f32 v164, v164, v165
	v_cvt_pk_bf16_f32 v165, v162, v163
	global_store_dwordx2 v[160:161], v[164:165], off
	v_pk_add_f32 v[162:163], v[94:95], 0 op_sel_hi:[1,0]
	v_pk_add_f32 v[164:165], v[92:93], 0 op_sel_hi:[1,0]
	v_readlane_b32 s70, v240, 28
	v_cvt_pk_bf16_f32 v164, v164, v165
	v_cvt_pk_bf16_f32 v165, v162, v163
	global_store_dwordx2 v[160:161], v[164:165], off offset:32
	v_pk_add_f32 v[162:163], v[82:83], 0 op_sel_hi:[1,0]
	v_pk_add_f32 v[164:165], v[80:81], 0 op_sel_hi:[1,0]
	v_readlane_b32 s71, v240, 29
	v_cvt_pk_bf16_f32 v164, v164, v165
	v_cvt_pk_bf16_f32 v165, v162, v163
	global_store_dwordx2 v[160:161], v[164:165], off offset:256
	v_pk_add_f32 v[162:163], v[74:75], 0 op_sel_hi:[1,0]
	v_pk_add_f32 v[164:165], v[72:73], 0 op_sel_hi:[1,0]
	v_readlane_b32 s74, v240, 32
	v_cvt_pk_bf16_f32 v164, v164, v165
	v_cvt_pk_bf16_f32 v165, v162, v163
	global_store_dwordx2 v[160:161], v[164:165], off offset:288
	v_mad_i64_i32 v[160:161], s[26:27], v140, s41, v[150:151]
	v_pk_add_f32 v[162:163], v[86:87], 0 op_sel_hi:[1,0]
	v_pk_add_f32 v[164:165], v[84:85], 0 op_sel_hi:[1,0]
	v_lshl_add_u64 v[160:161], v[160:161], 0, v[152:153]
	v_cvt_pk_bf16_f32 v164, v164, v165
	v_cvt_pk_bf16_f32 v165, v162, v163
	global_store_dwordx2 v[160:161], v[164:165], off
	v_pk_add_f32 v[162:163], v[78:79], 0 op_sel_hi:[1,0]
	v_pk_add_f32 v[164:165], v[76:77], 0 op_sel_hi:[1,0]
	v_readlane_b32 s75, v240, 33
	v_cvt_pk_bf16_f32 v164, v164, v165
	v_cvt_pk_bf16_f32 v165, v162, v163
	global_store_dwordx2 v[160:161], v[164:165], off offset:32
	v_pk_add_f32 v[162:163], v[70:71], 0 op_sel_hi:[1,0]
	v_pk_add_f32 v[164:165], v[68:69], 0 op_sel_hi:[1,0]
	v_readlane_b32 s76, v240, 34
	v_cvt_pk_bf16_f32 v164, v164, v165
	v_cvt_pk_bf16_f32 v165, v162, v163
	global_store_dwordx2 v[160:161], v[164:165], off offset:256
	v_pk_add_f32 v[162:163], v[66:67], 0 op_sel_hi:[1,0]
	v_pk_add_f32 v[164:165], v[64:65], 0 op_sel_hi:[1,0]
	v_readlane_b32 s77, v240, 35
	v_cvt_pk_bf16_f32 v164, v164, v165
	v_cvt_pk_bf16_f32 v165, v162, v163
	global_store_dwordx2 v[160:161], v[164:165], off offset:288
	v_mad_i64_i32 v[160:161], s[26:27], v141, s41, v[150:151]
	v_pk_add_f32 v[162:163], v[62:63], 0 op_sel_hi:[1,0]
	v_pk_add_f32 v[164:165], v[60:61], 0 op_sel_hi:[1,0]
	v_lshl_add_u64 v[160:161], v[160:161], 0, v[152:153]
	v_cvt_pk_bf16_f32 v164, v164, v165
	v_cvt_pk_bf16_f32 v165, v162, v163
	global_store_dwordx2 v[160:161], v[164:165], off
	v_pk_add_f32 v[162:163], v[58:59], 0 op_sel_hi:[1,0]
	v_pk_add_f32 v[164:165], v[56:57], 0 op_sel_hi:[1,0]
	v_add_u32_e32 v141, 0x90, v148
	v_cvt_pk_bf16_f32 v164, v164, v165
	v_cvt_pk_bf16_f32 v165, v162, v163
	global_store_dwordx2 v[160:161], v[164:165], off offset:32
	v_pk_add_f32 v[162:163], v[46:47], 0 op_sel_hi:[1,0]
	v_pk_add_f32 v[164:165], v[44:45], 0 op_sel_hi:[1,0]
	v_readlane_b32 s78, v240, 36
	v_cvt_pk_bf16_f32 v164, v164, v165
	v_cvt_pk_bf16_f32 v165, v162, v163
	global_store_dwordx2 v[160:161], v[164:165], off offset:256
	v_pk_add_f32 v[162:163], v[38:39], 0 op_sel_hi:[1,0]
	v_pk_add_f32 v[164:165], v[36:37], 0 op_sel_hi:[1,0]
	v_readlane_b32 s79, v240, 37
	v_cvt_pk_bf16_f32 v164, v164, v165
	v_cvt_pk_bf16_f32 v165, v162, v163
	global_store_dwordx2 v[160:161], v[164:165], off offset:288
	v_mad_i64_i32 v[160:161], s[26:27], v141, s41, v[150:151]
	v_pk_add_f32 v[162:163], v[54:55], 0 op_sel_hi:[1,0]
	v_pk_add_f32 v[164:165], v[52:53], 0 op_sel_hi:[1,0]
	v_lshl_add_u64 v[160:161], v[160:161], 0, v[152:153]
	v_cvt_pk_bf16_f32 v164, v164, v165
	v_cvt_pk_bf16_f32 v165, v162, v163
	global_store_dwordx2 v[160:161], v[164:165], off
	v_pk_add_f32 v[162:163], v[50:51], 0 op_sel_hi:[1,0]
	v_pk_add_f32 v[164:165], v[48:49], 0 op_sel_hi:[1,0]
	v_add_u32_e32 v141, 0xa0, v148
	v_cvt_pk_bf16_f32 v164, v164, v165
	v_cvt_pk_bf16_f32 v165, v162, v163
	global_store_dwordx2 v[160:161], v[164:165], off offset:32
	v_pk_add_f32 v[162:163], v[30:31], 0 op_sel_hi:[1,0]
	v_pk_add_f32 v[164:165], v[28:29], 0 op_sel_hi:[1,0]
	s_nop 0
	v_cvt_pk_bf16_f32 v164, v164, v165
	v_cvt_pk_bf16_f32 v165, v162, v163
	global_store_dwordx2 v[160:161], v[164:165], off offset:256
	v_pk_add_f32 v[162:163], v[22:23], 0 op_sel_hi:[1,0]
	v_pk_add_f32 v[164:165], v[20:21], 0 op_sel_hi:[1,0]
	s_nop 0
	v_cvt_pk_bf16_f32 v164, v164, v165
	v_cvt_pk_bf16_f32 v165, v162, v163
	global_store_dwordx2 v[160:161], v[164:165], off offset:288
	v_mad_i64_i32 v[160:161], s[26:27], v141, s41, v[150:151]
	v_pk_add_f32 v[162:163], v[42:43], 0 op_sel_hi:[1,0]
	v_pk_add_f32 v[164:165], v[40:41], 0 op_sel_hi:[1,0]
	v_lshl_add_u64 v[160:161], v[160:161], 0, v[152:153]
	v_cvt_pk_bf16_f32 v164, v164, v165
	v_cvt_pk_bf16_f32 v165, v162, v163
	global_store_dwordx2 v[160:161], v[164:165], off
	v_pk_add_f32 v[162:163], v[34:35], 0 op_sel_hi:[1,0]
	v_pk_add_f32 v[164:165], v[32:33], 0 op_sel_hi:[1,0]
	v_add_u32_e32 v141, 0xb0, v148
	v_cvt_pk_bf16_f32 v164, v164, v165
	v_cvt_pk_bf16_f32 v165, v162, v163
	global_store_dwordx2 v[160:161], v[164:165], off offset:32
	v_pk_add_f32 v[162:163], v[14:15], 0 op_sel_hi:[1,0]
	v_pk_add_f32 v[164:165], v[12:13], 0 op_sel_hi:[1,0]
	v_mad_i64_i32 v[150:151], s[26:27], v141, s41, v[150:151]
	v_cvt_pk_bf16_f32 v164, v164, v165
	v_cvt_pk_bf16_f32 v165, v162, v163
	global_store_dwordx2 v[160:161], v[164:165], off offset:256
	v_pk_add_f32 v[162:163], v[10:11], 0 op_sel_hi:[1,0]
	v_pk_add_f32 v[164:165], v[8:9], 0 op_sel_hi:[1,0]
	v_lshl_add_u64 v[150:151], v[150:151], 0, v[152:153]
	v_cvt_pk_bf16_f32 v164, v164, v165
	v_cvt_pk_bf16_f32 v165, v162, v163
	global_store_dwordx2 v[160:161], v[164:165], off offset:288
	v_pk_add_f32 v[152:153], v[26:27], 0 op_sel_hi:[1,0]
	v_pk_add_f32 v[160:161], v[24:25], 0 op_sel_hi:[1,0]
	s_mov_b64 s[26:27], 0
	v_cvt_pk_bf16_f32 v160, v160, v161
	v_cvt_pk_bf16_f32 v161, v152, v153
	global_store_dwordx2 v[150:151], v[160:161], off
	v_pk_add_f32 v[152:153], v[18:19], 0 op_sel_hi:[1,0]
	v_pk_add_f32 v[160:161], v[16:17], 0 op_sel_hi:[1,0]
	s_nop 0
	v_cvt_pk_bf16_f32 v160, v160, v161
	v_cvt_pk_bf16_f32 v161, v152, v153
	global_store_dwordx2 v[150:151], v[160:161], off offset:32
	v_pk_add_f32 v[152:153], v[6:7], 0 op_sel_hi:[1,0]
	v_pk_add_f32 v[160:161], v[4:5], 0 op_sel_hi:[1,0]
	s_nop 0
	v_cvt_pk_bf16_f32 v160, v160, v161
	v_cvt_pk_bf16_f32 v161, v152, v153
	global_store_dwordx2 v[150:151], v[160:161], off offset:256
	v_pk_add_f32 v[152:153], v[2:3], 0 op_sel_hi:[1,0]
	v_pk_add_f32 v[160:161], v[0:1], 0 op_sel_hi:[1,0]
	s_nop 0
	v_cvt_pk_bf16_f32 v160, v160, v161
	v_cvt_pk_bf16_f32 v161, v152, v153
	global_store_dwordx2 v[150:151], v[160:161], off offset:288

.LBB0_2676:
	ds_read_b128 v[128:131], v151
	ds_read_b128 v[144:147], v151 offset:1024
	ds_read_b128 v[154:157], v151 offset:2048
	ds_read_b128 v[158:161], v151 offset:3072
	s_add_i32 m0, s4, 0xc000
	ds_read_b128 v[162:165], v152
	ds_read_b128 v[166:169], v152 offset:1024
	ds_read_b128 v[170:173], v152 offset:2048
	ds_read_b128 v[174:177], v152 offset:3072
	ds_read_b128 v[178:181], v152 offset:4096
	ds_read_b128 v[182:185], v152 offset:5120
	ds_read_b128 v[186:189], v152 offset:6144
	ds_read_b128 v[190:193], v152 offset:7168
	global_load_lds_dwordx4 v136, s[26:27]
	v_lshl_add_u64 v[194:195], s[26:27], 0, v[138:139]
	s_add_i32 m0, s4, 0xe000
	s_nop 0
	global_load_lds_dwordx4 v[194:195], off
	s_waitcnt lgkmcnt(8)
	s_barrier
	s_waitcnt lgkmcnt(0)
	s_waitcnt lgkmcnt(0)
	v_mfma_f32_16x16x32_bf16 v[124:127], v[128:131], v[162:165], v[124:127]
	s_add_u32 s28, s26, 0x100
	s_addc_u32 s29, s27, 0
	s_cmp_eq_u32 s62, 60
	s_cselect_b32 s35, s17, s29
	s_cselect_b32 s34, s52, s28
	s_cselect_b32 s31, s15, s57
	s_cselect_b32 s30, s53, s56
	v_mfma_f32_16x16x32_bf16 v[92:95], v[154:157], v[162:165], v[92:95]
	v_mfma_f32_16x16x32_bf16 v[120:123], v[128:131], v[170:173], v[120:123]
	v_mfma_f32_16x16x32_bf16 v[88:91], v[154:157], v[170:173], v[88:91]
	v_mfma_f32_16x16x32_bf16 v[116:119], v[128:131], v[178:181], v[116:119]
	v_mfma_f32_16x16x32_bf16 v[84:87], v[154:157], v[178:181], v[84:87]
	v_mfma_f32_16x16x32_bf16 v[112:115], v[128:131], v[186:189], v[112:115]
	v_mfma_f32_16x16x32_bf16 v[80:83], v[154:157], v[186:189], v[80:83]
	v_mfma_f32_16x16x32_bf16 v[124:127], v[144:147], v[166:169], v[124:127]
	v_mfma_f32_16x16x32_bf16 v[92:95], v[158:161], v[166:169], v[92:95]
	v_mfma_f32_16x16x32_bf16 v[120:123], v[144:147], v[174:177], v[120:123]
	v_mfma_f32_16x16x32_bf16 v[88:91], v[158:161], v[174:177], v[88:91]
	v_mfma_f32_16x16x32_bf16 v[116:119], v[144:147], v[182:185], v[116:119]
	v_mfma_f32_16x16x32_bf16 v[84:87], v[158:161], v[182:185], v[84:87]
	v_mfma_f32_16x16x32_bf16 v[112:115], v[144:147], v[190:193], v[112:115]
	v_mfma_f32_16x16x32_bf16 v[80:83], v[158:161], v[190:193], v[80:83]
	s_barrier
	s_add_i32 s26, s43, s3
	v_lshl_add_u64 v[210:211], s[30:31], 0, v[132:133]
	s_mov_b32 m0, s26
	ds_read_b128 v[194:197], v153
	ds_read_b128 v[198:201], v153 offset:1024
	ds_read_b128 v[202:205], v153 offset:2048
	ds_read_b128 v[206:209], v153 offset:3072
	global_load_lds_dwordx4 v[210:211], off
	s_add_i32 m0, s26, 0x2000
	s_nop 0
	global_load_lds_dwordx4 v134, s[30:31]
	s_barrier
	s_waitcnt lgkmcnt(0)
	s_waitcnt lgkmcnt(0)
	v_mfma_f32_16x16x32_bf16 v[76:79], v[194:197], v[162:165], v[76:79]
	v_mfma_f32_16x16x32_bf16 v[48:51], v[202:205], v[162:165], v[48:51]
	v_mfma_f32_16x16x32_bf16 v[68:71], v[194:197], v[170:173], v[68:71]
	v_mfma_f32_16x16x32_bf16 v[40:43], v[202:205], v[170:173], v[40:43]
	v_mfma_f32_16x16x32_bf16 v[60:63], v[194:197], v[178:181], v[60:63]
	v_mfma_f32_16x16x32_bf16 v[36:39], v[202:205], v[178:181], v[36:39]
	v_mfma_f32_16x16x32_bf16 v[52:55], v[194:197], v[186:189], v[52:55]
	v_mfma_f32_16x16x32_bf16 v[28:31], v[202:205], v[186:189], v[28:31]
	v_mfma_f32_16x16x32_bf16 v[76:79], v[198:201], v[166:169], v[76:79]
	v_mfma_f32_16x16x32_bf16 v[48:51], v[206:209], v[166:169], v[48:51]
	v_mfma_f32_16x16x32_bf16 v[68:71], v[198:201], v[174:177], v[68:71]
	v_mfma_f32_16x16x32_bf16 v[40:43], v[206:209], v[174:177], v[40:43]
	v_mfma_f32_16x16x32_bf16 v[60:63], v[198:201], v[182:185], v[60:63]
	v_mfma_f32_16x16x32_bf16 v[36:39], v[206:209], v[182:185], v[36:39]
	v_mfma_f32_16x16x32_bf16 v[52:55], v[198:201], v[190:193], v[52:55]
	v_mfma_f32_16x16x32_bf16 v[28:31], v[206:209], v[190:193], v[28:31]
	s_mov_b32 m0, s4
	v_lshl_add_u64 v[214:215], s[34:35], 0, v[132:133]
	s_barrier
	ds_read_b128 v[162:165], v152 offset:16384
	ds_read_b128 v[166:169], v152 offset:17408
	ds_read_b128 v[170:173], v152 offset:18432
	ds_read_b128 v[174:177], v152 offset:19456
	ds_read_b128 v[178:181], v152 offset:20480
	ds_read_b128 v[182:185], v152 offset:21504
	ds_read_b128 v[186:189], v152 offset:22528
	ds_read_b128 v[190:193], v152 offset:23552
	global_load_lds_dwordx4 v[214:215], off
	v_lshl_add_u64 v[216:217], s[34:35], 0, v[134:135]
	s_mov_b32 m0, s5
	s_nop 0
	global_load_lds_dwordx4 v134, s[34:35]
	s_barrier
	s_waitcnt lgkmcnt(0)
	s_waitcnt lgkmcnt(0)
	v_mfma_f32_16x16x32_bf16 v[108:111], v[128:131], v[162:165], v[108:111]
	v_mfma_f32_16x16x32_bf16 v[72:75], v[154:157], v[162:165], v[72:75]
	v_mfma_f32_16x16x32_bf16 v[104:107], v[128:131], v[170:173], v[104:107]
	v_mfma_f32_16x16x32_bf16 v[64:67], v[154:157], v[170:173], v[64:67]
	v_mfma_f32_16x16x32_bf16 v[100:103], v[128:131], v[178:181], v[100:103]
	v_mfma_f32_16x16x32_bf16 v[56:59], v[154:157], v[178:181], v[56:59]
	v_mfma_f32_16x16x32_bf16 v[96:99], v[128:131], v[186:189], v[96:99]
	v_mfma_f32_16x16x32_bf16 v[44:47], v[154:157], v[186:189], v[44:47]
	v_mfma_f32_16x16x32_bf16 v[108:111], v[144:147], v[166:169], v[108:111]
	v_mfma_f32_16x16x32_bf16 v[72:75], v[158:161], v[166:169], v[72:75]
	v_mfma_f32_16x16x32_bf16 v[104:107], v[144:147], v[174:177], v[104:107]
	v_mfma_f32_16x16x32_bf16 v[64:67], v[158:161], v[174:177], v[64:67]
	v_mfma_f32_16x16x32_bf16 v[100:103], v[144:147], v[182:185], v[100:103]
	v_mfma_f32_16x16x32_bf16 v[56:59], v[158:161], v[182:185], v[56:59]
	v_mfma_f32_16x16x32_bf16 v[96:99], v[144:147], v[190:193], v[96:99]
	v_mfma_f32_16x16x32_bf16 v[44:47], v[158:161], v[190:193], v[44:47]
	s_barrier
	s_add_u32 s26, s30, 0x100000
	s_addc_u32 s27, s31, 0
	s_add_i32 s63, s46, s3
	v_lshl_add_u64 v[128:129], s[26:27], 0, v[132:133]
	s_mov_b32 m0, s63
	s_nop 0
	global_load_lds_dwordx4 v[128:129], off
	s_add_i32 m0, s63, 0x2000
	s_nop 0
	global_load_lds_dwordx4 v134, s[26:27]
	s_waitcnt vmcnt(6)
	s_barrier
	v_mfma_f32_16x16x32_bf16 v[32:35], v[194:197], v[162:165], v[32:35]
	v_mfma_f32_16x16x32_bf16 v[12:15], v[202:205], v[162:165], v[12:15]
	v_mfma_f32_16x16x32_bf16 v[24:27], v[194:197], v[170:173], v[24:27]
	v_mfma_f32_16x16x32_bf16 v[8:11], v[202:205], v[170:173], v[8:11]
	v_mfma_f32_16x16x32_bf16 v[20:23], v[194:197], v[178:181], v[20:23]
	v_mfma_f32_16x16x32_bf16 v[4:7], v[202:205], v[178:181], v[4:7]
	v_mfma_f32_16x16x32_bf16 v[16:19], v[194:197], v[186:189], v[16:19]
	v_mfma_f32_16x16x32_bf16 v[0:3], v[202:205], v[186:189], v[0:3]
	v_mfma_f32_16x16x32_bf16 v[32:35], v[198:201], v[166:169], v[32:35]
	v_mfma_f32_16x16x32_bf16 v[12:15], v[206:209], v[166:169], v[12:15]
	v_mfma_f32_16x16x32_bf16 v[24:27], v[198:201], v[174:177], v[24:27]
	v_mfma_f32_16x16x32_bf16 v[8:11], v[206:209], v[174:177], v[8:11]
	v_mfma_f32_16x16x32_bf16 v[20:23], v[198:201], v[182:185], v[20:23]
	v_mfma_f32_16x16x32_bf16 v[4:7], v[206:209], v[182:185], v[4:7]
	v_mfma_f32_16x16x32_bf16 v[16:19], v[198:201], v[190:193], v[16:19]
	v_mfma_f32_16x16x32_bf16 v[0:3], v[206:209], v[190:193], v[0:3]
	s_add_i32 s63, 0, 0x18000
	v_add_u32_e32 v158, s63, v149
	s_barrier
	ds_read_b128 v[128:131], v158
	ds_read_b128 v[144:147], v158 offset:1024
	ds_read_b128 v[154:157], v158 offset:2048
	ds_read_b128 v[158:161], v158 offset:3072
	s_add_u32 s26, s34, 0x100000
	s_addc_u32 s27, s35, 0
	s_mov_b32 m0, s23
	v_lshl_add_u64 v[194:195], s[26:27], 0, v[132:133]
	ds_read_b128 v[162:165], v152 offset:32768
	ds_read_b128 v[166:169], v152 offset:33792
	ds_read_b128 v[170:173], v152 offset:34816
	ds_read_b128 v[174:177], v152 offset:35840
	ds_read_b128 v[178:181], v152 offset:36864
	ds_read_b128 v[182:185], v152 offset:37888
	ds_read_b128 v[186:189], v152 offset:38912
	ds_read_b128 v[190:193], v152 offset:39936
	global_load_lds_dwordx4 v[194:195], off
	s_mov_b32 m0, s36
	s_nop 0
	global_load_lds_dwordx4 v134, s[26:27]
	s_waitcnt lgkmcnt(8)
	s_barrier
	s_waitcnt lgkmcnt(0)
	s_waitcnt lgkmcnt(0)
	v_mfma_f32_16x16x32_bf16 v[124:127], v[128:131], v[162:165], v[124:127]
	v_mfma_f32_16x16x32_bf16 v[92:95], v[154:157], v[162:165], v[92:95]
	v_mfma_f32_16x16x32_bf16 v[120:123], v[128:131], v[170:173], v[120:123]
	v_mfma_f32_16x16x32_bf16 v[88:91], v[154:157], v[170:173], v[88:91]
	v_mfma_f32_16x16x32_bf16 v[116:119], v[128:131], v[178:181], v[116:119]
	v_mfma_f32_16x16x32_bf16 v[84:87], v[154:157], v[178:181], v[84:87]
	v_mfma_f32_16x16x32_bf16 v[112:115], v[128:131], v[186:189], v[112:115]
	v_mfma_f32_16x16x32_bf16 v[80:83], v[154:157], v[186:189], v[80:83]
	v_mfma_f32_16x16x32_bf16 v[124:127], v[144:147], v[166:169], v[124:127]
	v_mfma_f32_16x16x32_bf16 v[92:95], v[158:161], v[166:169], v[92:95]
	v_mfma_f32_16x16x32_bf16 v[120:123], v[144:147], v[174:177], v[120:123]
	v_mfma_f32_16x16x32_bf16 v[88:91], v[158:161], v[174:177], v[88:91]
	v_mfma_f32_16x16x32_bf16 v[116:119], v[144:147], v[182:185], v[116:119]
	v_mfma_f32_16x16x32_bf16 v[84:87], v[158:161], v[182:185], v[84:87]
	v_mfma_f32_16x16x32_bf16 v[112:115], v[144:147], v[190:193], v[112:115]
	v_mfma_f32_16x16x32_bf16 v[80:83], v[158:161], v[190:193], v[80:83]
	s_barrier
	s_add_i32 s34, 0, 0x1c000
	s_add_i32 s26, s63, s3
	v_add_u32_e32 v206, s34, v149
	v_lshl_add_u64 v[210:211], v[210:211], 0, s[12:13]
	s_mov_b32 m0, s26
	ds_read_b128 v[194:197], v206
	ds_read_b128 v[198:201], v206 offset:1024
	ds_read_b128 v[202:205], v206 offset:2048
	ds_read_b128 v[206:209], v206 offset:3072
	global_load_lds_dwordx4 v[210:211], off
	s_add_u32 s98, s30, s12
	s_addc_u32 s99, s31, s13
	s_add_i32 m0, s26, 0x2000
	s_nop 0
	global_load_lds_dwordx4 v134, s[98:99]
	s_barrier
	s_waitcnt lgkmcnt(0)
	s_waitcnt lgkmcnt(0)
	v_mfma_f32_16x16x32_bf16 v[76:79], v[194:197], v[162:165], v[76:79]
	v_mfma_f32_16x16x32_bf16 v[48:51], v[202:205], v[162:165], v[48:51]
	v_mfma_f32_16x16x32_bf16 v[68:71], v[194:197], v[170:173], v[68:71]
	v_mfma_f32_16x16x32_bf16 v[40:43], v[202:205], v[170:173], v[40:43]
	v_mfma_f32_16x16x32_bf16 v[60:63], v[194:197], v[178:181], v[60:63]
	v_mfma_f32_16x16x32_bf16 v[36:39], v[202:205], v[178:181], v[36:39]
	v_mfma_f32_16x16x32_bf16 v[52:55], v[194:197], v[186:189], v[52:55]
	v_mfma_f32_16x16x32_bf16 v[28:31], v[202:205], v[186:189], v[28:31]
	v_mfma_f32_16x16x32_bf16 v[76:79], v[198:201], v[166:169], v[76:79]
	v_mfma_f32_16x16x32_bf16 v[48:51], v[206:209], v[166:169], v[48:51]
	v_mfma_f32_16x16x32_bf16 v[68:71], v[198:201], v[174:177], v[68:71]
	v_mfma_f32_16x16x32_bf16 v[40:43], v[206:209], v[174:177], v[40:43]
	v_mfma_f32_16x16x32_bf16 v[60:63], v[198:201], v[182:185], v[60:63]
	v_mfma_f32_16x16x32_bf16 v[36:39], v[206:209], v[182:185], v[36:39]
	v_mfma_f32_16x16x32_bf16 v[52:55], v[198:201], v[190:193], v[52:55]
	v_mfma_f32_16x16x32_bf16 v[28:31], v[206:209], v[190:193], v[28:31]
	s_mov_b32 m0, s38
	v_lshl_add_u64 v[210:211], v[214:215], 0, s[12:13]
	s_barrier
	ds_read_b128 v[162:165], v152 offset:49152
	ds_read_b128 v[166:169], v152 offset:50176
	ds_read_b128 v[170:173], v152 offset:51200
	ds_read_b128 v[174:177], v152 offset:52224
	ds_read_b128 v[178:181], v152 offset:53248
	ds_read_b128 v[182:185], v152 offset:54272
	ds_read_b128 v[186:189], v152 offset:55296
	ds_read_b128 v[190:193], v152 offset:56320
	global_load_lds_dwordx4 v[210:211], off
	v_lshl_add_u64 v[210:211], v[216:217], 0, s[12:13]
	s_mov_b32 m0, s39
	s_nop 0
	global_load_lds_dwordx4 v[210:211], off
	s_barrier
	s_waitcnt lgkmcnt(0)
	s_waitcnt lgkmcnt(0)
	v_mfma_f32_16x16x32_bf16 v[108:111], v[128:131], v[162:165], v[108:111]
	v_mfma_f32_16x16x32_bf16 v[72:75], v[154:157], v[162:165], v[72:75]
	v_mfma_f32_16x16x32_bf16 v[104:107], v[128:131], v[170:173], v[104:107]
	v_mfma_f32_16x16x32_bf16 v[64:67], v[154:157], v[170:173], v[64:67]
	v_mfma_f32_16x16x32_bf16 v[100:103], v[128:131], v[178:181], v[100:103]
	v_mfma_f32_16x16x32_bf16 v[56:59], v[154:157], v[178:181], v[56:59]
	v_mfma_f32_16x16x32_bf16 v[96:99], v[128:131], v[186:189], v[96:99]
	v_mfma_f32_16x16x32_bf16 v[44:47], v[154:157], v[186:189], v[44:47]
	v_mfma_f32_16x16x32_bf16 v[108:111], v[144:147], v[166:169], v[108:111]
	v_mfma_f32_16x16x32_bf16 v[72:75], v[158:161], v[166:169], v[72:75]
	v_mfma_f32_16x16x32_bf16 v[104:107], v[144:147], v[174:177], v[104:107]
	v_mfma_f32_16x16x32_bf16 v[64:67], v[158:161], v[174:177], v[64:67]
	v_mfma_f32_16x16x32_bf16 v[100:103], v[144:147], v[182:185], v[100:103]
	v_mfma_f32_16x16x32_bf16 v[56:59], v[158:161], v[182:185], v[56:59]
	v_mfma_f32_16x16x32_bf16 v[96:99], v[144:147], v[190:193], v[96:99]
	v_mfma_f32_16x16x32_bf16 v[44:47], v[158:161], v[190:193], v[44:47]
	s_barrier
	s_add_u32 s26, s30, 0x100080
	s_addc_u32 s27, s31, 0
	s_add_i32 s30, s34, s3
	v_lshl_add_u64 v[128:129], s[26:27], 0, v[132:133]
	s_mov_b32 m0, s30
	s_nop 0
	global_load_lds_dwordx4 v[128:129], off
	s_add_i32 m0, s30, 0x2000
	s_nop 0
	global_load_lds_dwordx4 v134, s[26:27]
	s_waitcnt vmcnt(6)
	s_barrier
	v_mfma_f32_16x16x32_bf16 v[32:35], v[194:197], v[162:165], v[32:35]
	v_mfma_f32_16x16x32_bf16 v[12:15], v[202:205], v[162:165], v[12:15]
	v_mfma_f32_16x16x32_bf16 v[24:27], v[194:197], v[170:173], v[24:27]
	v_mfma_f32_16x16x32_bf16 v[8:11], v[202:205], v[170:173], v[8:11]
	v_mfma_f32_16x16x32_bf16 v[20:23], v[194:197], v[178:181], v[20:23]
	v_mfma_f32_16x16x32_bf16 v[4:7], v[202:205], v[178:181], v[4:7]
	v_mfma_f32_16x16x32_bf16 v[16:19], v[194:197], v[186:189], v[16:19]
	v_mfma_f32_16x16x32_bf16 v[0:3], v[202:205], v[186:189], v[0:3]
	v_mfma_f32_16x16x32_bf16 v[32:35], v[198:201], v[166:169], v[32:35]
	v_mfma_f32_16x16x32_bf16 v[12:15], v[206:209], v[166:169], v[12:15]
	v_mfma_f32_16x16x32_bf16 v[24:27], v[198:201], v[174:177], v[24:27]
	v_mfma_f32_16x16x32_bf16 v[8:11], v[206:209], v[174:177], v[8:11]
	v_mfma_f32_16x16x32_bf16 v[20:23], v[198:201], v[182:185], v[20:23]
	v_mfma_f32_16x16x32_bf16 v[4:7], v[206:209], v[182:185], v[4:7]
	v_mfma_f32_16x16x32_bf16 v[16:19], v[198:201], v[190:193], v[16:19]
	v_mfma_f32_16x16x32_bf16 v[0:3], v[206:209], v[190:193], v[0:3]
	s_add_i32 s62, s62, 2
	s_add_u32 s56, s56, 0x100
	s_addc_u32 s57, s57, 0
	s_cmp_gt_u32 s62, 61
	s_mov_b64 s[26:27], s[28:29]
	s_barrier
	s_cbranch_scc0 .LBB0_2676
	s_cmp_lt_u32 s22, 32
	s_movk_i32 s15, 0x3000
	s_cselect_b32 s15, s15, 0x6000
	s_cmp_gt_i32 s22, 15
	v_lshl_add_u32 v158, s22, 8, v148
	s_cselect_b32 s15, s15, 0
	v_readlane_b32 s48, v240, 22
	v_lshl_or_b32 v128, s47, 8, v150
	s_lshl_b32 s15, s15, 2
	v_ashrrev_i32_e32 v159, 31, v158
	v_readlane_b32 s49, v240, 23
	v_readlane_b32 s50, v240, 24
	v_readlane_b32 s51, v240, 25
	v_readlane_b32 s52, v240, 26
	v_readlane_b32 s53, v240, 27
	s_add_u32 s26, s41, s15
	v_ashrrev_i32_e32 v129, 31, v128
	v_lshlrev_b64 v[146:147], 13, v[158:159]
	v_readlane_b32 s54, v240, 28
	v_readlane_b32 s55, v240, 29
	s_mov_b64 s[44:45], s[48:49]
	s_mov_b64 s[48:49], s[52:53]
	s_addc_u32 s27, s42, 0
	v_lshlrev_b64 v[160:161], 2, v[128:129]
	v_lshl_add_u64 v[146:147], s[48:49], 0, v[146:147]
	v_lshl_add_u64 v[144:145], s[26:27], 0, v[160:161]
	v_lshl_add_u64 v[146:147], v[146:147], 0, v[160:161]
	s_mov_b32 s15, 0x100000
	s_mov_b64 s[26:27], 0x100000
	v_readlane_b32 s58, v240, 32
	v_readlane_b32 s59, v240, 33
	v_readlane_b32 s62, v240, 36
	v_readlane_b32 s63, v240, 37
	s_mov_b32 s47, s14
	s_mov_b32 s22, s16
	s_mov_b64 s[28:29], s[20:21]
	v_readlane_b32 s56, v240, 30
	v_readlane_b32 s57, v240, 31
	v_readlane_b32 s60, v240, 34
	v_readlane_b32 s61, v240, 35
	s_mov_b64 s[50:51], s[54:55]
	v_or_b32_e32 v162, 16, v158
	v_ashrrev_i32_e32 v163, 31, v162
	v_lshlrev_b64 v[164:165], 13, v[162:163]
	v_lshl_add_u64 v[162:163], s[48:49], 0, v[164:165]
	v_lshl_add_u64 v[164:165], v[162:163], 0, v[160:161]
	v_or_b32_e32 v162, 32, v158
	v_ashrrev_i32_e32 v163, 31, v162
	v_lshlrev_b64 v[166:167], 13, v[162:163]
	v_lshl_add_u64 v[162:163], s[48:49], 0, v[166:167]
	v_lshl_add_u64 v[166:167], v[162:163], 0, v[160:161]
	v_or_b32_e32 v162, 48, v158
	v_ashrrev_i32_e32 v163, 31, v162
	v_lshlrev_b64 v[168:169], 13, v[162:163]
	v_lshl_add_u64 v[162:163], s[48:49], 0, v[168:169]
	v_lshl_add_u64 v[168:169], v[162:163], 0, v[160:161]
	v_add_co_u32_e32 v162, vcc, s15, v146
	s_mov_b32 s15, 0x120000
	s_nop 0
	v_addc_co_u32_e32 v163, vcc, 0, v147, vcc
	v_lshl_add_u64 v[170:171], v[146:147], 0, s[26:27]
	s_mov_b64 s[26:27], 0x120000
	v_add_co_u32_e32 v172, vcc, s15, v146
	s_mov_b32 s15, 0x140000
	s_nop 0
	v_addc_co_u32_e32 v173, vcc, 0, v147, vcc
	v_lshl_add_u64 v[174:175], v[146:147], 0, s[26:27]
	s_mov_b64 s[26:27], 0x140000
	v_add_co_u32_e32 v176, vcc, s15, v146
	s_mov_b32 s15, 0x160000
	s_nop 0
	v_addc_co_u32_e32 v177, vcc, 0, v147, vcc
	v_lshl_add_u64 v[178:179], v[146:147], 0, s[26:27]
	s_mov_b64 s[26:27], 0x160000
	v_add_co_u32_e32 v180, vcc, s15, v146
	v_lshl_add_u64 v[182:183], v[146:147], 0, s[26:27]
	s_nop 0
	v_addc_co_u32_e32 v181, vcc, 0, v147, vcc
	s_and_b64 vcc, exec, s[10:11]
	s_mov_b64 s[26:27], s[18:19]
	global_load_dwordx4 v[184:187], v[144:145], off
	global_load_dwordx4 v[188:191], v[146:147], off
	v_pk_add_f32 v[126:127], v[126:127], 0 op_sel_hi:[1,0]
	v_pk_add_f32 v[124:125], v[124:125], 0 op_sel_hi:[1,0]
	v_pk_add_f32 v[122:123], v[122:123], 0 op_sel_hi:[1,0]
	v_pk_add_f32 v[120:121], v[120:121], 0 op_sel_hi:[1,0]
	v_pk_add_f32 v[118:119], v[118:119], 0 op_sel_hi:[1,0]
	v_pk_add_f32 v[116:117], v[116:117], 0 op_sel_hi:[1,0]
	v_pk_add_f32 v[114:115], v[114:115], 0 op_sel_hi:[1,0]
	v_pk_add_f32 v[112:113], v[112:113], 0 op_sel_hi:[1,0]
	v_pk_add_f32 v[110:111], v[110:111], 0 op_sel_hi:[1,0]
	v_pk_add_f32 v[108:109], v[108:109], 0 op_sel_hi:[1,0]
	v_pk_add_f32 v[106:107], v[106:107], 0 op_sel_hi:[1,0]
	v_pk_add_f32 v[104:105], v[104:105], 0 op_sel_hi:[1,0]
	v_pk_add_f32 v[102:103], v[102:103], 0 op_sel_hi:[1,0]
	v_pk_add_f32 v[100:101], v[100:101], 0 op_sel_hi:[1,0]
	v_pk_add_f32 v[98:99], v[98:99], 0 op_sel_hi:[1,0]
	v_pk_add_f32 v[96:97], v[96:97], 0 op_sel_hi:[1,0]
	v_pk_add_f32 v[94:95], v[94:95], 0 op_sel_hi:[1,0]
	v_pk_add_f32 v[92:93], v[92:93], 0 op_sel_hi:[1,0]
	v_pk_add_f32 v[90:91], v[90:91], 0 op_sel_hi:[1,0]
	v_pk_add_f32 v[88:89], v[88:89], 0 op_sel_hi:[1,0]
	v_pk_add_f32 v[86:87], v[86:87], 0 op_sel_hi:[1,0]
	v_pk_add_f32 v[84:85], v[84:85], 0 op_sel_hi:[1,0]
	v_pk_add_f32 v[82:83], v[82:83], 0 op_sel_hi:[1,0]
	v_pk_add_f32 v[80:81], v[80:81], 0 op_sel_hi:[1,0]
	v_pk_add_f32 v[74:75], v[74:75], 0 op_sel_hi:[1,0]
	v_pk_add_f32 v[72:73], v[72:73], 0 op_sel_hi:[1,0]
	v_pk_add_f32 v[66:67], v[66:67], 0 op_sel_hi:[1,0]
	v_pk_add_f32 v[64:65], v[64:65], 0 op_sel_hi:[1,0]
	v_pk_add_f32 v[58:59], v[58:59], 0 op_sel_hi:[1,0]
	v_pk_add_f32 v[56:57], v[56:57], 0 op_sel_hi:[1,0]
	v_pk_add_f32 v[46:47], v[46:47], 0 op_sel_hi:[1,0]
	v_pk_add_f32 v[44:45], v[44:45], 0 op_sel_hi:[1,0]
	v_pk_add_f32 v[62:63], v[62:63], 0 op_sel_hi:[1,0]
	v_pk_add_f32 v[60:61], v[60:61], 0 op_sel_hi:[1,0]
	v_pk_add_f32 v[54:55], v[54:55], 0 op_sel_hi:[1,0]
	v_pk_add_f32 v[52:53], v[52:53], 0 op_sel_hi:[1,0]
	v_pk_add_f32 v[34:35], v[34:35], 0 op_sel_hi:[1,0]
	v_pk_add_f32 v[32:33], v[32:33], 0 op_sel_hi:[1,0]
	v_pk_add_f32 v[26:27], v[26:27], 0 op_sel_hi:[1,0]
	v_pk_add_f32 v[24:25], v[24:25], 0 op_sel_hi:[1,0]
	v_pk_add_f32 v[22:23], v[22:23], 0 op_sel_hi:[1,0]
	v_pk_add_f32 v[20:21], v[20:21], 0 op_sel_hi:[1,0]
	v_pk_add_f32 v[18:19], v[18:19], 0 op_sel_hi:[1,0]
	v_pk_add_f32 v[16:17], v[16:17], 0 op_sel_hi:[1,0]
	v_pk_add_f32 v[14:15], v[14:15], 0 op_sel_hi:[1,0]
	v_pk_add_f32 v[12:13], v[12:13], 0 op_sel_hi:[1,0]
	v_pk_add_f32 v[10:11], v[10:11], 0 op_sel_hi:[1,0]
	v_pk_add_f32 v[8:9], v[8:9], 0 op_sel_hi:[1,0]
	v_pk_add_f32 v[6:7], v[6:7], 0 op_sel_hi:[1,0]
	v_pk_add_f32 v[4:5], v[4:5], 0 op_sel_hi:[1,0]
	v_pk_add_f32 v[2:3], v[2:3], 0 op_sel_hi:[1,0]
	v_pk_add_f32 v[0:1], v[0:1], 0 op_sel_hi:[1,0]
	s_waitcnt vmcnt(0)
	v_pk_fma_f32 v[126:127], v[126:127], v[186:187], v[190:191]
	v_pk_fma_f32 v[124:125], v[124:125], v[184:185], v[188:189]
	global_store_dwordx4 v[146:147], v[124:127], off
	global_load_dwordx4 v[188:191], v[164:165], off
	global_load_dwordx4 v[192:195], v[166:167], off
	global_load_dwordx4 v[196:199], v[168:169], off
	global_load_dwordx4 v[200:203], v[162:163], off
	global_load_dwordx4 v[204:207], v[172:173], off
	global_load_dwordx4 v[208:211], v[176:177], off
	global_load_dwordx4 v[212:215], v[180:181], off
	global_load_dwordx4 v[216:219], v[144:145], off offset:64
	global_load_dwordx4 v[220:223], v[146:147], off offset:64
	global_load_dwordx4 v[224:227], v[164:165], off offset:64
	global_load_dwordx4 v[228:231], v[166:167], off offset:64
	global_load_dwordx4 v[232:235], v[168:169], off offset:64
	s_waitcnt vmcnt(11)
	v_pk_fma_f32 v[122:123], v[122:123], v[186:187], v[190:191]
	v_pk_fma_f32 v[120:121], v[120:121], v[184:185], v[188:189]
	global_store_dwordx4 v[164:165], v[120:123], off
	global_load_dwordx4 v[188:191], v[170:171], off offset:64
	s_waitcnt vmcnt(12)
	v_pk_fma_f32 v[118:119], v[118:119], v[186:187], v[194:195]
	v_pk_fma_f32 v[116:117], v[116:117], v[184:185], v[192:193]
	global_store_dwordx4 v[166:167], v[116:119], off
	global_load_dwordx4 v[192:195], v[174:175], off offset:64
	s_waitcnt vmcnt(13)
	v_pk_fma_f32 v[114:115], v[114:115], v[186:187], v[198:199]
	v_pk_fma_f32 v[112:113], v[112:113], v[184:185], v[196:197]
	global_store_dwordx4 v[168:169], v[112:115], off
	global_load_dwordx4 v[196:199], v[178:179], off offset:64
	s_waitcnt vmcnt(14)
	v_pk_fma_f32 v[110:111], v[110:111], v[186:187], v[202:203]
	v_pk_fma_f32 v[108:109], v[108:109], v[184:185], v[200:201]
	global_store_dwordx4 v[162:163], v[108:111], off
	global_load_dwordx4 v[200:203], v[182:183], off offset:64
	s_waitcnt vmcnt(15)
	v_pk_fma_f32 v[106:107], v[106:107], v[186:187], v[206:207]
	v_pk_fma_f32 v[104:105], v[104:105], v[184:185], v[204:205]
	global_store_dwordx4 v[172:173], v[104:107], off
	global_load_dwordx4 v[204:207], v[144:145], off offset:512
	s_waitcnt vmcnt(16)
	v_pk_fma_f32 v[102:103], v[102:103], v[186:187], v[210:211]
	v_pk_fma_f32 v[100:101], v[100:101], v[184:185], v[208:209]
	global_store_dwordx4 v[176:177], v[100:103], off
	global_load_dwordx4 v[208:211], v[146:147], off offset:512
	s_waitcnt vmcnt(17)
	v_pk_fma_f32 v[98:99], v[98:99], v[186:187], v[214:215]
	v_pk_fma_f32 v[96:97], v[96:97], v[184:185], v[212:213]
	global_store_dwordx4 v[180:181], v[96:99], off
	global_load_dwordx4 v[184:187], v[164:165], off offset:512
	s_waitcnt vmcnt(17)
	v_pk_fma_f32 v[94:95], v[94:95], v[218:219], v[222:223]
	v_pk_fma_f32 v[92:93], v[92:93], v[216:217], v[220:221]
	global_store_dwordx4 v[146:147], v[92:95], off offset:64
	global_load_dwordx4 v[212:215], v[166:167], off offset:512
	global_load_dwordx4 v[220:223], v[168:169], off offset:512
	s_waitcnt vmcnt(19)
	v_pk_fma_f32 v[90:91], v[90:91], v[218:219], v[226:227]
	v_pk_fma_f32 v[88:89], v[88:89], v[216:217], v[224:225]
	global_store_dwordx4 v[164:165], v[88:91], off offset:64
	global_load_dwordx4 v[224:227], v[170:171], off offset:512
	s_waitcnt vmcnt(20)
	v_pk_fma_f32 v[86:87], v[86:87], v[218:219], v[230:231]
	v_pk_fma_f32 v[84:85], v[84:85], v[216:217], v[228:229]
	global_store_dwordx4 v[166:167], v[84:87], off offset:64
	global_load_dwordx4 v[228:231], v[174:175], off offset:512
	s_waitcnt vmcnt(21)
	v_pk_fma_f32 v[82:83], v[82:83], v[218:219], v[234:235]
	v_pk_fma_f32 v[80:81], v[80:81], v[216:217], v[232:233]
	global_store_dwordx4 v[168:169], v[80:83], off offset:64
	global_load_dwordx4 v[232:235], v[178:179], off offset:512
	s_waitcnt vmcnt(21)
	v_pk_fma_f32 v[74:75], v[74:75], v[218:219], v[190:191]
	v_pk_fma_f32 v[72:73], v[72:73], v[216:217], v[188:189]
	global_store_dwordx4 v[170:171], v[72:75], off offset:64
	global_load_dwordx4 v[188:191], v[182:183], off offset:512
	s_waitcnt vmcnt(21)
	v_pk_fma_f32 v[66:67], v[66:67], v[218:219], v[194:195]
	v_pk_fma_f32 v[64:65], v[64:65], v[216:217], v[192:193]
	global_store_dwordx4 v[174:175], v[64:67], off offset:64
	global_load_dwordx4 v[192:195], v[144:145], off offset:576
	s_waitcnt vmcnt(21)
	v_pk_fma_f32 v[58:59], v[58:59], v[218:219], v[198:199]
	v_pk_fma_f32 v[56:57], v[56:57], v[216:217], v[196:197]
	global_store_dwordx4 v[178:179], v[56:59], off offset:64
	global_load_dwordx4 v[196:199], v[146:147], off offset:576
	v_pk_add_f32 v[64:65], v[78:79], 0 op_sel_hi:[1,0]
	v_pk_add_f32 v[66:67], v[76:77], 0 op_sel_hi:[1,0]
	s_waitcnt vmcnt(21)
	v_pk_fma_f32 v[46:47], v[46:47], v[218:219], v[202:203]
	v_pk_fma_f32 v[44:45], v[44:45], v[216:217], v[200:201]
	global_store_dwordx4 v[182:183], v[44:47], off offset:64
	global_load_dwordx4 v[200:203], v[164:165], off offset:576
	s_waitcnt vmcnt(19)
	v_pk_fma_f32 v[58:59], v[64:65], v[206:207], v[210:211]
	v_pk_fma_f32 v[56:57], v[66:67], v[204:205], v[208:209]
	global_store_dwordx4 v[146:147], v[56:59], off offset:512
	global_load_dwordx4 v[208:211], v[166:167], off offset:576
	global_load_dwordx4 v[216:219], v[168:169], off offset:576
	v_pk_add_f32 v[64:65], v[70:71], 0 op_sel_hi:[1,0]
	v_pk_add_f32 v[66:67], v[68:69], 0 op_sel_hi:[1,0]
	s_waitcnt vmcnt(20)
	v_pk_fma_f32 v[58:59], v[64:65], v[206:207], v[186:187]
	v_pk_fma_f32 v[56:57], v[66:67], v[204:205], v[184:185]
	global_store_dwordx4 v[164:165], v[56:59], off offset:512
	global_load_dwordx4 v[184:187], v[170:171], off offset:576
	s_waitcnt vmcnt(20)
	v_pk_fma_f32 v[58:59], v[62:63], v[206:207], v[214:215]
	v_pk_fma_f32 v[56:57], v[60:61], v[204:205], v[212:213]
	global_store_dwordx4 v[166:167], v[56:59], off offset:512
	global_load_dwordx4 v[212:215], v[174:175], off offset:576
	s_waitcnt vmcnt(21)
	v_pk_fma_f32 v[54:55], v[54:55], v[206:207], v[222:223]
	v_pk_fma_f32 v[52:53], v[52:53], v[204:205], v[220:221]
	global_store_dwordx4 v[168:169], v[52:55], off offset:512
	global_load_dwordx4 v[220:223], v[178:179], off offset:576
	s_waitcnt vmcnt(21)
	v_pk_fma_f32 v[34:35], v[34:35], v[206:207], v[226:227]
	v_pk_fma_f32 v[32:33], v[32:33], v[204:205], v[224:225]
	global_store_dwordx4 v[170:171], v[32:35], off offset:512
	global_load_dwordx4 v[224:227], v[182:183], off offset:576
	s_waitcnt vmcnt(21)
	v_pk_fma_f32 v[26:27], v[26:27], v[206:207], v[230:231]
	v_pk_fma_f32 v[24:25], v[24:25], v[204:205], v[228:229]
	global_store_dwordx4 v[174:175], v[24:27], off offset:512
	s_waitcnt vmcnt(20)
	v_pk_fma_f32 v[22:23], v[22:23], v[206:207], v[234:235]
	v_pk_fma_f32 v[20:21], v[20:21], v[204:205], v[232:233]
	global_store_dwordx4 v[178:179], v[20:23], off offset:512
	v_pk_add_f32 v[24:25], v[50:51], 0 op_sel_hi:[1,0]
	v_pk_add_f32 v[26:27], v[48:49], 0 op_sel_hi:[1,0]
	s_waitcnt vmcnt(19)
	v_pk_fma_f32 v[18:19], v[18:19], v[206:207], v[190:191]
	v_pk_fma_f32 v[16:17], v[16:17], v[204:205], v[188:189]
	global_store_dwordx4 v[182:183], v[16:19], off offset:512
	s_waitcnt vmcnt(16)
	v_pk_fma_f32 v[22:23], v[24:25], v[194:195], v[198:199]
	v_pk_fma_f32 v[20:21], v[26:27], v[192:193], v[196:197]
	global_store_dwordx4 v[146:147], v[20:23], off offset:576
	v_pk_add_f32 v[24:25], v[42:43], 0 op_sel_hi:[1,0]
	v_pk_add_f32 v[26:27], v[40:41], 0 op_sel_hi:[1,0]
	s_waitcnt vmcnt(15)
	v_pk_fma_f32 v[22:23], v[24:25], v[194:195], v[202:203]
	v_pk_fma_f32 v[20:21], v[26:27], v[192:193], v[200:201]
	global_store_dwordx4 v[164:165], v[20:23], off offset:576
	v_pk_add_f32 v[24:25], v[38:39], 0 op_sel_hi:[1,0]
	v_pk_add_f32 v[26:27], v[36:37], 0 op_sel_hi:[1,0]
	s_waitcnt vmcnt(14)
	v_pk_fma_f32 v[22:23], v[24:25], v[194:195], v[210:211]
	v_pk_fma_f32 v[20:21], v[26:27], v[192:193], v[208:209]
	global_store_dwordx4 v[166:167], v[20:23], off offset:576
	v_pk_add_f32 v[24:25], v[30:31], 0 op_sel_hi:[1,0]
	v_pk_add_f32 v[26:27], v[28:29], 0 op_sel_hi:[1,0]
	s_waitcnt vmcnt(14)
	v_pk_fma_f32 v[22:23], v[24:25], v[194:195], v[218:219]
	v_pk_fma_f32 v[20:21], v[26:27], v[192:193], v[216:217]
	global_store_dwordx4 v[168:169], v[20:23], off offset:576
	s_waitcnt vmcnt(13)
	v_pk_fma_f32 v[14:15], v[14:15], v[194:195], v[186:187]
	v_pk_fma_f32 v[12:13], v[12:13], v[192:193], v[184:185]
	global_store_dwordx4 v[170:171], v[12:15], off offset:576
	s_waitcnt vmcnt(12)
	v_pk_fma_f32 v[10:11], v[10:11], v[194:195], v[214:215]
	v_pk_fma_f32 v[8:9], v[8:9], v[192:193], v[212:213]
	global_store_dwordx4 v[174:175], v[8:11], off offset:576
	s_waitcnt vmcnt(11)
	v_pk_fma_f32 v[6:7], v[6:7], v[194:195], v[222:223]
	v_pk_fma_f32 v[4:5], v[4:5], v[192:193], v[220:221]
	global_store_dwordx4 v[178:179], v[4:7], off offset:576
	s_waitcnt vmcnt(10)
	v_pk_fma_f32 v[2:3], v[2:3], v[194:195], v[226:227]
	v_pk_fma_f32 v[0:1], v[0:1], v[192:193], v[224:225]
	global_store_dwordx4 v[182:183], v[0:3], off offset:576
	s_cbranch_vccz .LBB0_2669
	s_waitcnt vmcnt(0)
	s_mov_b64 s[54:55], s[58:59]
	s_mov_b64 s[58:59], s[62:63]
	s_cmpk_gt_u32 s1, 0xff
	s_cbranch_scc1 .LBB0_2680
	s_barrier

.LBB0_2688:
	ds_read_b128 v[142:145], v139
	ds_read_b128 v[146:149], v139 offset:1024
	ds_read_b128 v[150:153], v139 offset:2048
	ds_read_b128 v[154:157], v139 offset:3072
	v_lshl_add_u64 v[190:191], s[28:29], 0, v[132:133]
	s_add_i32 m0, s5, 0xc000
	ds_read_b128 v[158:161], v140
	ds_read_b128 v[162:165], v140 offset:1024
	ds_read_b128 v[166:169], v140 offset:2048
	ds_read_b128 v[170:173], v140 offset:3072
	ds_read_b128 v[174:177], v140 offset:4096
	ds_read_b128 v[178:181], v140 offset:5120
	ds_read_b128 v[182:185], v140 offset:6144
	ds_read_b128 v[186:189], v140 offset:7168
	global_load_lds_dwordx4 v[190:191], off
	s_add_i32 m0, s5, 0xe000
	s_nop 0
	global_load_lds_dwordx4 v134, s[28:29]
	s_waitcnt lgkmcnt(8)
	s_barrier
	s_waitcnt lgkmcnt(0)
	s_waitcnt lgkmcnt(0)
	v_mfma_f32_16x16x32_bf16 v[124:127], v[142:145], v[158:161], v[124:127]
	s_add_u32 s30, s28, 0x100
	s_addc_u32 s31, s29, 0
	s_cmp_eq_u32 s62, 4
	s_cselect_b32 s37, s19, s31
	s_cselect_b32 s36, s52, s30
	s_cselect_b32 s35, s17, s57
	s_cselect_b32 s34, s53, s56
	v_mfma_f32_16x16x32_bf16 v[120:123], v[150:153], v[158:161], v[120:123]
	v_mfma_f32_16x16x32_bf16 v[116:119], v[142:145], v[166:169], v[116:119]
	v_mfma_f32_16x16x32_bf16 v[112:115], v[150:153], v[166:169], v[112:115]
	v_mfma_f32_16x16x32_bf16 v[100:103], v[142:145], v[174:177], v[100:103]
	v_mfma_f32_16x16x32_bf16 v[96:99], v[150:153], v[174:177], v[96:99]
	v_mfma_f32_16x16x32_bf16 v[84:87], v[142:145], v[182:185], v[84:87]
	v_mfma_f32_16x16x32_bf16 v[80:83], v[150:153], v[182:185], v[80:83]
	v_mfma_f32_16x16x32_bf16 v[124:127], v[146:149], v[162:165], v[124:127]
	v_mfma_f32_16x16x32_bf16 v[120:123], v[154:157], v[162:165], v[120:123]
	v_mfma_f32_16x16x32_bf16 v[116:119], v[146:149], v[170:173], v[116:119]
	v_mfma_f32_16x16x32_bf16 v[112:115], v[154:157], v[170:173], v[112:115]
	v_mfma_f32_16x16x32_bf16 v[100:103], v[146:149], v[178:181], v[100:103]
	v_mfma_f32_16x16x32_bf16 v[96:99], v[154:157], v[178:181], v[96:99]
	v_mfma_f32_16x16x32_bf16 v[84:87], v[146:149], v[186:189], v[84:87]
	v_mfma_f32_16x16x32_bf16 v[80:83], v[154:157], v[186:189], v[80:83]
	s_barrier
	s_add_i32 s28, s43, s4
	s_mov_b32 m0, s28
	ds_read_b128 v[190:193], v141
	ds_read_b128 v[194:197], v141 offset:1024
	ds_read_b128 v[198:201], v141 offset:2048
	ds_read_b128 v[202:205], v141 offset:3072
	global_load_lds_dwordx4 v130, s[34:35]
	s_add_i32 m0, s28, 0x2000
	s_nop 0
	global_load_lds_dwordx4 v128, s[34:35]
	s_barrier
	s_waitcnt lgkmcnt(0)
	s_waitcnt lgkmcnt(0)
	v_mfma_f32_16x16x32_bf16 v[108:111], v[190:193], v[158:161], v[108:111]
	v_mfma_f32_16x16x32_bf16 v[104:107], v[198:201], v[158:161], v[104:107]
	v_mfma_f32_16x16x32_bf16 v[92:95], v[190:193], v[166:169], v[92:95]
	v_mfma_f32_16x16x32_bf16 v[88:91], v[198:201], v[166:169], v[88:91]
	v_mfma_f32_16x16x32_bf16 v[76:79], v[190:193], v[174:177], v[76:79]
	v_mfma_f32_16x16x32_bf16 v[72:75], v[198:201], v[174:177], v[72:75]
	v_mfma_f32_16x16x32_bf16 v[68:71], v[190:193], v[182:185], v[68:71]
	v_mfma_f32_16x16x32_bf16 v[64:67], v[198:201], v[182:185], v[64:67]
	v_mfma_f32_16x16x32_bf16 v[108:111], v[194:197], v[162:165], v[108:111]
	v_mfma_f32_16x16x32_bf16 v[104:107], v[202:205], v[162:165], v[104:107]
	v_mfma_f32_16x16x32_bf16 v[92:95], v[194:197], v[170:173], v[92:95]
	v_mfma_f32_16x16x32_bf16 v[88:91], v[202:205], v[170:173], v[88:91]
	v_mfma_f32_16x16x32_bf16 v[76:79], v[194:197], v[178:181], v[76:79]
	v_mfma_f32_16x16x32_bf16 v[72:75], v[202:205], v[178:181], v[72:75]
	v_mfma_f32_16x16x32_bf16 v[68:71], v[194:197], v[186:189], v[68:71]
	v_mfma_f32_16x16x32_bf16 v[64:67], v[202:205], v[186:189], v[64:67]
	s_mov_b32 m0, s5
	v_lshl_add_u64 v[210:211], s[36:37], 0, v[130:131]
	s_barrier
	ds_read_b128 v[158:161], v140 offset:16384
	ds_read_b128 v[162:165], v140 offset:17408
	ds_read_b128 v[166:169], v140 offset:18432
	ds_read_b128 v[170:173], v140 offset:19456
	ds_read_b128 v[174:177], v140 offset:20480
	ds_read_b128 v[178:181], v140 offset:21504
	ds_read_b128 v[182:185], v140 offset:22528
	ds_read_b128 v[186:189], v140 offset:23552
	global_load_lds_dwordx4 v130, s[36:37]
	v_lshl_add_u64 v[212:213], s[36:37], 0, v[128:129]
	s_mov_b32 m0, s11
	s_nop 0
	global_load_lds_dwordx4 v128, s[36:37]
	s_barrier
	s_waitcnt lgkmcnt(0)
	s_waitcnt lgkmcnt(0)
	v_mfma_f32_16x16x32_bf16 v[60:63], v[142:145], v[158:161], v[60:63]
	v_mfma_f32_16x16x32_bf16 v[56:59], v[150:153], v[158:161], v[56:59]
	v_mfma_f32_16x16x32_bf16 v[52:55], v[142:145], v[166:169], v[52:55]
	v_mfma_f32_16x16x32_bf16 v[48:51], v[150:153], v[166:169], v[48:51]
	v_mfma_f32_16x16x32_bf16 v[36:39], v[142:145], v[174:177], v[36:39]
	v_mfma_f32_16x16x32_bf16 v[32:35], v[150:153], v[174:177], v[32:35]
	v_mfma_f32_16x16x32_bf16 v[20:23], v[142:145], v[182:185], v[20:23]
	v_mfma_f32_16x16x32_bf16 v[16:19], v[150:153], v[182:185], v[16:19]
	v_mfma_f32_16x16x32_bf16 v[60:63], v[146:149], v[162:165], v[60:63]
	v_mfma_f32_16x16x32_bf16 v[56:59], v[154:157], v[162:165], v[56:59]
	v_mfma_f32_16x16x32_bf16 v[52:55], v[146:149], v[170:173], v[52:55]
	v_mfma_f32_16x16x32_bf16 v[48:51], v[154:157], v[170:173], v[48:51]
	v_mfma_f32_16x16x32_bf16 v[36:39], v[146:149], v[178:181], v[36:39]
	v_mfma_f32_16x16x32_bf16 v[32:35], v[154:157], v[178:181], v[32:35]
	v_mfma_f32_16x16x32_bf16 v[20:23], v[146:149], v[186:189], v[20:23]
	v_mfma_f32_16x16x32_bf16 v[16:19], v[154:157], v[186:189], v[16:19]
	s_barrier
	s_add_u32 s28, s34, 0x100000
	s_addc_u32 s29, s35, 0
	s_add_i32 s63, s46, s4
	s_mov_b32 m0, s63
	s_nop 0
	global_load_lds_dwordx4 v130, s[28:29]
	s_add_i32 m0, s63, 0x2000
	s_nop 0
	global_load_lds_dwordx4 v128, s[28:29]
	s_waitcnt vmcnt(6)
	s_barrier
	v_mfma_f32_16x16x32_bf16 v[44:47], v[190:193], v[158:161], v[44:47]
	v_mfma_f32_16x16x32_bf16 v[40:43], v[198:201], v[158:161], v[40:43]
	v_mfma_f32_16x16x32_bf16 v[28:31], v[190:193], v[166:169], v[28:31]
	v_mfma_f32_16x16x32_bf16 v[24:27], v[198:201], v[166:169], v[24:27]
	v_mfma_f32_16x16x32_bf16 v[12:15], v[190:193], v[174:177], v[12:15]
	v_mfma_f32_16x16x32_bf16 v[8:11], v[198:201], v[174:177], v[8:11]
	v_mfma_f32_16x16x32_bf16 v[4:7], v[190:193], v[182:185], v[4:7]
	v_mfma_f32_16x16x32_bf16 v[0:3], v[198:201], v[182:185], v[0:3]
	v_mfma_f32_16x16x32_bf16 v[44:47], v[194:197], v[162:165], v[44:47]
	v_mfma_f32_16x16x32_bf16 v[40:43], v[202:205], v[162:165], v[40:43]
	v_mfma_f32_16x16x32_bf16 v[28:31], v[194:197], v[170:173], v[28:31]
	v_mfma_f32_16x16x32_bf16 v[24:27], v[202:205], v[170:173], v[24:27]
	v_mfma_f32_16x16x32_bf16 v[12:15], v[194:197], v[178:181], v[12:15]
	v_mfma_f32_16x16x32_bf16 v[8:11], v[202:205], v[178:181], v[8:11]
	v_mfma_f32_16x16x32_bf16 v[4:7], v[194:197], v[186:189], v[4:7]
	v_mfma_f32_16x16x32_bf16 v[0:3], v[202:205], v[186:189], v[0:3]
	s_add_i32 s63, 0, 0x18000
	v_add_u32_e32 v154, s63, v137
	s_barrier
	ds_read_b128 v[142:145], v154
	ds_read_b128 v[146:149], v154 offset:1024
	ds_read_b128 v[150:153], v154 offset:2048
	ds_read_b128 v[154:157], v154 offset:3072
	s_add_u32 s28, s36, 0x100000
	s_addc_u32 s29, s37, 0
	s_mov_b32 m0, s13
	ds_read_b128 v[158:161], v140 offset:32768
	ds_read_b128 v[162:165], v140 offset:33792
	ds_read_b128 v[166:169], v140 offset:34816
	ds_read_b128 v[170:173], v140 offset:35840
	ds_read_b128 v[174:177], v140 offset:36864
	ds_read_b128 v[178:181], v140 offset:37888
	ds_read_b128 v[182:185], v140 offset:38912
	ds_read_b128 v[186:189], v140 offset:39936
	global_load_lds_dwordx4 v130, s[28:29]
	s_mov_b32 m0, s38
	s_nop 0
	global_load_lds_dwordx4 v128, s[28:29]
	s_waitcnt lgkmcnt(8)
	s_barrier
	s_waitcnt lgkmcnt(0)
	s_waitcnt lgkmcnt(0)
	v_mfma_f32_16x16x32_bf16 v[124:127], v[142:145], v[158:161], v[124:127]
	v_mfma_f32_16x16x32_bf16 v[120:123], v[150:153], v[158:161], v[120:123]
	v_mfma_f32_16x16x32_bf16 v[116:119], v[142:145], v[166:169], v[116:119]
	v_mfma_f32_16x16x32_bf16 v[112:115], v[150:153], v[166:169], v[112:115]
	v_mfma_f32_16x16x32_bf16 v[100:103], v[142:145], v[174:177], v[100:103]
	v_mfma_f32_16x16x32_bf16 v[96:99], v[150:153], v[174:177], v[96:99]
	v_mfma_f32_16x16x32_bf16 v[84:87], v[142:145], v[182:185], v[84:87]
	v_mfma_f32_16x16x32_bf16 v[80:83], v[150:153], v[182:185], v[80:83]
	v_mfma_f32_16x16x32_bf16 v[124:127], v[146:149], v[162:165], v[124:127]
	v_mfma_f32_16x16x32_bf16 v[120:123], v[154:157], v[162:165], v[120:123]
	v_mfma_f32_16x16x32_bf16 v[116:119], v[146:149], v[170:173], v[116:119]
	v_mfma_f32_16x16x32_bf16 v[112:115], v[154:157], v[170:173], v[112:115]
	v_mfma_f32_16x16x32_bf16 v[100:103], v[146:149], v[178:181], v[100:103]
	v_mfma_f32_16x16x32_bf16 v[96:99], v[154:157], v[178:181], v[96:99]
	v_mfma_f32_16x16x32_bf16 v[84:87], v[146:149], v[186:189], v[84:87]
	v_mfma_f32_16x16x32_bf16 v[80:83], v[154:157], v[186:189], v[80:83]
	s_barrier
	s_add_i32 s36, 0, 0x1c000
	s_add_i32 s28, s63, s4
	v_add_u32_e32 v202, s36, v137
	s_add_u32 s98, s34, s14
	s_addc_u32 s99, s35, s15
	s_mov_b32 m0, s28
	ds_read_b128 v[190:193], v202
	ds_read_b128 v[194:197], v202 offset:1024
	ds_read_b128 v[198:201], v202 offset:2048
	ds_read_b128 v[202:205], v202 offset:3072
	global_load_lds_dwordx4 v130, s[98:99]
	s_add_i32 m0, s28, 0x2000
	s_nop 0
	global_load_lds_dwordx4 v128, s[98:99]
	s_barrier
	s_waitcnt lgkmcnt(0)
	s_waitcnt lgkmcnt(0)
	v_mfma_f32_16x16x32_bf16 v[108:111], v[190:193], v[158:161], v[108:111]
	v_mfma_f32_16x16x32_bf16 v[104:107], v[198:201], v[158:161], v[104:107]
	v_mfma_f32_16x16x32_bf16 v[92:95], v[190:193], v[166:169], v[92:95]
	v_mfma_f32_16x16x32_bf16 v[88:91], v[198:201], v[166:169], v[88:91]
	v_mfma_f32_16x16x32_bf16 v[76:79], v[190:193], v[174:177], v[76:79]
	v_mfma_f32_16x16x32_bf16 v[72:75], v[198:201], v[174:177], v[72:75]
	v_mfma_f32_16x16x32_bf16 v[68:71], v[190:193], v[182:185], v[68:71]
	v_mfma_f32_16x16x32_bf16 v[64:67], v[198:201], v[182:185], v[64:67]
	v_mfma_f32_16x16x32_bf16 v[108:111], v[194:197], v[162:165], v[108:111]
	v_mfma_f32_16x16x32_bf16 v[104:107], v[202:205], v[162:165], v[104:107]
	v_mfma_f32_16x16x32_bf16 v[92:95], v[194:197], v[170:173], v[92:95]
	v_mfma_f32_16x16x32_bf16 v[88:91], v[202:205], v[170:173], v[88:91]
	v_mfma_f32_16x16x32_bf16 v[76:79], v[194:197], v[178:181], v[76:79]
	v_mfma_f32_16x16x32_bf16 v[72:75], v[202:205], v[178:181], v[72:75]
	v_mfma_f32_16x16x32_bf16 v[68:71], v[194:197], v[186:189], v[68:71]
	v_mfma_f32_16x16x32_bf16 v[64:67], v[202:205], v[186:189], v[64:67]
	s_mov_b32 m0, s41
	v_lshl_add_u64 v[206:207], v[210:211], 0, s[14:15]
	s_barrier
	ds_read_b128 v[158:161], v140 offset:49152
	ds_read_b128 v[162:165], v140 offset:50176
	ds_read_b128 v[166:169], v140 offset:51200
	ds_read_b128 v[170:173], v140 offset:52224
	ds_read_b128 v[174:177], v140 offset:53248
	ds_read_b128 v[178:181], v140 offset:54272
	ds_read_b128 v[182:185], v140 offset:55296
	ds_read_b128 v[186:189], v140 offset:56320
	global_load_lds_dwordx4 v[206:207], off
	v_lshl_add_u64 v[206:207], v[212:213], 0, s[14:15]
	s_mov_b32 m0, s42
	s_nop 0
	global_load_lds_dwordx4 v[206:207], off
	s_barrier
	s_waitcnt lgkmcnt(0)
	s_waitcnt lgkmcnt(0)
	v_mfma_f32_16x16x32_bf16 v[60:63], v[142:145], v[158:161], v[60:63]
	v_mfma_f32_16x16x32_bf16 v[56:59], v[150:153], v[158:161], v[56:59]
	v_mfma_f32_16x16x32_bf16 v[52:55], v[142:145], v[166:169], v[52:55]
	v_mfma_f32_16x16x32_bf16 v[48:51], v[150:153], v[166:169], v[48:51]
	v_mfma_f32_16x16x32_bf16 v[36:39], v[142:145], v[174:177], v[36:39]
	v_mfma_f32_16x16x32_bf16 v[32:35], v[150:153], v[174:177], v[32:35]
	v_mfma_f32_16x16x32_bf16 v[20:23], v[142:145], v[182:185], v[20:23]
	v_mfma_f32_16x16x32_bf16 v[16:19], v[150:153], v[182:185], v[16:19]
	v_mfma_f32_16x16x32_bf16 v[60:63], v[146:149], v[162:165], v[60:63]
	v_mfma_f32_16x16x32_bf16 v[56:59], v[154:157], v[162:165], v[56:59]
	v_mfma_f32_16x16x32_bf16 v[52:55], v[146:149], v[170:173], v[52:55]
	v_mfma_f32_16x16x32_bf16 v[48:51], v[154:157], v[170:173], v[48:51]
	v_mfma_f32_16x16x32_bf16 v[36:39], v[146:149], v[178:181], v[36:39]
	v_mfma_f32_16x16x32_bf16 v[32:35], v[154:157], v[178:181], v[32:35]
	v_mfma_f32_16x16x32_bf16 v[20:23], v[146:149], v[186:189], v[20:23]
	v_mfma_f32_16x16x32_bf16 v[16:19], v[154:157], v[186:189], v[16:19]
	s_barrier
	s_add_u32 s28, s34, 0x100080
	s_addc_u32 s29, s35, 0
	s_add_i32 s34, s36, s4
	s_mov_b32 m0, s34
	s_nop 0
	global_load_lds_dwordx4 v130, s[28:29]
	s_add_i32 m0, s34, 0x2000
	s_nop 0
	global_load_lds_dwordx4 v128, s[28:29]
	s_waitcnt vmcnt(6)
	s_barrier
	v_mfma_f32_16x16x32_bf16 v[44:47], v[190:193], v[158:161], v[44:47]
	v_mfma_f32_16x16x32_bf16 v[40:43], v[198:201], v[158:161], v[40:43]
	v_mfma_f32_16x16x32_bf16 v[28:31], v[190:193], v[166:169], v[28:31]
	v_mfma_f32_16x16x32_bf16 v[24:27], v[198:201], v[166:169], v[24:27]
	v_mfma_f32_16x16x32_bf16 v[12:15], v[190:193], v[174:177], v[12:15]
	v_mfma_f32_16x16x32_bf16 v[8:11], v[198:201], v[174:177], v[8:11]
	v_mfma_f32_16x16x32_bf16 v[4:7], v[190:193], v[182:185], v[4:7]
	v_mfma_f32_16x16x32_bf16 v[0:3], v[198:201], v[182:185], v[0:3]
	v_mfma_f32_16x16x32_bf16 v[44:47], v[194:197], v[162:165], v[44:47]
	v_mfma_f32_16x16x32_bf16 v[40:43], v[202:205], v[162:165], v[40:43]
	v_mfma_f32_16x16x32_bf16 v[28:31], v[194:197], v[170:173], v[28:31]
	v_mfma_f32_16x16x32_bf16 v[24:27], v[202:205], v[170:173], v[24:27]
	v_mfma_f32_16x16x32_bf16 v[12:15], v[194:197], v[178:181], v[12:15]
	v_mfma_f32_16x16x32_bf16 v[8:11], v[202:205], v[178:181], v[8:11]
	v_mfma_f32_16x16x32_bf16 v[4:7], v[194:197], v[186:189], v[4:7]
	v_mfma_f32_16x16x32_bf16 v[0:3], v[202:205], v[186:189], v[0:3]
	s_add_i32 s62, s62, 2
	s_add_u32 s56, s56, 0x100
	s_addc_u32 s57, s57, 0
	s_cmp_gt_u32 s62, 5
	s_mov_b64 s[28:29], s[30:31]
	s_barrier
	s_cbranch_scc0 .LBB0_2688
	s_ashr_i32 s17, s40, 1
	s_and_b32 s17, s17, 0xfffffe00
	s_lshl_b32 s12, s12, 8
	s_add_i32 s12, s12, s17
	v_readlane_b32 s48, v240, 22
	v_add_u32_e32 v144, s12, v136
	v_readlane_b32 s49, v240, 23
	v_readlane_b32 s50, v240, 24
	v_readlane_b32 s51, v240, 25
	v_readlane_b32 s52, v240, 26
	v_readlane_b32 s53, v240, 27
	v_lshl_or_b32 v142, s10, 8, v138
	v_ashrrev_i32_e32 v145, 31, v144
	v_readlane_b32 s54, v240, 28
	v_readlane_b32 s55, v240, 29
	v_readlane_b32 s58, v240, 32
	v_readlane_b32 s59, v240, 33
	v_readlane_b32 s62, v240, 36
	v_readlane_b32 s63, v240, 37
	s_mov_b64 s[44:45], s[48:49]
	s_mov_b64 s[48:49], s[52:53]
	v_ashrrev_i32_e32 v143, 31, v142
	v_lshlrev_b64 v[146:147], 13, v[144:145]
	s_mov_b64 s[50:51], s[54:55]
	s_mov_b64 s[54:55], s[58:59]
	s_mov_b64 s[58:59], s[62:63]
	v_lshl_add_u64 v[146:147], s[58:59], 0, v[146:147]
	v_lshlrev_b64 v[142:143], 2, v[142:143]
	v_lshl_add_u64 v[146:147], v[146:147], 0, v[142:143]
	global_store_dwordx4 v[146:147], v[124:127], off
	global_store_dwordx4 v[146:147], v[120:123], off offset:64
	global_store_dwordx4 v[146:147], v[108:111], off offset:512
	global_store_dwordx4 v[146:147], v[104:107], off offset:576
	s_mov_b32 s10, 0x100000
	s_mov_b64 s[28:29], 0x100000
	v_or_b32_e32 v104, 16, v144
	v_ashrrev_i32_e32 v105, 31, v104
	v_lshlrev_b64 v[104:105], 13, v[104:105]
	v_lshl_add_u64 v[104:105], s[58:59], 0, v[104:105]
	v_lshl_add_u64 v[104:105], v[104:105], 0, v[142:143]
	global_store_dwordx4 v[104:105], v[116:119], off
	global_store_dwordx4 v[104:105], v[112:115], off offset:64
	global_store_dwordx4 v[104:105], v[92:95], off offset:512
	global_store_dwordx4 v[104:105], v[88:91], off offset:576
	s_mov_b32 s40, s47
	s_mov_b32 s12, s18
	v_or_b32_e32 v88, 32, v144
	v_ashrrev_i32_e32 v89, 31, v88
	v_lshlrev_b64 v[88:89], 13, v[88:89]
	v_lshl_add_u64 v[88:89], s[58:59], 0, v[88:89]
	v_lshl_add_u64 v[88:89], v[88:89], 0, v[142:143]
	global_store_dwordx4 v[88:89], v[100:103], off
	global_store_dwordx4 v[88:89], v[96:99], off offset:64
	global_store_dwordx4 v[88:89], v[76:79], off offset:512
	global_store_dwordx4 v[88:89], v[72:75], off offset:576
	s_mov_b64 s[30:31], s[26:27]
	v_readlane_b32 s56, v240, 30
	v_or_b32_e32 v72, 48, v144
	v_ashrrev_i32_e32 v73, 31, v72
	v_lshlrev_b64 v[72:73], 13, v[72:73]
	v_lshl_add_u64 v[72:73], s[58:59], 0, v[72:73]
	v_lshl_add_u64 v[72:73], v[72:73], 0, v[142:143]
	global_store_dwordx4 v[72:73], v[84:87], off
	global_store_dwordx4 v[72:73], v[80:83], off offset:64
	global_store_dwordx4 v[72:73], v[68:71], off offset:512
	global_store_dwordx4 v[72:73], v[64:67], off offset:576
	v_readlane_b32 s57, v240, 31
	v_readlane_b32 s60, v240, 34
	v_add_co_u32_e32 v66, vcc, s10, v146
	s_mov_b32 s10, 0x120000
	s_nop 0
	v_addc_co_u32_e32 v67, vcc, 0, v147, vcc
	v_lshl_add_u64 v[64:65], v[146:147], 0, s[28:29]
	global_store_dwordx4 v[66:67], v[60:63], off
	global_store_dwordx4 v[64:65], v[56:59], off offset:64
	global_store_dwordx4 v[64:65], v[44:47], off offset:512
	global_store_dwordx4 v[64:65], v[40:43], off offset:576
	s_mov_b64 s[28:29], 0x120000
	v_readlane_b32 s61, v240, 35
	v_add_co_u32_e32 v42, vcc, s10, v146
	s_mov_b32 s10, 0x140000
	s_nop 0
	v_addc_co_u32_e32 v43, vcc, 0, v147, vcc
	v_lshl_add_u64 v[40:41], v[146:147], 0, s[28:29]
	global_store_dwordx4 v[42:43], v[52:55], off
	global_store_dwordx4 v[40:41], v[48:51], off offset:64
	global_store_dwordx4 v[40:41], v[28:31], off offset:512
	global_store_dwordx4 v[40:41], v[24:27], off offset:576
	s_mov_b64 s[28:29], 0x140000
	s_nop 0
	v_add_co_u32_e32 v26, vcc, s10, v146
	v_lshl_add_u64 v[24:25], v[146:147], 0, s[28:29]
	s_nop 0
	v_addc_co_u32_e32 v27, vcc, 0, v147, vcc
	global_store_dwordx4 v[26:27], v[36:39], off
	global_store_dwordx4 v[24:25], v[32:35], off offset:64
	global_store_dwordx4 v[24:25], v[12:15], off offset:512
	global_store_dwordx4 v[24:25], v[8:11], off offset:576
	s_mov_b64 s[28:29], 0x160000
	s_mov_b32 s10, s16
	v_add_co_u32_e32 v10, vcc, 0x160000, v146
	v_lshl_add_u64 v[8:9], v[146:147], 0, s[28:29]
	s_nop 0
	v_addc_co_u32_e32 v11, vcc, 0, v147, vcc
	s_and_b64 vcc, exec, s[20:21]
	s_mov_b64 s[28:29], s[22:23]
	global_store_dwordx4 v[10:11], v[20:23], off
	global_store_dwordx4 v[8:9], v[16:19], off offset:64
	global_store_dwordx4 v[8:9], v[4:7], off offset:512
	global_store_dwordx4 v[8:9], v[0:3], off offset:576
	s_cbranch_vccz .LBB0_2685
	s_waitcnt vmcnt(0)
	s_cmpk_gt_u32 s1, 0xff
	s_cbranch_scc1 .LBB0_2692
	s_barrier

.LBB0_2812:
	ds_read_b128 v[148:151], v144
	ds_read_b128 v[152:155], v144 offset:1024
	ds_read_b128 v[156:159], v144 offset:2048
	ds_read_b128 v[160:163], v144 offset:3072
	s_add_i32 m0, s5, 0xc000
	ds_read_b128 v[164:167], v145
	ds_read_b128 v[168:171], v145 offset:1024
	ds_read_b128 v[172:175], v145 offset:2048
	ds_read_b128 v[176:179], v145 offset:3072
	ds_read_b128 v[180:183], v145 offset:4096
	ds_read_b128 v[184:187], v145 offset:5120
	ds_read_b128 v[188:191], v145 offset:6144
	ds_read_b128 v[192:195], v145 offset:7168
	global_load_lds_dwordx4 v134, s[22:23]
	s_add_i32 m0, s5, 0xe000
	s_nop 0
	global_load_lds_dwordx4 v136, s[22:23]
	s_waitcnt lgkmcnt(8)
	s_barrier
	s_waitcnt lgkmcnt(0)
	s_waitcnt lgkmcnt(0)
	v_mfma_f32_16x16x32_bf16 v[124:127], v[148:151], v[164:167], v[124:127]
	s_add_u32 s26, s22, 0x100
	s_addc_u32 s27, s23, 0
	s_cmp_eq_u32 s57, 28
	s_cselect_b32 s31, s15, s27
	s_cselect_b32 s30, s47, s26
	s_cselect_b32 s29, s13, s56
	s_cselect_b32 s28, s52, s53
	v_mfma_f32_16x16x32_bf16 v[120:123], v[156:159], v[164:167], v[120:123]
	v_mfma_f32_16x16x32_bf16 v[108:111], v[148:151], v[172:175], v[108:111]
	v_mfma_f32_16x16x32_bf16 v[104:107], v[156:159], v[172:175], v[104:107]
	v_mfma_f32_16x16x32_bf16 v[92:95], v[148:151], v[180:183], v[92:95]
	v_mfma_f32_16x16x32_bf16 v[88:91], v[156:159], v[180:183], v[88:91]
	v_mfma_f32_16x16x32_bf16 v[76:79], v[148:151], v[188:191], v[76:79]
	v_mfma_f32_16x16x32_bf16 v[72:75], v[156:159], v[188:191], v[72:75]
	v_mfma_f32_16x16x32_bf16 v[124:127], v[152:155], v[168:171], v[124:127]
	v_mfma_f32_16x16x32_bf16 v[120:123], v[160:163], v[168:171], v[120:123]
	v_mfma_f32_16x16x32_bf16 v[108:111], v[152:155], v[176:179], v[108:111]
	v_mfma_f32_16x16x32_bf16 v[104:107], v[160:163], v[176:179], v[104:107]
	v_mfma_f32_16x16x32_bf16 v[92:95], v[152:155], v[184:187], v[92:95]
	v_mfma_f32_16x16x32_bf16 v[88:91], v[160:163], v[184:187], v[88:91]
	v_mfma_f32_16x16x32_bf16 v[76:79], v[152:155], v[192:195], v[76:79]
	v_mfma_f32_16x16x32_bf16 v[72:75], v[160:163], v[192:195], v[72:75]
	s_barrier
	s_add_i32 s22, s42, s2
	s_mov_b32 m0, s22
	ds_read_b128 v[196:199], v146
	ds_read_b128 v[200:203], v146 offset:1024
	ds_read_b128 v[204:207], v146 offset:2048
	ds_read_b128 v[208:211], v146 offset:3072
	global_load_lds_dwordx4 v130, s[28:29]
	s_add_i32 m0, s22, 0x2000
	s_nop 0
	global_load_lds_dwordx4 v128, s[28:29]
	s_barrier
	s_waitcnt lgkmcnt(0)
	s_waitcnt lgkmcnt(0)
	v_mfma_f32_16x16x32_bf16 v[116:119], v[196:199], v[164:167], v[116:119]
	v_mfma_f32_16x16x32_bf16 v[112:115], v[204:207], v[164:167], v[112:115]
	v_mfma_f32_16x16x32_bf16 v[100:103], v[196:199], v[172:175], v[100:103]
	v_mfma_f32_16x16x32_bf16 v[96:99], v[204:207], v[172:175], v[96:99]
	v_mfma_f32_16x16x32_bf16 v[84:87], v[196:199], v[180:183], v[84:87]
	v_mfma_f32_16x16x32_bf16 v[80:83], v[204:207], v[180:183], v[80:83]
	v_mfma_f32_16x16x32_bf16 v[68:71], v[196:199], v[188:191], v[68:71]
	v_mfma_f32_16x16x32_bf16 v[64:67], v[204:207], v[188:191], v[64:67]
	v_mfma_f32_16x16x32_bf16 v[116:119], v[200:203], v[168:171], v[116:119]
	v_mfma_f32_16x16x32_bf16 v[112:115], v[208:211], v[168:171], v[112:115]
	v_mfma_f32_16x16x32_bf16 v[100:103], v[200:203], v[176:179], v[100:103]
	v_mfma_f32_16x16x32_bf16 v[96:99], v[208:211], v[176:179], v[96:99]
	v_mfma_f32_16x16x32_bf16 v[84:87], v[200:203], v[184:187], v[84:87]
	v_mfma_f32_16x16x32_bf16 v[80:83], v[208:211], v[184:187], v[80:83]
	v_mfma_f32_16x16x32_bf16 v[68:71], v[200:203], v[192:195], v[68:71]
	v_mfma_f32_16x16x32_bf16 v[64:67], v[208:211], v[192:195], v[64:67]
	s_mov_b32 m0, s5
	v_lshl_add_u64 v[216:217], s[30:31], 0, v[130:131]
	s_barrier
	ds_read_b128 v[164:167], v145 offset:16384
	ds_read_b128 v[168:171], v145 offset:17408
	ds_read_b128 v[172:175], v145 offset:18432
	ds_read_b128 v[176:179], v145 offset:19456
	ds_read_b128 v[180:183], v145 offset:20480
	ds_read_b128 v[184:187], v145 offset:21504
	ds_read_b128 v[188:191], v145 offset:22528
	ds_read_b128 v[192:195], v145 offset:23552
	global_load_lds_dwordx4 v130, s[30:31]
	v_lshl_add_u64 v[218:219], s[30:31], 0, v[128:129]
	s_mov_b32 m0, s34
	s_nop 0
	global_load_lds_dwordx4 v128, s[30:31]
	s_barrier
	s_waitcnt lgkmcnt(0)
	s_waitcnt lgkmcnt(0)
	v_mfma_f32_16x16x32_bf16 v[60:63], v[148:151], v[164:167], v[60:63]
	v_mfma_f32_16x16x32_bf16 v[56:59], v[156:159], v[164:167], v[56:59]
	v_mfma_f32_16x16x32_bf16 v[44:47], v[148:151], v[172:175], v[44:47]
	v_mfma_f32_16x16x32_bf16 v[40:43], v[156:159], v[172:175], v[40:43]
	v_mfma_f32_16x16x32_bf16 v[28:31], v[148:151], v[180:183], v[28:31]
	v_mfma_f32_16x16x32_bf16 v[24:27], v[156:159], v[180:183], v[24:27]
	v_mfma_f32_16x16x32_bf16 v[12:15], v[148:151], v[188:191], v[12:15]
	v_mfma_f32_16x16x32_bf16 v[8:11], v[156:159], v[188:191], v[8:11]
	v_mfma_f32_16x16x32_bf16 v[60:63], v[152:155], v[168:171], v[60:63]
	v_mfma_f32_16x16x32_bf16 v[56:59], v[160:163], v[168:171], v[56:59]
	v_mfma_f32_16x16x32_bf16 v[44:47], v[152:155], v[176:179], v[44:47]
	v_mfma_f32_16x16x32_bf16 v[40:43], v[160:163], v[176:179], v[40:43]
	v_mfma_f32_16x16x32_bf16 v[28:31], v[152:155], v[184:187], v[28:31]
	v_mfma_f32_16x16x32_bf16 v[24:27], v[160:163], v[184:187], v[24:27]
	v_mfma_f32_16x16x32_bf16 v[12:15], v[152:155], v[192:195], v[12:15]
	v_mfma_f32_16x16x32_bf16 v[8:11], v[160:163], v[192:195], v[8:11]
	s_barrier
	s_add_u32 s22, s28, 0x80000
	s_addc_u32 s23, s29, 0
	s_add_i32 s60, s43, s2
	s_mov_b32 m0, s60
	s_nop 0
	global_load_lds_dwordx4 v130, s[22:23]
	s_add_i32 m0, s60, 0x2000
	s_nop 0
	global_load_lds_dwordx4 v128, s[22:23]
	s_waitcnt vmcnt(6)
	s_barrier
	v_mfma_f32_16x16x32_bf16 v[52:55], v[196:199], v[164:167], v[52:55]
	v_mfma_f32_16x16x32_bf16 v[48:51], v[204:207], v[164:167], v[48:51]
	v_mfma_f32_16x16x32_bf16 v[36:39], v[196:199], v[172:175], v[36:39]
	v_mfma_f32_16x16x32_bf16 v[32:35], v[204:207], v[172:175], v[32:35]
	v_mfma_f32_16x16x32_bf16 v[20:23], v[196:199], v[180:183], v[20:23]
	v_mfma_f32_16x16x32_bf16 v[16:19], v[204:207], v[180:183], v[16:19]
	v_mfma_f32_16x16x32_bf16 v[4:7], v[196:199], v[188:191], v[4:7]
	v_mfma_f32_16x16x32_bf16 v[0:3], v[204:207], v[188:191], v[0:3]
	v_mfma_f32_16x16x32_bf16 v[52:55], v[200:203], v[168:171], v[52:55]
	v_mfma_f32_16x16x32_bf16 v[48:51], v[208:211], v[168:171], v[48:51]
	v_mfma_f32_16x16x32_bf16 v[36:39], v[200:203], v[176:179], v[36:39]
	v_mfma_f32_16x16x32_bf16 v[32:35], v[208:211], v[176:179], v[32:35]
	v_mfma_f32_16x16x32_bf16 v[20:23], v[200:203], v[184:187], v[20:23]
	v_mfma_f32_16x16x32_bf16 v[16:19], v[208:211], v[184:187], v[16:19]
	v_mfma_f32_16x16x32_bf16 v[4:7], v[200:203], v[192:195], v[4:7]
	v_mfma_f32_16x16x32_bf16 v[0:3], v[208:211], v[192:195], v[0:3]
	s_add_i32 s60, 0, 0x18000
	v_add_u32_e32 v147, s60, v143
	s_barrier
	ds_read_b128 v[148:151], v147
	ds_read_b128 v[152:155], v147 offset:1024
	ds_read_b128 v[156:159], v147 offset:2048
	ds_read_b128 v[160:163], v147 offset:3072
	s_add_u32 s22, s30, 0x80000
	s_addc_u32 s23, s31, 0
	s_mov_b32 m0, s35
	ds_read_b128 v[164:167], v145 offset:32768
	ds_read_b128 v[168:171], v145 offset:33792
	ds_read_b128 v[172:175], v145 offset:34816
	ds_read_b128 v[176:179], v145 offset:35840
	ds_read_b128 v[180:183], v145 offset:36864
	ds_read_b128 v[184:187], v145 offset:37888
	ds_read_b128 v[188:191], v145 offset:38912
	ds_read_b128 v[192:195], v145 offset:39936
	global_load_lds_dwordx4 v130, s[22:23]
	s_mov_b32 m0, s36
	s_nop 0
	global_load_lds_dwordx4 v128, s[22:23]
	s_waitcnt lgkmcnt(8)
	s_barrier
	s_waitcnt lgkmcnt(0)
	s_waitcnt lgkmcnt(0)
	v_mfma_f32_16x16x32_bf16 v[124:127], v[148:151], v[164:167], v[124:127]
	v_mfma_f32_16x16x32_bf16 v[120:123], v[156:159], v[164:167], v[120:123]
	v_mfma_f32_16x16x32_bf16 v[108:111], v[148:151], v[172:175], v[108:111]
	v_mfma_f32_16x16x32_bf16 v[104:107], v[156:159], v[172:175], v[104:107]
	v_mfma_f32_16x16x32_bf16 v[92:95], v[148:151], v[180:183], v[92:95]
	v_mfma_f32_16x16x32_bf16 v[88:91], v[156:159], v[180:183], v[88:91]
	v_mfma_f32_16x16x32_bf16 v[76:79], v[148:151], v[188:191], v[76:79]
	v_mfma_f32_16x16x32_bf16 v[72:75], v[156:159], v[188:191], v[72:75]
	v_mfma_f32_16x16x32_bf16 v[124:127], v[152:155], v[168:171], v[124:127]
	v_mfma_f32_16x16x32_bf16 v[120:123], v[160:163], v[168:171], v[120:123]
	v_mfma_f32_16x16x32_bf16 v[108:111], v[152:155], v[176:179], v[108:111]
	v_mfma_f32_16x16x32_bf16 v[104:107], v[160:163], v[176:179], v[104:107]
	v_mfma_f32_16x16x32_bf16 v[92:95], v[152:155], v[184:187], v[92:95]
	v_mfma_f32_16x16x32_bf16 v[88:91], v[160:163], v[184:187], v[88:91]
	v_mfma_f32_16x16x32_bf16 v[76:79], v[152:155], v[192:195], v[76:79]
	v_mfma_f32_16x16x32_bf16 v[72:75], v[160:163], v[192:195], v[72:75]
	s_barrier
	s_add_i32 s30, 0, 0x1c000
	s_add_i32 s22, s60, s2
	v_add_u32_e32 v147, s30, v143
	s_add_u32 s98, s28, s10
	s_addc_u32 s99, s29, s11
	s_mov_b32 m0, s22
	ds_read_b128 v[196:199], v147
	ds_read_b128 v[200:203], v147 offset:1024
	ds_read_b128 v[204:207], v147 offset:2048
	ds_read_b128 v[208:211], v147 offset:3072
	global_load_lds_dwordx4 v130, s[98:99]
	s_add_i32 m0, s22, 0x2000
	s_nop 0
	global_load_lds_dwordx4 v128, s[98:99]
	s_barrier
	s_waitcnt lgkmcnt(0)
	s_waitcnt lgkmcnt(0)
	v_mfma_f32_16x16x32_bf16 v[116:119], v[196:199], v[164:167], v[116:119]
	v_mfma_f32_16x16x32_bf16 v[112:115], v[204:207], v[164:167], v[112:115]
	v_mfma_f32_16x16x32_bf16 v[100:103], v[196:199], v[172:175], v[100:103]
	v_mfma_f32_16x16x32_bf16 v[96:99], v[204:207], v[172:175], v[96:99]
	v_mfma_f32_16x16x32_bf16 v[84:87], v[196:199], v[180:183], v[84:87]
	v_mfma_f32_16x16x32_bf16 v[80:83], v[204:207], v[180:183], v[80:83]
	v_mfma_f32_16x16x32_bf16 v[68:71], v[196:199], v[188:191], v[68:71]
	v_mfma_f32_16x16x32_bf16 v[64:67], v[204:207], v[188:191], v[64:67]
	v_mfma_f32_16x16x32_bf16 v[116:119], v[200:203], v[168:171], v[116:119]
	v_mfma_f32_16x16x32_bf16 v[112:115], v[208:211], v[168:171], v[112:115]
	v_mfma_f32_16x16x32_bf16 v[100:103], v[200:203], v[176:179], v[100:103]
	v_mfma_f32_16x16x32_bf16 v[96:99], v[208:211], v[176:179], v[96:99]
	v_mfma_f32_16x16x32_bf16 v[84:87], v[200:203], v[184:187], v[84:87]
	v_mfma_f32_16x16x32_bf16 v[80:83], v[208:211], v[184:187], v[80:83]
	v_mfma_f32_16x16x32_bf16 v[68:71], v[200:203], v[192:195], v[68:71]
	v_mfma_f32_16x16x32_bf16 v[64:67], v[208:211], v[192:195], v[64:67]
	s_mov_b32 m0, s38
	v_lshl_add_u64 v[212:213], v[216:217], 0, s[10:11]
	s_barrier
	ds_read_b128 v[164:167], v145 offset:49152
	ds_read_b128 v[168:171], v145 offset:50176
	ds_read_b128 v[172:175], v145 offset:51200
	ds_read_b128 v[176:179], v145 offset:52224
	ds_read_b128 v[180:183], v145 offset:53248
	ds_read_b128 v[184:187], v145 offset:54272
	ds_read_b128 v[188:191], v145 offset:55296
	ds_read_b128 v[192:195], v145 offset:56320
	global_load_lds_dwordx4 v[212:213], off
	v_lshl_add_u64 v[212:213], v[218:219], 0, s[10:11]
	s_mov_b32 m0, s39
	s_nop 0
	global_load_lds_dwordx4 v[212:213], off
	s_barrier
	s_waitcnt lgkmcnt(0)
	s_waitcnt lgkmcnt(0)
	v_mfma_f32_16x16x32_bf16 v[60:63], v[148:151], v[164:167], v[60:63]
	v_mfma_f32_16x16x32_bf16 v[56:59], v[156:159], v[164:167], v[56:59]
	v_mfma_f32_16x16x32_bf16 v[44:47], v[148:151], v[172:175], v[44:47]
	v_mfma_f32_16x16x32_bf16 v[40:43], v[156:159], v[172:175], v[40:43]
	v_mfma_f32_16x16x32_bf16 v[28:31], v[148:151], v[180:183], v[28:31]
	v_mfma_f32_16x16x32_bf16 v[24:27], v[156:159], v[180:183], v[24:27]
	v_mfma_f32_16x16x32_bf16 v[12:15], v[148:151], v[188:191], v[12:15]
	v_mfma_f32_16x16x32_bf16 v[8:11], v[156:159], v[188:191], v[8:11]
	v_mfma_f32_16x16x32_bf16 v[60:63], v[152:155], v[168:171], v[60:63]
	v_mfma_f32_16x16x32_bf16 v[56:59], v[160:163], v[168:171], v[56:59]
	v_mfma_f32_16x16x32_bf16 v[44:47], v[152:155], v[176:179], v[44:47]
	v_mfma_f32_16x16x32_bf16 v[40:43], v[160:163], v[176:179], v[40:43]
	v_mfma_f32_16x16x32_bf16 v[28:31], v[152:155], v[184:187], v[28:31]
	v_mfma_f32_16x16x32_bf16 v[24:27], v[160:163], v[184:187], v[24:27]
	v_mfma_f32_16x16x32_bf16 v[12:15], v[152:155], v[192:195], v[12:15]
	v_mfma_f32_16x16x32_bf16 v[8:11], v[160:163], v[192:195], v[8:11]
	s_barrier
	s_add_u32 s22, s28, 0x80080
	s_addc_u32 s23, s29, 0
	s_add_i32 s28, s30, s2
	s_mov_b32 m0, s28
	s_nop 0
	global_load_lds_dwordx4 v130, s[22:23]
	s_add_i32 m0, s28, 0x2000
	s_nop 0
	global_load_lds_dwordx4 v128, s[22:23]
	s_waitcnt vmcnt(6)
	s_barrier
	v_mfma_f32_16x16x32_bf16 v[52:55], v[196:199], v[164:167], v[52:55]
	v_mfma_f32_16x16x32_bf16 v[48:51], v[204:207], v[164:167], v[48:51]
	v_mfma_f32_16x16x32_bf16 v[36:39], v[196:199], v[172:175], v[36:39]
	v_mfma_f32_16x16x32_bf16 v[32:35], v[204:207], v[172:175], v[32:35]
	v_mfma_f32_16x16x32_bf16 v[20:23], v[196:199], v[180:183], v[20:23]
	v_mfma_f32_16x16x32_bf16 v[16:19], v[204:207], v[180:183], v[16:19]
	v_mfma_f32_16x16x32_bf16 v[4:7], v[196:199], v[188:191], v[4:7]
	v_mfma_f32_16x16x32_bf16 v[0:3], v[204:207], v[188:191], v[0:3]
	v_mfma_f32_16x16x32_bf16 v[52:55], v[200:203], v[168:171], v[52:55]
	v_mfma_f32_16x16x32_bf16 v[48:51], v[208:211], v[168:171], v[48:51]
	v_mfma_f32_16x16x32_bf16 v[36:39], v[200:203], v[176:179], v[36:39]
	v_mfma_f32_16x16x32_bf16 v[32:35], v[208:211], v[176:179], v[32:35]
	v_mfma_f32_16x16x32_bf16 v[20:23], v[200:203], v[184:187], v[20:23]
	v_mfma_f32_16x16x32_bf16 v[16:19], v[208:211], v[184:187], v[16:19]
	v_mfma_f32_16x16x32_bf16 v[4:7], v[200:203], v[192:195], v[4:7]
	v_mfma_f32_16x16x32_bf16 v[0:3], v[208:211], v[192:195], v[0:3]
	s_add_i32 s57, s57, 2
	s_add_u32 s53, s53, 0x100
	s_addc_u32 s56, s56, 0
	s_cmp_gt_u32 s57, 29
	s_mov_b64 s[22:23], s[26:27]
	s_barrier
	s_cbranch_scc0 .LBB0_2812
	v_mul_f32_e32 v150, 0xbfb8aa3b, v124
	v_mul_f32_e32 v151, 0xbfb8aa3b, v125
	v_exp_f32_e32 v150, v150
	v_exp_f32_e32 v151, v151
	s_lshl_b32 s13, s21, 7
	v_lshl_add_u32 v147, s20, 8, v142
	v_add_f32_e32 v150, 1.0, v150
	v_add_f32_e32 v151, 1.0, v151
	v_rcp_f32_e32 v150, v150
	v_rcp_f32_e32 v151, v151
	s_or_b32 s20, s13, s40
	s_ashr_i32 s21, s20, 31
	v_mad_i64_i32 v[148:149], s[22:23], v147, s46, v[132:133]
	v_pk_mul_f32 v[124:125], v[124:125], v[150:151]
	s_lshl_b64 s[20:21], s[20:21], 1
	v_pk_mul_f32 v[120:121], v[120:121], v[124:125]
	s_and_b64 vcc, exec, s[8:9]
	v_cvt_pk_bf16_f32 v120, v120, v121
	v_mul_f32_e32 v121, 0xbfb8aa3b, v126
	v_exp_f32_e32 v121, v121
	s_mov_b64 s[26:27], s[18:19]
	v_add_f32_e32 v121, 1.0, v121
	v_rcp_f32_e32 v124, v121
	v_mul_f32_e32 v121, 0xbfb8aa3b, v127
	v_exp_f32_e32 v121, v121
	s_nop 0
	v_add_f32_e32 v121, 1.0, v121
	v_rcp_f32_e32 v125, v121
	s_nop 0
	v_pk_mul_f32 v[124:125], v[126:127], v[124:125]
	s_nop 0
	v_pk_mul_f32 v[122:123], v[122:123], v[124:125]
	s_nop 0
	v_cvt_pk_bf16_f32 v121, v122, v123
	v_lshl_add_u64 v[122:123], v[148:149], 0, s[20:21]
	global_store_dwordx2 v[122:123], v[120:121], off
	v_mul_f32_e32 v120, 0xbfb8aa3b, v116
	v_mul_f32_e32 v121, 0xbfb8aa3b, v117
	v_exp_f32_e32 v120, v120
	v_exp_f32_e32 v121, v121
	v_add_f32_e32 v120, 1.0, v120
	v_add_f32_e32 v121, 1.0, v121
	v_rcp_f32_e32 v120, v120
	v_rcp_f32_e32 v121, v121
	s_nop 0
	v_pk_mul_f32 v[116:117], v[116:117], v[120:121]
	s_nop 0
	v_pk_mul_f32 v[112:113], v[112:113], v[116:117]
	s_nop 0
	v_cvt_pk_bf16_f32 v112, v112, v113
	v_mul_f32_e32 v113, 0xbfb8aa3b, v118
	v_exp_f32_e32 v113, v113
	s_nop 0
	v_add_f32_e32 v113, 1.0, v113
	v_rcp_f32_e32 v116, v113
	v_mul_f32_e32 v113, 0xbfb8aa3b, v119
	v_exp_f32_e32 v113, v113
	s_nop 0
	v_add_f32_e32 v113, 1.0, v113
	v_rcp_f32_e32 v117, v113
	s_nop 0
	v_pk_mul_f32 v[116:117], v[118:119], v[116:117]
	s_nop 0
	v_pk_mul_f32 v[114:115], v[114:115], v[116:117]
	s_nop 0
	v_cvt_pk_bf16_f32 v113, v114, v115
	v_mul_f32_e32 v114, 0xbfb8aa3b, v108
	v_mul_f32_e32 v115, 0xbfb8aa3b, v109
	v_exp_f32_e32 v114, v114
	v_exp_f32_e32 v115, v115
	global_store_dwordx2 v[122:123], v[112:113], off offset:128
	v_or_b32_e32 v112, 16, v147
	v_add_f32_e32 v114, 1.0, v114
	v_add_f32_e32 v115, 1.0, v115
	v_rcp_f32_e32 v114, v114
	v_rcp_f32_e32 v115, v115
	v_mad_i64_i32 v[112:113], s[22:23], v112, s46, v[132:133]
	v_pk_mul_f32 v[108:109], v[108:109], v[114:115]
	s_nop 0
	v_pk_mul_f32 v[104:105], v[104:105], v[108:109]
	s_nop 0
	v_cvt_pk_bf16_f32 v104, v104, v105
	v_mul_f32_e32 v105, 0xbfb8aa3b, v110
	v_exp_f32_e32 v105, v105
	s_nop 0
	v_add_f32_e32 v105, 1.0, v105
	v_rcp_f32_e32 v108, v105
	v_mul_f32_e32 v105, 0xbfb8aa3b, v111
	v_exp_f32_e32 v105, v105
	s_nop 0
	v_add_f32_e32 v105, 1.0, v105
	v_rcp_f32_e32 v109, v105
	s_nop 0
	v_pk_mul_f32 v[108:109], v[110:111], v[108:109]
	s_nop 0
	v_pk_mul_f32 v[106:107], v[106:107], v[108:109]
	s_nop 0
	v_cvt_pk_bf16_f32 v105, v106, v107
	v_lshl_add_u64 v[106:107], v[112:113], 0, s[20:21]
	global_store_dwordx2 v[106:107], v[104:105], off
	v_mul_f32_e32 v104, 0xbfb8aa3b, v100
	v_mul_f32_e32 v105, 0xbfb8aa3b, v101
	v_exp_f32_e32 v104, v104
	v_exp_f32_e32 v105, v105
	v_add_f32_e32 v104, 1.0, v104
	v_add_f32_e32 v105, 1.0, v105
	v_rcp_f32_e32 v104, v104
	v_rcp_f32_e32 v105, v105
	s_nop 0
	v_pk_mul_f32 v[100:101], v[100:101], v[104:105]
	s_nop 0
	v_pk_mul_f32 v[96:97], v[96:97], v[100:101]
	s_nop 0
	v_cvt_pk_bf16_f32 v96, v96, v97
	v_mul_f32_e32 v97, 0xbfb8aa3b, v102
	v_exp_f32_e32 v97, v97
	s_nop 0
	v_add_f32_e32 v97, 1.0, v97
	v_rcp_f32_e32 v100, v97
	v_mul_f32_e32 v97, 0xbfb8aa3b, v103
	v_exp_f32_e32 v97, v97
	s_nop 0
	v_add_f32_e32 v97, 1.0, v97
	v_rcp_f32_e32 v101, v97
	s_nop 0
	v_pk_mul_f32 v[100:101], v[102:103], v[100:101]
	s_nop 0
	v_pk_mul_f32 v[98:99], v[98:99], v[100:101]
	s_nop 0
	v_cvt_pk_bf16_f32 v97, v98, v99
	v_mul_f32_e32 v98, 0xbfb8aa3b, v92
	v_mul_f32_e32 v99, 0xbfb8aa3b, v93
	v_exp_f32_e32 v98, v98
	v_exp_f32_e32 v99, v99
	global_store_dwordx2 v[106:107], v[96:97], off offset:128
	v_or_b32_e32 v96, 32, v147
	v_add_f32_e32 v98, 1.0, v98
	v_add_f32_e32 v99, 1.0, v99
	v_rcp_f32_e32 v98, v98
	v_rcp_f32_e32 v99, v99
	v_mad_i64_i32 v[96:97], s[22:23], v96, s46, v[132:133]
	v_pk_mul_f32 v[92:93], v[92:93], v[98:99]
	s_nop 0
	v_pk_mul_f32 v[88:89], v[88:89], v[92:93]
	s_nop 0
	v_cvt_pk_bf16_f32 v88, v88, v89
	v_mul_f32_e32 v89, 0xbfb8aa3b, v94
	v_exp_f32_e32 v89, v89
	s_nop 0
	v_add_f32_e32 v89, 1.0, v89
	v_rcp_f32_e32 v92, v89
	v_mul_f32_e32 v89, 0xbfb8aa3b, v95
	v_exp_f32_e32 v89, v89
	s_nop 0
	v_add_f32_e32 v89, 1.0, v89
	v_rcp_f32_e32 v93, v89
	s_nop 0
	v_pk_mul_f32 v[92:93], v[94:95], v[92:93]
	s_nop 0
	v_pk_mul_f32 v[90:91], v[90:91], v[92:93]
	s_nop 0
	v_cvt_pk_bf16_f32 v89, v90, v91
	v_lshl_add_u64 v[90:91], v[96:97], 0, s[20:21]
	global_store_dwordx2 v[90:91], v[88:89], off
	v_mul_f32_e32 v88, 0xbfb8aa3b, v84
	v_mul_f32_e32 v89, 0xbfb8aa3b, v85
	v_exp_f32_e32 v88, v88
	v_exp_f32_e32 v89, v89
	v_add_f32_e32 v88, 1.0, v88
	v_add_f32_e32 v89, 1.0, v89
	v_rcp_f32_e32 v88, v88
	v_rcp_f32_e32 v89, v89
	s_nop 0
	v_pk_mul_f32 v[84:85], v[84:85], v[88:89]
	s_nop 0
	v_pk_mul_f32 v[80:81], v[80:81], v[84:85]
	s_nop 0
	v_cvt_pk_bf16_f32 v80, v80, v81
	v_mul_f32_e32 v81, 0xbfb8aa3b, v86
	v_exp_f32_e32 v81, v81
	s_nop 0
	v_add_f32_e32 v81, 1.0, v81
	v_rcp_f32_e32 v84, v81
	v_mul_f32_e32 v81, 0xbfb8aa3b, v87
	v_exp_f32_e32 v81, v81
	s_nop 0
	v_add_f32_e32 v81, 1.0, v81
	v_rcp_f32_e32 v85, v81
	s_nop 0
	v_pk_mul_f32 v[84:85], v[86:87], v[84:85]
	s_nop 0
	v_pk_mul_f32 v[82:83], v[82:83], v[84:85]
	s_nop 0
	v_cvt_pk_bf16_f32 v81, v82, v83
	v_mul_f32_e32 v82, 0xbfb8aa3b, v76
	v_mul_f32_e32 v83, 0xbfb8aa3b, v77
	v_exp_f32_e32 v82, v82
	v_exp_f32_e32 v83, v83
	global_store_dwordx2 v[90:91], v[80:81], off offset:128
	v_or_b32_e32 v80, 48, v147
	v_add_f32_e32 v82, 1.0, v82
	v_add_f32_e32 v83, 1.0, v83
	v_rcp_f32_e32 v82, v82
	v_rcp_f32_e32 v83, v83
	v_mad_i64_i32 v[80:81], s[22:23], v80, s46, v[132:133]
	v_pk_mul_f32 v[76:77], v[76:77], v[82:83]
	s_nop 0
	v_pk_mul_f32 v[72:73], v[72:73], v[76:77]
	s_nop 0
	v_cvt_pk_bf16_f32 v72, v72, v73
	v_mul_f32_e32 v73, 0xbfb8aa3b, v78
	v_exp_f32_e32 v73, v73
	s_nop 0
	v_add_f32_e32 v73, 1.0, v73
	v_rcp_f32_e32 v76, v73
	v_mul_f32_e32 v73, 0xbfb8aa3b, v79
	v_exp_f32_e32 v73, v73
	s_nop 0
	v_add_f32_e32 v73, 1.0, v73
	v_rcp_f32_e32 v77, v73
	s_nop 0
	v_pk_mul_f32 v[76:77], v[78:79], v[76:77]
	s_nop 0
	v_pk_mul_f32 v[74:75], v[74:75], v[76:77]
	s_nop 0
	v_cvt_pk_bf16_f32 v73, v74, v75
	v_lshl_add_u64 v[74:75], v[80:81], 0, s[20:21]
	global_store_dwordx2 v[74:75], v[72:73], off
	v_mul_f32_e32 v72, 0xbfb8aa3b, v68
	v_mul_f32_e32 v73, 0xbfb8aa3b, v69
	v_exp_f32_e32 v72, v72
	v_exp_f32_e32 v73, v73
	v_add_f32_e32 v72, 1.0, v72
	v_add_f32_e32 v73, 1.0, v73
	v_rcp_f32_e32 v72, v72
	v_rcp_f32_e32 v73, v73
	s_nop 0
	v_pk_mul_f32 v[68:69], v[68:69], v[72:73]
	s_nop 0
	v_pk_mul_f32 v[64:65], v[64:65], v[68:69]
	s_nop 0
	v_cvt_pk_bf16_f32 v64, v64, v65
	v_mul_f32_e32 v65, 0xbfb8aa3b, v70
	v_exp_f32_e32 v65, v65
	s_nop 0
	v_add_f32_e32 v65, 1.0, v65
	v_rcp_f32_e32 v68, v65
	v_mul_f32_e32 v65, 0xbfb8aa3b, v71
	v_exp_f32_e32 v65, v65
	s_nop 0
	v_add_f32_e32 v65, 1.0, v65
	v_rcp_f32_e32 v69, v65
	s_nop 0
	v_pk_mul_f32 v[68:69], v[70:71], v[68:69]
	s_nop 0
	v_pk_mul_f32 v[66:67], v[66:67], v[68:69]
	s_nop 0
	v_cvt_pk_bf16_f32 v65, v66, v67
	v_mul_f32_e32 v66, 0xbfb8aa3b, v60
	v_mul_f32_e32 v67, 0xbfb8aa3b, v61
	v_exp_f32_e32 v66, v66
	v_exp_f32_e32 v67, v67
	global_store_dwordx2 v[74:75], v[64:65], off offset:128
	v_add_u32_e32 v64, 0x80, v147
	v_add_f32_e32 v66, 1.0, v66
	v_add_f32_e32 v67, 1.0, v67
	v_rcp_f32_e32 v66, v66
	v_rcp_f32_e32 v67, v67
	v_mad_i64_i32 v[64:65], s[22:23], v64, s46, v[132:133]
	v_pk_mul_f32 v[60:61], v[60:61], v[66:67]
	s_nop 0
	v_pk_mul_f32 v[56:57], v[56:57], v[60:61]
	s_nop 0
	v_cvt_pk_bf16_f32 v56, v56, v57
	v_mul_f32_e32 v57, 0xbfb8aa3b, v62
	v_exp_f32_e32 v57, v57
	s_nop 0
	v_add_f32_e32 v57, 1.0, v57
	v_rcp_f32_e32 v60, v57
	v_mul_f32_e32 v57, 0xbfb8aa3b, v63
	v_exp_f32_e32 v57, v57
	s_nop 0
	v_add_f32_e32 v57, 1.0, v57
	v_rcp_f32_e32 v61, v57
	s_nop 0
	v_pk_mul_f32 v[60:61], v[62:63], v[60:61]
	s_nop 0
	v_pk_mul_f32 v[58:59], v[58:59], v[60:61]
	s_nop 0
	v_cvt_pk_bf16_f32 v57, v58, v59
	v_lshl_add_u64 v[58:59], v[64:65], 0, s[20:21]
	global_store_dwordx2 v[58:59], v[56:57], off
	v_mul_f32_e32 v56, 0xbfb8aa3b, v52
	v_mul_f32_e32 v57, 0xbfb8aa3b, v53
	v_exp_f32_e32 v56, v56
	v_exp_f32_e32 v57, v57
	v_add_f32_e32 v56, 1.0, v56
	v_add_f32_e32 v57, 1.0, v57
	v_rcp_f32_e32 v56, v56
	v_rcp_f32_e32 v57, v57
	s_nop 0
	v_pk_mul_f32 v[52:53], v[52:53], v[56:57]
	s_nop 0
	v_pk_mul_f32 v[48:49], v[48:49], v[52:53]
	s_nop 0
	v_cvt_pk_bf16_f32 v48, v48, v49
	v_mul_f32_e32 v49, 0xbfb8aa3b, v54
	v_exp_f32_e32 v49, v49
	s_nop 0
	v_add_f32_e32 v49, 1.0, v49
	v_rcp_f32_e32 v52, v49
	v_mul_f32_e32 v49, 0xbfb8aa3b, v55
	v_exp_f32_e32 v49, v49
	s_nop 0
	v_add_f32_e32 v49, 1.0, v49
	v_rcp_f32_e32 v53, v49
	s_nop 0
	v_pk_mul_f32 v[52:53], v[54:55], v[52:53]
	s_nop 0
	v_pk_mul_f32 v[50:51], v[50:51], v[52:53]
	s_nop 0
	v_cvt_pk_bf16_f32 v49, v50, v51
	v_mul_f32_e32 v50, 0xbfb8aa3b, v44
	v_mul_f32_e32 v51, 0xbfb8aa3b, v45
	v_exp_f32_e32 v50, v50
	v_exp_f32_e32 v51, v51
	global_store_dwordx2 v[58:59], v[48:49], off offset:128
	v_add_u32_e32 v48, 0x90, v147
	v_add_f32_e32 v50, 1.0, v50
	v_add_f32_e32 v51, 1.0, v51
	v_rcp_f32_e32 v50, v50
	v_rcp_f32_e32 v51, v51
	v_mad_i64_i32 v[48:49], s[22:23], v48, s46, v[132:133]
	v_pk_mul_f32 v[44:45], v[44:45], v[50:51]
	s_nop 0
	v_pk_mul_f32 v[40:41], v[40:41], v[44:45]
	s_nop 0
	v_cvt_pk_bf16_f32 v40, v40, v41
	v_mul_f32_e32 v41, 0xbfb8aa3b, v46
	v_exp_f32_e32 v41, v41
	s_nop 0
	v_add_f32_e32 v41, 1.0, v41
	v_rcp_f32_e32 v44, v41
	v_mul_f32_e32 v41, 0xbfb8aa3b, v47
	v_exp_f32_e32 v41, v41
	s_nop 0
	v_add_f32_e32 v41, 1.0, v41
	v_rcp_f32_e32 v45, v41
	s_nop 0
	v_pk_mul_f32 v[44:45], v[46:47], v[44:45]
	s_nop 0
	v_pk_mul_f32 v[42:43], v[42:43], v[44:45]
	s_nop 0
	v_cvt_pk_bf16_f32 v41, v42, v43
	v_lshl_add_u64 v[42:43], v[48:49], 0, s[20:21]
	global_store_dwordx2 v[42:43], v[40:41], off
	v_mul_f32_e32 v40, 0xbfb8aa3b, v36
	v_mul_f32_e32 v41, 0xbfb8aa3b, v37
	v_exp_f32_e32 v40, v40
	v_exp_f32_e32 v41, v41
	v_add_f32_e32 v40, 1.0, v40
	v_add_f32_e32 v41, 1.0, v41
	v_rcp_f32_e32 v40, v40
	v_rcp_f32_e32 v41, v41
	s_nop 0
	v_pk_mul_f32 v[36:37], v[36:37], v[40:41]
	s_nop 0
	v_pk_mul_f32 v[32:33], v[32:33], v[36:37]
	s_nop 0
	v_cvt_pk_bf16_f32 v32, v32, v33
	v_mul_f32_e32 v33, 0xbfb8aa3b, v38
	v_exp_f32_e32 v33, v33
	s_nop 0
	v_add_f32_e32 v33, 1.0, v33
	v_rcp_f32_e32 v36, v33
	v_mul_f32_e32 v33, 0xbfb8aa3b, v39
	v_exp_f32_e32 v33, v33
	s_nop 0
	v_add_f32_e32 v33, 1.0, v33
	v_rcp_f32_e32 v37, v33
	s_nop 0
	v_pk_mul_f32 v[36:37], v[38:39], v[36:37]
	s_nop 0
	v_pk_mul_f32 v[34:35], v[34:35], v[36:37]
	s_nop 0
	v_cvt_pk_bf16_f32 v33, v34, v35
	v_mul_f32_e32 v34, 0xbfb8aa3b, v28
	v_mul_f32_e32 v35, 0xbfb8aa3b, v29
	v_exp_f32_e32 v34, v34
	v_exp_f32_e32 v35, v35
	global_store_dwordx2 v[42:43], v[32:33], off offset:128
	v_add_u32_e32 v32, 0xa0, v147
	v_add_f32_e32 v34, 1.0, v34
	v_add_f32_e32 v35, 1.0, v35
	v_rcp_f32_e32 v34, v34
	v_rcp_f32_e32 v35, v35
	v_mad_i64_i32 v[32:33], s[22:23], v32, s46, v[132:133]
	v_pk_mul_f32 v[28:29], v[28:29], v[34:35]
	s_nop 0
	v_pk_mul_f32 v[24:25], v[24:25], v[28:29]
	s_nop 0
	v_cvt_pk_bf16_f32 v24, v24, v25
	v_mul_f32_e32 v25, 0xbfb8aa3b, v30
	v_exp_f32_e32 v25, v25
	s_nop 0
	v_add_f32_e32 v25, 1.0, v25
	v_rcp_f32_e32 v28, v25
	v_mul_f32_e32 v25, 0xbfb8aa3b, v31
	v_exp_f32_e32 v25, v25
	s_nop 0
	v_add_f32_e32 v25, 1.0, v25
	v_rcp_f32_e32 v29, v25
	s_nop 0
	v_pk_mul_f32 v[28:29], v[30:31], v[28:29]
	s_nop 0
	v_pk_mul_f32 v[26:27], v[26:27], v[28:29]
	s_nop 0
	v_cvt_pk_bf16_f32 v25, v26, v27
	v_lshl_add_u64 v[26:27], v[32:33], 0, s[20:21]
	global_store_dwordx2 v[26:27], v[24:25], off
	v_mul_f32_e32 v24, 0xbfb8aa3b, v20
	v_mul_f32_e32 v25, 0xbfb8aa3b, v21
	v_exp_f32_e32 v24, v24
	v_exp_f32_e32 v25, v25
	v_add_f32_e32 v24, 1.0, v24
	v_add_f32_e32 v25, 1.0, v25
	v_rcp_f32_e32 v24, v24
	v_rcp_f32_e32 v25, v25
	s_nop 0
	v_pk_mul_f32 v[20:21], v[20:21], v[24:25]
	s_nop 0
	v_pk_mul_f32 v[16:17], v[16:17], v[20:21]
	s_nop 0
	v_cvt_pk_bf16_f32 v16, v16, v17
	v_mul_f32_e32 v17, 0xbfb8aa3b, v22
	v_exp_f32_e32 v17, v17
	s_nop 0
	v_add_f32_e32 v17, 1.0, v17
	v_rcp_f32_e32 v20, v17
	v_mul_f32_e32 v17, 0xbfb8aa3b, v23
	v_exp_f32_e32 v17, v17
	s_nop 0
	v_add_f32_e32 v17, 1.0, v17
	v_rcp_f32_e32 v21, v17
	s_nop 0
	v_pk_mul_f32 v[20:21], v[22:23], v[20:21]
	s_nop 0
	v_pk_mul_f32 v[18:19], v[18:19], v[20:21]
	s_nop 0
	v_cvt_pk_bf16_f32 v17, v18, v19
	v_mul_f32_e32 v18, 0xbfb8aa3b, v12
	v_mul_f32_e32 v19, 0xbfb8aa3b, v13
	v_exp_f32_e32 v18, v18
	v_exp_f32_e32 v19, v19
	global_store_dwordx2 v[26:27], v[16:17], off offset:128
	v_add_u32_e32 v16, 0xb0, v147
	v_add_f32_e32 v18, 1.0, v18
	v_add_f32_e32 v19, 1.0, v19
	v_rcp_f32_e32 v18, v18
	v_rcp_f32_e32 v19, v19
	v_mad_i64_i32 v[16:17], s[22:23], v16, s46, v[132:133]
	s_mov_b64 s[22:23], s[16:17]
	v_pk_mul_f32 v[12:13], v[12:13], v[18:19]
	s_nop 0
	v_pk_mul_f32 v[8:9], v[8:9], v[12:13]
	s_nop 0
	v_cvt_pk_bf16_f32 v8, v8, v9
	v_mul_f32_e32 v9, 0xbfb8aa3b, v14
	v_exp_f32_e32 v9, v9
	s_nop 0
	v_add_f32_e32 v9, 1.0, v9
	v_rcp_f32_e32 v12, v9
	v_mul_f32_e32 v9, 0xbfb8aa3b, v15
	v_exp_f32_e32 v9, v9
	s_nop 0
	v_add_f32_e32 v9, 1.0, v9
	v_rcp_f32_e32 v13, v9
	s_nop 0
	v_pk_mul_f32 v[12:13], v[14:15], v[12:13]
	s_nop 0
	v_pk_mul_f32 v[10:11], v[10:11], v[12:13]
	s_nop 0
	v_cvt_pk_bf16_f32 v9, v10, v11
	v_lshl_add_u64 v[10:11], v[16:17], 0, s[20:21]
	global_store_dwordx2 v[10:11], v[8:9], off
	v_mul_f32_e32 v8, 0xbfb8aa3b, v4
	v_mul_f32_e32 v9, 0xbfb8aa3b, v5
	v_exp_f32_e32 v8, v8
	v_exp_f32_e32 v9, v9
	s_mov_b32 s21, s12
	s_mov_b32 s20, s14
	v_add_f32_e32 v8, 1.0, v8
	v_add_f32_e32 v9, 1.0, v9
	v_rcp_f32_e32 v8, v8
	v_rcp_f32_e32 v9, v9
	s_nop 0
	v_pk_mul_f32 v[4:5], v[4:5], v[8:9]
	s_nop 0
	v_pk_mul_f32 v[0:1], v[0:1], v[4:5]
	s_nop 0
	v_cvt_pk_bf16_f32 v0, v0, v1
	v_mul_f32_e32 v1, 0xbfb8aa3b, v6
	v_exp_f32_e32 v1, v1
	s_nop 0
	v_add_f32_e32 v1, 1.0, v1
	v_rcp_f32_e32 v4, v1
	v_mul_f32_e32 v1, 0xbfb8aa3b, v7
	v_exp_f32_e32 v1, v1
	s_nop 0
	v_add_f32_e32 v1, 1.0, v1
	v_rcp_f32_e32 v5, v1
	s_nop 0
	v_pk_mul_f32 v[4:5], v[6:7], v[4:5]
	s_nop 0
	v_pk_mul_f32 v[2:3], v[2:3], v[4:5]
	s_nop 0
	v_cvt_pk_bf16_f32 v1, v2, v3
	global_store_dwordx2 v[10:11], v[0:1], off offset:128
	s_cbranch_vccz .LBB0_2809
	s_waitcnt vmcnt(0)
	s_cmpk_gt_u32 s1, 0xff
	s_cbranch_scc1 .LBB0_2816
	s_barrier

.LBB0_2911:
	ds_read_b128 v[128:131], v151
	ds_read_b128 v[144:147], v151 offset:1024
	ds_read_b128 v[154:157], v151 offset:2048
	ds_read_b128 v[158:161], v151 offset:3072
	s_add_i32 m0, s4, 0xc000
	ds_read_b128 v[162:165], v152
	ds_read_b128 v[166:169], v152 offset:1024
	ds_read_b128 v[170:173], v152 offset:2048
	ds_read_b128 v[174:177], v152 offset:3072
	ds_read_b128 v[178:181], v152 offset:4096
	ds_read_b128 v[182:185], v152 offset:5120
	ds_read_b128 v[186:189], v152 offset:6144
	ds_read_b128 v[190:193], v152 offset:7168
	global_load_lds_dwordx4 v136, s[16:17]
	v_lshl_add_u64 v[194:195], s[16:17], 0, v[138:139]
	s_add_i32 m0, s4, 0xe000
	s_nop 0
	global_load_lds_dwordx4 v[194:195], off
	s_waitcnt lgkmcnt(8)
	s_barrier
	s_waitcnt lgkmcnt(0)
	s_waitcnt lgkmcnt(0)
	v_mfma_f32_16x16x32_bf16 v[124:127], v[128:131], v[162:165], v[124:127]
	s_add_u32 s18, s16, 0x100
	s_addc_u32 s19, s17, 0
	s_cmpk_eq_i32 s46, 0x54
	s_cselect_b32 s23, s11, s19
	s_cselect_b32 s22, s10, s18
	s_cselect_b32 s21, s13, s43
	s_cselect_b32 s20, s12, s42
	v_mfma_f32_16x16x32_bf16 v[92:95], v[154:157], v[162:165], v[92:95]
	v_mfma_f32_16x16x32_bf16 v[120:123], v[128:131], v[170:173], v[120:123]
	v_mfma_f32_16x16x32_bf16 v[88:91], v[154:157], v[170:173], v[88:91]
	v_mfma_f32_16x16x32_bf16 v[116:119], v[128:131], v[178:181], v[116:119]
	v_mfma_f32_16x16x32_bf16 v[84:87], v[154:157], v[178:181], v[84:87]
	v_mfma_f32_16x16x32_bf16 v[112:115], v[128:131], v[186:189], v[112:115]
	v_mfma_f32_16x16x32_bf16 v[80:83], v[154:157], v[186:189], v[80:83]
	v_mfma_f32_16x16x32_bf16 v[124:127], v[144:147], v[166:169], v[124:127]
	v_mfma_f32_16x16x32_bf16 v[92:95], v[158:161], v[166:169], v[92:95]
	v_mfma_f32_16x16x32_bf16 v[120:123], v[144:147], v[174:177], v[120:123]
	v_mfma_f32_16x16x32_bf16 v[88:91], v[158:161], v[174:177], v[88:91]
	v_mfma_f32_16x16x32_bf16 v[116:119], v[144:147], v[182:185], v[116:119]
	v_mfma_f32_16x16x32_bf16 v[84:87], v[158:161], v[182:185], v[84:87]
	v_mfma_f32_16x16x32_bf16 v[112:115], v[144:147], v[190:193], v[112:115]
	v_mfma_f32_16x16x32_bf16 v[80:83], v[158:161], v[190:193], v[80:83]
	s_barrier
	s_add_i32 s16, s36, s3
	v_lshl_add_u64 v[210:211], s[20:21], 0, v[132:133]
	s_mov_b32 m0, s16
	ds_read_b128 v[194:197], v153
	ds_read_b128 v[198:201], v153 offset:1024
	ds_read_b128 v[202:205], v153 offset:2048
	ds_read_b128 v[206:209], v153 offset:3072
	global_load_lds_dwordx4 v[210:211], off
	s_add_i32 m0, s16, 0x2000
	s_nop 0
	global_load_lds_dwordx4 v134, s[20:21]
	s_barrier
	s_waitcnt lgkmcnt(0)
	s_waitcnt lgkmcnt(0)
	v_mfma_f32_16x16x32_bf16 v[76:79], v[194:197], v[162:165], v[76:79]
	v_mfma_f32_16x16x32_bf16 v[48:51], v[202:205], v[162:165], v[48:51]
	v_mfma_f32_16x16x32_bf16 v[68:71], v[194:197], v[170:173], v[68:71]
	v_mfma_f32_16x16x32_bf16 v[40:43], v[202:205], v[170:173], v[40:43]
	v_mfma_f32_16x16x32_bf16 v[60:63], v[194:197], v[178:181], v[60:63]
	v_mfma_f32_16x16x32_bf16 v[36:39], v[202:205], v[178:181], v[36:39]
	v_mfma_f32_16x16x32_bf16 v[52:55], v[194:197], v[186:189], v[52:55]
	v_mfma_f32_16x16x32_bf16 v[28:31], v[202:205], v[186:189], v[28:31]
	v_mfma_f32_16x16x32_bf16 v[76:79], v[198:201], v[166:169], v[76:79]
	v_mfma_f32_16x16x32_bf16 v[48:51], v[206:209], v[166:169], v[48:51]
	v_mfma_f32_16x16x32_bf16 v[68:71], v[198:201], v[174:177], v[68:71]
	v_mfma_f32_16x16x32_bf16 v[40:43], v[206:209], v[174:177], v[40:43]
	v_mfma_f32_16x16x32_bf16 v[60:63], v[198:201], v[182:185], v[60:63]
	v_mfma_f32_16x16x32_bf16 v[36:39], v[206:209], v[182:185], v[36:39]
	v_mfma_f32_16x16x32_bf16 v[52:55], v[198:201], v[190:193], v[52:55]
	v_mfma_f32_16x16x32_bf16 v[28:31], v[206:209], v[190:193], v[28:31]
	s_mov_b32 m0, s4
	v_lshl_add_u64 v[214:215], s[22:23], 0, v[132:133]
	s_barrier
	ds_read_b128 v[162:165], v152 offset:16384
	ds_read_b128 v[166:169], v152 offset:17408
	ds_read_b128 v[170:173], v152 offset:18432
	ds_read_b128 v[174:177], v152 offset:19456
	ds_read_b128 v[178:181], v152 offset:20480
	ds_read_b128 v[182:185], v152 offset:21504
	ds_read_b128 v[186:189], v152 offset:22528
	ds_read_b128 v[190:193], v152 offset:23552
	global_load_lds_dwordx4 v[214:215], off
	v_lshl_add_u64 v[216:217], s[22:23], 0, v[134:135]
	s_mov_b32 m0, s5
	s_nop 0
	global_load_lds_dwordx4 v134, s[22:23]
	s_barrier
	s_waitcnt lgkmcnt(0)
	s_waitcnt lgkmcnt(0)
	v_mfma_f32_16x16x32_bf16 v[108:111], v[128:131], v[162:165], v[108:111]
	v_mfma_f32_16x16x32_bf16 v[72:75], v[154:157], v[162:165], v[72:75]
	v_mfma_f32_16x16x32_bf16 v[104:107], v[128:131], v[170:173], v[104:107]
	v_mfma_f32_16x16x32_bf16 v[64:67], v[154:157], v[170:173], v[64:67]
	v_mfma_f32_16x16x32_bf16 v[100:103], v[128:131], v[178:181], v[100:103]
	v_mfma_f32_16x16x32_bf16 v[56:59], v[154:157], v[178:181], v[56:59]
	v_mfma_f32_16x16x32_bf16 v[96:99], v[128:131], v[186:189], v[96:99]
	v_mfma_f32_16x16x32_bf16 v[44:47], v[154:157], v[186:189], v[44:47]
	v_mfma_f32_16x16x32_bf16 v[108:111], v[144:147], v[166:169], v[108:111]
	v_mfma_f32_16x16x32_bf16 v[72:75], v[158:161], v[166:169], v[72:75]
	v_mfma_f32_16x16x32_bf16 v[104:107], v[144:147], v[174:177], v[104:107]
	v_mfma_f32_16x16x32_bf16 v[64:67], v[158:161], v[174:177], v[64:67]
	v_mfma_f32_16x16x32_bf16 v[100:103], v[144:147], v[182:185], v[100:103]
	v_mfma_f32_16x16x32_bf16 v[56:59], v[158:161], v[182:185], v[56:59]
	v_mfma_f32_16x16x32_bf16 v[96:99], v[144:147], v[190:193], v[96:99]
	v_mfma_f32_16x16x32_bf16 v[44:47], v[158:161], v[190:193], v[44:47]
	s_barrier
	s_add_u32 s16, s20, 0x160000
	s_addc_u32 s17, s21, 0
	s_add_i32 s47, s37, s3
	v_lshl_add_u64 v[128:129], s[16:17], 0, v[132:133]
	s_mov_b32 m0, s47
	s_nop 0
	global_load_lds_dwordx4 v[128:129], off
	s_add_i32 m0, s47, 0x2000
	s_nop 0
	global_load_lds_dwordx4 v134, s[16:17]
	s_waitcnt vmcnt(6)
	s_barrier
	v_mfma_f32_16x16x32_bf16 v[32:35], v[194:197], v[162:165], v[32:35]
	v_mfma_f32_16x16x32_bf16 v[12:15], v[202:205], v[162:165], v[12:15]
	v_mfma_f32_16x16x32_bf16 v[24:27], v[194:197], v[170:173], v[24:27]
	v_mfma_f32_16x16x32_bf16 v[8:11], v[202:205], v[170:173], v[8:11]
	v_mfma_f32_16x16x32_bf16 v[20:23], v[194:197], v[178:181], v[20:23]
	v_mfma_f32_16x16x32_bf16 v[4:7], v[202:205], v[178:181], v[4:7]
	v_mfma_f32_16x16x32_bf16 v[16:19], v[194:197], v[186:189], v[16:19]
	v_mfma_f32_16x16x32_bf16 v[0:3], v[202:205], v[186:189], v[0:3]
	v_mfma_f32_16x16x32_bf16 v[32:35], v[198:201], v[166:169], v[32:35]
	v_mfma_f32_16x16x32_bf16 v[12:15], v[206:209], v[166:169], v[12:15]
	v_mfma_f32_16x16x32_bf16 v[24:27], v[198:201], v[174:177], v[24:27]
	v_mfma_f32_16x16x32_bf16 v[8:11], v[206:209], v[174:177], v[8:11]
	v_mfma_f32_16x16x32_bf16 v[20:23], v[198:201], v[182:185], v[20:23]
	v_mfma_f32_16x16x32_bf16 v[4:7], v[206:209], v[182:185], v[4:7]
	v_mfma_f32_16x16x32_bf16 v[16:19], v[198:201], v[190:193], v[16:19]
	v_mfma_f32_16x16x32_bf16 v[0:3], v[206:209], v[190:193], v[0:3]
	s_add_i32 s47, 0, 0x18000
	v_add_u32_e32 v158, s47, v149
	s_barrier
	ds_read_b128 v[128:131], v158
	ds_read_b128 v[144:147], v158 offset:1024
	ds_read_b128 v[154:157], v158 offset:2048
	ds_read_b128 v[158:161], v158 offset:3072
	s_add_u32 s16, s22, 0x160000
	s_addc_u32 s17, s23, 0
	s_mov_b32 m0, s26
	v_lshl_add_u64 v[194:195], s[16:17], 0, v[132:133]
	ds_read_b128 v[162:165], v152 offset:32768
	ds_read_b128 v[166:169], v152 offset:33792
	ds_read_b128 v[170:173], v152 offset:34816
	ds_read_b128 v[174:177], v152 offset:35840
	ds_read_b128 v[178:181], v152 offset:36864
	ds_read_b128 v[182:185], v152 offset:37888
	ds_read_b128 v[186:189], v152 offset:38912
	ds_read_b128 v[190:193], v152 offset:39936
	global_load_lds_dwordx4 v[194:195], off
	s_mov_b32 m0, s27
	s_nop 0
	global_load_lds_dwordx4 v134, s[16:17]
	s_waitcnt lgkmcnt(8)
	s_barrier
	s_waitcnt lgkmcnt(0)
	s_waitcnt lgkmcnt(0)
	v_mfma_f32_16x16x32_bf16 v[124:127], v[128:131], v[162:165], v[124:127]
	v_mfma_f32_16x16x32_bf16 v[92:95], v[154:157], v[162:165], v[92:95]
	v_mfma_f32_16x16x32_bf16 v[120:123], v[128:131], v[170:173], v[120:123]
	v_mfma_f32_16x16x32_bf16 v[88:91], v[154:157], v[170:173], v[88:91]
	v_mfma_f32_16x16x32_bf16 v[116:119], v[128:131], v[178:181], v[116:119]
	v_mfma_f32_16x16x32_bf16 v[84:87], v[154:157], v[178:181], v[84:87]
	v_mfma_f32_16x16x32_bf16 v[112:115], v[128:131], v[186:189], v[112:115]
	v_mfma_f32_16x16x32_bf16 v[80:83], v[154:157], v[186:189], v[80:83]
	v_mfma_f32_16x16x32_bf16 v[124:127], v[144:147], v[166:169], v[124:127]
	v_mfma_f32_16x16x32_bf16 v[92:95], v[158:161], v[166:169], v[92:95]
	v_mfma_f32_16x16x32_bf16 v[120:123], v[144:147], v[174:177], v[120:123]
	v_mfma_f32_16x16x32_bf16 v[88:91], v[158:161], v[174:177], v[88:91]
	v_mfma_f32_16x16x32_bf16 v[116:119], v[144:147], v[182:185], v[116:119]
	v_mfma_f32_16x16x32_bf16 v[84:87], v[158:161], v[182:185], v[84:87]
	v_mfma_f32_16x16x32_bf16 v[112:115], v[144:147], v[190:193], v[112:115]
	v_mfma_f32_16x16x32_bf16 v[80:83], v[158:161], v[190:193], v[80:83]
	s_barrier
	s_add_i32 s22, 0, 0x1c000
	s_add_i32 s16, s47, s3
	v_add_u32_e32 v206, s22, v149
	v_lshl_add_u64 v[210:211], v[210:211], 0, s[14:15]
	s_mov_b32 m0, s16
	ds_read_b128 v[194:197], v206
	ds_read_b128 v[198:201], v206 offset:1024
	ds_read_b128 v[202:205], v206 offset:2048
	ds_read_b128 v[206:209], v206 offset:3072
	global_load_lds_dwordx4 v[210:211], off
	s_add_u32 s98, s20, s14
	s_addc_u32 s99, s21, s15
	s_add_i32 m0, s16, 0x2000
	s_nop 0
	global_load_lds_dwordx4 v134, s[98:99]
	s_barrier
	s_waitcnt lgkmcnt(0)
	s_waitcnt lgkmcnt(0)
	v_mfma_f32_16x16x32_bf16 v[76:79], v[194:197], v[162:165], v[76:79]
	v_mfma_f32_16x16x32_bf16 v[48:51], v[202:205], v[162:165], v[48:51]
	v_mfma_f32_16x16x32_bf16 v[68:71], v[194:197], v[170:173], v[68:71]
	v_mfma_f32_16x16x32_bf16 v[40:43], v[202:205], v[170:173], v[40:43]
	v_mfma_f32_16x16x32_bf16 v[60:63], v[194:197], v[178:181], v[60:63]
	v_mfma_f32_16x16x32_bf16 v[36:39], v[202:205], v[178:181], v[36:39]
	v_mfma_f32_16x16x32_bf16 v[52:55], v[194:197], v[186:189], v[52:55]
	v_mfma_f32_16x16x32_bf16 v[28:31], v[202:205], v[186:189], v[28:31]
	v_mfma_f32_16x16x32_bf16 v[76:79], v[198:201], v[166:169], v[76:79]
	v_mfma_f32_16x16x32_bf16 v[48:51], v[206:209], v[166:169], v[48:51]
	v_mfma_f32_16x16x32_bf16 v[68:71], v[198:201], v[174:177], v[68:71]
	v_mfma_f32_16x16x32_bf16 v[40:43], v[206:209], v[174:177], v[40:43]
	v_mfma_f32_16x16x32_bf16 v[60:63], v[198:201], v[182:185], v[60:63]
	v_mfma_f32_16x16x32_bf16 v[36:39], v[206:209], v[182:185], v[36:39]
	v_mfma_f32_16x16x32_bf16 v[52:55], v[198:201], v[190:193], v[52:55]
	v_mfma_f32_16x16x32_bf16 v[28:31], v[206:209], v[190:193], v[28:31]
	s_mov_b32 m0, s29
	v_lshl_add_u64 v[210:211], v[214:215], 0, s[14:15]
	s_barrier
	ds_read_b128 v[162:165], v152 offset:49152
	ds_read_b128 v[166:169], v152 offset:50176
	ds_read_b128 v[170:173], v152 offset:51200
	ds_read_b128 v[174:177], v152 offset:52224
	ds_read_b128 v[178:181], v152 offset:53248
	ds_read_b128 v[182:185], v152 offset:54272
	ds_read_b128 v[186:189], v152 offset:55296
	ds_read_b128 v[190:193], v152 offset:56320
	global_load_lds_dwordx4 v[210:211], off
	v_lshl_add_u64 v[210:211], v[216:217], 0, s[14:15]
	s_mov_b32 m0, s30
	s_nop 0
	global_load_lds_dwordx4 v[210:211], off
	s_barrier
	s_waitcnt lgkmcnt(0)
	s_waitcnt lgkmcnt(0)
	v_mfma_f32_16x16x32_bf16 v[108:111], v[128:131], v[162:165], v[108:111]
	v_mfma_f32_16x16x32_bf16 v[72:75], v[154:157], v[162:165], v[72:75]
	v_mfma_f32_16x16x32_bf16 v[104:107], v[128:131], v[170:173], v[104:107]
	v_mfma_f32_16x16x32_bf16 v[64:67], v[154:157], v[170:173], v[64:67]
	v_mfma_f32_16x16x32_bf16 v[100:103], v[128:131], v[178:181], v[100:103]
	v_mfma_f32_16x16x32_bf16 v[56:59], v[154:157], v[178:181], v[56:59]
	v_mfma_f32_16x16x32_bf16 v[96:99], v[128:131], v[186:189], v[96:99]
	v_mfma_f32_16x16x32_bf16 v[44:47], v[154:157], v[186:189], v[44:47]
	v_mfma_f32_16x16x32_bf16 v[108:111], v[144:147], v[166:169], v[108:111]
	v_mfma_f32_16x16x32_bf16 v[72:75], v[158:161], v[166:169], v[72:75]
	v_mfma_f32_16x16x32_bf16 v[104:107], v[144:147], v[174:177], v[104:107]
	v_mfma_f32_16x16x32_bf16 v[64:67], v[158:161], v[174:177], v[64:67]
	v_mfma_f32_16x16x32_bf16 v[100:103], v[144:147], v[182:185], v[100:103]
	v_mfma_f32_16x16x32_bf16 v[56:59], v[158:161], v[182:185], v[56:59]
	v_mfma_f32_16x16x32_bf16 v[96:99], v[144:147], v[190:193], v[96:99]
	v_mfma_f32_16x16x32_bf16 v[44:47], v[158:161], v[190:193], v[44:47]
	s_barrier
	s_add_u32 s16, s20, 0x160080
	s_addc_u32 s17, s21, 0
	s_add_i32 s20, s22, s3
	v_lshl_add_u64 v[128:129], s[16:17], 0, v[132:133]
	s_mov_b32 m0, s20
	s_nop 0
	global_load_lds_dwordx4 v[128:129], off
	s_add_i32 m0, s20, 0x2000
	s_nop 0
	global_load_lds_dwordx4 v134, s[16:17]
	s_waitcnt vmcnt(6)
	s_barrier
	v_mfma_f32_16x16x32_bf16 v[32:35], v[194:197], v[162:165], v[32:35]
	v_mfma_f32_16x16x32_bf16 v[12:15], v[202:205], v[162:165], v[12:15]
	v_mfma_f32_16x16x32_bf16 v[24:27], v[194:197], v[170:173], v[24:27]
	v_mfma_f32_16x16x32_bf16 v[8:11], v[202:205], v[170:173], v[8:11]
	v_mfma_f32_16x16x32_bf16 v[20:23], v[194:197], v[178:181], v[20:23]
	v_mfma_f32_16x16x32_bf16 v[4:7], v[202:205], v[178:181], v[4:7]
	v_mfma_f32_16x16x32_bf16 v[16:19], v[194:197], v[186:189], v[16:19]
	v_mfma_f32_16x16x32_bf16 v[0:3], v[202:205], v[186:189], v[0:3]
	v_mfma_f32_16x16x32_bf16 v[32:35], v[198:201], v[166:169], v[32:35]
	v_mfma_f32_16x16x32_bf16 v[12:15], v[206:209], v[166:169], v[12:15]
	v_mfma_f32_16x16x32_bf16 v[24:27], v[198:201], v[174:177], v[24:27]
	v_mfma_f32_16x16x32_bf16 v[8:11], v[206:209], v[174:177], v[8:11]
	v_mfma_f32_16x16x32_bf16 v[20:23], v[198:201], v[182:185], v[20:23]
	v_mfma_f32_16x16x32_bf16 v[4:7], v[206:209], v[182:185], v[4:7]
	v_mfma_f32_16x16x32_bf16 v[16:19], v[198:201], v[190:193], v[16:19]
	v_mfma_f32_16x16x32_bf16 v[0:3], v[206:209], v[190:193], v[0:3]
	s_add_i32 s46, s46, 2
	s_add_u32 s42, s42, 0x100
	s_addc_u32 s43, s43, 0
	s_cmpk_gt_u32 s46, 0x55
	s_mov_b64 s[16:17], s[18:19]
	s_barrier
	s_cbranch_scc0 .LBB0_2911
	s_cmp_lt_u32 s40, 32
	s_movk_i32 s16, 0x3000
	s_cselect_b32 s16, s16, 0x6000
	s_cmp_gt_i32 s40, 15
	v_lshl_add_u32 v158, s40, 8, v148
	s_cselect_b32 s16, s16, 0
	v_lshl_or_b32 v128, s41, 8, v150
	s_lshl_b32 s16, s16, 2
	v_ashrrev_i32_e32 v159, 31, v158
	s_add_u32 s16, s34, s16
	v_ashrrev_i32_e32 v129, 31, v128
	v_lshlrev_b64 v[146:147], 13, v[158:159]
	s_addc_u32 s17, s35, 0
	v_lshlrev_b64 v[160:161], 2, v[128:129]
	v_lshl_add_u64 v[146:147], s[48:49], 0, v[146:147]
	v_lshl_add_u64 v[144:145], s[16:17], 0, v[160:161]
	v_lshl_add_u64 v[146:147], v[146:147], 0, v[160:161]
	s_mov_b64 s[16:17], 0x100000
	s_mov_b32 s41, s38
	s_mov_b32 s40, s39
	s_mov_b64 s[18:19], s[12:13]
	v_or_b32_e32 v162, 16, v158
	v_ashrrev_i32_e32 v163, 31, v162
	v_lshlrev_b64 v[164:165], 13, v[162:163]
	v_lshl_add_u64 v[162:163], s[48:49], 0, v[164:165]
	v_lshl_add_u64 v[164:165], v[162:163], 0, v[160:161]
	v_or_b32_e32 v162, 32, v158
	v_ashrrev_i32_e32 v163, 31, v162
	v_lshlrev_b64 v[166:167], 13, v[162:163]
	v_lshl_add_u64 v[162:163], s[48:49], 0, v[166:167]
	v_lshl_add_u64 v[166:167], v[162:163], 0, v[160:161]
	v_or_b32_e32 v162, 48, v158
	v_ashrrev_i32_e32 v163, 31, v162
	v_lshlrev_b64 v[168:169], 13, v[162:163]
	v_lshl_add_u64 v[162:163], s[48:49], 0, v[168:169]
	v_lshl_add_u64 v[168:169], v[162:163], 0, v[160:161]
	v_lshl_add_u64 v[162:163], v[146:147], 0, s[16:17]
	s_mov_b32 s16, 0x100000
	v_add_co_u32_e32 v170, vcc, s16, v146
	s_mov_b64 s[16:17], 0x120000
	s_nop 0
	v_addc_co_u32_e32 v171, vcc, 0, v147, vcc
	v_lshl_add_u64 v[172:173], v[146:147], 0, s[16:17]
	s_mov_b32 s16, 0x120000
	v_add_co_u32_e32 v174, vcc, s16, v146
	s_mov_b64 s[16:17], 0x140000
	s_nop 0
	v_addc_co_u32_e32 v175, vcc, 0, v147, vcc
	v_lshl_add_u64 v[176:177], v[146:147], 0, s[16:17]
	s_mov_b32 s16, 0x140000
	v_add_co_u32_e32 v178, vcc, s16, v146
	s_mov_b64 s[16:17], 0x160000
	s_nop 0
	v_addc_co_u32_e32 v179, vcc, 0, v147, vcc
	v_lshl_add_u64 v[180:181], v[146:147], 0, s[16:17]
	s_mov_b32 s16, 0x160000
	v_add_co_u32_e32 v182, vcc, s16, v146
	s_mov_b64 s[16:17], s[10:11]
	s_nop 0
	v_addc_co_u32_e32 v183, vcc, 0, v147, vcc
	s_and_b64 vcc, exec, s[8:9]
	global_load_dwordx4 v[184:187], v[144:145], off
	global_load_dwordx4 v[188:191], v[146:147], off
	v_pk_add_f32 v[126:127], v[126:127], 0 op_sel_hi:[1,0]
	v_pk_add_f32 v[124:125], v[124:125], 0 op_sel_hi:[1,0]
	v_pk_add_f32 v[122:123], v[122:123], 0 op_sel_hi:[1,0]
	v_pk_add_f32 v[120:121], v[120:121], 0 op_sel_hi:[1,0]
	v_pk_add_f32 v[118:119], v[118:119], 0 op_sel_hi:[1,0]
	v_pk_add_f32 v[116:117], v[116:117], 0 op_sel_hi:[1,0]
	v_pk_add_f32 v[114:115], v[114:115], 0 op_sel_hi:[1,0]
	v_pk_add_f32 v[112:113], v[112:113], 0 op_sel_hi:[1,0]
	v_pk_add_f32 v[110:111], v[110:111], 0 op_sel_hi:[1,0]
	v_pk_add_f32 v[108:109], v[108:109], 0 op_sel_hi:[1,0]
	v_pk_add_f32 v[106:107], v[106:107], 0 op_sel_hi:[1,0]
	v_pk_add_f32 v[104:105], v[104:105], 0 op_sel_hi:[1,0]
	v_pk_add_f32 v[102:103], v[102:103], 0 op_sel_hi:[1,0]
	v_pk_add_f32 v[100:101], v[100:101], 0 op_sel_hi:[1,0]
	v_pk_add_f32 v[98:99], v[98:99], 0 op_sel_hi:[1,0]
	v_pk_add_f32 v[96:97], v[96:97], 0 op_sel_hi:[1,0]
	v_pk_add_f32 v[94:95], v[94:95], 0 op_sel_hi:[1,0]
	v_pk_add_f32 v[92:93], v[92:93], 0 op_sel_hi:[1,0]
	v_pk_add_f32 v[90:91], v[90:91], 0 op_sel_hi:[1,0]
	v_pk_add_f32 v[88:89], v[88:89], 0 op_sel_hi:[1,0]
	v_pk_add_f32 v[86:87], v[86:87], 0 op_sel_hi:[1,0]
	v_pk_add_f32 v[84:85], v[84:85], 0 op_sel_hi:[1,0]
	v_pk_add_f32 v[82:83], v[82:83], 0 op_sel_hi:[1,0]
	v_pk_add_f32 v[80:81], v[80:81], 0 op_sel_hi:[1,0]
	v_pk_add_f32 v[74:75], v[74:75], 0 op_sel_hi:[1,0]
	v_pk_add_f32 v[72:73], v[72:73], 0 op_sel_hi:[1,0]
	v_pk_add_f32 v[66:67], v[66:67], 0 op_sel_hi:[1,0]
	v_pk_add_f32 v[64:65], v[64:65], 0 op_sel_hi:[1,0]
	v_pk_add_f32 v[58:59], v[58:59], 0 op_sel_hi:[1,0]
	v_pk_add_f32 v[56:57], v[56:57], 0 op_sel_hi:[1,0]
	v_pk_add_f32 v[46:47], v[46:47], 0 op_sel_hi:[1,0]
	v_pk_add_f32 v[44:45], v[44:45], 0 op_sel_hi:[1,0]
	v_pk_add_f32 v[62:63], v[62:63], 0 op_sel_hi:[1,0]
	v_pk_add_f32 v[60:61], v[60:61], 0 op_sel_hi:[1,0]
	v_pk_add_f32 v[54:55], v[54:55], 0 op_sel_hi:[1,0]
	v_pk_add_f32 v[52:53], v[52:53], 0 op_sel_hi:[1,0]
	v_pk_add_f32 v[34:35], v[34:35], 0 op_sel_hi:[1,0]
	v_pk_add_f32 v[32:33], v[32:33], 0 op_sel_hi:[1,0]
	v_pk_add_f32 v[26:27], v[26:27], 0 op_sel_hi:[1,0]
	v_pk_add_f32 v[24:25], v[24:25], 0 op_sel_hi:[1,0]
	v_pk_add_f32 v[22:23], v[22:23], 0 op_sel_hi:[1,0]
	v_pk_add_f32 v[20:21], v[20:21], 0 op_sel_hi:[1,0]
	v_pk_add_f32 v[18:19], v[18:19], 0 op_sel_hi:[1,0]
	v_pk_add_f32 v[16:17], v[16:17], 0 op_sel_hi:[1,0]
	v_pk_add_f32 v[14:15], v[14:15], 0 op_sel_hi:[1,0]
	v_pk_add_f32 v[12:13], v[12:13], 0 op_sel_hi:[1,0]
	v_pk_add_f32 v[10:11], v[10:11], 0 op_sel_hi:[1,0]
	v_pk_add_f32 v[8:9], v[8:9], 0 op_sel_hi:[1,0]
	v_pk_add_f32 v[6:7], v[6:7], 0 op_sel_hi:[1,0]
	v_pk_add_f32 v[4:5], v[4:5], 0 op_sel_hi:[1,0]
	v_pk_add_f32 v[2:3], v[2:3], 0 op_sel_hi:[1,0]
	v_pk_add_f32 v[0:1], v[0:1], 0 op_sel_hi:[1,0]
	s_waitcnt vmcnt(0)
	v_pk_fma_f32 v[126:127], v[126:127], v[186:187], v[190:191]
	v_pk_fma_f32 v[124:125], v[124:125], v[184:185], v[188:189]
	global_store_dwordx4 v[146:147], v[124:127], off
	global_load_dwordx4 v[188:191], v[164:165], off
	global_load_dwordx4 v[192:195], v[166:167], off
	global_load_dwordx4 v[196:199], v[168:169], off
	global_load_dwordx4 v[200:203], v[170:171], off
	global_load_dwordx4 v[204:207], v[174:175], off
	global_load_dwordx4 v[208:211], v[178:179], off
	global_load_dwordx4 v[212:215], v[182:183], off
	global_load_dwordx4 v[216:219], v[144:145], off offset:64
	global_load_dwordx4 v[220:223], v[146:147], off offset:64
	global_load_dwordx4 v[224:227], v[164:165], off offset:64
	global_load_dwordx4 v[228:231], v[166:167], off offset:64
	global_load_dwordx4 v[232:235], v[168:169], off offset:64
	s_waitcnt vmcnt(11)
	v_pk_fma_f32 v[122:123], v[122:123], v[186:187], v[190:191]
	v_pk_fma_f32 v[120:121], v[120:121], v[184:185], v[188:189]
	global_store_dwordx4 v[164:165], v[120:123], off
	global_load_dwordx4 v[188:191], v[162:163], off offset:64
	s_waitcnt vmcnt(12)
	v_pk_fma_f32 v[118:119], v[118:119], v[186:187], v[194:195]
	v_pk_fma_f32 v[116:117], v[116:117], v[184:185], v[192:193]
	global_store_dwordx4 v[166:167], v[116:119], off
	global_load_dwordx4 v[192:195], v[172:173], off offset:64
	s_waitcnt vmcnt(13)
	v_pk_fma_f32 v[114:115], v[114:115], v[186:187], v[198:199]
	v_pk_fma_f32 v[112:113], v[112:113], v[184:185], v[196:197]
	global_store_dwordx4 v[168:169], v[112:115], off
	global_load_dwordx4 v[196:199], v[176:177], off offset:64
	s_waitcnt vmcnt(14)
	v_pk_fma_f32 v[110:111], v[110:111], v[186:187], v[202:203]
	v_pk_fma_f32 v[108:109], v[108:109], v[184:185], v[200:201]
	global_store_dwordx4 v[170:171], v[108:111], off
	global_load_dwordx4 v[200:203], v[180:181], off offset:64
	s_waitcnt vmcnt(15)
	v_pk_fma_f32 v[106:107], v[106:107], v[186:187], v[206:207]
	v_pk_fma_f32 v[104:105], v[104:105], v[184:185], v[204:205]
	global_store_dwordx4 v[174:175], v[104:107], off
	global_load_dwordx4 v[204:207], v[144:145], off offset:512
	s_waitcnt vmcnt(16)
	v_pk_fma_f32 v[102:103], v[102:103], v[186:187], v[210:211]
	v_pk_fma_f32 v[100:101], v[100:101], v[184:185], v[208:209]
	global_store_dwordx4 v[178:179], v[100:103], off
	global_load_dwordx4 v[208:211], v[146:147], off offset:512
	s_waitcnt vmcnt(17)
	v_pk_fma_f32 v[98:99], v[98:99], v[186:187], v[214:215]
	v_pk_fma_f32 v[96:97], v[96:97], v[184:185], v[212:213]
	global_store_dwordx4 v[182:183], v[96:99], off
	global_load_dwordx4 v[184:187], v[164:165], off offset:512
	s_waitcnt vmcnt(17)
	v_pk_fma_f32 v[94:95], v[94:95], v[218:219], v[222:223]
	v_pk_fma_f32 v[92:93], v[92:93], v[216:217], v[220:221]
	global_store_dwordx4 v[146:147], v[92:95], off offset:64
	global_load_dwordx4 v[212:215], v[166:167], off offset:512
	global_load_dwordx4 v[220:223], v[168:169], off offset:512
	s_waitcnt vmcnt(19)
	v_pk_fma_f32 v[90:91], v[90:91], v[218:219], v[226:227]
	v_pk_fma_f32 v[88:89], v[88:89], v[216:217], v[224:225]
	global_store_dwordx4 v[164:165], v[88:91], off offset:64
	global_load_dwordx4 v[224:227], v[162:163], off offset:512
	s_waitcnt vmcnt(20)
	v_pk_fma_f32 v[86:87], v[86:87], v[218:219], v[230:231]
	v_pk_fma_f32 v[84:85], v[84:85], v[216:217], v[228:229]
	global_store_dwordx4 v[166:167], v[84:87], off offset:64
	global_load_dwordx4 v[228:231], v[172:173], off offset:512
	s_waitcnt vmcnt(21)
	v_pk_fma_f32 v[82:83], v[82:83], v[218:219], v[234:235]
	v_pk_fma_f32 v[80:81], v[80:81], v[216:217], v[232:233]
	global_store_dwordx4 v[168:169], v[80:83], off offset:64
	global_load_dwordx4 v[232:235], v[176:177], off offset:512
	s_waitcnt vmcnt(21)
	v_pk_fma_f32 v[74:75], v[74:75], v[218:219], v[190:191]
	v_pk_fma_f32 v[72:73], v[72:73], v[216:217], v[188:189]
	global_store_dwordx4 v[162:163], v[72:75], off offset:64
	global_load_dwordx4 v[188:191], v[180:181], off offset:512
	s_waitcnt vmcnt(21)
	v_pk_fma_f32 v[66:67], v[66:67], v[218:219], v[194:195]
	v_pk_fma_f32 v[64:65], v[64:65], v[216:217], v[192:193]
	global_store_dwordx4 v[172:173], v[64:67], off offset:64
	global_load_dwordx4 v[192:195], v[144:145], off offset:576
	s_waitcnt vmcnt(21)
	v_pk_fma_f32 v[58:59], v[58:59], v[218:219], v[198:199]
	v_pk_fma_f32 v[56:57], v[56:57], v[216:217], v[196:197]
	global_store_dwordx4 v[176:177], v[56:59], off offset:64
	global_load_dwordx4 v[196:199], v[146:147], off offset:576
	v_pk_add_f32 v[64:65], v[78:79], 0 op_sel_hi:[1,0]
	v_pk_add_f32 v[66:67], v[76:77], 0 op_sel_hi:[1,0]
	s_waitcnt vmcnt(21)
	v_pk_fma_f32 v[46:47], v[46:47], v[218:219], v[202:203]
	v_pk_fma_f32 v[44:45], v[44:45], v[216:217], v[200:201]
	global_store_dwordx4 v[180:181], v[44:47], off offset:64
	global_load_dwordx4 v[200:203], v[164:165], off offset:576
	s_waitcnt vmcnt(19)
	v_pk_fma_f32 v[58:59], v[64:65], v[206:207], v[210:211]
	v_pk_fma_f32 v[56:57], v[66:67], v[204:205], v[208:209]
	global_store_dwordx4 v[146:147], v[56:59], off offset:512
	global_load_dwordx4 v[208:211], v[166:167], off offset:576
	global_load_dwordx4 v[216:219], v[168:169], off offset:576
	v_pk_add_f32 v[64:65], v[70:71], 0 op_sel_hi:[1,0]
	v_pk_add_f32 v[66:67], v[68:69], 0 op_sel_hi:[1,0]
	s_waitcnt vmcnt(20)
	v_pk_fma_f32 v[58:59], v[64:65], v[206:207], v[186:187]
	v_pk_fma_f32 v[56:57], v[66:67], v[204:205], v[184:185]
	global_store_dwordx4 v[164:165], v[56:59], off offset:512
	global_load_dwordx4 v[184:187], v[162:163], off offset:576
	s_waitcnt vmcnt(20)
	v_pk_fma_f32 v[58:59], v[62:63], v[206:207], v[214:215]
	v_pk_fma_f32 v[56:57], v[60:61], v[204:205], v[212:213]
	global_store_dwordx4 v[166:167], v[56:59], off offset:512
	global_load_dwordx4 v[212:215], v[172:173], off offset:576
	s_waitcnt vmcnt(21)
	v_pk_fma_f32 v[54:55], v[54:55], v[206:207], v[222:223]
	v_pk_fma_f32 v[52:53], v[52:53], v[204:205], v[220:221]
	global_store_dwordx4 v[168:169], v[52:55], off offset:512
	global_load_dwordx4 v[220:223], v[176:177], off offset:576
	s_waitcnt vmcnt(21)
	v_pk_fma_f32 v[34:35], v[34:35], v[206:207], v[226:227]
	v_pk_fma_f32 v[32:33], v[32:33], v[204:205], v[224:225]
	global_store_dwordx4 v[162:163], v[32:35], off offset:512
	global_load_dwordx4 v[224:227], v[180:181], off offset:576
	s_waitcnt vmcnt(21)
	v_pk_fma_f32 v[26:27], v[26:27], v[206:207], v[230:231]
	v_pk_fma_f32 v[24:25], v[24:25], v[204:205], v[228:229]
	global_store_dwordx4 v[172:173], v[24:27], off offset:512
	s_waitcnt vmcnt(20)
	v_pk_fma_f32 v[22:23], v[22:23], v[206:207], v[234:235]
	v_pk_fma_f32 v[20:21], v[20:21], v[204:205], v[232:233]
	global_store_dwordx4 v[176:177], v[20:23], off offset:512
	v_pk_add_f32 v[24:25], v[50:51], 0 op_sel_hi:[1,0]
	v_pk_add_f32 v[26:27], v[48:49], 0 op_sel_hi:[1,0]
	s_waitcnt vmcnt(19)
	v_pk_fma_f32 v[18:19], v[18:19], v[206:207], v[190:191]
	v_pk_fma_f32 v[16:17], v[16:17], v[204:205], v[188:189]
	global_store_dwordx4 v[180:181], v[16:19], off offset:512
	s_waitcnt vmcnt(16)
	v_pk_fma_f32 v[22:23], v[24:25], v[194:195], v[198:199]
	v_pk_fma_f32 v[20:21], v[26:27], v[192:193], v[196:197]
	global_store_dwordx4 v[146:147], v[20:23], off offset:576
	v_pk_add_f32 v[24:25], v[42:43], 0 op_sel_hi:[1,0]
	v_pk_add_f32 v[26:27], v[40:41], 0 op_sel_hi:[1,0]
	s_waitcnt vmcnt(15)
	v_pk_fma_f32 v[22:23], v[24:25], v[194:195], v[202:203]
	v_pk_fma_f32 v[20:21], v[26:27], v[192:193], v[200:201]
	global_store_dwordx4 v[164:165], v[20:23], off offset:576
	v_pk_add_f32 v[24:25], v[38:39], 0 op_sel_hi:[1,0]
	v_pk_add_f32 v[26:27], v[36:37], 0 op_sel_hi:[1,0]
	s_waitcnt vmcnt(14)
	v_pk_fma_f32 v[22:23], v[24:25], v[194:195], v[210:211]
	v_pk_fma_f32 v[20:21], v[26:27], v[192:193], v[208:209]
	global_store_dwordx4 v[166:167], v[20:23], off offset:576
	v_pk_add_f32 v[24:25], v[30:31], 0 op_sel_hi:[1,0]
	v_pk_add_f32 v[26:27], v[28:29], 0 op_sel_hi:[1,0]
	s_waitcnt vmcnt(14)
	v_pk_fma_f32 v[22:23], v[24:25], v[194:195], v[218:219]
	v_pk_fma_f32 v[20:21], v[26:27], v[192:193], v[216:217]
	global_store_dwordx4 v[168:169], v[20:23], off offset:576
	s_waitcnt vmcnt(13)
	v_pk_fma_f32 v[14:15], v[14:15], v[194:195], v[186:187]
	v_pk_fma_f32 v[12:13], v[12:13], v[192:193], v[184:185]
	global_store_dwordx4 v[162:163], v[12:15], off offset:576
	s_waitcnt vmcnt(12)
	v_pk_fma_f32 v[10:11], v[10:11], v[194:195], v[214:215]
	v_pk_fma_f32 v[8:9], v[8:9], v[192:193], v[212:213]
	global_store_dwordx4 v[172:173], v[8:11], off offset:576
	s_waitcnt vmcnt(11)
	v_pk_fma_f32 v[6:7], v[6:7], v[194:195], v[222:223]
	v_pk_fma_f32 v[4:5], v[4:5], v[192:193], v[220:221]
	global_store_dwordx4 v[176:177], v[4:7], off offset:576
	s_waitcnt vmcnt(10)
	v_pk_fma_f32 v[2:3], v[2:3], v[194:195], v[226:227]
	v_pk_fma_f32 v[0:1], v[0:1], v[192:193], v[224:225]
	global_store_dwordx4 v[180:181], v[0:3], off offset:576
	s_cbranch_vccz .LBB0_2900
	s_waitcnt vmcnt(0)
	s_cmpk_gt_u32 s1, 0xff
	s_cbranch_scc1 .LBB0_2915
	s_barrier

.LBB0_2927:
	ds_read_b128 v[144:147], v139
	ds_read_b128 v[148:151], v139 offset:1024
	ds_read_b128 v[152:155], v139 offset:2048
	ds_read_b128 v[156:159], v139 offset:3072
	s_mov_b32 m0, s31
	v_lshl_add_u64 v[192:193], s[14:15], 0, v[132:133]
	ds_read_b128 v[160:163], v140
	ds_read_b128 v[164:167], v140 offset:1024
	ds_read_b128 v[168:171], v140 offset:2048
	ds_read_b128 v[172:175], v140 offset:3072
	ds_read_b128 v[176:179], v140 offset:4096
	ds_read_b128 v[180:183], v140 offset:5120
	ds_read_b128 v[184:187], v140 offset:6144
	ds_read_b128 v[188:191], v140 offset:7168
	global_load_lds_dwordx4 v[192:193], off
	s_mov_b32 m0, s34
	s_nop 0
	global_load_lds_dwordx4 v134, s[14:15]
	s_waitcnt lgkmcnt(8)
	s_barrier
	s_waitcnt lgkmcnt(0)
	s_waitcnt lgkmcnt(0)
	v_mfma_f32_16x16x32_bf16 v[124:127], v[144:147], v[160:163], v[124:127]
	s_add_u32 s16, s14, 0x100
	s_addc_u32 s17, s15, 0
	s_cmp_eq_u32 s47, 4
	s_cselect_b32 s21, s13, s17
	s_cselect_b32 s20, s12, s16
	s_cselect_b32 s19, s7, s46
	s_cselect_b32 s18, s6, s43
	v_mfma_f32_16x16x32_bf16 v[120:123], v[152:155], v[160:163], v[120:123]
	v_mfma_f32_16x16x32_bf16 v[116:119], v[144:147], v[168:171], v[116:119]
	v_mfma_f32_16x16x32_bf16 v[112:115], v[152:155], v[168:171], v[112:115]
	v_mfma_f32_16x16x32_bf16 v[100:103], v[144:147], v[176:179], v[100:103]
	v_mfma_f32_16x16x32_bf16 v[96:99], v[152:155], v[176:179], v[96:99]
	v_mfma_f32_16x16x32_bf16 v[84:87], v[144:147], v[184:187], v[84:87]
	v_mfma_f32_16x16x32_bf16 v[80:83], v[152:155], v[184:187], v[80:83]
	v_mfma_f32_16x16x32_bf16 v[124:127], v[148:151], v[164:167], v[124:127]
	v_mfma_f32_16x16x32_bf16 v[120:123], v[156:159], v[164:167], v[120:123]
	v_mfma_f32_16x16x32_bf16 v[116:119], v[148:151], v[172:175], v[116:119]
	v_mfma_f32_16x16x32_bf16 v[112:115], v[156:159], v[172:175], v[112:115]
	v_mfma_f32_16x16x32_bf16 v[100:103], v[148:151], v[180:183], v[100:103]
	v_mfma_f32_16x16x32_bf16 v[96:99], v[156:159], v[180:183], v[96:99]
	v_mfma_f32_16x16x32_bf16 v[84:87], v[148:151], v[188:191], v[84:87]
	v_mfma_f32_16x16x32_bf16 v[80:83], v[156:159], v[188:191], v[80:83]
	s_barrier
	s_mov_b32 m0, s35
	ds_read_b128 v[192:195], v141
	ds_read_b128 v[196:199], v141 offset:1024
	ds_read_b128 v[200:203], v141 offset:2048
	ds_read_b128 v[204:207], v141 offset:3072
	global_load_lds_dwordx4 v130, s[18:19]
	s_mov_b32 m0, s36
	s_nop 0
	global_load_lds_dwordx4 v128, s[18:19]
	s_barrier
	s_waitcnt lgkmcnt(0)
	s_waitcnt lgkmcnt(0)
	v_mfma_f32_16x16x32_bf16 v[108:111], v[192:195], v[160:163], v[108:111]
	v_mfma_f32_16x16x32_bf16 v[104:107], v[200:203], v[160:163], v[104:107]
	v_mfma_f32_16x16x32_bf16 v[92:95], v[192:195], v[168:171], v[92:95]
	v_mfma_f32_16x16x32_bf16 v[88:91], v[200:203], v[168:171], v[88:91]
	v_mfma_f32_16x16x32_bf16 v[76:79], v[192:195], v[176:179], v[76:79]
	v_mfma_f32_16x16x32_bf16 v[72:75], v[200:203], v[176:179], v[72:75]
	v_mfma_f32_16x16x32_bf16 v[68:71], v[192:195], v[184:187], v[68:71]
	v_mfma_f32_16x16x32_bf16 v[64:67], v[200:203], v[184:187], v[64:67]
	v_mfma_f32_16x16x32_bf16 v[108:111], v[196:199], v[164:167], v[108:111]
	v_mfma_f32_16x16x32_bf16 v[104:107], v[204:207], v[164:167], v[104:107]
	v_mfma_f32_16x16x32_bf16 v[92:95], v[196:199], v[172:175], v[92:95]
	v_mfma_f32_16x16x32_bf16 v[88:91], v[204:207], v[172:175], v[88:91]
	v_mfma_f32_16x16x32_bf16 v[76:79], v[196:199], v[180:183], v[76:79]
	v_mfma_f32_16x16x32_bf16 v[72:75], v[204:207], v[180:183], v[72:75]
	v_mfma_f32_16x16x32_bf16 v[68:71], v[196:199], v[188:191], v[68:71]
	v_mfma_f32_16x16x32_bf16 v[64:67], v[204:207], v[188:191], v[64:67]
	s_mov_b32 m0, s3
	v_lshl_add_u64 v[212:213], s[20:21], 0, v[130:131]
	s_barrier
	ds_read_b128 v[160:163], v140 offset:16384
	ds_read_b128 v[164:167], v140 offset:17408
	ds_read_b128 v[168:171], v140 offset:18432
	ds_read_b128 v[172:175], v140 offset:19456
	ds_read_b128 v[176:179], v140 offset:20480
	ds_read_b128 v[180:183], v140 offset:21504
	ds_read_b128 v[184:187], v140 offset:22528
	ds_read_b128 v[188:191], v140 offset:23552
	global_load_lds_dwordx4 v130, s[20:21]
	v_lshl_add_u64 v[214:215], s[20:21], 0, v[128:129]
	s_mov_b32 m0, s4
	s_nop 0
	global_load_lds_dwordx4 v128, s[20:21]
	s_barrier
	s_waitcnt lgkmcnt(0)
	s_waitcnt lgkmcnt(0)
	v_mfma_f32_16x16x32_bf16 v[60:63], v[144:147], v[160:163], v[60:63]
	v_mfma_f32_16x16x32_bf16 v[56:59], v[152:155], v[160:163], v[56:59]
	v_mfma_f32_16x16x32_bf16 v[52:55], v[144:147], v[168:171], v[52:55]
	v_mfma_f32_16x16x32_bf16 v[48:51], v[152:155], v[168:171], v[48:51]
	v_mfma_f32_16x16x32_bf16 v[36:39], v[144:147], v[176:179], v[36:39]
	v_mfma_f32_16x16x32_bf16 v[32:35], v[152:155], v[176:179], v[32:35]
	v_mfma_f32_16x16x32_bf16 v[20:23], v[144:147], v[184:187], v[20:23]
	v_mfma_f32_16x16x32_bf16 v[16:19], v[152:155], v[184:187], v[16:19]
	v_mfma_f32_16x16x32_bf16 v[60:63], v[148:151], v[164:167], v[60:63]
	v_mfma_f32_16x16x32_bf16 v[56:59], v[156:159], v[164:167], v[56:59]
	v_mfma_f32_16x16x32_bf16 v[52:55], v[148:151], v[172:175], v[52:55]
	v_mfma_f32_16x16x32_bf16 v[48:51], v[156:159], v[172:175], v[48:51]
	v_mfma_f32_16x16x32_bf16 v[36:39], v[148:151], v[180:183], v[36:39]
	v_mfma_f32_16x16x32_bf16 v[32:35], v[156:159], v[180:183], v[32:35]
	v_mfma_f32_16x16x32_bf16 v[20:23], v[148:151], v[188:191], v[20:23]
	v_mfma_f32_16x16x32_bf16 v[16:19], v[156:159], v[188:191], v[16:19]
	s_barrier
	s_add_u32 s14, s18, 0x160000
	s_addc_u32 s15, s19, 0
	s_mov_b32 m0, s37
	global_load_lds_dwordx4 v130, s[14:15]
	s_mov_b32 m0, s38
	s_nop 0
	global_load_lds_dwordx4 v128, s[14:15]
	s_waitcnt vmcnt(6)
	s_barrier
	v_mfma_f32_16x16x32_bf16 v[44:47], v[192:195], v[160:163], v[44:47]
	v_mfma_f32_16x16x32_bf16 v[40:43], v[200:203], v[160:163], v[40:43]
	v_mfma_f32_16x16x32_bf16 v[28:31], v[192:195], v[168:171], v[28:31]
	v_mfma_f32_16x16x32_bf16 v[24:27], v[200:203], v[168:171], v[24:27]
	v_mfma_f32_16x16x32_bf16 v[12:15], v[192:195], v[176:179], v[12:15]
	v_mfma_f32_16x16x32_bf16 v[8:11], v[200:203], v[176:179], v[8:11]
	v_mfma_f32_16x16x32_bf16 v[4:7], v[192:195], v[184:187], v[4:7]
	v_mfma_f32_16x16x32_bf16 v[0:3], v[200:203], v[184:187], v[0:3]
	v_mfma_f32_16x16x32_bf16 v[44:47], v[196:199], v[164:167], v[44:47]
	v_mfma_f32_16x16x32_bf16 v[40:43], v[204:207], v[164:167], v[40:43]
	v_mfma_f32_16x16x32_bf16 v[28:31], v[196:199], v[172:175], v[28:31]
	v_mfma_f32_16x16x32_bf16 v[24:27], v[204:207], v[172:175], v[24:27]
	v_mfma_f32_16x16x32_bf16 v[12:15], v[196:199], v[180:183], v[12:15]
	v_mfma_f32_16x16x32_bf16 v[8:11], v[204:207], v[180:183], v[8:11]
	v_mfma_f32_16x16x32_bf16 v[4:7], v[196:199], v[188:191], v[4:7]
	v_mfma_f32_16x16x32_bf16 v[0:3], v[204:207], v[188:191], v[0:3]
	s_barrier
	ds_read_b128 v[144:147], v142
	ds_read_b128 v[148:151], v142 offset:1024
	ds_read_b128 v[152:155], v142 offset:2048
	ds_read_b128 v[156:159], v142 offset:3072
	s_add_u32 s14, s20, 0x160000
	s_addc_u32 s15, s21, 0
	s_mov_b32 m0, s5
	ds_read_b128 v[160:163], v140 offset:32768
	ds_read_b128 v[164:167], v140 offset:33792
	ds_read_b128 v[168:171], v140 offset:34816
	ds_read_b128 v[172:175], v140 offset:35840
	ds_read_b128 v[176:179], v140 offset:36864
	ds_read_b128 v[180:183], v140 offset:37888
	ds_read_b128 v[184:187], v140 offset:38912
	ds_read_b128 v[188:191], v140 offset:39936
	global_load_lds_dwordx4 v130, s[14:15]
	s_mov_b32 m0, s22
	s_nop 0
	global_load_lds_dwordx4 v128, s[14:15]
	s_waitcnt lgkmcnt(8)
	s_barrier
	s_waitcnt lgkmcnt(0)
	s_waitcnt lgkmcnt(0)
	v_mfma_f32_16x16x32_bf16 v[124:127], v[144:147], v[160:163], v[124:127]
	v_mfma_f32_16x16x32_bf16 v[120:123], v[152:155], v[160:163], v[120:123]
	v_mfma_f32_16x16x32_bf16 v[116:119], v[144:147], v[168:171], v[116:119]
	v_mfma_f32_16x16x32_bf16 v[112:115], v[152:155], v[168:171], v[112:115]
	v_mfma_f32_16x16x32_bf16 v[100:103], v[144:147], v[176:179], v[100:103]
	v_mfma_f32_16x16x32_bf16 v[96:99], v[152:155], v[176:179], v[96:99]
	v_mfma_f32_16x16x32_bf16 v[84:87], v[144:147], v[184:187], v[84:87]
	v_mfma_f32_16x16x32_bf16 v[80:83], v[152:155], v[184:187], v[80:83]
	v_mfma_f32_16x16x32_bf16 v[124:127], v[148:151], v[164:167], v[124:127]
	v_mfma_f32_16x16x32_bf16 v[120:123], v[156:159], v[164:167], v[120:123]
	v_mfma_f32_16x16x32_bf16 v[116:119], v[148:151], v[172:175], v[116:119]
	v_mfma_f32_16x16x32_bf16 v[112:115], v[156:159], v[172:175], v[112:115]
	v_mfma_f32_16x16x32_bf16 v[100:103], v[148:151], v[180:183], v[100:103]
	v_mfma_f32_16x16x32_bf16 v[96:99], v[156:159], v[180:183], v[96:99]
	v_mfma_f32_16x16x32_bf16 v[84:87], v[148:151], v[188:191], v[84:87]
	v_mfma_f32_16x16x32_bf16 v[80:83], v[156:159], v[188:191], v[80:83]
	s_barrier
	s_add_i32 s20, 0, 0x1c000
	s_add_i32 s14, s39, s2
	v_add_u32_e32 v143, s20, v137
	s_add_u32 s98, s18, s8
	s_addc_u32 s99, s19, s9
	s_mov_b32 m0, s14
	ds_read_b128 v[192:195], v143
	ds_read_b128 v[196:199], v143 offset:1024
	ds_read_b128 v[200:203], v143 offset:2048
	ds_read_b128 v[204:207], v143 offset:3072
	global_load_lds_dwordx4 v130, s[98:99]
	s_add_i32 m0, s14, 0x2000
	s_nop 0
	global_load_lds_dwordx4 v128, s[98:99]
	s_barrier
	s_waitcnt lgkmcnt(0)
	s_waitcnt lgkmcnt(0)
	v_mfma_f32_16x16x32_bf16 v[108:111], v[192:195], v[160:163], v[108:111]
	v_mfma_f32_16x16x32_bf16 v[104:107], v[200:203], v[160:163], v[104:107]
	v_mfma_f32_16x16x32_bf16 v[92:95], v[192:195], v[168:171], v[92:95]
	v_mfma_f32_16x16x32_bf16 v[88:91], v[200:203], v[168:171], v[88:91]
	v_mfma_f32_16x16x32_bf16 v[76:79], v[192:195], v[176:179], v[76:79]
	v_mfma_f32_16x16x32_bf16 v[72:75], v[200:203], v[176:179], v[72:75]
	v_mfma_f32_16x16x32_bf16 v[68:71], v[192:195], v[184:187], v[68:71]
	v_mfma_f32_16x16x32_bf16 v[64:67], v[200:203], v[184:187], v[64:67]
	v_mfma_f32_16x16x32_bf16 v[108:111], v[196:199], v[164:167], v[108:111]
	v_mfma_f32_16x16x32_bf16 v[104:107], v[204:207], v[164:167], v[104:107]
	v_mfma_f32_16x16x32_bf16 v[92:95], v[196:199], v[172:175], v[92:95]
	v_mfma_f32_16x16x32_bf16 v[88:91], v[204:207], v[172:175], v[88:91]
	v_mfma_f32_16x16x32_bf16 v[76:79], v[196:199], v[180:183], v[76:79]
	v_mfma_f32_16x16x32_bf16 v[72:75], v[204:207], v[180:183], v[72:75]
	v_mfma_f32_16x16x32_bf16 v[68:71], v[196:199], v[188:191], v[68:71]
	v_mfma_f32_16x16x32_bf16 v[64:67], v[204:207], v[188:191], v[64:67]
	s_mov_b32 m0, s29
	v_lshl_add_u64 v[208:209], v[212:213], 0, s[8:9]
	s_barrier
	ds_read_b128 v[160:163], v140 offset:49152
	ds_read_b128 v[164:167], v140 offset:50176
	ds_read_b128 v[168:171], v140 offset:51200
	ds_read_b128 v[172:175], v140 offset:52224
	ds_read_b128 v[176:179], v140 offset:53248
	ds_read_b128 v[180:183], v140 offset:54272
	ds_read_b128 v[184:187], v140 offset:55296
	ds_read_b128 v[188:191], v140 offset:56320
	global_load_lds_dwordx4 v[208:209], off
	v_lshl_add_u64 v[208:209], v[214:215], 0, s[8:9]
	s_mov_b32 m0, s30
	s_nop 0
	global_load_lds_dwordx4 v[208:209], off
	s_barrier
	s_waitcnt lgkmcnt(0)
	s_waitcnt lgkmcnt(0)
	v_mfma_f32_16x16x32_bf16 v[60:63], v[144:147], v[160:163], v[60:63]
	v_mfma_f32_16x16x32_bf16 v[56:59], v[152:155], v[160:163], v[56:59]
	v_mfma_f32_16x16x32_bf16 v[52:55], v[144:147], v[168:171], v[52:55]
	v_mfma_f32_16x16x32_bf16 v[48:51], v[152:155], v[168:171], v[48:51]
	v_mfma_f32_16x16x32_bf16 v[36:39], v[144:147], v[176:179], v[36:39]
	v_mfma_f32_16x16x32_bf16 v[32:35], v[152:155], v[176:179], v[32:35]
	v_mfma_f32_16x16x32_bf16 v[20:23], v[144:147], v[184:187], v[20:23]
	v_mfma_f32_16x16x32_bf16 v[16:19], v[152:155], v[184:187], v[16:19]
	v_mfma_f32_16x16x32_bf16 v[60:63], v[148:151], v[164:167], v[60:63]
	v_mfma_f32_16x16x32_bf16 v[56:59], v[156:159], v[164:167], v[56:59]
	v_mfma_f32_16x16x32_bf16 v[52:55], v[148:151], v[172:175], v[52:55]
	v_mfma_f32_16x16x32_bf16 v[48:51], v[156:159], v[172:175], v[48:51]
	v_mfma_f32_16x16x32_bf16 v[36:39], v[148:151], v[180:183], v[36:39]
	v_mfma_f32_16x16x32_bf16 v[32:35], v[156:159], v[180:183], v[32:35]
	v_mfma_f32_16x16x32_bf16 v[20:23], v[148:151], v[188:191], v[20:23]
	v_mfma_f32_16x16x32_bf16 v[16:19], v[156:159], v[188:191], v[16:19]
	s_barrier
	s_add_u32 s14, s18, 0x160080
	s_addc_u32 s15, s19, 0
	s_add_i32 s18, s20, s2
	s_mov_b32 m0, s18
	s_nop 0
	global_load_lds_dwordx4 v130, s[14:15]
	s_add_i32 m0, s18, 0x2000
	s_nop 0
	global_load_lds_dwordx4 v128, s[14:15]
	s_waitcnt vmcnt(6)
	s_barrier
	v_mfma_f32_16x16x32_bf16 v[44:47], v[192:195], v[160:163], v[44:47]
	v_mfma_f32_16x16x32_bf16 v[40:43], v[200:203], v[160:163], v[40:43]
	v_mfma_f32_16x16x32_bf16 v[28:31], v[192:195], v[168:171], v[28:31]
	v_mfma_f32_16x16x32_bf16 v[24:27], v[200:203], v[168:171], v[24:27]
	v_mfma_f32_16x16x32_bf16 v[12:15], v[192:195], v[176:179], v[12:15]
	v_mfma_f32_16x16x32_bf16 v[8:11], v[200:203], v[176:179], v[8:11]
	v_mfma_f32_16x16x32_bf16 v[4:7], v[192:195], v[184:187], v[4:7]
	v_mfma_f32_16x16x32_bf16 v[0:3], v[200:203], v[184:187], v[0:3]
	v_mfma_f32_16x16x32_bf16 v[44:47], v[196:199], v[164:167], v[44:47]
	v_mfma_f32_16x16x32_bf16 v[40:43], v[204:207], v[164:167], v[40:43]
	v_mfma_f32_16x16x32_bf16 v[28:31], v[196:199], v[172:175], v[28:31]
	v_mfma_f32_16x16x32_bf16 v[24:27], v[204:207], v[172:175], v[24:27]
	v_mfma_f32_16x16x32_bf16 v[12:15], v[196:199], v[180:183], v[12:15]
	v_mfma_f32_16x16x32_bf16 v[8:11], v[204:207], v[180:183], v[8:11]
	v_mfma_f32_16x16x32_bf16 v[4:7], v[196:199], v[188:191], v[4:7]
	v_mfma_f32_16x16x32_bf16 v[0:3], v[204:207], v[188:191], v[0:3]
	s_add_i32 s47, s47, 2
	s_add_u32 s43, s43, 0x100
	s_addc_u32 s46, s46, 0
	s_cmp_gt_u32 s47, 5
	s_mov_b64 s[14:15], s[16:17]
	s_barrier
	s_cbranch_scc0 .LBB0_2927
	s_ashr_i32 s14, s28, 1
	s_and_b32 s14, s14, 0xfffffe00
	s_lshl_b32 s15, s27, 8
	s_add_i32 s15, s15, s14
	v_add_u32_e32 v146, s15, v136
	v_lshl_or_b32 v144, s26, 8, v138
	v_ashrrev_i32_e32 v147, 31, v146
	v_ashrrev_i32_e32 v145, 31, v144
	v_lshlrev_b64 v[148:149], 13, v[146:147]
	v_lshl_add_u64 v[148:149], s[58:59], 0, v[148:149]
	v_lshlrev_b64 v[144:145], 2, v[144:145]
	v_lshl_add_u64 v[148:149], v[148:149], 0, v[144:145]
	global_store_dwordx4 v[148:149], v[124:127], off
	global_store_dwordx4 v[148:149], v[120:123], off offset:64
	global_store_dwordx4 v[148:149], v[108:111], off offset:512
	global_store_dwordx4 v[148:149], v[104:107], off offset:576
	s_mov_b64 s[14:15], 0x100000
	s_mov_b32 s28, s41
	v_or_b32_e32 v104, 16, v146
	v_ashrrev_i32_e32 v105, 31, v104
	v_lshlrev_b64 v[104:105], 13, v[104:105]
	v_lshl_add_u64 v[104:105], s[58:59], 0, v[104:105]
	v_lshl_add_u64 v[104:105], v[104:105], 0, v[144:145]
	global_store_dwordx4 v[104:105], v[116:119], off
	global_store_dwordx4 v[104:105], v[112:115], off offset:64
	global_store_dwordx4 v[104:105], v[92:95], off offset:512
	global_store_dwordx4 v[104:105], v[88:91], off offset:576
	s_mov_b32 s26, s40
	s_mov_b32 s27, s42
	v_or_b32_e32 v88, 32, v146
	v_ashrrev_i32_e32 v89, 31, v88
	v_lshlrev_b64 v[88:89], 13, v[88:89]
	v_lshl_add_u64 v[88:89], s[58:59], 0, v[88:89]
	v_lshl_add_u64 v[88:89], v[88:89], 0, v[144:145]
	global_store_dwordx4 v[88:89], v[100:103], off
	global_store_dwordx4 v[88:89], v[96:99], off offset:64
	global_store_dwordx4 v[88:89], v[76:79], off offset:512
	global_store_dwordx4 v[88:89], v[72:75], off offset:576
	s_mov_b64 s[16:17], s[6:7]
	s_nop 0
	v_or_b32_e32 v72, 48, v146
	v_ashrrev_i32_e32 v73, 31, v72
	v_lshlrev_b64 v[72:73], 13, v[72:73]
	v_lshl_add_u64 v[72:73], s[58:59], 0, v[72:73]
	v_lshl_add_u64 v[72:73], v[72:73], 0, v[144:145]
	global_store_dwordx4 v[72:73], v[84:87], off
	global_store_dwordx4 v[72:73], v[80:83], off offset:64
	global_store_dwordx4 v[72:73], v[68:71], off offset:512
	global_store_dwordx4 v[72:73], v[64:67], off offset:576
	s_nop 1
	v_lshl_add_u64 v[64:65], v[148:149], 0, s[14:15]
	s_mov_b32 s14, 0x100000
	v_add_co_u32_e32 v66, vcc, s14, v148
	s_mov_b64 s[14:15], 0x120000
	s_nop 0
	v_addc_co_u32_e32 v67, vcc, 0, v149, vcc
	global_store_dwordx4 v[66:67], v[60:63], off
	global_store_dwordx4 v[64:65], v[56:59], off offset:64
	global_store_dwordx4 v[64:65], v[44:47], off offset:512
	global_store_dwordx4 v[64:65], v[40:43], off offset:576
	s_nop 1
	v_lshl_add_u64 v[40:41], v[148:149], 0, s[14:15]
	s_mov_b32 s14, 0x120000
	v_add_co_u32_e32 v42, vcc, s14, v148
	s_mov_b64 s[14:15], 0x140000
	s_nop 0
	v_addc_co_u32_e32 v43, vcc, 0, v149, vcc
	global_store_dwordx4 v[42:43], v[52:55], off
	global_store_dwordx4 v[40:41], v[48:51], off offset:64
	global_store_dwordx4 v[40:41], v[28:31], off offset:512
	global_store_dwordx4 v[40:41], v[24:27], off offset:576
	s_nop 1
	v_lshl_add_u64 v[24:25], v[148:149], 0, s[14:15]
	s_mov_b32 s14, 0x140000
	v_add_co_u32_e32 v26, vcc, s14, v148
	s_mov_b64 s[14:15], 0x160000
	s_nop 0
	v_addc_co_u32_e32 v27, vcc, 0, v149, vcc
	global_store_dwordx4 v[26:27], v[36:39], off
	global_store_dwordx4 v[24:25], v[32:35], off offset:64
	global_store_dwordx4 v[24:25], v[12:15], off offset:512
	global_store_dwordx4 v[24:25], v[8:11], off offset:576
	s_nop 1
	v_add_co_u32_e32 v10, vcc, 0x160000, v148
	v_lshl_add_u64 v[8:9], v[148:149], 0, s[14:15]
	s_nop 0
	v_addc_co_u32_e32 v11, vcc, 0, v149, vcc
	s_and_b64 vcc, exec, s[10:11]
	s_mov_b64 s[14:15], s[12:13]
	global_store_dwordx4 v[10:11], v[20:23], off
	global_store_dwordx4 v[8:9], v[16:19], off offset:64
	global_store_dwordx4 v[8:9], v[4:7], off offset:512
	global_store_dwordx4 v[8:9], v[0:3], off offset:576
	s_cbranch_vccz .LBB0_2920
	s_waitcnt vmcnt(0)
	s_cmpk_gt_u32 s1, 0xff
	s_cbranch_scc1 .LBB0_2931
	s_barrier

.LBB0_3276:
	ds_read_b128 v[128:131], v183
	ds_read_b128 v[132:135], v183 offset:1024
	ds_read_b128 v[136:139], v183 offset:2048
	ds_read_b128 v[140:143], v183 offset:3072
	v_lshl_add_u64 v[194:195], s[34:35], 0, v[160:161]
	s_add_i32 m0, s5, 0xc000
	ds_read_b128 v[144:147], v184
	ds_read_b128 v[148:151], v184 offset:1024
	ds_read_b128 v[152:155], v184 offset:2048
	ds_read_b128 v[168:171], v184 offset:3072
	ds_read_b128 v[172:175], v184 offset:4096
	ds_read_b128 v[176:179], v184 offset:5120
	ds_read_b128 v[186:189], v184 offset:6144
	ds_read_b128 v[190:193], v184 offset:7168
	global_load_lds_dwordx4 v[194:195], off
	v_lshl_add_u64 v[194:195], s[34:35], 0, v[162:163]
	s_add_i32 m0, s5, 0xe000
	s_nop 0
	global_load_lds_dwordx4 v[194:195], off
	s_waitcnt lgkmcnt(8)
	s_barrier
	s_waitcnt lgkmcnt(0)
	s_waitcnt lgkmcnt(0)
	v_mfma_f32_16x16x32_bf16 v[124:127], v[128:131], v[144:147], v[124:127]
	s_add_u32 s36, s34, 0x100
	s_addc_u32 s37, s35, 0
	s_cmp_eq_u32 s64, 28
	s_cselect_b32 s41, s23, s37
	s_cselect_b32 s40, s60, s36
	s_cselect_b32 s39, s21, s63
	s_cselect_b32 s38, s61, s62
	v_mfma_f32_16x16x32_bf16 v[120:123], v[136:139], v[144:147], v[120:123]
	v_mfma_f32_16x16x32_bf16 v[116:119], v[128:131], v[152:155], v[116:119]
	v_mfma_f32_16x16x32_bf16 v[112:115], v[136:139], v[152:155], v[112:115]
	v_mfma_f32_16x16x32_bf16 v[104:107], v[128:131], v[172:175], v[104:107]
	v_mfma_f32_16x16x32_bf16 v[108:111], v[136:139], v[172:175], v[108:111]
	v_mfma_f32_16x16x32_bf16 v[96:99], v[128:131], v[186:189], v[96:99]
	v_mfma_f32_16x16x32_bf16 v[100:103], v[136:139], v[186:189], v[100:103]
	v_mfma_f32_16x16x32_bf16 v[124:127], v[132:135], v[148:151], v[124:127]
	v_mfma_f32_16x16x32_bf16 v[120:123], v[140:143], v[148:151], v[120:123]
	v_mfma_f32_16x16x32_bf16 v[116:119], v[132:135], v[168:171], v[116:119]
	v_mfma_f32_16x16x32_bf16 v[112:115], v[140:143], v[168:171], v[112:115]
	v_mfma_f32_16x16x32_bf16 v[104:107], v[132:135], v[176:179], v[104:107]
	v_mfma_f32_16x16x32_bf16 v[108:111], v[140:143], v[176:179], v[108:111]
	v_mfma_f32_16x16x32_bf16 v[96:99], v[132:135], v[190:193], v[96:99]
	v_mfma_f32_16x16x32_bf16 v[100:103], v[140:143], v[190:193], v[100:103]
	s_barrier
	s_add_i32 s34, s54, s4
	v_lshl_add_u64 v[210:211], s[38:39], 0, v[156:157]
	s_mov_b32 m0, s34
	ds_read_b128 v[194:197], v185
	ds_read_b128 v[198:201], v185 offset:1024
	ds_read_b128 v[202:205], v185 offset:2048
	ds_read_b128 v[206:209], v185 offset:3072
	global_load_lds_dwordx4 v[210:211], off
	v_lshl_add_u64 v[212:213], s[38:39], 0, v[158:159]
	s_add_i32 m0, s34, 0x2000
	s_nop 0
	global_load_lds_dwordx4 v[212:213], off
	s_barrier
	s_waitcnt lgkmcnt(0)
	s_waitcnt lgkmcnt(0)
	v_mfma_f32_16x16x32_bf16 v[56:59], v[194:197], v[144:147], v[56:59]
	v_mfma_f32_16x16x32_bf16 v[60:63], v[202:205], v[144:147], v[60:63]
	v_mfma_f32_16x16x32_bf16 v[48:51], v[194:197], v[152:155], v[48:51]
	v_mfma_f32_16x16x32_bf16 v[52:55], v[202:205], v[152:155], v[52:55]
	v_mfma_f32_16x16x32_bf16 v[40:43], v[194:197], v[172:175], v[40:43]
	v_mfma_f32_16x16x32_bf16 v[44:47], v[202:205], v[172:175], v[44:47]
	v_mfma_f32_16x16x32_bf16 v[32:35], v[194:197], v[186:189], v[32:35]
	v_mfma_f32_16x16x32_bf16 v[36:39], v[202:205], v[186:189], v[36:39]
	v_mfma_f32_16x16x32_bf16 v[56:59], v[198:201], v[148:151], v[56:59]
	v_mfma_f32_16x16x32_bf16 v[60:63], v[206:209], v[148:151], v[60:63]
	v_mfma_f32_16x16x32_bf16 v[48:51], v[198:201], v[168:171], v[48:51]
	v_mfma_f32_16x16x32_bf16 v[52:55], v[206:209], v[168:171], v[52:55]
	v_mfma_f32_16x16x32_bf16 v[40:43], v[198:201], v[176:179], v[40:43]
	v_mfma_f32_16x16x32_bf16 v[44:47], v[206:209], v[176:179], v[44:47]
	v_mfma_f32_16x16x32_bf16 v[32:35], v[198:201], v[190:193], v[32:35]
	v_mfma_f32_16x16x32_bf16 v[36:39], v[206:209], v[190:193], v[36:39]
	s_mov_b32 m0, s5
	v_lshl_add_u64 v[214:215], s[40:41], 0, v[156:157]
	s_barrier
	ds_read_b128 v[144:147], v184 offset:16384
	ds_read_b128 v[148:151], v184 offset:17408
	ds_read_b128 v[152:155], v184 offset:18432
	ds_read_b128 v[168:171], v184 offset:19456
	ds_read_b128 v[172:175], v184 offset:20480
	ds_read_b128 v[176:179], v184 offset:21504
	ds_read_b128 v[186:189], v184 offset:22528
	ds_read_b128 v[190:193], v184 offset:23552
	global_load_lds_dwordx4 v[214:215], off
	v_lshl_add_u64 v[216:217], s[40:41], 0, v[158:159]
	s_mov_b32 m0, s31
	s_nop 0
	global_load_lds_dwordx4 v[216:217], off
	s_barrier
	s_waitcnt lgkmcnt(0)
	s_waitcnt lgkmcnt(0)
	v_mfma_f32_16x16x32_bf16 v[88:91], v[128:131], v[144:147], v[88:91]
	v_mfma_f32_16x16x32_bf16 v[92:95], v[136:139], v[144:147], v[92:95]
	v_mfma_f32_16x16x32_bf16 v[80:83], v[128:131], v[152:155], v[80:83]
	v_mfma_f32_16x16x32_bf16 v[84:87], v[136:139], v[152:155], v[84:87]
	v_mfma_f32_16x16x32_bf16 v[72:75], v[128:131], v[172:175], v[72:75]
	v_mfma_f32_16x16x32_bf16 v[76:79], v[136:139], v[172:175], v[76:79]
	v_mfma_f32_16x16x32_bf16 v[64:67], v[128:131], v[186:189], v[64:67]
	v_mfma_f32_16x16x32_bf16 v[68:71], v[136:139], v[186:189], v[68:71]
	v_mfma_f32_16x16x32_bf16 v[88:91], v[132:135], v[148:151], v[88:91]
	v_mfma_f32_16x16x32_bf16 v[92:95], v[140:143], v[148:151], v[92:95]
	v_mfma_f32_16x16x32_bf16 v[80:83], v[132:135], v[168:171], v[80:83]
	v_mfma_f32_16x16x32_bf16 v[84:87], v[140:143], v[168:171], v[84:87]
	v_mfma_f32_16x16x32_bf16 v[72:75], v[132:135], v[176:179], v[72:75]
	v_mfma_f32_16x16x32_bf16 v[76:79], v[140:143], v[176:179], v[76:79]
	v_mfma_f32_16x16x32_bf16 v[64:67], v[132:135], v[190:193], v[64:67]
	v_mfma_f32_16x16x32_bf16 v[68:71], v[140:143], v[190:193], v[68:71]
	s_barrier
	s_add_u32 s34, s38, 0x80000
	s_addc_u32 s35, s39, 0
	s_add_i32 s65, s55, s4
	v_lshl_add_u64 v[128:129], s[34:35], 0, v[156:157]
	s_mov_b32 m0, s65
	s_nop 0
	global_load_lds_dwordx4 v[128:129], off
	v_lshl_add_u64 v[128:129], s[34:35], 0, v[158:159]
	s_add_i32 m0, s65, 0x2000
	s_nop 0
	global_load_lds_dwordx4 v[128:129], off
	s_waitcnt vmcnt(6)
	s_barrier
	v_mfma_f32_16x16x32_bf16 v[24:27], v[194:197], v[144:147], v[24:27]
	v_mfma_f32_16x16x32_bf16 v[28:31], v[202:205], v[144:147], v[28:31]
	v_mfma_f32_16x16x32_bf16 v[16:19], v[194:197], v[152:155], v[16:19]
	v_mfma_f32_16x16x32_bf16 v[20:23], v[202:205], v[152:155], v[20:23]
	v_mfma_f32_16x16x32_bf16 v[8:11], v[194:197], v[172:175], v[8:11]
	v_mfma_f32_16x16x32_bf16 v[12:15], v[202:205], v[172:175], v[12:15]
	v_mfma_f32_16x16x32_bf16 v[0:3], v[194:197], v[186:189], v[0:3]
	v_mfma_f32_16x16x32_bf16 v[4:7], v[202:205], v[186:189], v[4:7]
	v_mfma_f32_16x16x32_bf16 v[24:27], v[198:201], v[148:151], v[24:27]
	v_mfma_f32_16x16x32_bf16 v[28:31], v[206:209], v[148:151], v[28:31]
	v_mfma_f32_16x16x32_bf16 v[16:19], v[198:201], v[168:171], v[16:19]
	v_mfma_f32_16x16x32_bf16 v[20:23], v[206:209], v[168:171], v[20:23]
	v_mfma_f32_16x16x32_bf16 v[8:11], v[198:201], v[176:179], v[8:11]
	v_mfma_f32_16x16x32_bf16 v[12:15], v[206:209], v[176:179], v[12:15]
	v_mfma_f32_16x16x32_bf16 v[0:3], v[198:201], v[190:193], v[0:3]
	v_mfma_f32_16x16x32_bf16 v[4:7], v[206:209], v[190:193], v[4:7]
	s_add_i32 s65, 0, 0x18000
	v_add_u32_e32 v140, s65, v181
	s_barrier
	ds_read_b128 v[128:131], v140
	ds_read_b128 v[132:135], v140 offset:1024
	ds_read_b128 v[136:139], v140 offset:2048
	ds_read_b128 v[140:143], v140 offset:3072
	s_add_u32 s34, s40, 0x80000
	s_addc_u32 s35, s41, 0
	s_mov_b32 m0, s42
	v_lshl_add_u64 v[194:195], s[34:35], 0, v[156:157]
	ds_read_b128 v[144:147], v184 offset:32768
	ds_read_b128 v[148:151], v184 offset:33792
	ds_read_b128 v[152:155], v184 offset:34816
	ds_read_b128 v[168:171], v184 offset:35840
	ds_read_b128 v[172:175], v184 offset:36864
	ds_read_b128 v[176:179], v184 offset:37888
	ds_read_b128 v[186:189], v184 offset:38912
	ds_read_b128 v[190:193], v184 offset:39936
	global_load_lds_dwordx4 v[194:195], off
	v_lshl_add_u64 v[194:195], s[34:35], 0, v[158:159]
	s_mov_b32 m0, s43
	s_nop 0
	global_load_lds_dwordx4 v[194:195], off
	s_waitcnt lgkmcnt(8)
	s_barrier
	s_waitcnt lgkmcnt(0)
	s_waitcnt lgkmcnt(0)
	v_mfma_f32_16x16x32_bf16 v[124:127], v[128:131], v[144:147], v[124:127]
	v_mfma_f32_16x16x32_bf16 v[120:123], v[136:139], v[144:147], v[120:123]
	v_mfma_f32_16x16x32_bf16 v[116:119], v[128:131], v[152:155], v[116:119]
	v_mfma_f32_16x16x32_bf16 v[112:115], v[136:139], v[152:155], v[112:115]
	v_mfma_f32_16x16x32_bf16 v[104:107], v[128:131], v[172:175], v[104:107]
	v_mfma_f32_16x16x32_bf16 v[108:111], v[136:139], v[172:175], v[108:111]
	v_mfma_f32_16x16x32_bf16 v[96:99], v[128:131], v[186:189], v[96:99]
	v_mfma_f32_16x16x32_bf16 v[100:103], v[136:139], v[186:189], v[100:103]
	v_mfma_f32_16x16x32_bf16 v[124:127], v[132:135], v[148:151], v[124:127]
	v_mfma_f32_16x16x32_bf16 v[120:123], v[140:143], v[148:151], v[120:123]
	v_mfma_f32_16x16x32_bf16 v[116:119], v[132:135], v[168:171], v[116:119]
	v_mfma_f32_16x16x32_bf16 v[112:115], v[140:143], v[168:171], v[112:115]
	v_mfma_f32_16x16x32_bf16 v[104:107], v[132:135], v[176:179], v[104:107]
	v_mfma_f32_16x16x32_bf16 v[108:111], v[140:143], v[176:179], v[108:111]
	v_mfma_f32_16x16x32_bf16 v[96:99], v[132:135], v[190:193], v[96:99]
	v_mfma_f32_16x16x32_bf16 v[100:103], v[140:143], v[190:193], v[100:103]
	s_barrier
	s_add_i32 s40, 0, 0x1c000
	s_add_i32 s34, s65, s4
	v_add_u32_e32 v206, s40, v181
	v_lshl_add_u64 v[210:211], v[210:211], 0, s[10:11]
	s_mov_b32 m0, s34
	ds_read_b128 v[194:197], v206
	ds_read_b128 v[198:201], v206 offset:1024
	ds_read_b128 v[202:205], v206 offset:2048
	ds_read_b128 v[206:209], v206 offset:3072
	global_load_lds_dwordx4 v[210:211], off
	v_lshl_add_u64 v[210:211], v[212:213], 0, s[10:11]
	s_add_i32 m0, s34, 0x2000
	s_nop 0
	global_load_lds_dwordx4 v[210:211], off
	s_barrier
	s_waitcnt lgkmcnt(0)
	s_waitcnt lgkmcnt(0)
	v_mfma_f32_16x16x32_bf16 v[56:59], v[194:197], v[144:147], v[56:59]
	v_mfma_f32_16x16x32_bf16 v[60:63], v[202:205], v[144:147], v[60:63]
	v_mfma_f32_16x16x32_bf16 v[48:51], v[194:197], v[152:155], v[48:51]
	v_mfma_f32_16x16x32_bf16 v[52:55], v[202:205], v[152:155], v[52:55]
	v_mfma_f32_16x16x32_bf16 v[40:43], v[194:197], v[172:175], v[40:43]
	v_mfma_f32_16x16x32_bf16 v[44:47], v[202:205], v[172:175], v[44:47]
	v_mfma_f32_16x16x32_bf16 v[32:35], v[194:197], v[186:189], v[32:35]
	v_mfma_f32_16x16x32_bf16 v[36:39], v[202:205], v[186:189], v[36:39]
	v_mfma_f32_16x16x32_bf16 v[56:59], v[198:201], v[148:151], v[56:59]
	v_mfma_f32_16x16x32_bf16 v[60:63], v[206:209], v[148:151], v[60:63]
	v_mfma_f32_16x16x32_bf16 v[48:51], v[198:201], v[168:171], v[48:51]
	v_mfma_f32_16x16x32_bf16 v[52:55], v[206:209], v[168:171], v[52:55]
	v_mfma_f32_16x16x32_bf16 v[40:43], v[198:201], v[176:179], v[40:43]
	v_mfma_f32_16x16x32_bf16 v[44:47], v[206:209], v[176:179], v[44:47]
	v_mfma_f32_16x16x32_bf16 v[32:35], v[198:201], v[190:193], v[32:35]
	v_mfma_f32_16x16x32_bf16 v[36:39], v[206:209], v[190:193], v[36:39]
	s_mov_b32 m0, s47
	v_lshl_add_u64 v[210:211], v[214:215], 0, s[10:11]
	s_barrier
	ds_read_b128 v[144:147], v184 offset:49152
	ds_read_b128 v[148:151], v184 offset:50176
	ds_read_b128 v[152:155], v184 offset:51200
	ds_read_b128 v[168:171], v184 offset:52224
	ds_read_b128 v[172:175], v184 offset:53248
	ds_read_b128 v[176:179], v184 offset:54272
	ds_read_b128 v[186:189], v184 offset:55296
	ds_read_b128 v[190:193], v184 offset:56320
	global_load_lds_dwordx4 v[210:211], off
	v_lshl_add_u64 v[210:211], v[216:217], 0, s[10:11]
	s_mov_b32 m0, s50
	s_nop 0
	global_load_lds_dwordx4 v[210:211], off
	s_barrier
	s_waitcnt lgkmcnt(0)
	s_waitcnt lgkmcnt(0)
	v_mfma_f32_16x16x32_bf16 v[88:91], v[128:131], v[144:147], v[88:91]
	v_mfma_f32_16x16x32_bf16 v[92:95], v[136:139], v[144:147], v[92:95]
	v_mfma_f32_16x16x32_bf16 v[80:83], v[128:131], v[152:155], v[80:83]
	v_mfma_f32_16x16x32_bf16 v[84:87], v[136:139], v[152:155], v[84:87]
	v_mfma_f32_16x16x32_bf16 v[72:75], v[128:131], v[172:175], v[72:75]
	v_mfma_f32_16x16x32_bf16 v[76:79], v[136:139], v[172:175], v[76:79]
	v_mfma_f32_16x16x32_bf16 v[64:67], v[128:131], v[186:189], v[64:67]
	v_mfma_f32_16x16x32_bf16 v[68:71], v[136:139], v[186:189], v[68:71]
	v_mfma_f32_16x16x32_bf16 v[88:91], v[132:135], v[148:151], v[88:91]
	v_mfma_f32_16x16x32_bf16 v[92:95], v[140:143], v[148:151], v[92:95]
	v_mfma_f32_16x16x32_bf16 v[80:83], v[132:135], v[168:171], v[80:83]
	v_mfma_f32_16x16x32_bf16 v[84:87], v[140:143], v[168:171], v[84:87]
	v_mfma_f32_16x16x32_bf16 v[72:75], v[132:135], v[176:179], v[72:75]
	v_mfma_f32_16x16x32_bf16 v[76:79], v[140:143], v[176:179], v[76:79]
	v_mfma_f32_16x16x32_bf16 v[64:67], v[132:135], v[190:193], v[64:67]
	v_mfma_f32_16x16x32_bf16 v[68:71], v[140:143], v[190:193], v[68:71]
	s_barrier
	s_add_u32 s34, s38, 0x80080
	s_addc_u32 s35, s39, 0
	s_add_i32 s38, s40, s4
	v_lshl_add_u64 v[128:129], s[34:35], 0, v[156:157]
	s_mov_b32 m0, s38
	s_nop 0
	global_load_lds_dwordx4 v[128:129], off
	v_lshl_add_u64 v[128:129], s[34:35], 0, v[158:159]
	s_add_i32 m0, s38, 0x2000
	s_nop 0
	global_load_lds_dwordx4 v[128:129], off
	s_waitcnt vmcnt(6)
	s_barrier
	v_mfma_f32_16x16x32_bf16 v[24:27], v[194:197], v[144:147], v[24:27]
	v_mfma_f32_16x16x32_bf16 v[28:31], v[202:205], v[144:147], v[28:31]
	v_mfma_f32_16x16x32_bf16 v[16:19], v[194:197], v[152:155], v[16:19]
	v_mfma_f32_16x16x32_bf16 v[20:23], v[202:205], v[152:155], v[20:23]
	v_mfma_f32_16x16x32_bf16 v[8:11], v[194:197], v[172:175], v[8:11]
	v_mfma_f32_16x16x32_bf16 v[12:15], v[202:205], v[172:175], v[12:15]
	v_mfma_f32_16x16x32_bf16 v[0:3], v[194:197], v[186:189], v[0:3]
	v_mfma_f32_16x16x32_bf16 v[4:7], v[202:205], v[186:189], v[4:7]
	v_mfma_f32_16x16x32_bf16 v[24:27], v[198:201], v[148:151], v[24:27]
	v_mfma_f32_16x16x32_bf16 v[28:31], v[206:209], v[148:151], v[28:31]
	v_mfma_f32_16x16x32_bf16 v[16:19], v[198:201], v[168:171], v[16:19]
	v_mfma_f32_16x16x32_bf16 v[20:23], v[206:209], v[168:171], v[20:23]
	v_mfma_f32_16x16x32_bf16 v[8:11], v[198:201], v[176:179], v[8:11]
	v_mfma_f32_16x16x32_bf16 v[12:15], v[206:209], v[176:179], v[12:15]
	v_mfma_f32_16x16x32_bf16 v[0:3], v[198:201], v[190:193], v[0:3]
	v_mfma_f32_16x16x32_bf16 v[4:7], v[206:209], v[190:193], v[4:7]
	s_add_i32 s64, s64, 2
	s_add_u32 s62, s62, 0x100
	s_addc_u32 s63, s63, 0
	s_cmp_gt_u32 s64, 29
	s_mov_b64 s[34:35], s[36:37]
	s_barrier
	s_cbranch_scc0 .LBB0_3276
	v_lshl_or_b32 v168, s59, 7, v182
	v_ashrrev_i32_e32 v169, 31, v168
	v_lshlrev_b64 v[140:141], 2, v[168:169]
	v_lshl_add_u64 v[128:129], s[12:13], 0, v[140:141]
	global_load_dwordx4 v[132:135], v[128:129], off
	v_lshl_add_u64 v[128:129], s[8:9], 0, v[140:141]
	s_cmp_lt_u32 s30, 32
	s_movk_i32 s21, 0x3000
	global_load_dwordx4 v[128:131], v[128:129], off
	s_cselect_b32 s21, s21, 0x6000
	s_cmp_gt_i32 s30, 15
	s_cselect_b32 s21, s21, 0
	s_lshl_b32 s21, s21, 2
	s_add_u32 s34, s52, s21
	s_addc_u32 s35, s53, 0
	v_lshl_add_u64 v[170:171], s[34:35], 0, v[140:141]
	v_lshl_add_u32 v142, s30, 8, v180
	global_load_dwordx4 v[136:139], v[170:171], off
	v_or_b32_e32 v144, 16, v142
	v_readlane_b32 s60, v240, 22
	v_ashrrev_i32_e32 v143, 31, v142
	v_ashrrev_i32_e32 v145, 31, v144
	v_readlane_b32 s64, v240, 26
	v_readlane_b32 s65, v240, 27
	v_lshlrev_b64 v[146:147], 13, v[142:143]
	s_mov_b64 s[40:41], s[64:65]
	v_lshlrev_b64 v[144:145], 13, v[144:145]
	v_lshl_add_u64 v[146:147], s[40:41], 0, v[146:147]
	v_lshl_add_u64 v[144:145], s[40:41], 0, v[144:145]
	v_lshl_add_u64 v[174:175], v[146:147], 0, v[140:141]
	v_lshl_add_u64 v[172:173], v[144:145], 0, v[140:141]
	global_load_dwordx4 v[148:151], v[174:175], off
	global_load_dwordx4 v[152:155], v[172:173], off
	v_or_b32_e32 v144, 32, v142
	v_or_b32_e32 v142, 48, v142
	v_ashrrev_i32_e32 v145, 31, v144
	v_ashrrev_i32_e32 v143, 31, v142
	v_lshlrev_b64 v[144:145], 13, v[144:145]
	v_lshlrev_b64 v[142:143], 13, v[142:143]
	v_lshl_add_u64 v[144:145], s[40:41], 0, v[144:145]
	v_lshl_add_u64 v[142:143], s[40:41], 0, v[142:143]
	v_lshl_add_u64 v[178:179], v[144:145], 0, v[140:141]
	v_lshl_add_u64 v[176:177], v[142:143], 0, v[140:141]
	global_load_dwordx4 v[140:143], v[174:175], off offset:256
	global_load_dwordx4 v[186:189], v[178:179], off
	global_load_dwordx4 v[190:193], v[176:177], off
	global_load_dwordx4 v[144:147], v[172:173], off offset:256
	s_mov_b32 s21, 0x100000
	s_mov_b64 s[34:35], 0x100000
	s_mov_b32 s59, s20
	s_mov_b32 s30, s22
	s_mov_b64 s[36:37], s[28:29]
	v_readlane_b32 s61, v240, 23
	v_readlane_b32 s62, v240, 24
	v_readlane_b32 s63, v240, 25
	v_readlane_b32 s66, v240, 28
	v_readlane_b32 s67, v240, 29
	v_readlane_b32 s68, v240, 30
	v_readlane_b32 s69, v240, 31
	v_readlane_b32 s70, v240, 32
	v_readlane_b32 s71, v240, 33
	v_readlane_b32 s72, v240, 34
	v_readlane_b32 s73, v240, 35
	v_readlane_b32 s74, v240, 36
	v_readlane_b32 s75, v240, 37
	s_waitcnt vmcnt(0)
	v_add_f32_e32 v169, v120, v132
	v_add_f32_e32 v194, v121, v133
	v_add_f32_e32 v195, v122, v134
	v_add_f32_e32 v196, v123, v135
	v_pk_add_f32 v[120:121], v[126:127], v[130:131]
	v_pk_add_f32 v[122:123], v[124:125], v[128:129]
	v_add_f32_e32 v124, v112, v132
	v_add_f32_e32 v125, v113, v133
	v_add_f32_e32 v126, v114, v134
	v_add_f32_e32 v127, v115, v135
	v_pk_add_f32 v[112:113], v[118:119], v[130:131]
	v_pk_add_f32 v[114:115], v[116:117], v[128:129]
	v_mul_f32_e32 v116, 0xbfb8aa3b, v169
	v_mul_f32_e32 v117, 0xbfb8aa3b, v194
	v_mul_f32_e32 v118, 0xbfb8aa3b, v195
	v_mul_f32_e32 v119, 0xbfb8aa3b, v196
	v_mul_f32_e32 v124, 0xbfb8aa3b, v124
	v_mul_f32_e32 v125, 0xbfb8aa3b, v125
	v_mul_f32_e32 v126, 0xbfb8aa3b, v126
	v_mul_f32_e32 v127, 0xbfb8aa3b, v127
	v_exp_f32_e32 v169, v116
	v_exp_f32_e32 v194, v117
	v_exp_f32_e32 v195, v118
	v_exp_f32_e32 v196, v119
	v_exp_f32_e32 v124, v124
	v_exp_f32_e32 v125, v125
	v_exp_f32_e32 v126, v126
	v_exp_f32_e32 v127, v127
	v_add_f32_e32 v108, v108, v132
	v_mul_f32_e32 v108, 0xbfb8aa3b, v108
	v_pk_mul_f32 v[116:117], v[138:139], v[120:121]
	v_pk_mul_f32 v[118:119], v[136:137], v[122:123]
	v_pk_mul_f32 v[120:121], v[138:139], v[112:113]
	v_pk_mul_f32 v[122:123], v[136:137], v[114:115]
	v_add_f32_e32 v112, 1.0, v169
	v_add_f32_e32 v113, 1.0, v194
	v_add_f32_e32 v114, 1.0, v195
	v_add_f32_e32 v115, 1.0, v196
	v_add_f32_e32 v124, 1.0, v124
	v_add_f32_e32 v125, 1.0, v125
	v_add_f32_e32 v126, 1.0, v126
	v_add_f32_e32 v127, 1.0, v127
	v_rcp_f32_e32 v112, v112
	v_rcp_f32_e32 v113, v113
	v_rcp_f32_e32 v114, v114
	v_rcp_f32_e32 v115, v115
	v_rcp_f32_e32 v124, v124
	v_rcp_f32_e32 v126, v126
	v_rcp_f32_e32 v127, v127
	v_rcp_f32_e32 v125, v125
	v_exp_f32_e32 v108, v108
	v_add_f32_e32 v109, v109, v133
	v_mul_f32_e32 v109, 0xbfb8aa3b, v109
	v_exp_f32_e32 v109, v109
	v_pk_fma_f32 v[114:115], v[116:117], v[114:115], v[150:151]
	v_pk_fma_f32 v[112:113], v[118:119], v[112:113], v[148:149]
	v_pk_fma_f32 v[118:119], v[120:121], v[126:127], v[154:155]
	v_pk_fma_f32 v[116:117], v[122:123], v[124:125], v[152:153]
	v_add_f32_e32 v108, 1.0, v108
	global_store_dwordx4 v[174:175], v[112:115], off
	global_store_dwordx4 v[172:173], v[116:119], off
	v_add_f32_e32 v100, v100, v132
	v_rcp_f32_e32 v112, v108
	v_add_f32_e32 v108, v110, v134
	v_add_co_u32_e32 v116, vcc, s21, v174
	v_mul_f32_e32 v108, 0xbfb8aa3b, v108
	s_nop 0
	v_addc_co_u32_e32 v117, vcc, 0, v175, vcc
	v_add_f32_e32 v113, 1.0, v109
	v_exp_f32_e32 v114, v108
	v_add_f32_e32 v115, v111, v135
	global_load_dwordx4 v[108:111], v[116:117], off
	v_mul_f32_e32 v115, 0xbfb8aa3b, v115
	v_exp_f32_e32 v115, v115
	v_add_f32_e32 v114, 1.0, v114
	v_mul_f32_e32 v100, 0xbfb8aa3b, v100
	v_rcp_f32_e32 v113, v113
	v_add_f32_e32 v115, 1.0, v115
	v_rcp_f32_e32 v114, v114
	v_rcp_f32_e32 v115, v115
	v_exp_f32_e32 v100, v100
	v_pk_add_f32 v[106:107], v[106:107], v[130:131]
	v_pk_add_f32 v[104:105], v[104:105], v[128:129]
	v_pk_mul_f32 v[118:119], v[138:139], v[106:107]
	v_pk_mul_f32 v[120:121], v[136:137], v[104:105]
	v_pk_fma_f32 v[114:115], v[118:119], v[114:115], v[188:189]
	v_pk_fma_f32 v[112:113], v[120:121], v[112:113], v[186:187]
	v_add_f32_e32 v100, 1.0, v100
	global_store_dwordx4 v[178:179], v[112:115], off
	v_add_f32_e32 v101, v101, v133
	v_mul_f32_e32 v101, 0xbfb8aa3b, v101
	v_rcp_f32_e32 v112, v100
	v_add_f32_e32 v100, v102, v134
	v_mul_f32_e32 v100, 0xbfb8aa3b, v100
	v_exp_f32_e32 v114, v100
	v_add_f32_e32 v100, v103, v135
	v_mul_f32_e32 v115, 0xbfb8aa3b, v100
	v_exp_f32_e32 v101, v101
	v_exp_f32_e32 v115, v115
	v_add_f32_e32 v114, 1.0, v114
	v_rcp_f32_e32 v114, v114
	v_add_f32_e32 v113, 1.0, v101
	v_add_f32_e32 v115, 1.0, v115
	v_rcp_f32_e32 v113, v113
	v_rcp_f32_e32 v115, v115
	v_pk_add_f32 v[98:99], v[98:99], v[130:131]
	v_pk_add_f32 v[96:97], v[96:97], v[128:129]
	v_pk_mul_f32 v[120:121], v[138:139], v[98:99]
	v_pk_mul_f32 v[122:123], v[136:137], v[96:97]
	v_add_f32_e32 v92, v92, v132
	v_pk_fma_f32 v[114:115], v[120:121], v[114:115], v[192:193]
	v_pk_fma_f32 v[112:113], v[122:123], v[112:113], v[190:191]
	v_mul_f32_e32 v92, 0xbfb8aa3b, v92
	global_store_dwordx4 v[176:177], v[112:115], off
	v_add_co_u32_e32 v118, vcc, s56, v174
	s_nop 0
	v_exp_f32_e32 v112, v92
	v_add_f32_e32 v92, v93, v133
	v_mul_f32_e32 v92, 0xbfb8aa3b, v92
	v_addc_co_u32_e32 v119, vcc, 0, v175, vcc
	v_exp_f32_e32 v113, v92
	v_add_f32_e32 v94, v94, v134
	v_add_f32_e32 v95, v95, v135
	global_load_dwordx4 v[100:103], v[118:119], off
	v_mul_f32_e32 v94, 0xbfb8aa3b, v94
	v_mul_f32_e32 v95, 0xbfb8aa3b, v95
	v_add_co_u32_e32 v122, vcc, s57, v174
	v_exp_f32_e32 v94, v94
	v_exp_f32_e32 v95, v95
	v_add_f32_e32 v112, 1.0, v112
	v_addc_co_u32_e32 v123, vcc, 0, v175, vcc
	v_rcp_f32_e32 v120, v112
	v_add_f32_e32 v121, 1.0, v113
	global_load_dwordx4 v[112:115], v[122:123], off
	v_add_f32_e32 v94, 1.0, v94
	v_add_f32_e32 v95, 1.0, v95
	v_rcp_f32_e32 v94, v94
	v_rcp_f32_e32 v95, v95
	v_rcp_f32_e32 v121, v121
	v_pk_add_f32 v[90:91], v[90:91], v[130:131]
	v_pk_add_f32 v[88:89], v[88:89], v[128:129]
	v_pk_mul_f32 v[124:125], v[138:139], v[90:91]
	v_pk_mul_f32 v[126:127], v[136:137], v[88:89]
	v_add_f32_e32 v84, v84, v132
	v_mul_f32_e32 v84, 0xbfb8aa3b, v84
	v_add_f32_e32 v86, v86, v134
	v_add_f32_e32 v87, v87, v135
	v_mul_f32_e32 v86, 0xbfb8aa3b, v86
	s_waitcnt vmcnt(0)
	v_pk_fma_f32 v[110:111], v[124:125], v[94:95], v[110:111]
	v_add_co_u32_e32 v94, vcc, s58, v174
	v_pk_fma_f32 v[108:109], v[126:127], v[120:121], v[108:109]
	s_nop 0
	v_addc_co_u32_e32 v95, vcc, 0, v175, vcc
	global_store_dwordx4 v[116:117], v[108:111], off
	global_load_dwordx4 v[108:111], v[94:95], off
	v_exp_f32_e32 v116, v84
	v_add_f32_e32 v84, v85, v133
	v_mul_f32_e32 v87, 0xbfb8aa3b, v87
	v_mul_f32_e32 v84, 0xbfb8aa3b, v84
	v_exp_f32_e32 v86, v86
	v_exp_f32_e32 v87, v87
	v_exp_f32_e32 v117, v84
	v_add_f32_e32 v78, v78, v134
	v_add_f32_e32 v79, v79, v135
	v_mul_f32_e32 v78, 0xbfb8aa3b, v78
	v_mul_f32_e32 v79, 0xbfb8aa3b, v79
	v_exp_f32_e32 v78, v78
	v_exp_f32_e32 v79, v79
	v_add_f32_e32 v86, 1.0, v86
	v_add_f32_e32 v87, 1.0, v87
	v_add_f32_e32 v116, 1.0, v116
	v_add_f32_e32 v117, 1.0, v117
	v_rcp_f32_e32 v86, v86
	v_rcp_f32_e32 v87, v87
	v_rcp_f32_e32 v116, v116
	v_rcp_f32_e32 v117, v117
	v_pk_add_f32 v[82:83], v[82:83], v[130:131]
	v_add_f32_e32 v76, v76, v132
	v_add_f32_e32 v78, 1.0, v78
	v_add_f32_e32 v79, 1.0, v79
	v_pk_add_f32 v[80:81], v[80:81], v[128:129]
	v_pk_mul_f32 v[120:121], v[138:139], v[82:83]
	v_mul_f32_e32 v76, 0xbfb8aa3b, v76
	v_rcp_f32_e32 v78, v78
	v_rcp_f32_e32 v79, v79
	v_pk_mul_f32 v[124:125], v[136:137], v[80:81]
	v_pk_add_f32 v[74:75], v[74:75], v[130:131]
	v_add_f32_e32 v68, v68, v132
	v_add_f32_e32 v70, v70, v134
	v_add_f32_e32 v71, v71, v135
	v_mul_f32_e32 v68, 0xbfb8aa3b, v68
	v_mul_f32_e32 v70, 0xbfb8aa3b, v70
	v_mul_f32_e32 v71, 0xbfb8aa3b, v71
	v_exp_f32_e32 v70, v70
	v_exp_f32_e32 v71, v71
	v_pk_add_f32 v[72:73], v[72:73], v[128:129]
	v_pk_add_f32 v[66:67], v[66:67], v[130:131]
	v_add_f32_e32 v70, 1.0, v70
	v_add_f32_e32 v71, 1.0, v71
	v_rcp_f32_e32 v70, v70
	v_pk_fma_f32 v[102:103], v[120:121], v[86:87], v[102:103]
	v_exp_f32_e32 v86, v76
	v_add_f32_e32 v76, v77, v133
	v_pk_fma_f32 v[100:101], v[124:125], v[116:117], v[100:101]
	v_mul_f32_e32 v76, 0xbfb8aa3b, v76
	global_store_dwordx4 v[118:119], v[100:103], off
	v_exp_f32_e32 v87, v76
	v_add_f32_e32 v86, 1.0, v86
	v_pk_mul_f32 v[100:101], v[138:139], v[74:75]
	v_rcp_f32_e32 v86, v86
	v_add_f32_e32 v87, 1.0, v87
	v_rcp_f32_e32 v87, v87
	v_pk_fma_f32 v[102:103], v[100:101], v[78:79], v[114:115]
	v_exp_f32_e32 v78, v68
	v_add_f32_e32 v68, v69, v133
	v_mul_f32_e32 v68, 0xbfb8aa3b, v68
	v_exp_f32_e32 v79, v68
	v_rcp_f32_e32 v71, v71
	v_add_f32_e32 v78, 1.0, v78
	v_pk_mul_f32 v[116:117], v[136:137], v[72:73]
	v_add_f32_e32 v79, 1.0, v79
	v_rcp_f32_e32 v78, v78
	v_rcp_f32_e32 v79, v79
	v_pk_fma_f32 v[100:101], v[116:117], v[86:87], v[112:113]
	v_pk_mul_f32 v[86:87], v[138:139], v[66:67]
	global_store_dwordx4 v[122:123], v[100:103], off
	v_pk_add_f32 v[64:65], v[64:65], v[128:129]
	v_lshl_add_u64 v[92:93], v[174:175], 0, s[34:35]
	v_pk_mul_f32 v[100:101], v[136:137], v[64:65]
	v_lshl_add_u64 v[84:85], v[174:175], 0, s[14:15]
	v_lshl_add_u64 v[76:77], v[174:175], 0, s[16:17]
	v_lshl_add_u64 v[68:69], v[174:175], 0, s[18:19]
	global_load_dwordx4 v[104:107], v[178:179], off offset:256
	global_load_dwordx4 v[96:99], v[176:177], off offset:256
	s_waitcnt vmcnt(0)
	v_pk_fma_f32 v[102:103], v[86:87], v[70:71], v[110:111]
	v_or_b32_e32 v70, 64, v168
	v_ashrrev_i32_e32 v71, 31, v70
	v_pk_fma_f32 v[100:101], v[100:101], v[78:79], v[108:109]
	v_lshlrev_b64 v[70:71], 2, v[70:71]
	global_store_dwordx4 v[94:95], v[100:103], off
	v_lshl_add_u64 v[78:79], s[12:13], 0, v[70:71]
	global_load_dwordx4 v[100:103], v[78:79], off
	v_lshl_add_u64 v[70:71], s[8:9], 0, v[70:71]
	global_load_dwordx4 v[88:91], v[92:93], off offset:256
	global_load_dwordx4 v[80:83], v[84:85], off offset:256
	global_load_dwordx4 v[72:75], v[76:77], off offset:256
	global_load_dwordx4 v[64:67], v[68:69], off offset:256
	global_load_dwordx4 v[108:111], v[70:71], off
	global_load_dwordx4 v[112:115], v[170:171], off offset:256
	s_and_b64 vcc, exec, s[6:7]
	s_mov_b64 s[34:35], s[26:27]
	s_waitcnt vmcnt(0)
	v_add_f32_e32 v60, v60, v100
	v_add_f32_e32 v61, v61, v101
	v_add_f32_e32 v62, v62, v102
	v_add_f32_e32 v63, v63, v103
	v_add_f32_e32 v52, v52, v100
	v_add_f32_e32 v53, v53, v101
	v_add_f32_e32 v54, v54, v102
	v_add_f32_e32 v55, v55, v103
	v_add_f32_e32 v44, v44, v100
	v_add_f32_e32 v45, v45, v101
	v_add_f32_e32 v46, v46, v102
	v_add_f32_e32 v47, v47, v103
	v_add_f32_e32 v36, v36, v100
	v_add_f32_e32 v37, v37, v101
	v_add_f32_e32 v38, v38, v102
	v_add_f32_e32 v39, v39, v103
	v_add_f32_e32 v28, v28, v100
	v_add_f32_e32 v29, v29, v101
	v_add_f32_e32 v30, v30, v102
	v_add_f32_e32 v31, v31, v103
	v_add_f32_e32 v20, v20, v100
	v_add_f32_e32 v21, v21, v101
	v_add_f32_e32 v22, v22, v102
	v_add_f32_e32 v23, v23, v103
	v_add_f32_e32 v12, v12, v100
	v_add_f32_e32 v13, v13, v101
	v_add_f32_e32 v14, v14, v102
	v_add_f32_e32 v15, v15, v103
	v_add_f32_e32 v4, v4, v100
	v_add_f32_e32 v5, v5, v101
	v_add_f32_e32 v6, v6, v102
	v_add_f32_e32 v7, v7, v103
	v_mul_f32_e32 v60, 0xbfb8aa3b, v60
	v_mul_f32_e32 v61, 0xbfb8aa3b, v61
	v_mul_f32_e32 v62, 0xbfb8aa3b, v62
	v_mul_f32_e32 v63, 0xbfb8aa3b, v63
	v_mul_f32_e32 v52, 0xbfb8aa3b, v52
	v_mul_f32_e32 v53, 0xbfb8aa3b, v53
	v_mul_f32_e32 v54, 0xbfb8aa3b, v54
	v_mul_f32_e32 v55, 0xbfb8aa3b, v55
	v_mul_f32_e32 v44, 0xbfb8aa3b, v44
	v_mul_f32_e32 v45, 0xbfb8aa3b, v45
	v_mul_f32_e32 v46, 0xbfb8aa3b, v46
	v_mul_f32_e32 v47, 0xbfb8aa3b, v47
	v_mul_f32_e32 v36, 0xbfb8aa3b, v36
	v_mul_f32_e32 v37, 0xbfb8aa3b, v37
	v_mul_f32_e32 v38, 0xbfb8aa3b, v38
	v_mul_f32_e32 v39, 0xbfb8aa3b, v39
	v_mul_f32_e32 v28, 0xbfb8aa3b, v28
	v_mul_f32_e32 v29, 0xbfb8aa3b, v29
	v_mul_f32_e32 v30, 0xbfb8aa3b, v30
	v_mul_f32_e32 v31, 0xbfb8aa3b, v31
	v_mul_f32_e32 v20, 0xbfb8aa3b, v20
	v_mul_f32_e32 v21, 0xbfb8aa3b, v21
	v_mul_f32_e32 v22, 0xbfb8aa3b, v22
	v_mul_f32_e32 v23, 0xbfb8aa3b, v23
	v_mul_f32_e32 v12, 0xbfb8aa3b, v12
	v_mul_f32_e32 v13, 0xbfb8aa3b, v13
	v_mul_f32_e32 v14, 0xbfb8aa3b, v14
	v_mul_f32_e32 v15, 0xbfb8aa3b, v15
	v_mul_f32_e32 v4, 0xbfb8aa3b, v4
	v_mul_f32_e32 v5, 0xbfb8aa3b, v5
	v_mul_f32_e32 v6, 0xbfb8aa3b, v6
	v_mul_f32_e32 v7, 0xbfb8aa3b, v7
	v_exp_f32_e32 v60, v60
	v_exp_f32_e32 v61, v61
	v_exp_f32_e32 v62, v62
	v_exp_f32_e32 v63, v63
	v_exp_f32_e32 v52, v52
	v_exp_f32_e32 v53, v53
	v_exp_f32_e32 v54, v54
	v_exp_f32_e32 v55, v55
	v_exp_f32_e32 v44, v44
	v_exp_f32_e32 v45, v45
	v_exp_f32_e32 v46, v46
	v_exp_f32_e32 v47, v47
	v_exp_f32_e32 v36, v36
	v_exp_f32_e32 v37, v37
	v_exp_f32_e32 v38, v38
	v_exp_f32_e32 v39, v39
	v_exp_f32_e32 v28, v28
	v_exp_f32_e32 v29, v29
	v_exp_f32_e32 v30, v30
	v_exp_f32_e32 v31, v31
	v_exp_f32_e32 v20, v20
	v_exp_f32_e32 v21, v21
	v_exp_f32_e32 v22, v22
	v_exp_f32_e32 v23, v23
	v_exp_f32_e32 v12, v12
	v_exp_f32_e32 v13, v13
	v_exp_f32_e32 v14, v14
	v_exp_f32_e32 v15, v15
	v_exp_f32_e32 v4, v4
	v_exp_f32_e32 v5, v5
	v_exp_f32_e32 v6, v6
	v_exp_f32_e32 v7, v7
	v_add_f32_e32 v60, 1.0, v60
	v_add_f32_e32 v61, 1.0, v61
	v_add_f32_e32 v62, 1.0, v62
	v_add_f32_e32 v63, 1.0, v63
	v_add_f32_e32 v52, 1.0, v52
	v_add_f32_e32 v53, 1.0, v53
	v_add_f32_e32 v54, 1.0, v54
	v_add_f32_e32 v55, 1.0, v55
	v_add_f32_e32 v44, 1.0, v44
	v_add_f32_e32 v45, 1.0, v45
	v_add_f32_e32 v46, 1.0, v46
	v_add_f32_e32 v47, 1.0, v47
	v_add_f32_e32 v36, 1.0, v36
	v_add_f32_e32 v37, 1.0, v37
	v_add_f32_e32 v38, 1.0, v38
	v_add_f32_e32 v39, 1.0, v39
	v_add_f32_e32 v28, 1.0, v28
	v_add_f32_e32 v29, 1.0, v29
	v_add_f32_e32 v30, 1.0, v30
	v_add_f32_e32 v31, 1.0, v31
	v_add_f32_e32 v20, 1.0, v20
	v_add_f32_e32 v21, 1.0, v21
	v_add_f32_e32 v22, 1.0, v22
	v_add_f32_e32 v23, 1.0, v23
	v_add_f32_e32 v12, 1.0, v12
	v_add_f32_e32 v13, 1.0, v13
	v_add_f32_e32 v14, 1.0, v14
	v_add_f32_e32 v15, 1.0, v15
	v_add_f32_e32 v4, 1.0, v4
	v_add_f32_e32 v5, 1.0, v5
	v_add_f32_e32 v6, 1.0, v6
	v_add_f32_e32 v7, 1.0, v7
	v_rcp_f32_e32 v60, v60
	v_rcp_f32_e32 v61, v61
	v_rcp_f32_e32 v62, v62
	v_rcp_f32_e32 v63, v63
	v_rcp_f32_e32 v52, v52
	v_rcp_f32_e32 v53, v53
	v_rcp_f32_e32 v54, v54
	v_rcp_f32_e32 v55, v55
	v_rcp_f32_e32 v44, v44
	v_rcp_f32_e32 v45, v45
	v_rcp_f32_e32 v46, v46
	v_rcp_f32_e32 v47, v47
	v_rcp_f32_e32 v36, v36
	v_rcp_f32_e32 v37, v37
	v_rcp_f32_e32 v38, v38
	v_rcp_f32_e32 v39, v39
	v_rcp_f32_e32 v28, v28
	v_rcp_f32_e32 v29, v29
	v_rcp_f32_e32 v30, v30
	v_rcp_f32_e32 v31, v31
	v_rcp_f32_e32 v20, v20
	v_rcp_f32_e32 v21, v21
	v_rcp_f32_e32 v22, v22
	v_rcp_f32_e32 v23, v23
	v_rcp_f32_e32 v12, v12
	v_rcp_f32_e32 v13, v13
	v_rcp_f32_e32 v14, v14
	v_rcp_f32_e32 v15, v15
	v_rcp_f32_e32 v4, v4
	v_rcp_f32_e32 v5, v5
	v_rcp_f32_e32 v6, v6
	v_rcp_f32_e32 v7, v7
	v_pk_add_f32 v[58:59], v[58:59], v[110:111]
	v_pk_add_f32 v[56:57], v[56:57], v[108:109]
	v_pk_add_f32 v[50:51], v[50:51], v[110:111]
	v_pk_add_f32 v[48:49], v[48:49], v[108:109]
	v_pk_add_f32 v[42:43], v[42:43], v[110:111]
	v_pk_add_f32 v[40:41], v[40:41], v[108:109]
	v_pk_add_f32 v[34:35], v[34:35], v[110:111]
	v_pk_add_f32 v[32:33], v[32:33], v[108:109]
	v_pk_add_f32 v[26:27], v[26:27], v[110:111]
	v_pk_add_f32 v[24:25], v[24:25], v[108:109]
	v_pk_add_f32 v[18:19], v[18:19], v[110:111]
	v_pk_add_f32 v[16:17], v[16:17], v[108:109]
	v_pk_add_f32 v[10:11], v[10:11], v[110:111]
	v_pk_add_f32 v[8:9], v[8:9], v[108:109]
	v_pk_add_f32 v[2:3], v[2:3], v[110:111]
	v_pk_add_f32 v[0:1], v[0:1], v[108:109]
	v_pk_mul_f32 v[58:59], v[114:115], v[58:59]
	v_pk_mul_f32 v[56:57], v[112:113], v[56:57]
	v_pk_mul_f32 v[50:51], v[114:115], v[50:51]
	v_pk_mul_f32 v[48:49], v[112:113], v[48:49]
	v_pk_mul_f32 v[42:43], v[114:115], v[42:43]
	v_pk_mul_f32 v[40:41], v[112:113], v[40:41]
	v_pk_mul_f32 v[34:35], v[114:115], v[34:35]
	v_pk_mul_f32 v[32:33], v[112:113], v[32:33]
	v_pk_mul_f32 v[26:27], v[114:115], v[26:27]
	v_pk_mul_f32 v[24:25], v[112:113], v[24:25]
	v_pk_mul_f32 v[18:19], v[114:115], v[18:19]
	v_pk_mul_f32 v[16:17], v[112:113], v[16:17]
	v_pk_mul_f32 v[10:11], v[114:115], v[10:11]
	v_pk_mul_f32 v[8:9], v[112:113], v[8:9]
	v_pk_mul_f32 v[2:3], v[114:115], v[2:3]
	v_pk_mul_f32 v[0:1], v[112:113], v[0:1]
	v_pk_fma_f32 v[58:59], v[58:59], v[62:63], v[142:143]
	v_pk_fma_f32 v[56:57], v[56:57], v[60:61], v[140:141]
	v_pk_fma_f32 v[48:49], v[48:49], v[52:53], v[144:145]
	v_pk_fma_f32 v[50:51], v[50:51], v[54:55], v[146:147]
	v_pk_fma_f32 v[40:41], v[40:41], v[44:45], v[104:105]
	v_pk_fma_f32 v[42:43], v[42:43], v[46:47], v[106:107]
	v_pk_fma_f32 v[32:33], v[32:33], v[36:37], v[96:97]
	v_pk_fma_f32 v[34:35], v[34:35], v[38:39], v[98:99]
	v_pk_fma_f32 v[24:25], v[24:25], v[28:29], v[88:89]
	v_pk_fma_f32 v[26:27], v[26:27], v[30:31], v[90:91]
	v_pk_fma_f32 v[16:17], v[16:17], v[20:21], v[80:81]
	v_pk_fma_f32 v[18:19], v[18:19], v[22:23], v[82:83]
	v_pk_fma_f32 v[8:9], v[8:9], v[12:13], v[72:73]
	v_pk_fma_f32 v[10:11], v[10:11], v[14:15], v[74:75]
	v_pk_fma_f32 v[0:1], v[0:1], v[4:5], v[64:65]
	v_pk_fma_f32 v[2:3], v[2:3], v[6:7], v[66:67]
	global_store_dwordx4 v[174:175], v[56:59], off offset:256
	global_store_dwordx4 v[172:173], v[48:51], off offset:256
	global_store_dwordx4 v[178:179], v[40:43], off offset:256
	global_store_dwordx4 v[176:177], v[32:35], off offset:256
	global_store_dwordx4 v[92:93], v[24:27], off offset:256
	global_store_dwordx4 v[84:85], v[16:19], off offset:256
	global_store_dwordx4 v[76:77], v[8:11], off offset:256
	global_store_dwordx4 v[68:69], v[0:3], off offset:256
	s_cbranch_vccz .LBB0_3269
	s_waitcnt vmcnt(0)
	s_cmpk_gt_u32 s0, 0xff
	s_cbranch_scc1 .LBB0_3280
	s_barrier

.LBB0_3443:
	ds_read_b128 v[148:151], v144
	ds_read_b128 v[152:155], v144 offset:1024
	ds_read_b128 v[156:159], v144 offset:2048
	ds_read_b128 v[160:163], v144 offset:3072
	s_add_i32 m0, s26, 0xc000
	ds_read_b128 v[164:167], v145
	ds_read_b128 v[168:171], v145 offset:1024
	ds_read_b128 v[172:175], v145 offset:2048
	ds_read_b128 v[176:179], v145 offset:3072
	ds_read_b128 v[180:183], v145 offset:4096
	ds_read_b128 v[184:187], v145 offset:5120
	ds_read_b128 v[188:191], v145 offset:6144
	ds_read_b128 v[192:195], v145 offset:7168
	global_load_lds_dwordx4 v134, s[18:19]
	s_add_i32 m0, s26, 0xe000
	s_nop 0
	global_load_lds_dwordx4 v136, s[18:19]
	s_waitcnt lgkmcnt(8)
	s_barrier
	s_waitcnt lgkmcnt(0)
	s_waitcnt lgkmcnt(0)
	v_mfma_f32_16x16x32_bf16 v[124:127], v[148:151], v[164:167], v[124:127]
	s_add_u32 s20, s18, 0x100
	s_addc_u32 s21, s19, 0
	s_cmp_eq_u32 s46, 28
	s_cselect_b32 s25, s11, s21
	s_cselect_b32 s24, s40, s20
	s_cselect_b32 s23, s9, s43
	s_cselect_b32 s22, s41, s42
	v_mfma_f32_16x16x32_bf16 v[120:123], v[156:159], v[164:167], v[120:123]
	v_mfma_f32_16x16x32_bf16 v[108:111], v[148:151], v[172:175], v[108:111]
	v_mfma_f32_16x16x32_bf16 v[104:107], v[156:159], v[172:175], v[104:107]
	v_mfma_f32_16x16x32_bf16 v[92:95], v[148:151], v[180:183], v[92:95]
	v_mfma_f32_16x16x32_bf16 v[88:91], v[156:159], v[180:183], v[88:91]
	v_mfma_f32_16x16x32_bf16 v[76:79], v[148:151], v[188:191], v[76:79]
	v_mfma_f32_16x16x32_bf16 v[72:75], v[156:159], v[188:191], v[72:75]
	v_mfma_f32_16x16x32_bf16 v[124:127], v[152:155], v[168:171], v[124:127]
	v_mfma_f32_16x16x32_bf16 v[120:123], v[160:163], v[168:171], v[120:123]
	v_mfma_f32_16x16x32_bf16 v[108:111], v[152:155], v[176:179], v[108:111]
	v_mfma_f32_16x16x32_bf16 v[104:107], v[160:163], v[176:179], v[104:107]
	v_mfma_f32_16x16x32_bf16 v[92:95], v[152:155], v[184:187], v[92:95]
	v_mfma_f32_16x16x32_bf16 v[88:91], v[160:163], v[184:187], v[88:91]
	v_mfma_f32_16x16x32_bf16 v[76:79], v[152:155], v[192:195], v[76:79]
	v_mfma_f32_16x16x32_bf16 v[72:75], v[160:163], v[192:195], v[72:75]
	s_barrier
	s_add_i32 s18, s37, s1
	s_mov_b32 m0, s18
	ds_read_b128 v[196:199], v146
	ds_read_b128 v[200:203], v146 offset:1024
	ds_read_b128 v[204:207], v146 offset:2048
	ds_read_b128 v[208:211], v146 offset:3072
	global_load_lds_dwordx4 v130, s[22:23]
	s_add_i32 m0, s18, 0x2000
	s_nop 0
	global_load_lds_dwordx4 v128, s[22:23]
	s_barrier
	s_waitcnt lgkmcnt(0)
	s_waitcnt lgkmcnt(0)
	v_mfma_f32_16x16x32_bf16 v[116:119], v[196:199], v[164:167], v[116:119]
	v_mfma_f32_16x16x32_bf16 v[112:115], v[204:207], v[164:167], v[112:115]
	v_mfma_f32_16x16x32_bf16 v[100:103], v[196:199], v[172:175], v[100:103]
	v_mfma_f32_16x16x32_bf16 v[96:99], v[204:207], v[172:175], v[96:99]
	v_mfma_f32_16x16x32_bf16 v[84:87], v[196:199], v[180:183], v[84:87]
	v_mfma_f32_16x16x32_bf16 v[80:83], v[204:207], v[180:183], v[80:83]
	v_mfma_f32_16x16x32_bf16 v[68:71], v[196:199], v[188:191], v[68:71]
	v_mfma_f32_16x16x32_bf16 v[64:67], v[204:207], v[188:191], v[64:67]
	v_mfma_f32_16x16x32_bf16 v[116:119], v[200:203], v[168:171], v[116:119]
	v_mfma_f32_16x16x32_bf16 v[112:115], v[208:211], v[168:171], v[112:115]
	v_mfma_f32_16x16x32_bf16 v[100:103], v[200:203], v[176:179], v[100:103]
	v_mfma_f32_16x16x32_bf16 v[96:99], v[208:211], v[176:179], v[96:99]
	v_mfma_f32_16x16x32_bf16 v[84:87], v[200:203], v[184:187], v[84:87]
	v_mfma_f32_16x16x32_bf16 v[80:83], v[208:211], v[184:187], v[80:83]
	v_mfma_f32_16x16x32_bf16 v[68:71], v[200:203], v[192:195], v[68:71]
	v_mfma_f32_16x16x32_bf16 v[64:67], v[208:211], v[192:195], v[64:67]
	s_mov_b32 m0, s26
	v_lshl_add_u64 v[216:217], s[24:25], 0, v[130:131]
	s_barrier
	ds_read_b128 v[164:167], v145 offset:16384
	ds_read_b128 v[168:171], v145 offset:17408
	ds_read_b128 v[172:175], v145 offset:18432
	ds_read_b128 v[176:179], v145 offset:19456
	ds_read_b128 v[180:183], v145 offset:20480
	ds_read_b128 v[184:187], v145 offset:21504
	ds_read_b128 v[188:191], v145 offset:22528
	ds_read_b128 v[192:195], v145 offset:23552
	global_load_lds_dwordx4 v130, s[24:25]
	v_lshl_add_u64 v[218:219], s[24:25], 0, v[128:129]
	s_mov_b32 m0, s27
	s_nop 0
	global_load_lds_dwordx4 v128, s[24:25]
	s_barrier
	s_waitcnt lgkmcnt(0)
	s_waitcnt lgkmcnt(0)
	v_mfma_f32_16x16x32_bf16 v[60:63], v[148:151], v[164:167], v[60:63]
	v_mfma_f32_16x16x32_bf16 v[56:59], v[156:159], v[164:167], v[56:59]
	v_mfma_f32_16x16x32_bf16 v[44:47], v[148:151], v[172:175], v[44:47]
	v_mfma_f32_16x16x32_bf16 v[40:43], v[156:159], v[172:175], v[40:43]
	v_mfma_f32_16x16x32_bf16 v[28:31], v[148:151], v[180:183], v[28:31]
	v_mfma_f32_16x16x32_bf16 v[24:27], v[156:159], v[180:183], v[24:27]
	v_mfma_f32_16x16x32_bf16 v[12:15], v[148:151], v[188:191], v[12:15]
	v_mfma_f32_16x16x32_bf16 v[8:11], v[156:159], v[188:191], v[8:11]
	v_mfma_f32_16x16x32_bf16 v[60:63], v[152:155], v[168:171], v[60:63]
	v_mfma_f32_16x16x32_bf16 v[56:59], v[160:163], v[168:171], v[56:59]
	v_mfma_f32_16x16x32_bf16 v[44:47], v[152:155], v[176:179], v[44:47]
	v_mfma_f32_16x16x32_bf16 v[40:43], v[160:163], v[176:179], v[40:43]
	v_mfma_f32_16x16x32_bf16 v[28:31], v[152:155], v[184:187], v[28:31]
	v_mfma_f32_16x16x32_bf16 v[24:27], v[160:163], v[184:187], v[24:27]
	v_mfma_f32_16x16x32_bf16 v[12:15], v[152:155], v[192:195], v[12:15]
	v_mfma_f32_16x16x32_bf16 v[8:11], v[160:163], v[192:195], v[8:11]
	s_barrier
	s_add_u32 s18, s22, 0x80000
	s_addc_u32 s19, s23, 0
	s_add_i32 s47, s38, s1
	s_mov_b32 m0, s47
	s_nop 0
	global_load_lds_dwordx4 v130, s[18:19]
	s_add_i32 m0, s47, 0x2000
	s_nop 0
	global_load_lds_dwordx4 v128, s[18:19]
	s_waitcnt vmcnt(6)
	s_barrier
	v_mfma_f32_16x16x32_bf16 v[52:55], v[196:199], v[164:167], v[52:55]
	v_mfma_f32_16x16x32_bf16 v[48:51], v[204:207], v[164:167], v[48:51]
	v_mfma_f32_16x16x32_bf16 v[36:39], v[196:199], v[172:175], v[36:39]
	v_mfma_f32_16x16x32_bf16 v[32:35], v[204:207], v[172:175], v[32:35]
	v_mfma_f32_16x16x32_bf16 v[20:23], v[196:199], v[180:183], v[20:23]
	v_mfma_f32_16x16x32_bf16 v[16:19], v[204:207], v[180:183], v[16:19]
	v_mfma_f32_16x16x32_bf16 v[4:7], v[196:199], v[188:191], v[4:7]
	v_mfma_f32_16x16x32_bf16 v[0:3], v[204:207], v[188:191], v[0:3]
	v_mfma_f32_16x16x32_bf16 v[52:55], v[200:203], v[168:171], v[52:55]
	v_mfma_f32_16x16x32_bf16 v[48:51], v[208:211], v[168:171], v[48:51]
	v_mfma_f32_16x16x32_bf16 v[36:39], v[200:203], v[176:179], v[36:39]
	v_mfma_f32_16x16x32_bf16 v[32:35], v[208:211], v[176:179], v[32:35]
	v_mfma_f32_16x16x32_bf16 v[20:23], v[200:203], v[184:187], v[20:23]
	v_mfma_f32_16x16x32_bf16 v[16:19], v[208:211], v[184:187], v[16:19]
	v_mfma_f32_16x16x32_bf16 v[4:7], v[200:203], v[192:195], v[4:7]
	v_mfma_f32_16x16x32_bf16 v[0:3], v[208:211], v[192:195], v[0:3]
	s_add_i32 s47, 0, 0x18000
	v_add_u32_e32 v147, s47, v143
	s_barrier
	ds_read_b128 v[148:151], v147
	ds_read_b128 v[152:155], v147 offset:1024
	ds_read_b128 v[156:159], v147 offset:2048
	ds_read_b128 v[160:163], v147 offset:3072
	s_add_u32 s18, s24, 0x80000
	s_addc_u32 s19, s25, 0
	s_mov_b32 m0, s28
	ds_read_b128 v[164:167], v145 offset:32768
	ds_read_b128 v[168:171], v145 offset:33792
	ds_read_b128 v[172:175], v145 offset:34816
	ds_read_b128 v[176:179], v145 offset:35840
	ds_read_b128 v[180:183], v145 offset:36864
	ds_read_b128 v[184:187], v145 offset:37888
	ds_read_b128 v[188:191], v145 offset:38912
	ds_read_b128 v[192:195], v145 offset:39936
	global_load_lds_dwordx4 v130, s[18:19]
	s_mov_b32 m0, s29
	s_nop 0
	global_load_lds_dwordx4 v128, s[18:19]
	s_waitcnt lgkmcnt(8)
	s_barrier
	s_waitcnt lgkmcnt(0)
	s_waitcnt lgkmcnt(0)
	v_mfma_f32_16x16x32_bf16 v[124:127], v[148:151], v[164:167], v[124:127]
	v_mfma_f32_16x16x32_bf16 v[120:123], v[156:159], v[164:167], v[120:123]
	v_mfma_f32_16x16x32_bf16 v[108:111], v[148:151], v[172:175], v[108:111]
	v_mfma_f32_16x16x32_bf16 v[104:107], v[156:159], v[172:175], v[104:107]
	v_mfma_f32_16x16x32_bf16 v[92:95], v[148:151], v[180:183], v[92:95]
	v_mfma_f32_16x16x32_bf16 v[88:91], v[156:159], v[180:183], v[88:91]
	v_mfma_f32_16x16x32_bf16 v[76:79], v[148:151], v[188:191], v[76:79]
	v_mfma_f32_16x16x32_bf16 v[72:75], v[156:159], v[188:191], v[72:75]
	v_mfma_f32_16x16x32_bf16 v[124:127], v[152:155], v[168:171], v[124:127]
	v_mfma_f32_16x16x32_bf16 v[120:123], v[160:163], v[168:171], v[120:123]
	v_mfma_f32_16x16x32_bf16 v[108:111], v[152:155], v[176:179], v[108:111]
	v_mfma_f32_16x16x32_bf16 v[104:107], v[160:163], v[176:179], v[104:107]
	v_mfma_f32_16x16x32_bf16 v[92:95], v[152:155], v[184:187], v[92:95]
	v_mfma_f32_16x16x32_bf16 v[88:91], v[160:163], v[184:187], v[88:91]
	v_mfma_f32_16x16x32_bf16 v[76:79], v[152:155], v[192:195], v[76:79]
	v_mfma_f32_16x16x32_bf16 v[72:75], v[160:163], v[192:195], v[72:75]
	s_barrier
	s_add_i32 s24, 0, 0x1c000
	s_add_i32 s18, s47, s1
	v_add_u32_e32 v147, s24, v143
	s_add_u32 s98, s22, s6
	s_addc_u32 s99, s23, s7
	s_mov_b32 m0, s18
	ds_read_b128 v[196:199], v147
	ds_read_b128 v[200:203], v147 offset:1024
	ds_read_b128 v[204:207], v147 offset:2048
	ds_read_b128 v[208:211], v147 offset:3072
	global_load_lds_dwordx4 v130, s[98:99]
	s_add_i32 m0, s18, 0x2000
	s_nop 0
	global_load_lds_dwordx4 v128, s[98:99]
	s_barrier
	s_waitcnt lgkmcnt(0)
	s_waitcnt lgkmcnt(0)
	v_mfma_f32_16x16x32_bf16 v[116:119], v[196:199], v[164:167], v[116:119]
	v_mfma_f32_16x16x32_bf16 v[112:115], v[204:207], v[164:167], v[112:115]
	v_mfma_f32_16x16x32_bf16 v[100:103], v[196:199], v[172:175], v[100:103]
	v_mfma_f32_16x16x32_bf16 v[96:99], v[204:207], v[172:175], v[96:99]
	v_mfma_f32_16x16x32_bf16 v[84:87], v[196:199], v[180:183], v[84:87]
	v_mfma_f32_16x16x32_bf16 v[80:83], v[204:207], v[180:183], v[80:83]
	v_mfma_f32_16x16x32_bf16 v[68:71], v[196:199], v[188:191], v[68:71]
	v_mfma_f32_16x16x32_bf16 v[64:67], v[204:207], v[188:191], v[64:67]
	v_mfma_f32_16x16x32_bf16 v[116:119], v[200:203], v[168:171], v[116:119]
	v_mfma_f32_16x16x32_bf16 v[112:115], v[208:211], v[168:171], v[112:115]
	v_mfma_f32_16x16x32_bf16 v[100:103], v[200:203], v[176:179], v[100:103]
	v_mfma_f32_16x16x32_bf16 v[96:99], v[208:211], v[176:179], v[96:99]
	v_mfma_f32_16x16x32_bf16 v[84:87], v[200:203], v[184:187], v[84:87]
	v_mfma_f32_16x16x32_bf16 v[80:83], v[208:211], v[184:187], v[80:83]
	v_mfma_f32_16x16x32_bf16 v[68:71], v[200:203], v[192:195], v[68:71]
	v_mfma_f32_16x16x32_bf16 v[64:67], v[208:211], v[192:195], v[64:67]
	s_mov_b32 m0, s31
	v_lshl_add_u64 v[212:213], v[216:217], 0, s[6:7]
	s_barrier
	ds_read_b128 v[164:167], v145 offset:49152
	ds_read_b128 v[168:171], v145 offset:50176
	ds_read_b128 v[172:175], v145 offset:51200
	ds_read_b128 v[176:179], v145 offset:52224
	ds_read_b128 v[180:183], v145 offset:53248
	ds_read_b128 v[184:187], v145 offset:54272
	ds_read_b128 v[188:191], v145 offset:55296
	ds_read_b128 v[192:195], v145 offset:56320
	global_load_lds_dwordx4 v[212:213], off
	v_lshl_add_u64 v[212:213], v[218:219], 0, s[6:7]
	s_mov_b32 m0, s34
	s_nop 0
	global_load_lds_dwordx4 v[212:213], off
	s_barrier
	s_waitcnt lgkmcnt(0)
	s_waitcnt lgkmcnt(0)
	v_mfma_f32_16x16x32_bf16 v[60:63], v[148:151], v[164:167], v[60:63]
	v_mfma_f32_16x16x32_bf16 v[56:59], v[156:159], v[164:167], v[56:59]
	v_mfma_f32_16x16x32_bf16 v[44:47], v[148:151], v[172:175], v[44:47]
	v_mfma_f32_16x16x32_bf16 v[40:43], v[156:159], v[172:175], v[40:43]
	v_mfma_f32_16x16x32_bf16 v[28:31], v[148:151], v[180:183], v[28:31]
	v_mfma_f32_16x16x32_bf16 v[24:27], v[156:159], v[180:183], v[24:27]
	v_mfma_f32_16x16x32_bf16 v[12:15], v[148:151], v[188:191], v[12:15]
	v_mfma_f32_16x16x32_bf16 v[8:11], v[156:159], v[188:191], v[8:11]
	v_mfma_f32_16x16x32_bf16 v[60:63], v[152:155], v[168:171], v[60:63]
	v_mfma_f32_16x16x32_bf16 v[56:59], v[160:163], v[168:171], v[56:59]
	v_mfma_f32_16x16x32_bf16 v[44:47], v[152:155], v[176:179], v[44:47]
	v_mfma_f32_16x16x32_bf16 v[40:43], v[160:163], v[176:179], v[40:43]
	v_mfma_f32_16x16x32_bf16 v[28:31], v[152:155], v[184:187], v[28:31]
	v_mfma_f32_16x16x32_bf16 v[24:27], v[160:163], v[184:187], v[24:27]
	v_mfma_f32_16x16x32_bf16 v[12:15], v[152:155], v[192:195], v[12:15]
	v_mfma_f32_16x16x32_bf16 v[8:11], v[160:163], v[192:195], v[8:11]
	s_barrier
	s_add_u32 s18, s22, 0x80080
	s_addc_u32 s19, s23, 0
	s_add_i32 s22, s24, s1
	s_mov_b32 m0, s22
	s_nop 0
	global_load_lds_dwordx4 v130, s[18:19]
	s_add_i32 m0, s22, 0x2000
	s_nop 0
	global_load_lds_dwordx4 v128, s[18:19]
	s_waitcnt vmcnt(6)
	s_barrier
	v_mfma_f32_16x16x32_bf16 v[52:55], v[196:199], v[164:167], v[52:55]
	v_mfma_f32_16x16x32_bf16 v[48:51], v[204:207], v[164:167], v[48:51]
	v_mfma_f32_16x16x32_bf16 v[36:39], v[196:199], v[172:175], v[36:39]
	v_mfma_f32_16x16x32_bf16 v[32:35], v[204:207], v[172:175], v[32:35]
	v_mfma_f32_16x16x32_bf16 v[20:23], v[196:199], v[180:183], v[20:23]
	v_mfma_f32_16x16x32_bf16 v[16:19], v[204:207], v[180:183], v[16:19]
	v_mfma_f32_16x16x32_bf16 v[4:7], v[196:199], v[188:191], v[4:7]
	v_mfma_f32_16x16x32_bf16 v[0:3], v[204:207], v[188:191], v[0:3]
	v_mfma_f32_16x16x32_bf16 v[52:55], v[200:203], v[168:171], v[52:55]
	v_mfma_f32_16x16x32_bf16 v[48:51], v[208:211], v[168:171], v[48:51]
	v_mfma_f32_16x16x32_bf16 v[36:39], v[200:203], v[176:179], v[36:39]
	v_mfma_f32_16x16x32_bf16 v[32:35], v[208:211], v[176:179], v[32:35]
	v_mfma_f32_16x16x32_bf16 v[20:23], v[200:203], v[184:187], v[20:23]
	v_mfma_f32_16x16x32_bf16 v[16:19], v[208:211], v[184:187], v[16:19]
	v_mfma_f32_16x16x32_bf16 v[4:7], v[200:203], v[192:195], v[4:7]
	v_mfma_f32_16x16x32_bf16 v[0:3], v[208:211], v[192:195], v[0:3]
	s_add_i32 s46, s46, 2
	s_add_u32 s42, s42, 0x100
	s_addc_u32 s43, s43, 0
	s_cmp_gt_u32 s46, 29
	s_mov_b64 s[18:19], s[20:21]
	s_barrier
	s_cbranch_scc0 .LBB0_3443
	v_mul_f32_e32 v148, 0xbfb8aa3b, v124
	v_exp_f32_e32 v150, v148
	v_mul_f32_e32 v148, 0xbfb8aa3b, v125
	v_exp_f32_e32 v151, v148
	v_mul_f32_e32 v152, 0xbfb8aa3b, v126
	v_mul_f32_e32 v153, 0xbfb8aa3b, v127
	v_exp_f32_e32 v152, v152
	v_exp_f32_e32 v153, v153
	v_add_f32_e32 v150, 1.0, v150
	v_add_f32_e32 v151, 1.0, v151
	v_rcp_f32_e32 v150, v150
	v_rcp_f32_e32 v151, v151
	v_add_f32_e32 v152, 1.0, v152
	v_add_f32_e32 v153, 1.0, v153
	v_rcp_f32_e32 v152, v152
	v_rcp_f32_e32 v153, v153
	v_pk_mul_f32 v[124:125], v[124:125], v[150:151]
	s_lshl_b32 s9, s17, 7
	v_pk_mul_f32 v[120:121], v[120:121], v[124:125]
	v_pk_mul_f32 v[124:125], v[126:127], v[152:153]
	v_lshl_add_u32 v147, s16, 8, v142
	v_pk_mul_f32 v[122:123], v[122:123], v[124:125]
	v_mul_f32_e32 v124, 0xbfb8aa3b, v116
	v_mul_f32_e32 v125, 0xbfb8aa3b, v117
	s_or_b32 s16, s9, s35
	v_exp_f32_e32 v124, v124
	v_exp_f32_e32 v125, v125
	s_ashr_i32 s17, s16, 31
	v_mad_i64_i32 v[148:149], s[18:19], v147, s39, v[132:133]
	s_lshl_b64 s[16:17], s[16:17], 1
	v_cvt_pk_bf16_f32 v120, v120, v121
	v_cvt_pk_bf16_f32 v121, v122, v123
	v_lshl_add_u64 v[122:123], v[148:149], 0, s[16:17]
	global_store_dwordx2 v[122:123], v[120:121], off
	v_add_f32_e32 v120, 1.0, v124
	v_add_f32_e32 v121, 1.0, v125
	v_mul_f32_e32 v124, 0xbfb8aa3b, v118
	v_mul_f32_e32 v125, 0xbfb8aa3b, v119
	v_exp_f32_e32 v124, v124
	v_exp_f32_e32 v125, v125
	v_rcp_f32_e32 v120, v120
	v_rcp_f32_e32 v121, v121
	v_add_f32_e32 v124, 1.0, v124
	v_add_f32_e32 v125, 1.0, v125
	v_rcp_f32_e32 v124, v124
	v_rcp_f32_e32 v125, v125
	v_pk_mul_f32 v[116:117], v[116:117], v[120:121]
	s_and_b64 vcc, exec, s[4:5]
	v_pk_mul_f32 v[112:113], v[112:113], v[116:117]
	v_pk_mul_f32 v[116:117], v[118:119], v[124:125]
	v_cvt_pk_bf16_f32 v112, v112, v113
	v_pk_mul_f32 v[114:115], v[114:115], v[116:117]
	v_mul_f32_e32 v116, 0xbfb8aa3b, v110
	v_cvt_pk_bf16_f32 v113, v114, v115
	global_store_dwordx2 v[122:123], v[112:113], off offset:128
	v_mul_f32_e32 v113, 0xbfb8aa3b, v108
	v_exp_f32_e32 v114, v113
	v_mul_f32_e32 v113, 0xbfb8aa3b, v109
	v_exp_f32_e32 v115, v113
	v_mul_f32_e32 v117, 0xbfb8aa3b, v111
	v_exp_f32_e32 v116, v116
	v_exp_f32_e32 v117, v117
	v_add_f32_e32 v114, 1.0, v114
	v_add_f32_e32 v115, 1.0, v115
	v_rcp_f32_e32 v114, v114
	v_rcp_f32_e32 v115, v115
	v_add_f32_e32 v116, 1.0, v116
	v_add_f32_e32 v117, 1.0, v117
	v_rcp_f32_e32 v116, v116
	v_rcp_f32_e32 v117, v117
	v_pk_mul_f32 v[108:109], v[108:109], v[114:115]
	v_or_b32_e32 v112, 16, v147
	v_pk_mul_f32 v[104:105], v[104:105], v[108:109]
	v_pk_mul_f32 v[108:109], v[110:111], v[116:117]
	v_mad_i64_i32 v[112:113], s[18:19], v112, s39, v[132:133]
	v_pk_mul_f32 v[106:107], v[106:107], v[108:109]
	v_mul_f32_e32 v108, 0xbfb8aa3b, v100
	v_mul_f32_e32 v109, 0xbfb8aa3b, v101
	v_exp_f32_e32 v108, v108
	v_exp_f32_e32 v109, v109
	v_cvt_pk_bf16_f32 v104, v104, v105
	v_cvt_pk_bf16_f32 v105, v106, v107
	v_lshl_add_u64 v[106:107], v[112:113], 0, s[16:17]
	global_store_dwordx2 v[106:107], v[104:105], off
	v_add_f32_e32 v104, 1.0, v108
	v_add_f32_e32 v105, 1.0, v109
	v_mul_f32_e32 v108, 0xbfb8aa3b, v102
	v_mul_f32_e32 v109, 0xbfb8aa3b, v103
	v_exp_f32_e32 v108, v108
	v_exp_f32_e32 v109, v109
	v_rcp_f32_e32 v104, v104
	v_rcp_f32_e32 v105, v105
	v_add_f32_e32 v108, 1.0, v108
	v_add_f32_e32 v109, 1.0, v109
	v_rcp_f32_e32 v108, v108
	v_rcp_f32_e32 v109, v109
	v_pk_mul_f32 v[100:101], v[100:101], v[104:105]
	s_mov_b64 s[20:21], s[14:15]
	v_pk_mul_f32 v[96:97], v[96:97], v[100:101]
	v_pk_mul_f32 v[100:101], v[102:103], v[108:109]
	v_cvt_pk_bf16_f32 v96, v96, v97
	v_pk_mul_f32 v[98:99], v[98:99], v[100:101]
	v_mul_f32_e32 v100, 0xbfb8aa3b, v94
	v_cvt_pk_bf16_f32 v97, v98, v99
	global_store_dwordx2 v[106:107], v[96:97], off offset:128
	v_mul_f32_e32 v97, 0xbfb8aa3b, v92
	v_exp_f32_e32 v98, v97
	v_mul_f32_e32 v97, 0xbfb8aa3b, v93
	v_exp_f32_e32 v99, v97
	v_mul_f32_e32 v101, 0xbfb8aa3b, v95
	v_exp_f32_e32 v100, v100
	v_exp_f32_e32 v101, v101
	v_add_f32_e32 v98, 1.0, v98
	v_add_f32_e32 v99, 1.0, v99
	v_rcp_f32_e32 v98, v98
	v_rcp_f32_e32 v99, v99
	v_add_f32_e32 v100, 1.0, v100
	v_add_f32_e32 v101, 1.0, v101
	v_rcp_f32_e32 v100, v100
	v_rcp_f32_e32 v101, v101
	v_pk_mul_f32 v[92:93], v[92:93], v[98:99]
	v_or_b32_e32 v96, 32, v147
	v_pk_mul_f32 v[88:89], v[88:89], v[92:93]
	v_pk_mul_f32 v[92:93], v[94:95], v[100:101]
	v_mad_i64_i32 v[96:97], s[18:19], v96, s39, v[132:133]
	v_pk_mul_f32 v[90:91], v[90:91], v[92:93]
	v_mul_f32_e32 v92, 0xbfb8aa3b, v84
	v_mul_f32_e32 v93, 0xbfb8aa3b, v85
	v_exp_f32_e32 v92, v92
	v_exp_f32_e32 v93, v93
	v_cvt_pk_bf16_f32 v88, v88, v89
	v_cvt_pk_bf16_f32 v89, v90, v91
	v_lshl_add_u64 v[90:91], v[96:97], 0, s[16:17]
	global_store_dwordx2 v[90:91], v[88:89], off
	v_add_f32_e32 v88, 1.0, v92
	v_add_f32_e32 v89, 1.0, v93
	v_mul_f32_e32 v92, 0xbfb8aa3b, v86
	v_mul_f32_e32 v93, 0xbfb8aa3b, v87
	v_exp_f32_e32 v92, v92
	v_exp_f32_e32 v93, v93
	v_rcp_f32_e32 v88, v88
	v_rcp_f32_e32 v89, v89
	v_add_f32_e32 v92, 1.0, v92
	v_add_f32_e32 v93, 1.0, v93
	v_rcp_f32_e32 v92, v92
	v_rcp_f32_e32 v93, v93
	v_pk_mul_f32 v[84:85], v[84:85], v[88:89]
	s_nop 0
	v_pk_mul_f32 v[80:81], v[80:81], v[84:85]
	v_pk_mul_f32 v[84:85], v[86:87], v[92:93]
	v_cvt_pk_bf16_f32 v80, v80, v81
	v_pk_mul_f32 v[82:83], v[82:83], v[84:85]
	v_mul_f32_e32 v84, 0xbfb8aa3b, v78
	v_cvt_pk_bf16_f32 v81, v82, v83
	global_store_dwordx2 v[90:91], v[80:81], off offset:128
	v_mul_f32_e32 v81, 0xbfb8aa3b, v76
	v_exp_f32_e32 v82, v81
	v_mul_f32_e32 v81, 0xbfb8aa3b, v77
	v_exp_f32_e32 v83, v81
	v_mul_f32_e32 v85, 0xbfb8aa3b, v79
	v_exp_f32_e32 v84, v84
	v_exp_f32_e32 v85, v85
	v_add_f32_e32 v82, 1.0, v82
	v_add_f32_e32 v83, 1.0, v83
	v_rcp_f32_e32 v82, v82
	v_rcp_f32_e32 v83, v83
	v_add_f32_e32 v84, 1.0, v84
	v_add_f32_e32 v85, 1.0, v85
	v_rcp_f32_e32 v84, v84
	v_rcp_f32_e32 v85, v85
	v_pk_mul_f32 v[76:77], v[76:77], v[82:83]
	v_or_b32_e32 v80, 48, v147
	v_pk_mul_f32 v[72:73], v[72:73], v[76:77]
	v_pk_mul_f32 v[76:77], v[78:79], v[84:85]
	v_mad_i64_i32 v[80:81], s[18:19], v80, s39, v[132:133]
	v_pk_mul_f32 v[74:75], v[74:75], v[76:77]
	v_mul_f32_e32 v76, 0xbfb8aa3b, v68
	v_mul_f32_e32 v77, 0xbfb8aa3b, v69
	v_exp_f32_e32 v76, v76
	v_exp_f32_e32 v77, v77
	v_cvt_pk_bf16_f32 v72, v72, v73
	v_cvt_pk_bf16_f32 v73, v74, v75
	v_lshl_add_u64 v[74:75], v[80:81], 0, s[16:17]
	global_store_dwordx2 v[74:75], v[72:73], off
	v_add_f32_e32 v72, 1.0, v76
	v_add_f32_e32 v73, 1.0, v77
	v_mul_f32_e32 v76, 0xbfb8aa3b, v70
	v_mul_f32_e32 v77, 0xbfb8aa3b, v71
	v_exp_f32_e32 v76, v76
	v_exp_f32_e32 v77, v77
	v_rcp_f32_e32 v72, v72
	v_rcp_f32_e32 v73, v73
	v_add_f32_e32 v76, 1.0, v76
	v_add_f32_e32 v77, 1.0, v77
	v_rcp_f32_e32 v76, v76
	v_rcp_f32_e32 v77, v77
	v_pk_mul_f32 v[68:69], v[68:69], v[72:73]
	s_nop 0
	v_pk_mul_f32 v[64:65], v[64:65], v[68:69]
	v_pk_mul_f32 v[68:69], v[70:71], v[76:77]
	v_cvt_pk_bf16_f32 v64, v64, v65
	v_pk_mul_f32 v[66:67], v[66:67], v[68:69]
	v_mul_f32_e32 v68, 0xbfb8aa3b, v62
	v_cvt_pk_bf16_f32 v65, v66, v67
	global_store_dwordx2 v[74:75], v[64:65], off offset:128
	v_mul_f32_e32 v65, 0xbfb8aa3b, v60
	v_exp_f32_e32 v66, v65
	v_mul_f32_e32 v65, 0xbfb8aa3b, v61
	v_exp_f32_e32 v67, v65
	v_mul_f32_e32 v69, 0xbfb8aa3b, v63
	v_exp_f32_e32 v68, v68
	v_exp_f32_e32 v69, v69
	v_add_f32_e32 v66, 1.0, v66
	v_add_f32_e32 v67, 1.0, v67
	v_rcp_f32_e32 v66, v66
	v_rcp_f32_e32 v67, v67
	v_add_f32_e32 v68, 1.0, v68
	v_add_f32_e32 v69, 1.0, v69
	v_rcp_f32_e32 v68, v68
	v_rcp_f32_e32 v69, v69
	v_pk_mul_f32 v[60:61], v[60:61], v[66:67]
	v_add_u32_e32 v64, 0x80, v147
	v_pk_mul_f32 v[56:57], v[56:57], v[60:61]
	v_pk_mul_f32 v[60:61], v[62:63], v[68:69]
	v_mad_i64_i32 v[64:65], s[18:19], v64, s39, v[132:133]
	v_pk_mul_f32 v[58:59], v[58:59], v[60:61]
	v_mul_f32_e32 v60, 0xbfb8aa3b, v52
	v_mul_f32_e32 v61, 0xbfb8aa3b, v53
	v_exp_f32_e32 v60, v60
	v_exp_f32_e32 v61, v61
	v_cvt_pk_bf16_f32 v56, v56, v57
	v_cvt_pk_bf16_f32 v57, v58, v59
	v_lshl_add_u64 v[58:59], v[64:65], 0, s[16:17]
	global_store_dwordx2 v[58:59], v[56:57], off
	v_add_f32_e32 v56, 1.0, v60
	v_add_f32_e32 v57, 1.0, v61
	v_mul_f32_e32 v60, 0xbfb8aa3b, v54
	v_mul_f32_e32 v61, 0xbfb8aa3b, v55
	v_exp_f32_e32 v60, v60
	v_exp_f32_e32 v61, v61
	v_rcp_f32_e32 v56, v56
	v_rcp_f32_e32 v57, v57
	v_add_f32_e32 v60, 1.0, v60
	v_add_f32_e32 v61, 1.0, v61
	v_rcp_f32_e32 v60, v60
	v_rcp_f32_e32 v61, v61
	v_pk_mul_f32 v[52:53], v[52:53], v[56:57]
	s_nop 0
	v_pk_mul_f32 v[48:49], v[48:49], v[52:53]
	v_pk_mul_f32 v[52:53], v[54:55], v[60:61]
	v_cvt_pk_bf16_f32 v48, v48, v49
	v_pk_mul_f32 v[50:51], v[50:51], v[52:53]
	v_mul_f32_e32 v52, 0xbfb8aa3b, v46
	v_cvt_pk_bf16_f32 v49, v50, v51
	global_store_dwordx2 v[58:59], v[48:49], off offset:128
	v_mul_f32_e32 v49, 0xbfb8aa3b, v44
	v_exp_f32_e32 v50, v49
	v_mul_f32_e32 v49, 0xbfb8aa3b, v45
	v_exp_f32_e32 v51, v49
	v_mul_f32_e32 v53, 0xbfb8aa3b, v47
	v_exp_f32_e32 v52, v52
	v_exp_f32_e32 v53, v53
	v_add_f32_e32 v50, 1.0, v50
	v_add_f32_e32 v51, 1.0, v51
	v_rcp_f32_e32 v50, v50
	v_rcp_f32_e32 v51, v51
	v_add_f32_e32 v52, 1.0, v52
	v_add_f32_e32 v53, 1.0, v53
	v_rcp_f32_e32 v52, v52
	v_rcp_f32_e32 v53, v53
	v_pk_mul_f32 v[44:45], v[44:45], v[50:51]
	v_add_u32_e32 v48, 0x90, v147
	v_pk_mul_f32 v[40:41], v[40:41], v[44:45]
	v_pk_mul_f32 v[44:45], v[46:47], v[52:53]
	v_mad_i64_i32 v[48:49], s[18:19], v48, s39, v[132:133]
	v_pk_mul_f32 v[42:43], v[42:43], v[44:45]
	v_mul_f32_e32 v44, 0xbfb8aa3b, v36
	v_mul_f32_e32 v45, 0xbfb8aa3b, v37
	v_exp_f32_e32 v44, v44
	v_exp_f32_e32 v45, v45
	v_cvt_pk_bf16_f32 v40, v40, v41
	v_cvt_pk_bf16_f32 v41, v42, v43
	v_lshl_add_u64 v[42:43], v[48:49], 0, s[16:17]
	global_store_dwordx2 v[42:43], v[40:41], off
	v_add_f32_e32 v40, 1.0, v44
	v_add_f32_e32 v41, 1.0, v45
	v_mul_f32_e32 v44, 0xbfb8aa3b, v38
	v_mul_f32_e32 v45, 0xbfb8aa3b, v39
	v_exp_f32_e32 v44, v44
	v_exp_f32_e32 v45, v45
	v_rcp_f32_e32 v40, v40
	v_rcp_f32_e32 v41, v41
	v_add_f32_e32 v44, 1.0, v44
	v_add_f32_e32 v45, 1.0, v45
	v_rcp_f32_e32 v44, v44
	v_rcp_f32_e32 v45, v45
	v_pk_mul_f32 v[36:37], v[36:37], v[40:41]
	s_nop 0
	v_pk_mul_f32 v[32:33], v[32:33], v[36:37]
	v_pk_mul_f32 v[36:37], v[38:39], v[44:45]
	v_cvt_pk_bf16_f32 v32, v32, v33
	v_pk_mul_f32 v[34:35], v[34:35], v[36:37]
	v_mul_f32_e32 v36, 0xbfb8aa3b, v30
	v_cvt_pk_bf16_f32 v33, v34, v35
	global_store_dwordx2 v[42:43], v[32:33], off offset:128
	v_mul_f32_e32 v33, 0xbfb8aa3b, v28
	v_exp_f32_e32 v34, v33
	v_mul_f32_e32 v33, 0xbfb8aa3b, v29
	v_exp_f32_e32 v35, v33
	v_mul_f32_e32 v37, 0xbfb8aa3b, v31
	v_exp_f32_e32 v36, v36
	v_exp_f32_e32 v37, v37
	v_add_f32_e32 v34, 1.0, v34
	v_add_f32_e32 v35, 1.0, v35
	v_rcp_f32_e32 v34, v34
	v_rcp_f32_e32 v35, v35
	v_add_f32_e32 v36, 1.0, v36
	v_add_f32_e32 v37, 1.0, v37
	v_rcp_f32_e32 v36, v36
	v_rcp_f32_e32 v37, v37
	v_pk_mul_f32 v[28:29], v[28:29], v[34:35]
	v_add_u32_e32 v32, 0xa0, v147
	v_pk_mul_f32 v[24:25], v[24:25], v[28:29]
	v_pk_mul_f32 v[28:29], v[30:31], v[36:37]
	v_mad_i64_i32 v[32:33], s[18:19], v32, s39, v[132:133]
	v_pk_mul_f32 v[26:27], v[26:27], v[28:29]
	v_mul_f32_e32 v28, 0xbfb8aa3b, v20
	v_mul_f32_e32 v29, 0xbfb8aa3b, v21
	v_exp_f32_e32 v28, v28
	v_exp_f32_e32 v29, v29
	v_cvt_pk_bf16_f32 v24, v24, v25
	v_cvt_pk_bf16_f32 v25, v26, v27
	v_lshl_add_u64 v[26:27], v[32:33], 0, s[16:17]
	global_store_dwordx2 v[26:27], v[24:25], off
	v_add_f32_e32 v24, 1.0, v28
	v_add_f32_e32 v25, 1.0, v29
	v_mul_f32_e32 v28, 0xbfb8aa3b, v22
	v_mul_f32_e32 v29, 0xbfb8aa3b, v23
	v_exp_f32_e32 v28, v28
	v_exp_f32_e32 v29, v29
	v_rcp_f32_e32 v24, v24
	v_rcp_f32_e32 v25, v25
	v_add_f32_e32 v28, 1.0, v28
	v_add_f32_e32 v29, 1.0, v29
	v_rcp_f32_e32 v28, v28
	v_rcp_f32_e32 v29, v29
	v_pk_mul_f32 v[20:21], v[20:21], v[24:25]
	s_nop 0
	v_pk_mul_f32 v[16:17], v[16:17], v[20:21]
	v_pk_mul_f32 v[20:21], v[22:23], v[28:29]
	v_cvt_pk_bf16_f32 v16, v16, v17
	v_pk_mul_f32 v[18:19], v[18:19], v[20:21]
	v_mul_f32_e32 v20, 0xbfb8aa3b, v14
	v_cvt_pk_bf16_f32 v17, v18, v19
	global_store_dwordx2 v[26:27], v[16:17], off offset:128
	v_mul_f32_e32 v17, 0xbfb8aa3b, v12
	v_exp_f32_e32 v18, v17
	v_mul_f32_e32 v17, 0xbfb8aa3b, v13
	v_exp_f32_e32 v19, v17
	v_mul_f32_e32 v21, 0xbfb8aa3b, v15
	v_exp_f32_e32 v20, v20
	v_exp_f32_e32 v21, v21
	v_add_f32_e32 v18, 1.0, v18
	v_add_f32_e32 v19, 1.0, v19
	v_rcp_f32_e32 v18, v18
	v_rcp_f32_e32 v19, v19
	v_add_f32_e32 v20, 1.0, v20
	v_add_f32_e32 v21, 1.0, v21
	v_rcp_f32_e32 v20, v20
	v_rcp_f32_e32 v21, v21
	v_pk_mul_f32 v[12:13], v[12:13], v[18:19]
	v_add_u32_e32 v16, 0xb0, v147
	v_pk_mul_f32 v[8:9], v[8:9], v[12:13]
	v_pk_mul_f32 v[12:13], v[14:15], v[20:21]
	v_mad_i64_i32 v[16:17], s[18:19], v16, s39, v[132:133]
	v_pk_mul_f32 v[10:11], v[10:11], v[12:13]
	v_mul_f32_e32 v12, 0xbfb8aa3b, v4
	v_mul_f32_e32 v13, 0xbfb8aa3b, v5
	v_exp_f32_e32 v12, v12
	v_exp_f32_e32 v13, v13
	v_cvt_pk_bf16_f32 v8, v8, v9
	v_cvt_pk_bf16_f32 v9, v10, v11
	v_lshl_add_u64 v[10:11], v[16:17], 0, s[16:17]
	global_store_dwordx2 v[10:11], v[8:9], off
	v_add_f32_e32 v8, 1.0, v12
	v_add_f32_e32 v9, 1.0, v13
	v_mul_f32_e32 v12, 0xbfb8aa3b, v6
	v_mul_f32_e32 v13, 0xbfb8aa3b, v7
	v_exp_f32_e32 v12, v12
	v_exp_f32_e32 v13, v13
	v_rcp_f32_e32 v8, v8
	v_rcp_f32_e32 v9, v9
	v_add_f32_e32 v12, 1.0, v12
	v_add_f32_e32 v13, 1.0, v13
	v_rcp_f32_e32 v12, v12
	v_rcp_f32_e32 v13, v13
	v_pk_mul_f32 v[4:5], v[4:5], v[8:9]
	s_mov_b32 s17, s8
	v_pk_mul_f32 v[0:1], v[0:1], v[4:5]
	v_pk_mul_f32 v[4:5], v[6:7], v[12:13]
	v_cvt_pk_bf16_f32 v0, v0, v1
	v_pk_mul_f32 v[2:3], v[2:3], v[4:5]
	s_mov_b32 s16, s10
	v_cvt_pk_bf16_f32 v1, v2, v3
	s_mov_b64 s[18:19], s[12:13]
	global_store_dwordx2 v[10:11], v[0:1], off offset:128
	s_cbranch_vccz .LBB0_3440
	s_waitcnt vmcnt(0)
	s_cmpk_gt_u32 s0, 0xff
	s_cbranch_scc1 .LBB0_3447
	s_barrier

.LBB0_3542:
	ds_read_b128 v[128:131], v217
	ds_read_b128 v[132:135], v217 offset:1024
	ds_read_b128 v[136:139], v217 offset:2048
	ds_read_b128 v[140:143], v217 offset:3072
	v_lshl_add_u64 v[188:189], s[18:19], 0, v[168:169]
	s_add_i32 m0, s27, 0xc000
	ds_read_b128 v[144:147], v218
	ds_read_b128 v[148:151], v218 offset:1024
	ds_read_b128 v[152:155], v218 offset:2048
	ds_read_b128 v[156:159], v218 offset:3072
	ds_read_b128 v[160:163], v218 offset:4096
	ds_read_b128 v[176:179], v218 offset:5120
	ds_read_b128 v[180:183], v218 offset:6144
	ds_read_b128 v[184:187], v218 offset:7168
	global_load_lds_dwordx4 v[188:189], off
	v_lshl_add_u64 v[188:189], s[18:19], 0, v[170:171]
	s_add_i32 m0, s27, 0xe000
	s_nop 0
	global_load_lds_dwordx4 v[188:189], off
	s_waitcnt lgkmcnt(8)
	s_barrier
	s_waitcnt lgkmcnt(0)
	s_waitcnt lgkmcnt(0)
	v_mfma_f32_16x16x32_bf16 v[124:127], v[128:131], v[144:147], v[124:127]
	s_add_u32 s20, s18, 0x100
	s_addc_u32 s21, s19, 0
	s_cmpk_eq_i32 s54, 0x54
	s_cselect_b32 s25, s7, s21
	s_cselect_b32 s24, s6, s20
	s_cselect_b32 s23, s5, s53
	s_cselect_b32 s22, s4, s52
	v_mfma_f32_16x16x32_bf16 v[104:107], v[136:139], v[144:147], v[104:107]
	v_mfma_f32_16x16x32_bf16 v[120:123], v[128:131], v[152:155], v[120:123]
	v_mfma_f32_16x16x32_bf16 v[96:99], v[136:139], v[152:155], v[96:99]
	v_mfma_f32_16x16x32_bf16 v[116:119], v[128:131], v[160:163], v[116:119]
	v_mfma_f32_16x16x32_bf16 v[92:95], v[136:139], v[160:163], v[92:95]
	v_mfma_f32_16x16x32_bf16 v[112:115], v[128:131], v[180:183], v[112:115]
	v_mfma_f32_16x16x32_bf16 v[88:91], v[136:139], v[180:183], v[88:91]
	v_mfma_f32_16x16x32_bf16 v[124:127], v[132:135], v[148:151], v[124:127]
	v_mfma_f32_16x16x32_bf16 v[104:107], v[140:143], v[148:151], v[104:107]
	v_mfma_f32_16x16x32_bf16 v[120:123], v[132:135], v[156:159], v[120:123]
	v_mfma_f32_16x16x32_bf16 v[96:99], v[140:143], v[156:159], v[96:99]
	v_mfma_f32_16x16x32_bf16 v[116:119], v[132:135], v[176:179], v[116:119]
	v_mfma_f32_16x16x32_bf16 v[92:95], v[140:143], v[176:179], v[92:95]
	v_mfma_f32_16x16x32_bf16 v[112:115], v[132:135], v[184:187], v[112:115]
	v_mfma_f32_16x16x32_bf16 v[88:91], v[140:143], v[184:187], v[88:91]
	s_barrier
	s_add_i32 s18, s39, s26
	v_lshl_add_u64 v[204:205], s[22:23], 0, v[164:165]
	s_mov_b32 m0, s18
	ds_read_b128 v[188:191], v219
	ds_read_b128 v[192:195], v219 offset:1024
	ds_read_b128 v[196:199], v219 offset:2048
	ds_read_b128 v[200:203], v219 offset:3072
	global_load_lds_dwordx4 v[204:205], off
	v_lshl_add_u64 v[206:207], s[22:23], 0, v[166:167]
	s_add_i32 m0, s18, 0x2000
	s_nop 0
	global_load_lds_dwordx4 v[206:207], off
	s_barrier
	s_waitcnt lgkmcnt(0)
	s_waitcnt lgkmcnt(0)
	v_mfma_f32_16x16x32_bf16 v[72:75], v[188:191], v[144:147], v[72:75]
	v_mfma_f32_16x16x32_bf16 v[44:47], v[196:199], v[144:147], v[44:47]
	v_mfma_f32_16x16x32_bf16 v[64:67], v[188:191], v[152:155], v[64:67]
	v_mfma_f32_16x16x32_bf16 v[40:43], v[196:199], v[152:155], v[40:43]
	v_mfma_f32_16x16x32_bf16 v[56:59], v[188:191], v[160:163], v[56:59]
	v_mfma_f32_16x16x32_bf16 v[36:39], v[196:199], v[160:163], v[36:39]
	v_mfma_f32_16x16x32_bf16 v[48:51], v[188:191], v[180:183], v[48:51]
	v_mfma_f32_16x16x32_bf16 v[28:31], v[196:199], v[180:183], v[28:31]
	v_mfma_f32_16x16x32_bf16 v[72:75], v[192:195], v[148:151], v[72:75]
	v_mfma_f32_16x16x32_bf16 v[44:47], v[200:203], v[148:151], v[44:47]
	v_mfma_f32_16x16x32_bf16 v[64:67], v[192:195], v[156:159], v[64:67]
	v_mfma_f32_16x16x32_bf16 v[40:43], v[200:203], v[156:159], v[40:43]
	v_mfma_f32_16x16x32_bf16 v[56:59], v[192:195], v[176:179], v[56:59]
	v_mfma_f32_16x16x32_bf16 v[36:39], v[200:203], v[176:179], v[36:39]
	v_mfma_f32_16x16x32_bf16 v[48:51], v[192:195], v[184:187], v[48:51]
	v_mfma_f32_16x16x32_bf16 v[28:31], v[200:203], v[184:187], v[28:31]
	s_mov_b32 m0, s27
	v_lshl_add_u64 v[208:209], s[24:25], 0, v[164:165]
	s_barrier
	ds_read_b128 v[144:147], v218 offset:16384
	ds_read_b128 v[148:151], v218 offset:17408
	ds_read_b128 v[152:155], v218 offset:18432
	ds_read_b128 v[156:159], v218 offset:19456
	ds_read_b128 v[160:163], v218 offset:20480
	ds_read_b128 v[176:179], v218 offset:21504
	ds_read_b128 v[180:183], v218 offset:22528
	ds_read_b128 v[184:187], v218 offset:23552
	global_load_lds_dwordx4 v[208:209], off
	v_lshl_add_u64 v[210:211], s[24:25], 0, v[166:167]
	s_mov_b32 m0, s28
	s_nop 0
	global_load_lds_dwordx4 v[210:211], off
	s_barrier
	s_waitcnt lgkmcnt(0)
	s_waitcnt lgkmcnt(0)
	v_mfma_f32_16x16x32_bf16 v[108:111], v[128:131], v[144:147], v[108:111]
	v_mfma_f32_16x16x32_bf16 v[76:79], v[136:139], v[144:147], v[76:79]
	v_mfma_f32_16x16x32_bf16 v[100:103], v[128:131], v[152:155], v[100:103]
	v_mfma_f32_16x16x32_bf16 v[68:71], v[136:139], v[152:155], v[68:71]
	v_mfma_f32_16x16x32_bf16 v[84:87], v[128:131], v[160:163], v[84:87]
	v_mfma_f32_16x16x32_bf16 v[60:63], v[136:139], v[160:163], v[60:63]
	v_mfma_f32_16x16x32_bf16 v[80:83], v[128:131], v[180:183], v[80:83]
	v_mfma_f32_16x16x32_bf16 v[52:55], v[136:139], v[180:183], v[52:55]
	v_mfma_f32_16x16x32_bf16 v[108:111], v[132:135], v[148:151], v[108:111]
	v_mfma_f32_16x16x32_bf16 v[76:79], v[140:143], v[148:151], v[76:79]
	v_mfma_f32_16x16x32_bf16 v[100:103], v[132:135], v[156:159], v[100:103]
	v_mfma_f32_16x16x32_bf16 v[68:71], v[140:143], v[156:159], v[68:71]
	v_mfma_f32_16x16x32_bf16 v[84:87], v[132:135], v[176:179], v[84:87]
	v_mfma_f32_16x16x32_bf16 v[60:63], v[140:143], v[176:179], v[60:63]
	v_mfma_f32_16x16x32_bf16 v[80:83], v[132:135], v[184:187], v[80:83]
	v_mfma_f32_16x16x32_bf16 v[52:55], v[140:143], v[184:187], v[52:55]
	s_barrier
	s_add_u32 s18, s22, 0x160000
	s_addc_u32 s19, s23, 0
	s_add_i32 s55, s40, s26
	v_lshl_add_u64 v[128:129], s[18:19], 0, v[164:165]
	s_mov_b32 m0, s55
	s_nop 0
	global_load_lds_dwordx4 v[128:129], off
	v_lshl_add_u64 v[128:129], s[18:19], 0, v[166:167]
	s_add_i32 m0, s55, 0x2000
	s_nop 0
	global_load_lds_dwordx4 v[128:129], off
	s_waitcnt vmcnt(6)
	s_barrier
	v_mfma_f32_16x16x32_bf16 v[32:35], v[188:191], v[144:147], v[32:35]
	v_mfma_f32_16x16x32_bf16 v[12:15], v[196:199], v[144:147], v[12:15]
	v_mfma_f32_16x16x32_bf16 v[24:27], v[188:191], v[152:155], v[24:27]
	v_mfma_f32_16x16x32_bf16 v[8:11], v[196:199], v[152:155], v[8:11]
	v_mfma_f32_16x16x32_bf16 v[20:23], v[188:191], v[160:163], v[20:23]
	v_mfma_f32_16x16x32_bf16 v[4:7], v[196:199], v[160:163], v[4:7]
	v_mfma_f32_16x16x32_bf16 v[16:19], v[188:191], v[180:183], v[16:19]
	v_mfma_f32_16x16x32_bf16 v[0:3], v[196:199], v[180:183], v[0:3]
	v_mfma_f32_16x16x32_bf16 v[32:35], v[192:195], v[148:151], v[32:35]
	v_mfma_f32_16x16x32_bf16 v[12:15], v[200:203], v[148:151], v[12:15]
	v_mfma_f32_16x16x32_bf16 v[24:27], v[192:195], v[156:159], v[24:27]
	v_mfma_f32_16x16x32_bf16 v[8:11], v[200:203], v[156:159], v[8:11]
	v_mfma_f32_16x16x32_bf16 v[20:23], v[192:195], v[176:179], v[20:23]
	v_mfma_f32_16x16x32_bf16 v[4:7], v[200:203], v[176:179], v[4:7]
	v_mfma_f32_16x16x32_bf16 v[16:19], v[192:195], v[184:187], v[16:19]
	v_mfma_f32_16x16x32_bf16 v[0:3], v[200:203], v[184:187], v[0:3]
	s_add_i32 s55, 0, 0x18000
	v_add_u32_e32 v140, s55, v215
	s_barrier
	ds_read_b128 v[128:131], v140
	ds_read_b128 v[132:135], v140 offset:1024
	ds_read_b128 v[136:139], v140 offset:2048
	ds_read_b128 v[140:143], v140 offset:3072
	s_add_u32 s18, s24, 0x160000
	s_addc_u32 s19, s25, 0
	s_mov_b32 m0, s29
	v_lshl_add_u64 v[188:189], s[18:19], 0, v[164:165]
	ds_read_b128 v[144:147], v218 offset:32768
	ds_read_b128 v[148:151], v218 offset:33792
	ds_read_b128 v[152:155], v218 offset:34816
	ds_read_b128 v[156:159], v218 offset:35840
	ds_read_b128 v[160:163], v218 offset:36864
	ds_read_b128 v[176:179], v218 offset:37888
	ds_read_b128 v[180:183], v218 offset:38912
	ds_read_b128 v[184:187], v218 offset:39936
	global_load_lds_dwordx4 v[188:189], off
	v_lshl_add_u64 v[188:189], s[18:19], 0, v[166:167]
	s_mov_b32 m0, s30
	s_nop 0
	global_load_lds_dwordx4 v[188:189], off
	s_waitcnt lgkmcnt(8)
	s_barrier
	s_waitcnt lgkmcnt(0)
	s_waitcnt lgkmcnt(0)
	v_mfma_f32_16x16x32_bf16 v[124:127], v[128:131], v[144:147], v[124:127]
	v_mfma_f32_16x16x32_bf16 v[104:107], v[136:139], v[144:147], v[104:107]
	v_mfma_f32_16x16x32_bf16 v[120:123], v[128:131], v[152:155], v[120:123]
	v_mfma_f32_16x16x32_bf16 v[96:99], v[136:139], v[152:155], v[96:99]
	v_mfma_f32_16x16x32_bf16 v[116:119], v[128:131], v[160:163], v[116:119]
	v_mfma_f32_16x16x32_bf16 v[92:95], v[136:139], v[160:163], v[92:95]
	v_mfma_f32_16x16x32_bf16 v[112:115], v[128:131], v[180:183], v[112:115]
	v_mfma_f32_16x16x32_bf16 v[88:91], v[136:139], v[180:183], v[88:91]
	v_mfma_f32_16x16x32_bf16 v[124:127], v[132:135], v[148:151], v[124:127]
	v_mfma_f32_16x16x32_bf16 v[104:107], v[140:143], v[148:151], v[104:107]
	v_mfma_f32_16x16x32_bf16 v[120:123], v[132:135], v[156:159], v[120:123]
	v_mfma_f32_16x16x32_bf16 v[96:99], v[140:143], v[156:159], v[96:99]
	v_mfma_f32_16x16x32_bf16 v[116:119], v[132:135], v[176:179], v[116:119]
	v_mfma_f32_16x16x32_bf16 v[92:95], v[140:143], v[176:179], v[92:95]
	v_mfma_f32_16x16x32_bf16 v[112:115], v[132:135], v[184:187], v[112:115]
	v_mfma_f32_16x16x32_bf16 v[88:91], v[140:143], v[184:187], v[88:91]
	s_barrier
	s_add_i32 s24, 0, 0x1c000
	s_add_i32 s18, s55, s26
	v_add_u32_e32 v200, s24, v215
	v_lshl_add_u64 v[204:205], v[204:205], 0, s[10:11]
	s_mov_b32 m0, s18
	ds_read_b128 v[188:191], v200
	ds_read_b128 v[192:195], v200 offset:1024
	ds_read_b128 v[196:199], v200 offset:2048
	ds_read_b128 v[200:203], v200 offset:3072
	global_load_lds_dwordx4 v[204:205], off
	v_lshl_add_u64 v[204:205], v[206:207], 0, s[10:11]
	s_add_i32 m0, s18, 0x2000
	s_nop 0
	global_load_lds_dwordx4 v[204:205], off
	s_barrier
	s_waitcnt lgkmcnt(0)
	s_waitcnt lgkmcnt(0)
	v_mfma_f32_16x16x32_bf16 v[72:75], v[188:191], v[144:147], v[72:75]
	v_mfma_f32_16x16x32_bf16 v[44:47], v[196:199], v[144:147], v[44:47]
	v_mfma_f32_16x16x32_bf16 v[64:67], v[188:191], v[152:155], v[64:67]
	v_mfma_f32_16x16x32_bf16 v[40:43], v[196:199], v[152:155], v[40:43]
	v_mfma_f32_16x16x32_bf16 v[56:59], v[188:191], v[160:163], v[56:59]
	v_mfma_f32_16x16x32_bf16 v[36:39], v[196:199], v[160:163], v[36:39]
	v_mfma_f32_16x16x32_bf16 v[48:51], v[188:191], v[180:183], v[48:51]
	v_mfma_f32_16x16x32_bf16 v[28:31], v[196:199], v[180:183], v[28:31]
	v_mfma_f32_16x16x32_bf16 v[72:75], v[192:195], v[148:151], v[72:75]
	v_mfma_f32_16x16x32_bf16 v[44:47], v[200:203], v[148:151], v[44:47]
	v_mfma_f32_16x16x32_bf16 v[64:67], v[192:195], v[156:159], v[64:67]
	v_mfma_f32_16x16x32_bf16 v[40:43], v[200:203], v[156:159], v[40:43]
	v_mfma_f32_16x16x32_bf16 v[56:59], v[192:195], v[176:179], v[56:59]
	v_mfma_f32_16x16x32_bf16 v[36:39], v[200:203], v[176:179], v[36:39]
	v_mfma_f32_16x16x32_bf16 v[48:51], v[192:195], v[184:187], v[48:51]
	v_mfma_f32_16x16x32_bf16 v[28:31], v[200:203], v[184:187], v[28:31]
	s_mov_b32 m0, s34
	v_lshl_add_u64 v[204:205], v[208:209], 0, s[10:11]
	s_barrier
	ds_read_b128 v[144:147], v218 offset:49152
	ds_read_b128 v[148:151], v218 offset:50176
	ds_read_b128 v[152:155], v218 offset:51200
	ds_read_b128 v[156:159], v218 offset:52224
	ds_read_b128 v[160:163], v218 offset:53248
	ds_read_b128 v[176:179], v218 offset:54272
	ds_read_b128 v[180:183], v218 offset:55296
	ds_read_b128 v[184:187], v218 offset:56320
	global_load_lds_dwordx4 v[204:205], off
	v_lshl_add_u64 v[204:205], v[210:211], 0, s[10:11]
	s_mov_b32 m0, s35
	s_nop 0
	global_load_lds_dwordx4 v[204:205], off
	s_barrier
	s_waitcnt lgkmcnt(0)
	s_waitcnt lgkmcnt(0)
	v_mfma_f32_16x16x32_bf16 v[108:111], v[128:131], v[144:147], v[108:111]
	v_mfma_f32_16x16x32_bf16 v[76:79], v[136:139], v[144:147], v[76:79]
	v_mfma_f32_16x16x32_bf16 v[100:103], v[128:131], v[152:155], v[100:103]
	v_mfma_f32_16x16x32_bf16 v[68:71], v[136:139], v[152:155], v[68:71]
	v_mfma_f32_16x16x32_bf16 v[84:87], v[128:131], v[160:163], v[84:87]
	v_mfma_f32_16x16x32_bf16 v[60:63], v[136:139], v[160:163], v[60:63]
	v_mfma_f32_16x16x32_bf16 v[80:83], v[128:131], v[180:183], v[80:83]
	v_mfma_f32_16x16x32_bf16 v[52:55], v[136:139], v[180:183], v[52:55]
	v_mfma_f32_16x16x32_bf16 v[108:111], v[132:135], v[148:151], v[108:111]
	v_mfma_f32_16x16x32_bf16 v[76:79], v[140:143], v[148:151], v[76:79]
	v_mfma_f32_16x16x32_bf16 v[100:103], v[132:135], v[156:159], v[100:103]
	v_mfma_f32_16x16x32_bf16 v[68:71], v[140:143], v[156:159], v[68:71]
	v_mfma_f32_16x16x32_bf16 v[84:87], v[132:135], v[176:179], v[84:87]
	v_mfma_f32_16x16x32_bf16 v[60:63], v[140:143], v[176:179], v[60:63]
	v_mfma_f32_16x16x32_bf16 v[80:83], v[132:135], v[184:187], v[80:83]
	v_mfma_f32_16x16x32_bf16 v[52:55], v[140:143], v[184:187], v[52:55]
	s_barrier
	s_add_u32 s18, s22, 0x160080
	s_addc_u32 s19, s23, 0
	s_add_i32 s22, s24, s26
	v_lshl_add_u64 v[128:129], s[18:19], 0, v[164:165]
	s_mov_b32 m0, s22
	s_nop 0
	global_load_lds_dwordx4 v[128:129], off
	v_lshl_add_u64 v[128:129], s[18:19], 0, v[166:167]
	s_add_i32 m0, s22, 0x2000
	s_nop 0
	global_load_lds_dwordx4 v[128:129], off
	s_waitcnt vmcnt(6)
	s_barrier
	v_mfma_f32_16x16x32_bf16 v[32:35], v[188:191], v[144:147], v[32:35]
	v_mfma_f32_16x16x32_bf16 v[12:15], v[196:199], v[144:147], v[12:15]
	v_mfma_f32_16x16x32_bf16 v[24:27], v[188:191], v[152:155], v[24:27]
	v_mfma_f32_16x16x32_bf16 v[8:11], v[196:199], v[152:155], v[8:11]
	v_mfma_f32_16x16x32_bf16 v[20:23], v[188:191], v[160:163], v[20:23]
	v_mfma_f32_16x16x32_bf16 v[4:7], v[196:199], v[160:163], v[4:7]
	v_mfma_f32_16x16x32_bf16 v[16:19], v[188:191], v[180:183], v[16:19]
	v_mfma_f32_16x16x32_bf16 v[0:3], v[196:199], v[180:183], v[0:3]
	v_mfma_f32_16x16x32_bf16 v[32:35], v[192:195], v[148:151], v[32:35]
	v_mfma_f32_16x16x32_bf16 v[12:15], v[200:203], v[148:151], v[12:15]
	v_mfma_f32_16x16x32_bf16 v[24:27], v[192:195], v[156:159], v[24:27]
	v_mfma_f32_16x16x32_bf16 v[8:11], v[200:203], v[156:159], v[8:11]
	v_mfma_f32_16x16x32_bf16 v[20:23], v[192:195], v[176:179], v[20:23]
	v_mfma_f32_16x16x32_bf16 v[4:7], v[200:203], v[176:179], v[4:7]
	v_mfma_f32_16x16x32_bf16 v[16:19], v[192:195], v[184:187], v[16:19]
	v_mfma_f32_16x16x32_bf16 v[0:3], v[200:203], v[184:187], v[0:3]
	s_add_i32 s54, s54, 2
	s_add_u32 s52, s52, 0x100
	s_addc_u32 s53, s53, 0
	s_cmpk_gt_u32 s54, 0x55
	s_mov_b64 s[18:19], s[20:21]
	s_barrier
	s_cbranch_scc0 .LBB0_3542
	s_cmp_lt_u32 s50, 32
	v_lshl_add_u32 v144, s50, 8, v214
	v_lshl_or_b32 v128, s51, 8, v216
	s_cselect_b32 s18, s41, 0x6000
	s_cmp_gt_i32 s50, 15
	v_readlane_b32 s48, v240, 22
	v_ashrrev_i32_e32 v145, 31, v144
	v_readlane_b32 s49, v240, 23
	v_readlane_b32 s52, v240, 26
	v_readlane_b32 s53, v240, 27
	v_ashrrev_i32_e32 v129, 31, v128
	v_lshlrev_b64 v[132:133], 13, v[144:145]
	s_mov_b64 s[48:49], s[52:53]
	s_cselect_b32 s18, s18, 0
	v_lshlrev_b64 v[146:147], 2, v[128:129]
	v_lshl_add_u64 v[132:133], s[48:49], 0, v[132:133]
	v_or_b32_e32 v136, 16, v144
	s_lshl_b32 s18, s18, 2
	v_lshl_add_u64 v[176:177], v[132:133], 0, v[146:147]
	v_ashrrev_i32_e32 v137, 31, v136
	v_or_b32_e32 v140, 32, v144
	v_or_b32_e32 v144, 48, v144
	s_add_u32 s18, s37, s18
	v_lshlrev_b64 v[136:137], 13, v[136:137]
	v_ashrrev_i32_e32 v141, 31, v140
	v_ashrrev_i32_e32 v145, 31, v144
	v_add_co_u32_e32 v188, vcc, s42, v176
	s_addc_u32 s19, s38, 0
	v_lshl_add_u64 v[136:137], s[48:49], 0, v[136:137]
	v_lshlrev_b64 v[140:141], 13, v[140:141]
	v_lshlrev_b64 v[144:145], 13, v[144:145]
	v_addc_co_u32_e32 v189, vcc, 0, v177, vcc
	v_lshl_add_u64 v[180:181], s[18:19], 0, v[146:147]
	v_lshl_add_u64 v[178:179], v[136:137], 0, v[146:147]
	v_lshl_add_u64 v[140:141], s[48:49], 0, v[140:141]
	v_lshl_add_u64 v[144:145], s[48:49], 0, v[144:145]
	v_add_co_u32_e32 v192, vcc, s43, v176
	global_load_dwordx4 v[128:131], v[180:181], off
	global_load_dwordx4 v[132:135], v[176:177], off
	global_load_dwordx4 v[136:139], v[178:179], off
	v_lshl_add_u64 v[182:183], v[140:141], 0, v[146:147]
	v_lshl_add_u64 v[184:185], v[144:145], 0, v[146:147]
	v_addc_co_u32_e32 v193, vcc, 0, v177, vcc
	global_load_dwordx4 v[140:143], v[182:183], off
	global_load_dwordx4 v[144:147], v[184:185], off
	global_load_dwordx4 v[160:163], v[188:189], off
	global_load_dwordx4 v[156:159], v[192:193], off
	v_add_co_u32_e32 v190, vcc, s44, v176
	v_pk_add_f32 v[194:195], v[126:127], 0 op_sel_hi:[1,0]
	s_nop 0
	v_addc_co_u32_e32 v191, vcc, 0, v177, vcc
	global_load_dwordx4 v[152:155], v[190:191], off
	v_add_co_u32_e32 v186, vcc, s45, v176
	v_pk_add_f32 v[196:197], v[124:125], 0 op_sel_hi:[1,0]
	s_nop 0
	v_addc_co_u32_e32 v187, vcc, 0, v177, vcc
	global_load_dwordx4 v[148:151], v[186:187], off
	v_pk_add_f32 v[198:199], v[122:123], 0 op_sel_hi:[1,0]
	v_pk_add_f32 v[200:201], v[120:121], 0 op_sel_hi:[1,0]
	v_pk_add_f32 v[202:203], v[118:119], 0 op_sel_hi:[1,0]
	v_pk_add_f32 v[204:205], v[116:117], 0 op_sel_hi:[1,0]
	v_pk_add_f32 v[206:207], v[114:115], 0 op_sel_hi:[1,0]
	v_pk_add_f32 v[208:209], v[112:113], 0 op_sel_hi:[1,0]
	v_pk_add_f32 v[210:211], v[110:111], 0 op_sel_hi:[1,0]
	v_pk_add_f32 v[212:213], v[108:109], 0 op_sel_hi:[1,0]
	v_pk_add_f32 v[126:127], v[102:103], 0 op_sel_hi:[1,0]
	v_pk_add_f32 v[100:101], v[100:101], 0 op_sel_hi:[1,0]
	v_lshl_add_u64 v[102:103], v[176:177], 0, s[12:13]
	global_load_dwordx4 v[108:111], v[176:177], off offset:64
	global_load_dwordx4 v[112:115], v[178:179], off offset:64
	global_load_dwordx4 v[116:119], v[182:183], off offset:64
	global_load_dwordx4 v[120:123], v[184:185], off offset:64
	global_load_dwordx4 v[220:223], v[102:103], off offset:576
	v_lshl_add_u64 v[124:125], v[176:177], 0, s[14:15]
	v_pk_add_f32 v[106:107], v[106:107], 0 op_sel_hi:[1,0]
	v_pk_add_f32 v[104:105], v[104:105], 0 op_sel_hi:[1,0]
	v_pk_add_f32 v[98:99], v[98:99], 0 op_sel_hi:[1,0]
	v_pk_add_f32 v[96:97], v[96:97], 0 op_sel_hi:[1,0]
	v_pk_add_f32 v[74:75], v[74:75], 0 op_sel_hi:[1,0]
	v_pk_add_f32 v[72:73], v[72:73], 0 op_sel_hi:[1,0]
	v_pk_add_f32 v[66:67], v[66:67], 0 op_sel_hi:[1,0]
	v_pk_add_f32 v[64:65], v[64:65], 0 op_sel_hi:[1,0]
	v_pk_add_f32 v[58:59], v[58:59], 0 op_sel_hi:[1,0]
	v_pk_add_f32 v[56:57], v[56:57], 0 op_sel_hi:[1,0]
	v_readlane_b32 s50, v240, 24
	v_readlane_b32 s51, v240, 25
	v_pk_add_f32 v[46:47], v[46:47], 0 op_sel_hi:[1,0]
	v_pk_add_f32 v[44:45], v[44:45], 0 op_sel_hi:[1,0]
	v_pk_add_f32 v[42:43], v[42:43], 0 op_sel_hi:[1,0]
	v_pk_add_f32 v[40:41], v[40:41], 0 op_sel_hi:[1,0]
	v_pk_add_f32 v[38:39], v[38:39], 0 op_sel_hi:[1,0]
	v_pk_add_f32 v[36:37], v[36:37], 0 op_sel_hi:[1,0]
	v_pk_add_f32 v[30:31], v[30:31], 0 op_sel_hi:[1,0]
	v_pk_add_f32 v[28:29], v[28:29], 0 op_sel_hi:[1,0]
	s_mov_b32 s51, s46
	s_mov_b64 s[20:21], s[4:5]
	s_mov_b64 s[18:19], s[6:7]
	s_mov_b32 s50, s47
	s_and_b64 vcc, exec, s[0:1]
	v_readlane_b32 s54, v240, 28
	v_readlane_b32 s55, v240, 29
	v_readlane_b32 s56, v240, 30
	v_readlane_b32 s57, v240, 31
	v_readlane_b32 s58, v240, 32
	v_readlane_b32 s59, v240, 33
	v_readlane_b32 s60, v240, 34
	v_readlane_b32 s61, v240, 35
	v_readlane_b32 s62, v240, 36
	v_readlane_b32 s63, v240, 37
	s_waitcnt vmcnt(0)
	v_pk_fma_f32 v[134:135], v[194:195], v[130:131], v[134:135]
	v_pk_fma_f32 v[132:133], v[196:197], v[128:129], v[132:133]
	v_pk_fma_f32 v[138:139], v[198:199], v[130:131], v[138:139]
	v_pk_fma_f32 v[136:137], v[200:201], v[128:129], v[136:137]
	v_pk_add_f32 v[194:195], v[54:55], 0 op_sel_hi:[1,0]
	v_pk_add_f32 v[196:197], v[52:53], 0 op_sel_hi:[1,0]
	v_pk_fma_f32 v[142:143], v[202:203], v[130:131], v[142:143]
	v_pk_fma_f32 v[140:141], v[204:205], v[128:129], v[140:141]
	v_pk_fma_f32 v[146:147], v[206:207], v[130:131], v[146:147]
	v_pk_fma_f32 v[144:145], v[208:209], v[128:129], v[144:145]
	v_pk_fma_f32 v[162:163], v[210:211], v[130:131], v[162:163]
	v_pk_fma_f32 v[160:161], v[212:213], v[128:129], v[160:161]
	global_store_dwordx4 v[176:177], v[132:135], off
	global_store_dwordx4 v[178:179], v[136:139], off
	global_store_dwordx4 v[182:183], v[140:143], off
	global_store_dwordx4 v[184:185], v[144:147], off
	global_store_dwordx4 v[188:189], v[160:163], off
	v_pk_fma_f32 v[138:139], v[126:127], v[130:131], v[158:159]
	v_pk_fma_f32 v[136:137], v[100:101], v[128:129], v[156:157]
	global_store_dwordx4 v[192:193], v[136:139], off
	v_pk_add_f32 v[126:127], v[86:87], 0 op_sel_hi:[1,0]
	v_lshl_add_u64 v[100:101], v[176:177], 0, s[16:17]
	v_pk_add_f32 v[136:137], v[84:85], 0 op_sel_hi:[1,0]
	v_pk_fma_f32 v[138:139], v[126:127], v[130:131], v[154:155]
	v_pk_fma_f32 v[136:137], v[136:137], v[128:129], v[152:153]
	global_store_dwordx4 v[190:191], v[136:139], off
	v_pk_add_f32 v[126:127], v[82:83], 0 op_sel_hi:[1,0]
	v_lshl_add_u64 v[152:153], v[176:177], 0, s[8:9]
	v_pk_add_f32 v[136:137], v[80:81], 0 op_sel_hi:[1,0]
	v_pk_fma_f32 v[130:131], v[126:127], v[130:131], v[150:151]
	v_pk_fma_f32 v[128:129], v[136:137], v[128:129], v[148:149]
	global_store_dwordx4 v[186:187], v[128:131], off
	global_load_dwordx4 v[132:135], v[124:125], off offset:576
	global_load_dwordx4 v[84:87], v[100:101], off offset:576
	global_load_dwordx4 v[80:83], v[152:153], off offset:576
	s_nop 0
	global_load_dwordx4 v[126:129], v[180:181], off offset:64
	global_load_dwordx4 v[136:139], v[102:103], off offset:64
	global_load_dwordx4 v[140:143], v[124:125], off offset:64
	global_load_dwordx4 v[144:147], v[100:101], off offset:64
	global_load_dwordx4 v[148:151], v[152:153], off offset:64
	v_pk_add_f32 v[130:131], v[94:95], 0 op_sel_hi:[1,0]
	v_pk_add_f32 v[154:155], v[92:93], 0 op_sel_hi:[1,0]
	v_pk_add_f32 v[156:157], v[90:91], 0 op_sel_hi:[1,0]
	v_pk_add_f32 v[158:159], v[88:89], 0 op_sel_hi:[1,0]
	v_pk_add_f32 v[160:161], v[78:79], 0 op_sel_hi:[1,0]
	v_pk_add_f32 v[162:163], v[76:77], 0 op_sel_hi:[1,0]
	v_pk_add_f32 v[186:187], v[70:71], 0 op_sel_hi:[1,0]
	v_pk_add_f32 v[188:189], v[68:69], 0 op_sel_hi:[1,0]
	v_pk_add_f32 v[190:191], v[62:63], 0 op_sel_hi:[1,0]
	v_pk_add_f32 v[192:193], v[60:61], 0 op_sel_hi:[1,0]
	global_load_dwordx4 v[52:55], v[176:177], off offset:512
	global_load_dwordx4 v[60:63], v[102:103], off offset:512
	global_load_dwordx4 v[68:71], v[124:125], off offset:512
	global_load_dwordx4 v[76:79], v[100:101], off offset:512
	global_load_dwordx4 v[88:91], v[152:153], off offset:512
	s_waitcnt vmcnt(0)
	v_pk_fma_f32 v[94:95], v[106:107], v[128:129], v[110:111]
	v_pk_fma_f32 v[92:93], v[104:105], v[126:127], v[108:109]
	v_pk_fma_f32 v[98:99], v[98:99], v[128:129], v[114:115]
	v_pk_fma_f32 v[96:97], v[96:97], v[126:127], v[112:113]
	v_pk_fma_f32 v[106:107], v[130:131], v[128:129], v[118:119]
	v_pk_fma_f32 v[104:105], v[154:155], v[126:127], v[116:117]
	v_pk_fma_f32 v[110:111], v[156:157], v[128:129], v[122:123]
	v_pk_fma_f32 v[108:109], v[158:159], v[126:127], v[120:121]
	v_pk_fma_f32 v[114:115], v[160:161], v[128:129], v[138:139]
	v_pk_fma_f32 v[112:113], v[162:163], v[126:127], v[136:137]
	v_pk_fma_f32 v[118:119], v[186:187], v[128:129], v[142:143]
	v_pk_fma_f32 v[116:117], v[188:189], v[126:127], v[140:141]
	v_pk_fma_f32 v[122:123], v[190:191], v[128:129], v[146:147]
	v_pk_fma_f32 v[120:121], v[192:193], v[126:127], v[144:145]
	v_pk_fma_f32 v[128:129], v[194:195], v[128:129], v[150:151]
	v_pk_fma_f32 v[126:127], v[196:197], v[126:127], v[148:149]
	global_store_dwordx4 v[176:177], v[92:95], off offset:64
	global_store_dwordx4 v[178:179], v[96:99], off offset:64
	global_store_dwordx4 v[182:183], v[104:107], off offset:64
	global_store_dwordx4 v[184:185], v[108:111], off offset:64
	global_store_dwordx4 v[102:103], v[112:115], off offset:64
	global_store_dwordx4 v[124:125], v[116:119], off offset:64
	global_store_dwordx4 v[100:101], v[120:123], off offset:64
	global_store_dwordx4 v[152:153], v[126:129], off offset:64
	global_load_dwordx4 v[92:95], v[180:181], off offset:512
	global_load_dwordx4 v[96:99], v[178:179], off offset:512
	global_load_dwordx4 v[104:107], v[182:183], off offset:512
	global_load_dwordx4 v[108:111], v[184:185], off offset:512
	v_pk_add_f32 v[112:113], v[50:51], 0 op_sel_hi:[1,0]
	v_pk_add_f32 v[114:115], v[48:49], 0 op_sel_hi:[1,0]
	v_pk_add_f32 v[116:117], v[34:35], 0 op_sel_hi:[1,0]
	v_pk_add_f32 v[118:119], v[32:33], 0 op_sel_hi:[1,0]
	v_pk_add_f32 v[120:121], v[26:27], 0 op_sel_hi:[1,0]
	v_pk_add_f32 v[122:123], v[24:25], 0 op_sel_hi:[1,0]
	v_pk_add_f32 v[126:127], v[22:23], 0 op_sel_hi:[1,0]
	v_pk_add_f32 v[128:129], v[20:21], 0 op_sel_hi:[1,0]
	v_pk_add_f32 v[130:131], v[18:19], 0 op_sel_hi:[1,0]
	v_pk_add_f32 v[136:137], v[16:17], 0 op_sel_hi:[1,0]
	global_load_dwordx4 v[16:19], v[176:177], off offset:576
	global_load_dwordx4 v[20:23], v[178:179], off offset:576
	global_load_dwordx4 v[24:27], v[182:183], off offset:576
	global_load_dwordx4 v[32:35], v[184:185], off offset:576
	s_waitcnt vmcnt(0)
	v_pk_fma_f32 v[50:51], v[74:75], v[94:95], v[54:55]
	v_pk_fma_f32 v[48:49], v[72:73], v[92:93], v[52:53]
	v_pk_fma_f32 v[54:55], v[66:67], v[94:95], v[98:99]
	v_pk_fma_f32 v[52:53], v[64:65], v[92:93], v[96:97]
	v_pk_fma_f32 v[58:59], v[58:59], v[94:95], v[106:107]
	v_pk_fma_f32 v[56:57], v[56:57], v[92:93], v[104:105]
	v_pk_fma_f32 v[66:67], v[112:113], v[94:95], v[110:111]
	v_pk_fma_f32 v[64:65], v[114:115], v[92:93], v[108:109]
	v_pk_fma_f32 v[62:63], v[116:117], v[94:95], v[62:63]
	v_pk_fma_f32 v[60:61], v[118:119], v[92:93], v[60:61]
	v_pk_fma_f32 v[70:71], v[120:121], v[94:95], v[70:71]
	v_pk_fma_f32 v[68:69], v[122:123], v[92:93], v[68:69]
	v_pk_fma_f32 v[74:75], v[126:127], v[94:95], v[78:79]
	v_pk_fma_f32 v[72:73], v[128:129], v[92:93], v[76:77]
	v_pk_fma_f32 v[78:79], v[130:131], v[94:95], v[90:91]
	v_pk_fma_f32 v[76:77], v[136:137], v[92:93], v[88:89]
	global_store_dwordx4 v[176:177], v[48:51], off offset:512
	global_store_dwordx4 v[178:179], v[52:55], off offset:512
	global_store_dwordx4 v[182:183], v[56:59], off offset:512
	global_store_dwordx4 v[184:185], v[64:67], off offset:512
	global_store_dwordx4 v[102:103], v[60:63], off offset:512
	global_store_dwordx4 v[124:125], v[68:71], off offset:512
	global_store_dwordx4 v[100:101], v[72:75], off offset:512
	global_store_dwordx4 v[152:153], v[76:79], off offset:512
	global_load_dwordx4 v[48:51], v[180:181], off offset:576
	v_pk_add_f32 v[52:53], v[14:15], 0 op_sel_hi:[1,0]
	v_pk_add_f32 v[54:55], v[12:13], 0 op_sel_hi:[1,0]
	v_pk_add_f32 v[56:57], v[10:11], 0 op_sel_hi:[1,0]
	v_pk_add_f32 v[58:59], v[8:9], 0 op_sel_hi:[1,0]
	v_pk_add_f32 v[60:61], v[6:7], 0 op_sel_hi:[1,0]
	v_pk_add_f32 v[62:63], v[4:5], 0 op_sel_hi:[1,0]
	v_pk_add_f32 v[64:65], v[2:3], 0 op_sel_hi:[1,0]
	v_pk_add_f32 v[66:67], v[0:1], 0 op_sel_hi:[1,0]
	s_waitcnt vmcnt(0)
	v_pk_fma_f32 v[2:3], v[46:47], v[50:51], v[18:19]
	v_pk_fma_f32 v[0:1], v[44:45], v[48:49], v[16:17]
	v_pk_fma_f32 v[6:7], v[42:43], v[50:51], v[22:23]
	v_pk_fma_f32 v[4:5], v[40:41], v[48:49], v[20:21]
	v_pk_fma_f32 v[10:11], v[38:39], v[50:51], v[26:27]
	v_pk_fma_f32 v[8:9], v[36:37], v[48:49], v[24:25]
	v_pk_fma_f32 v[14:15], v[30:31], v[50:51], v[34:35]
	v_pk_fma_f32 v[12:13], v[28:29], v[48:49], v[32:33]
	v_pk_fma_f32 v[18:19], v[52:53], v[50:51], v[222:223]
	v_pk_fma_f32 v[16:17], v[54:55], v[48:49], v[220:221]
	v_pk_fma_f32 v[22:23], v[56:57], v[50:51], v[134:135]
	v_pk_fma_f32 v[20:21], v[58:59], v[48:49], v[132:133]
	v_pk_fma_f32 v[26:27], v[60:61], v[50:51], v[86:87]
	v_pk_fma_f32 v[24:25], v[62:63], v[48:49], v[84:85]
	v_pk_fma_f32 v[30:31], v[64:65], v[50:51], v[82:83]
	v_pk_fma_f32 v[28:29], v[66:67], v[48:49], v[80:81]
	global_store_dwordx4 v[176:177], v[0:3], off offset:576
	global_store_dwordx4 v[178:179], v[4:7], off offset:576
	global_store_dwordx4 v[182:183], v[8:11], off offset:576
	global_store_dwordx4 v[184:185], v[12:15], off offset:576
	global_store_dwordx4 v[102:103], v[16:19], off offset:576
	global_store_dwordx4 v[124:125], v[20:23], off offset:576
	global_store_dwordx4 v[100:101], v[24:27], off offset:576
	global_store_dwordx4 v[152:153], v[28:31], off offset:576
	s_cbranch_vccz .LBB0_3531
	s_waitcnt vmcnt(0)
	s_cmpk_gt_u32 s2, 0xff
	s_cbranch_scc1 .LBB0_3546
	s_barrier
